# A/B of the GEMM main loops' per-phase s_setprio flips: all 112 s_setprio removed (timing-only change) on top of the deferred-conversion build
# speedup vs baseline: 1.0190x; 1.0190x over previous
; #define PG8_STAGE(bufoff, gbase, voff) do { _Pragma("unroll") for (int _i = 0; _i < 2; ++_i) \
;         __builtin_amdgcn_global_load_lds((const unsigned*)((const char*)(gbase) + (voff)[_i]), (LAS unsigned*)(lds + (bufoff) + ldsw + _i * 8192), 16, 0, 0); } while (0)
; #define PG8_LDA(dst, b, h) do { _Pragma("unroll") for (int m = 0; m < 4; ++m) _Pragma("unroll") for (int k = 0; k < 2; ++k) dst[m][k] = *(const LAS bf16x8*)(lds + PG8_SA(b, h) + aoff + m * 2048 + k * 1024); } while (0)
; #define PG8_LDB(dst, b, h) do { _Pragma("unroll") for (int n = 0; n < 2; ++n) _Pragma("unroll") for (int k = 0; k < 2; ++k) dst[n][k] = *(const LAS bf16x8*)(lds + PG8_SB(b, h) + boff + n * 2048 + k * 1024); } while (0)
; #define PG8_MMA(ai, bj, At, Bt) do { __builtin_amdgcn_s_setprio(1); _Pragma("unroll") for (int m = 0; m < 4; ++m) _Pragma("unroll") for (int n = 0; n < 2; ++n) _Pragma("unroll") for (int k = 0; k < 2; ++k) \
;         acc[ai][bj][m][n] = __builtin_amdgcn_mfma_f32_16x16x32_bf16(Bt[n][k], At[m][k], acc[ai][bj][m][n], 0, 0, 0); __builtin_amdgcn_s_setprio(0); } while (0)
; #define PG8_WAIT_L(n) asm volatile("s_waitcnt lgkmcnt(" #n ")" ::: "memory")
; #define PG8_BAR __builtin_amdgcn_s_barrier()
; #define PG8_SCHED __builtin_amdgcn_sched_barrier(0)
; template <class Epi, class Sched>
; __device__ __forceinline__ void gemm_phase(LAS unsigned char* lds, const Gemm g, const Sched& S, const Epi& E) {
;     ...
;             PG8_LDB(B0, 0, 0); PG8_SCHED; PG8_LDA(At, 0, 0); PG8_STAGE(PG8_SA(1, 1), a1 + hstepA, voffA);
;             PG8_WAIT_L(8); PG8_BAR; PG8_WAIT_L(0); PG8_MMA(0, 0, At, B0); PG8_BAR; PG8_SCHED;
;             PG8_LDB(B1, 0, 1); PG8_STAGE(PG8_SB(0, 0), b2, voffB);
;             PG8_BAR; PG8_WAIT_L(0); PG8_MMA(0, 1, At, B1); PG8_BAR;
;             PG8_LDA(At, 0, 1); PG8_STAGE(PG8_SA(0, 0), a2, voffA);
;             PG8_BAR; PG8_WAIT_L(0); PG8_MMA(1, 0, At, B0); PG8_BAR; PG8_SCHED;
.LBB0_197:
	s_add_u32 s54, s52, 0xfff80080
	s_addc_u32 s55, s53, -1
	s_add_i32 s67, 0, 0x10000
	v_add_u32_e32 v146, s67, v139
	ds_read_b128 v[170:173], v146
	ds_read_b128 v[174:177], v146 offset:1024
	ds_read_b128 v[178:181], v146 offset:2048
	ds_read_b128 v[182:185], v146 offset:3072
	s_cmp_eq_u32 s66, 28
	s_cselect_b32 s57, s37, s55
	s_cselect_b32 s56, s51, s54
	s_cselect_b32 s55, s1, vcc_hi
	s_cselect_b32 s54, s93, vcc_lo
	v_lshl_add_u64 v[146:147], s[52:53], 0, v[142:143]
	s_add_i32 m0, s26, 0xc000
	ds_read_b128 v[186:189], v150
	ds_read_b128 v[190:193], v150 offset:1024
	ds_read_b128 v[194:197], v150 offset:2048
	ds_read_b128 v[210:213], v150 offset:3072
	ds_read_b128 v[214:217], v150 offset:4096
	ds_read_b128 v[218:221], v150 offset:5120
	ds_read_b128 v[222:225], v150 offset:6144
	ds_read_b128 v[226:229], v150 offset:7168
	global_load_lds_dwordx4 v[146:147], off
	v_lshl_add_u64 v[146:147], s[52:53], 0, v[144:145]
	s_add_i32 m0, s26, 0xe000
	s_nop 0
	global_load_lds_dwordx4 v[146:147], off
	s_waitcnt lgkmcnt(8)
	s_barrier
	s_waitcnt lgkmcnt(0)
	s_waitcnt lgkmcnt(0)
	v_mfma_f32_16x16x32_bf16 v[126:129], v[170:173], v[186:189], v[126:129]
	v_mfma_f32_16x16x32_bf16 v[122:125], v[178:181], v[186:189], v[122:125]
	v_mfma_f32_16x16x32_bf16 v[110:113], v[170:173], v[194:197], v[110:113]
	v_mfma_f32_16x16x32_bf16 v[106:109], v[178:181], v[194:197], v[106:109]
	v_mfma_f32_16x16x32_bf16 v[94:97], v[170:173], v[214:217], v[94:97]
	v_mfma_f32_16x16x32_bf16 v[90:93], v[178:181], v[214:217], v[90:93]
	v_mfma_f32_16x16x32_bf16 v[78:81], v[170:173], v[222:225], v[78:81]
	v_mfma_f32_16x16x32_bf16 v[74:77], v[178:181], v[222:225], v[74:77]
	v_mfma_f32_16x16x32_bf16 v[126:129], v[174:177], v[190:193], v[126:129]
	v_mfma_f32_16x16x32_bf16 v[122:125], v[182:185], v[190:193], v[122:125]
	v_mfma_f32_16x16x32_bf16 v[110:113], v[174:177], v[210:213], v[110:113]
	v_mfma_f32_16x16x32_bf16 v[106:109], v[182:185], v[210:213], v[106:109]
	v_mfma_f32_16x16x32_bf16 v[94:97], v[174:177], v[218:221], v[94:97]
	v_mfma_f32_16x16x32_bf16 v[90:93], v[182:185], v[218:221], v[90:93]
	v_mfma_f32_16x16x32_bf16 v[78:81], v[174:177], v[226:229], v[78:81]
	v_mfma_f32_16x16x32_bf16 v[74:77], v[182:185], v[226:229], v[74:77]
	s_barrier
	s_add_i32 s23, 0, 0x14000
	v_add_u32_e32 v146, s23, v139
	s_add_i32 s67, s67, s25
	ds_read_b128 v[230:233], v146
	ds_read_b128 v[234:237], v146 offset:1024
	ds_read_b128 v[238:241], v146 offset:2048
	ds_read_b128 v[242:245], v146 offset:3072
	v_lshl_add_u64 v[146:147], s[54:55], 0, v[132:133]
	s_mov_b32 m0, s67
	v_lshl_add_u64 v[152:153], s[54:55], 0, v[136:137]
	global_load_lds_dwordx4 v[146:147], off
	s_add_i32 m0, s67, 0x2000
	s_nop 0
	global_load_lds_dwordx4 v[152:153], off
	s_barrier
	s_waitcnt lgkmcnt(0)
	s_waitcnt lgkmcnt(0)
	v_mfma_f32_16x16x32_bf16 v[118:121], v[230:233], v[186:189], v[118:121]
	v_mfma_f32_16x16x32_bf16 v[114:117], v[238:241], v[186:189], v[114:117]
	v_mfma_f32_16x16x32_bf16 v[102:105], v[230:233], v[194:197], v[102:105]
	v_mfma_f32_16x16x32_bf16 v[98:101], v[238:241], v[194:197], v[98:101]
	v_mfma_f32_16x16x32_bf16 v[86:89], v[230:233], v[214:217], v[86:89]
	v_mfma_f32_16x16x32_bf16 v[82:85], v[238:241], v[214:217], v[82:85]
	v_mfma_f32_16x16x32_bf16 v[70:73], v[230:233], v[222:225], v[70:73]
	v_mfma_f32_16x16x32_bf16 v[66:69], v[238:241], v[222:225], v[66:69]
	v_mfma_f32_16x16x32_bf16 v[118:121], v[234:237], v[190:193], v[118:121]
	v_mfma_f32_16x16x32_bf16 v[114:117], v[242:245], v[190:193], v[114:117]
	v_mfma_f32_16x16x32_bf16 v[102:105], v[234:237], v[210:213], v[102:105]
	v_mfma_f32_16x16x32_bf16 v[98:101], v[242:245], v[210:213], v[98:101]
	v_mfma_f32_16x16x32_bf16 v[86:89], v[234:237], v[218:221], v[86:89]
	v_mfma_f32_16x16x32_bf16 v[82:85], v[242:245], v[218:221], v[82:85]
	v_mfma_f32_16x16x32_bf16 v[70:73], v[234:237], v[226:229], v[70:73]
	v_mfma_f32_16x16x32_bf16 v[66:69], v[242:245], v[226:229], v[66:69]
	s_mov_b32 m0, s26
	v_lshl_add_u64 v[198:199], s[56:57], 0, v[130:131]
	s_barrier
	ds_read_b128 v[186:189], v150 offset:16384
	ds_read_b128 v[190:193], v150 offset:17408
	ds_read_b128 v[194:197], v150 offset:18432
	ds_read_b128 v[210:213], v150 offset:19456
	ds_read_b128 v[214:217], v150 offset:20480
	ds_read_b128 v[218:221], v150 offset:21504
	ds_read_b128 v[222:225], v150 offset:22528
	ds_read_b128 v[226:229], v150 offset:23552
	global_load_lds_dwordx4 v[198:199], off
	v_lshl_add_u64 v[246:247], s[56:57], 0, v[134:135]
	s_mov_b32 m0, s27
	s_nop 0
	global_load_lds_dwordx4 v[246:247], off
	s_barrier
	s_waitcnt lgkmcnt(0)
	s_waitcnt lgkmcnt(0)
	v_mfma_f32_16x16x32_bf16 v[62:65], v[170:173], v[186:189], v[62:65]
	v_mfma_f32_16x16x32_bf16 v[58:61], v[178:181], v[186:189], v[58:61]
	v_mfma_f32_16x16x32_bf16 v[46:49], v[170:173], v[194:197], v[46:49]
	v_mfma_f32_16x16x32_bf16 v[42:45], v[178:181], v[194:197], v[42:45]
	v_mfma_f32_16x16x32_bf16 v[30:33], v[170:173], v[214:217], v[30:33]
	v_mfma_f32_16x16x32_bf16 v[26:29], v[178:181], v[214:217], v[26:29]
	v_mfma_f32_16x16x32_bf16 v[14:17], v[170:173], v[222:225], v[14:17]
	v_mfma_f32_16x16x32_bf16 v[10:13], v[178:181], v[222:225], v[10:13]
	v_mfma_f32_16x16x32_bf16 v[62:65], v[174:177], v[190:193], v[62:65]
	v_mfma_f32_16x16x32_bf16 v[58:61], v[182:185], v[190:193], v[58:61]
	v_mfma_f32_16x16x32_bf16 v[46:49], v[174:177], v[210:213], v[46:49]
	v_mfma_f32_16x16x32_bf16 v[42:45], v[182:185], v[210:213], v[42:45]
	v_mfma_f32_16x16x32_bf16 v[30:33], v[174:177], v[218:221], v[30:33]
	v_mfma_f32_16x16x32_bf16 v[26:29], v[182:185], v[218:221], v[26:29]
	v_mfma_f32_16x16x32_bf16 v[14:17], v[174:177], v[226:229], v[14:17]
	v_mfma_f32_16x16x32_bf16 v[10:13], v[182:185], v[226:229], v[10:13]
	s_barrier
; #define PG8_STAGE(bufoff, gbase, voff) do { _Pragma("unroll") for (int _i = 0; _i < 2; ++_i) \
;         __builtin_amdgcn_global_load_lds((const unsigned*)((const char*)(gbase) + (voff)[_i]), (LAS unsigned*)(lds + (bufoff) + ldsw + _i * 8192), 16, 0, 0); } while (0)
; #define PG8_LDA(dst, b, h) do { _Pragma("unroll") for (int m = 0; m < 4; ++m) _Pragma("unroll") for (int k = 0; k < 2; ++k) dst[m][k] = *(const LAS bf16x8*)(lds + PG8_SA(b, h) + aoff + m * 2048 + k * 1024); } while (0)
; #define PG8_LDB(dst, b, h) do { _Pragma("unroll") for (int n = 0; n < 2; ++n) _Pragma("unroll") for (int k = 0; k < 2; ++k) dst[n][k] = *(const LAS bf16x8*)(lds + PG8_SB(b, h) + boff + n * 2048 + k * 1024); } while (0)
; #define PG8_MMA(ai, bj, At, Bt) do { __builtin_amdgcn_s_setprio(1); _Pragma("unroll") for (int m = 0; m < 4; ++m) _Pragma("unroll") for (int n = 0; n < 2; ++n) _Pragma("unroll") for (int k = 0; k < 2; ++k) \
;         acc[ai][bj][m][n] = __builtin_amdgcn_mfma_f32_16x16x32_bf16(Bt[n][k], At[m][k], acc[ai][bj][m][n], 0, 0, 0); __builtin_amdgcn_s_setprio(0); } while (0)
; #define PG8_WAIT_V(n) asm volatile("s_waitcnt vmcnt(" #n ")" ::: "memory")
; #define PG8_WAIT_L(n) asm volatile("s_waitcnt lgkmcnt(" #n ")" ::: "memory")
; #define PG8_BAR __builtin_amdgcn_s_barrier()
; #define PG8_SCHED __builtin_amdgcn_sched_barrier(0)
; template <class Epi, class Sched>
; __device__ __forceinline__ void gemm_phase(LAS unsigned char* lds, const Gemm g, const Sched& S, const Epi& E) {
;     ...
;             PG8_STAGE(PG8_SB(0, 1), b2 + hstepB, voffB);
;             PG8_WAIT_V(6); PG8_BAR; PG8_MMA(1, 1, At, B1); PG8_BAR;
;             PG8_LDB(B0, 1, 0); PG8_SCHED; PG8_LDA(At, 1, 0); PG8_STAGE(PG8_SA(0, 1), a2 + hstepA, voffA);
;             PG8_WAIT_L(8); PG8_BAR; PG8_WAIT_L(0); PG8_MMA(0, 0, At, B0); PG8_BAR; PG8_SCHED;
;             PG8_LDB(B1, 1, 1); PG8_STAGE(PG8_SB(1, 0), b3, voffB);
	s_add_u32 s84, s54, 0x80000
	s_addc_u32 s85, s55, 0
	s_add_i32 s23, s23, s25
	v_lshl_add_u64 v[170:171], s[84:85], 0, v[132:133]
	s_mov_b32 m0, s23
	s_nop 0
	global_load_lds_dwordx4 v[170:171], off
	v_lshl_add_u64 v[170:171], s[84:85], 0, v[136:137]
	s_add_i32 m0, s23, 0x2000
	s_nop 0
	global_load_lds_dwordx4 v[170:171], off
	s_waitcnt vmcnt(6)
	s_barrier
	v_mfma_f32_16x16x32_bf16 v[54:57], v[230:233], v[186:189], v[54:57]
	v_mfma_f32_16x16x32_bf16 v[50:53], v[238:241], v[186:189], v[50:53]
	v_mfma_f32_16x16x32_bf16 v[38:41], v[230:233], v[194:197], v[38:41]
	v_mfma_f32_16x16x32_bf16 v[34:37], v[238:241], v[194:197], v[34:37]
	v_mfma_f32_16x16x32_bf16 v[22:25], v[230:233], v[214:217], v[22:25]
	v_mfma_f32_16x16x32_bf16 v[18:21], v[238:241], v[214:217], v[18:21]
	v_mfma_f32_16x16x32_bf16 v[6:9], v[230:233], v[222:225], v[6:9]
	v_mfma_f32_16x16x32_bf16 v[2:5], v[238:241], v[222:225], v[2:5]
	v_mfma_f32_16x16x32_bf16 v[54:57], v[234:237], v[190:193], v[54:57]
	v_mfma_f32_16x16x32_bf16 v[50:53], v[242:245], v[190:193], v[50:53]
	v_mfma_f32_16x16x32_bf16 v[38:41], v[234:237], v[210:213], v[38:41]
	v_mfma_f32_16x16x32_bf16 v[34:37], v[242:245], v[210:213], v[34:37]
	v_mfma_f32_16x16x32_bf16 v[22:25], v[234:237], v[218:221], v[22:25]
	v_mfma_f32_16x16x32_bf16 v[18:21], v[242:245], v[218:221], v[18:21]
	v_mfma_f32_16x16x32_bf16 v[6:9], v[234:237], v[226:229], v[6:9]
	v_mfma_f32_16x16x32_bf16 v[2:5], v[242:245], v[226:229], v[2:5]
	s_add_i32 s23, 0, 0x18000
	v_add_u32_e32 v151, s23, v139
	s_barrier
	ds_read_b128 v[170:173], v151
	ds_read_b128 v[174:177], v151 offset:1024
	ds_read_b128 v[178:181], v151 offset:2048
	ds_read_b128 v[182:185], v151 offset:3072
	s_add_u32 s56, s56, 0x80000
	s_addc_u32 s57, s57, 0
	s_mov_b32 m0, s28
	v_lshl_add_u64 v[230:231], s[56:57], 0, v[130:131]
	ds_read_b128 v[186:189], v150 offset:32768
	ds_read_b128 v[190:193], v150 offset:33792
	ds_read_b128 v[194:197], v150 offset:34816
	ds_read_b128 v[210:213], v150 offset:35840
	ds_read_b128 v[214:217], v150 offset:36864
	ds_read_b128 v[218:221], v150 offset:37888
	ds_read_b128 v[222:225], v150 offset:38912
	ds_read_b128 v[226:229], v150 offset:39936
	global_load_lds_dwordx4 v[230:231], off
	v_lshl_add_u64 v[230:231], s[56:57], 0, v[134:135]
	s_mov_b32 m0, s29
	s_nop 0
	global_load_lds_dwordx4 v[230:231], off
	s_waitcnt lgkmcnt(8)
	s_barrier
	s_waitcnt lgkmcnt(0)
	s_waitcnt lgkmcnt(0)
	v_mfma_f32_16x16x32_bf16 v[126:129], v[170:173], v[186:189], v[126:129]
	v_mfma_f32_16x16x32_bf16 v[122:125], v[178:181], v[186:189], v[122:125]
	v_mfma_f32_16x16x32_bf16 v[110:113], v[170:173], v[194:197], v[110:113]
	v_mfma_f32_16x16x32_bf16 v[106:109], v[178:181], v[194:197], v[106:109]
	v_mfma_f32_16x16x32_bf16 v[94:97], v[170:173], v[214:217], v[94:97]
	v_mfma_f32_16x16x32_bf16 v[90:93], v[178:181], v[214:217], v[90:93]
	v_mfma_f32_16x16x32_bf16 v[78:81], v[170:173], v[222:225], v[78:81]
	v_mfma_f32_16x16x32_bf16 v[74:77], v[178:181], v[222:225], v[74:77]
	v_mfma_f32_16x16x32_bf16 v[126:129], v[174:177], v[190:193], v[126:129]
	v_mfma_f32_16x16x32_bf16 v[122:125], v[182:185], v[190:193], v[122:125]
	v_mfma_f32_16x16x32_bf16 v[110:113], v[174:177], v[210:213], v[110:113]
	v_mfma_f32_16x16x32_bf16 v[106:109], v[182:185], v[210:213], v[106:109]
	v_mfma_f32_16x16x32_bf16 v[94:97], v[174:177], v[218:221], v[94:97]
	v_mfma_f32_16x16x32_bf16 v[90:93], v[182:185], v[218:221], v[90:93]
	v_mfma_f32_16x16x32_bf16 v[78:81], v[174:177], v[226:229], v[78:81]
	v_mfma_f32_16x16x32_bf16 v[74:77], v[182:185], v[226:229], v[74:77]
	s_barrier
	s_add_i32 s56, 0, 0x1c000
	s_add_i32 s23, s23, s25
	v_add_u32_e32 v151, s56, v139
	v_lshl_add_u64 v[146:147], v[146:147], 0, s[10:11]
	s_mov_b32 m0, s23
	ds_read_b128 v[230:233], v151
	ds_read_b128 v[234:237], v151 offset:1024
	ds_read_b128 v[238:241], v151 offset:2048
	ds_read_b128 v[242:245], v151 offset:3072
	global_load_lds_dwordx4 v[146:147], off
	v_lshl_add_u64 v[146:147], v[152:153], 0, s[10:11]
	s_add_i32 m0, s23, 0x2000
	s_nop 0
	global_load_lds_dwordx4 v[146:147], off
	s_barrier
; #define PG8_STAGE(bufoff, gbase, voff) do { _Pragma("unroll") for (int _i = 0; _i < 2; ++_i) \
;         __builtin_amdgcn_global_load_lds((const unsigned*)((const char*)(gbase) + (voff)[_i]), (LAS unsigned*)(lds + (bufoff) + ldsw + _i * 8192), 16, 0, 0); } while (0)
; #define PG8_LDA(dst, b, h) do { _Pragma("unroll") for (int m = 0; m < 4; ++m) _Pragma("unroll") for (int k = 0; k < 2; ++k) dst[m][k] = *(const LAS bf16x8*)(lds + PG8_SA(b, h) + aoff + m * 2048 + k * 1024); } while (0)
; #define PG8_MMA(ai, bj, At, Bt) do { __builtin_amdgcn_s_setprio(1); _Pragma("unroll") for (int m = 0; m < 4; ++m) _Pragma("unroll") for (int n = 0; n < 2; ++n) _Pragma("unroll") for (int k = 0; k < 2; ++k) \
;         acc[ai][bj][m][n] = __builtin_amdgcn_mfma_f32_16x16x32_bf16(Bt[n][k], At[m][k], acc[ai][bj][m][n], 0, 0, 0); __builtin_amdgcn_s_setprio(0); } while (0)
; #define PG8_WAIT_V(n) asm volatile("s_waitcnt vmcnt(" #n ")" ::: "memory")
; #define PG8_WAIT_L(n) asm volatile("s_waitcnt lgkmcnt(" #n ")" ::: "memory")
; #define PG8_BAR __builtin_amdgcn_s_barrier()
; #define PG8_SCHED __builtin_amdgcn_sched_barrier(0)
;     __device__ __forceinline__ void operator()(const f32x4 (&acc)[2][2][4][2], const Unit& u, int ui, const LAS float* rtab, int wr, int wc, int fr, int fq) const {
;         const int row0 = u.pm * BM + wr * 64 + fr; const int colt = u.pn * BM; const int t = colt >> shift; const int lc0 = (colt & ((1 << shift) - 1)) + wc * 32 + 8 * fq;
;         bf16_t* base = (t == 0) ? Q : ((t == 1) ? K : V);
; template <class Epi, class Sched>
; __device__ __forceinline__ void gemm_phase(LAS unsigned char* lds, const Gemm g, const Sched& S, const Epi& E) {
;     ...
;             PG8_BAR; PG8_WAIT_L(0); PG8_MMA(0, 1, At, B1); PG8_BAR;
;             PG8_LDA(At, 1, 1); PG8_STAGE(PG8_SA(1, 0), a3, voffA);
;             PG8_BAR; PG8_WAIT_L(0); PG8_MMA(1, 0, At, B0); PG8_BAR; PG8_SCHED;
;             PG8_STAGE(PG8_SB(1, 1), b3 + hstepB, voffB);
;             PG8_WAIT_V(6); PG8_BAR; PG8_MMA(1, 1, At, B1); PG8_BAR;
;         }
	s_waitcnt lgkmcnt(0)
	s_waitcnt lgkmcnt(0)
	v_mfma_f32_16x16x32_bf16 v[118:121], v[230:233], v[186:189], v[118:121]
	v_mfma_f32_16x16x32_bf16 v[114:117], v[238:241], v[186:189], v[114:117]
	v_mfma_f32_16x16x32_bf16 v[102:105], v[230:233], v[194:197], v[102:105]
	v_mfma_f32_16x16x32_bf16 v[98:101], v[238:241], v[194:197], v[98:101]
	v_mfma_f32_16x16x32_bf16 v[86:89], v[230:233], v[214:217], v[86:89]
	v_mfma_f32_16x16x32_bf16 v[82:85], v[238:241], v[214:217], v[82:85]
	v_mfma_f32_16x16x32_bf16 v[70:73], v[230:233], v[222:225], v[70:73]
	v_mfma_f32_16x16x32_bf16 v[66:69], v[238:241], v[222:225], v[66:69]
	v_mfma_f32_16x16x32_bf16 v[118:121], v[234:237], v[190:193], v[118:121]
	v_mfma_f32_16x16x32_bf16 v[114:117], v[242:245], v[190:193], v[114:117]
	v_mfma_f32_16x16x32_bf16 v[102:105], v[234:237], v[210:213], v[102:105]
	v_mfma_f32_16x16x32_bf16 v[98:101], v[242:245], v[210:213], v[98:101]
	v_mfma_f32_16x16x32_bf16 v[86:89], v[234:237], v[218:221], v[86:89]
	v_mfma_f32_16x16x32_bf16 v[82:85], v[242:245], v[218:221], v[82:85]
	v_mfma_f32_16x16x32_bf16 v[70:73], v[234:237], v[226:229], v[70:73]
	v_mfma_f32_16x16x32_bf16 v[66:69], v[242:245], v[226:229], v[66:69]
	s_mov_b32 m0, s35
	v_lshl_add_u64 v[146:147], v[198:199], 0, s[10:11]
	s_barrier
	ds_read_b128 v[186:189], v150 offset:49152
	ds_read_b128 v[190:193], v150 offset:50176
	ds_read_b128 v[194:197], v150 offset:51200
	ds_read_b128 v[210:213], v150 offset:52224
	ds_read_b128 v[214:217], v150 offset:53248
	ds_read_b128 v[218:221], v150 offset:54272
	ds_read_b128 v[222:225], v150 offset:55296
	ds_read_b128 v[226:229], v150 offset:56320
	global_load_lds_dwordx4 v[146:147], off
	v_lshl_add_u64 v[146:147], v[246:247], 0, s[10:11]
	s_mov_b32 m0, s45
	s_nop 0
	global_load_lds_dwordx4 v[146:147], off
	s_barrier
	s_waitcnt lgkmcnt(0)
	s_waitcnt lgkmcnt(0)
	v_mfma_f32_16x16x32_bf16 v[62:65], v[170:173], v[186:189], v[62:65]
	v_mfma_f32_16x16x32_bf16 v[58:61], v[178:181], v[186:189], v[58:61]
	v_mfma_f32_16x16x32_bf16 v[46:49], v[170:173], v[194:197], v[46:49]
	v_mfma_f32_16x16x32_bf16 v[42:45], v[178:181], v[194:197], v[42:45]
	v_mfma_f32_16x16x32_bf16 v[30:33], v[170:173], v[214:217], v[30:33]
	v_mfma_f32_16x16x32_bf16 v[26:29], v[178:181], v[214:217], v[26:29]
	v_mfma_f32_16x16x32_bf16 v[14:17], v[170:173], v[222:225], v[14:17]
	v_mfma_f32_16x16x32_bf16 v[10:13], v[178:181], v[222:225], v[10:13]
	v_mfma_f32_16x16x32_bf16 v[62:65], v[174:177], v[190:193], v[62:65]
	v_mfma_f32_16x16x32_bf16 v[58:61], v[182:185], v[190:193], v[58:61]
	v_mfma_f32_16x16x32_bf16 v[46:49], v[174:177], v[210:213], v[46:49]
	v_mfma_f32_16x16x32_bf16 v[42:45], v[182:185], v[210:213], v[42:45]
	v_mfma_f32_16x16x32_bf16 v[30:33], v[174:177], v[218:221], v[30:33]
	v_mfma_f32_16x16x32_bf16 v[26:29], v[182:185], v[218:221], v[26:29]
	v_mfma_f32_16x16x32_bf16 v[14:17], v[174:177], v[226:229], v[14:17]
	v_mfma_f32_16x16x32_bf16 v[10:13], v[182:185], v[226:229], v[10:13]
	s_barrier
	s_add_u32 s54, s54, 0x80080
	s_addc_u32 s55, s55, 0
	s_add_i32 s23, s56, s25
	v_lshl_add_u64 v[146:147], s[54:55], 0, v[132:133]
	s_mov_b32 m0, s23
	s_nop 0
	global_load_lds_dwordx4 v[146:147], off
	v_lshl_add_u64 v[146:147], s[54:55], 0, v[136:137]
	s_add_i32 m0, s23, 0x2000
	s_nop 0
	global_load_lds_dwordx4 v[146:147], off
	s_waitcnt vmcnt(6)
	s_barrier
	v_mfma_f32_16x16x32_bf16 v[54:57], v[230:233], v[186:189], v[54:57]
	v_mfma_f32_16x16x32_bf16 v[50:53], v[238:241], v[186:189], v[50:53]
	v_mfma_f32_16x16x32_bf16 v[38:41], v[230:233], v[194:197], v[38:41]
	v_mfma_f32_16x16x32_bf16 v[34:37], v[238:241], v[194:197], v[34:37]
	v_mfma_f32_16x16x32_bf16 v[22:25], v[230:233], v[214:217], v[22:25]
	v_mfma_f32_16x16x32_bf16 v[18:21], v[238:241], v[214:217], v[18:21]
	v_mfma_f32_16x16x32_bf16 v[6:9], v[230:233], v[222:225], v[6:9]
	v_mfma_f32_16x16x32_bf16 v[2:5], v[238:241], v[222:225], v[2:5]
	v_mfma_f32_16x16x32_bf16 v[54:57], v[234:237], v[190:193], v[54:57]
	v_mfma_f32_16x16x32_bf16 v[50:53], v[242:245], v[190:193], v[50:53]
	v_mfma_f32_16x16x32_bf16 v[38:41], v[234:237], v[210:213], v[38:41]
	v_mfma_f32_16x16x32_bf16 v[34:37], v[242:245], v[210:213], v[34:37]
	v_mfma_f32_16x16x32_bf16 v[22:25], v[234:237], v[218:221], v[22:25]
	v_mfma_f32_16x16x32_bf16 v[18:21], v[242:245], v[218:221], v[18:21]
	v_mfma_f32_16x16x32_bf16 v[6:9], v[234:237], v[226:229], v[6:9]
	v_mfma_f32_16x16x32_bf16 v[2:5], v[242:245], v[226:229], v[2:5]
	s_add_i32 s66, s66, 2
	s_add_u32 s52, s52, 0x100
	s_addc_u32 s53, s53, 0
	s_add_u32 vcc_lo, vcc_lo, 0x100
	s_addc_u32 vcc_hi, vcc_hi, 0
	s_cmp_gt_u32 s66, 29
	s_barrier
	s_cbranch_scc0 .LBB0_197
	s_lshl_b32 s37, s50, 8
	s_ashr_i32 s1, s37, s31
	s_cmp_lt_i32 s1, 1
	s_cbranch_scc1 .LBB0_202
	s_cmp_eq_u32 s1, 1
	s_mov_b64 s[52:53], -1
	s_cbranch_scc0 .LBB0_201
	s_mov_b64 s[52:53], 0

; #define PG8_STAGE(bufoff, gbase, voff) do { _Pragma("unroll") for (int _i = 0; _i < 2; ++_i) \
;         __builtin_amdgcn_global_load_lds((const unsigned*)((const char*)(gbase) + (voff)[_i]), (LAS unsigned*)(lds + (bufoff) + ldsw + _i * 8192), 16, 0, 0); } while (0)
; #define PG8_LDA(dst, b, h) do { _Pragma("unroll") for (int m = 0; m < 4; ++m) _Pragma("unroll") for (int k = 0; k < 2; ++k) dst[m][k] = *(const LAS bf16x8*)(lds + PG8_SA(b, h) + aoff + m * 2048 + k * 1024); } while (0)
; #define PG8_LDB(dst, b, h) do { _Pragma("unroll") for (int n = 0; n < 2; ++n) _Pragma("unroll") for (int k = 0; k < 2; ++k) dst[n][k] = *(const LAS bf16x8*)(lds + PG8_SB(b, h) + boff + n * 2048 + k * 1024); } while (0)
; #define PG8_MMA(ai, bj, At, Bt) do { __builtin_amdgcn_s_setprio(1); _Pragma("unroll") for (int m = 0; m < 4; ++m) _Pragma("unroll") for (int n = 0; n < 2; ++n) _Pragma("unroll") for (int k = 0; k < 2; ++k) \
;         acc[ai][bj][m][n] = __builtin_amdgcn_mfma_f32_16x16x32_bf16(Bt[n][k], At[m][k], acc[ai][bj][m][n], 0, 0, 0); __builtin_amdgcn_s_setprio(0); } while (0)
; #define PG8_WAIT_L(n) asm volatile("s_waitcnt lgkmcnt(" #n ")" ::: "memory")
; #define PG8_BAR __builtin_amdgcn_s_barrier()
; #define PG8_SCHED __builtin_amdgcn_sched_barrier(0)
; template <class Epi, class Sched>
; __device__ __forceinline__ void gemm_phase(LAS unsigned char* lds, const Gemm g, const Sched& S, const Epi& E) {
;     ...
;             PG8_LDB(B0, 0, 0); PG8_SCHED; PG8_LDA(At, 0, 0); PG8_STAGE(PG8_SA(1, 1), a1 + hstepA, voffA);
;             PG8_WAIT_L(8); PG8_BAR; PG8_WAIT_L(0); PG8_MMA(0, 0, At, B0); PG8_BAR; PG8_SCHED;
;             PG8_LDB(B1, 0, 1); PG8_STAGE(PG8_SB(0, 0), b2, voffB);
;             PG8_BAR; PG8_WAIT_L(0); PG8_MMA(0, 1, At, B1); PG8_BAR;
;             PG8_LDA(At, 0, 1); PG8_STAGE(PG8_SA(0, 0), a2, voffA);
;             PG8_BAR; PG8_WAIT_L(0); PG8_MMA(1, 0, At, B0); PG8_BAR; PG8_SCHED;
.LBB0_580:
	s_add_u32 s42, s40, 0x100
	s_addc_u32 s43, s41, 0
	s_add_i32 s24, 0, 0x10000
	v_add_u32_e32 v162, s24, v144
	ds_read_b128 v[146:149], v162
	ds_read_b128 v[150:153], v162 offset:1024
	ds_read_b128 v[170:173], v162 offset:2048
	ds_read_b128 v[174:177], v162 offset:3072
	s_cmp_eq_u32 s58, 4
	s_cselect_b32 s47, s1, s43
	s_cselect_b32 s46, s0, s42
	s_cselect_b32 s45, s54, s57
	s_cselect_b32 s44, s55, s56
	v_lshl_add_u64 v[198:199], s[40:41], 0, v[140:141]
	s_add_i32 m0, s28, 0xc000
	ds_read_b128 v[178:181], v145
	ds_read_b128 v[182:185], v145 offset:1024
	ds_read_b128 v[186:189], v145 offset:2048
	ds_read_b128 v[190:193], v145 offset:3072
	ds_read_b128 v[194:197], v145 offset:4096
	ds_read_b128 v[210:213], v145 offset:5120
	ds_read_b128 v[214:217], v145 offset:6144
	ds_read_b128 v[218:221], v145 offset:7168
	global_load_lds_dwordx4 v[198:199], off
	v_lshl_add_u64 v[198:199], s[40:41], 0, v[142:143]
	s_add_i32 m0, s28, 0xe000
	s_nop 0
	global_load_lds_dwordx4 v[198:199], off
	s_waitcnt lgkmcnt(8)
	s_barrier
	s_waitcnt lgkmcnt(0)
	s_waitcnt lgkmcnt(0)
	v_mfma_f32_16x16x32_bf16 v[126:129], v[146:149], v[178:181], v[126:129]
	v_mfma_f32_16x16x32_bf16 v[122:125], v[170:173], v[178:181], v[122:125]
	v_mfma_f32_16x16x32_bf16 v[118:121], v[146:149], v[186:189], v[118:121]
	v_mfma_f32_16x16x32_bf16 v[114:117], v[170:173], v[186:189], v[114:117]
	v_mfma_f32_16x16x32_bf16 v[106:109], v[146:149], v[194:197], v[106:109]
	v_mfma_f32_16x16x32_bf16 v[98:101], v[170:173], v[194:197], v[98:101]
	v_mfma_f32_16x16x32_bf16 v[90:93], v[146:149], v[214:217], v[90:93]
	v_mfma_f32_16x16x32_bf16 v[82:85], v[170:173], v[214:217], v[82:85]
	v_mfma_f32_16x16x32_bf16 v[126:129], v[150:153], v[182:185], v[126:129]
	v_mfma_f32_16x16x32_bf16 v[122:125], v[174:177], v[182:185], v[122:125]
	v_mfma_f32_16x16x32_bf16 v[118:121], v[150:153], v[190:193], v[118:121]
	v_mfma_f32_16x16x32_bf16 v[114:117], v[174:177], v[190:193], v[114:117]
	v_mfma_f32_16x16x32_bf16 v[106:109], v[150:153], v[210:213], v[106:109]
	v_mfma_f32_16x16x32_bf16 v[98:101], v[174:177], v[210:213], v[98:101]
	v_mfma_f32_16x16x32_bf16 v[90:93], v[150:153], v[218:221], v[90:93]
	v_mfma_f32_16x16x32_bf16 v[82:85], v[174:177], v[218:221], v[82:85]
	s_barrier
	s_add_i32 s25, 0, 0x14000
	s_add_i32 s23, s24, s26
	v_add_u32_e32 v162, s25, v144
	v_lshl_add_u64 v[198:199], s[44:45], 0, v[134:135]
	s_mov_b32 m0, s23
	ds_read_b128 v[222:225], v162
	ds_read_b128 v[226:229], v162 offset:1024
	ds_read_b128 v[230:233], v162 offset:2048
	ds_read_b128 v[234:237], v162 offset:3072
	global_load_lds_dwordx4 v[198:199], off
	v_lshl_add_u64 v[238:239], s[44:45], 0, v[130:131]
	s_add_i32 m0, s23, 0x2000
	s_nop 0
	global_load_lds_dwordx4 v[238:239], off
	s_barrier
	s_waitcnt lgkmcnt(0)
	s_waitcnt lgkmcnt(0)
	v_mfma_f32_16x16x32_bf16 v[110:113], v[222:225], v[178:181], v[110:113]
	v_mfma_f32_16x16x32_bf16 v[102:105], v[230:233], v[178:181], v[102:105]
	v_mfma_f32_16x16x32_bf16 v[94:97], v[222:225], v[186:189], v[94:97]
	v_mfma_f32_16x16x32_bf16 v[86:89], v[230:233], v[186:189], v[86:89]
	v_mfma_f32_16x16x32_bf16 v[78:81], v[222:225], v[194:197], v[78:81]
	v_mfma_f32_16x16x32_bf16 v[74:77], v[230:233], v[194:197], v[74:77]
	v_mfma_f32_16x16x32_bf16 v[70:73], v[222:225], v[214:217], v[70:73]
	v_mfma_f32_16x16x32_bf16 v[66:69], v[230:233], v[214:217], v[66:69]
	v_mfma_f32_16x16x32_bf16 v[110:113], v[226:229], v[182:185], v[110:113]
	v_mfma_f32_16x16x32_bf16 v[102:105], v[234:237], v[182:185], v[102:105]
	v_mfma_f32_16x16x32_bf16 v[94:97], v[226:229], v[190:193], v[94:97]
	v_mfma_f32_16x16x32_bf16 v[86:89], v[234:237], v[190:193], v[86:89]
	v_mfma_f32_16x16x32_bf16 v[78:81], v[226:229], v[210:213], v[78:81]
	v_mfma_f32_16x16x32_bf16 v[74:77], v[234:237], v[210:213], v[74:77]
	v_mfma_f32_16x16x32_bf16 v[70:73], v[226:229], v[218:221], v[70:73]
	v_mfma_f32_16x16x32_bf16 v[66:69], v[234:237], v[218:221], v[66:69]
	s_mov_b32 m0, s28
	v_lshl_add_u64 v[240:241], s[46:47], 0, v[136:137]
	s_barrier
	ds_read_b128 v[178:181], v145 offset:16384
	ds_read_b128 v[182:185], v145 offset:17408
	ds_read_b128 v[186:189], v145 offset:18432
	ds_read_b128 v[190:193], v145 offset:19456
	ds_read_b128 v[194:197], v145 offset:20480
	ds_read_b128 v[210:213], v145 offset:21504
	ds_read_b128 v[214:217], v145 offset:22528
	ds_read_b128 v[218:221], v145 offset:23552
	global_load_lds_dwordx4 v[240:241], off
	v_lshl_add_u64 v[242:243], s[46:47], 0, v[132:133]
	s_mov_b32 m0, s29
	s_nop 0
	global_load_lds_dwordx4 v[242:243], off
	s_barrier
	s_waitcnt lgkmcnt(0)
	s_waitcnt lgkmcnt(0)
	v_mfma_f32_16x16x32_bf16 v[62:65], v[146:149], v[178:181], v[62:65]
	v_mfma_f32_16x16x32_bf16 v[58:61], v[170:173], v[178:181], v[58:61]
	v_mfma_f32_16x16x32_bf16 v[54:57], v[146:149], v[186:189], v[54:57]
	v_mfma_f32_16x16x32_bf16 v[50:53], v[170:173], v[186:189], v[50:53]
	v_mfma_f32_16x16x32_bf16 v[38:41], v[146:149], v[194:197], v[38:41]
	v_mfma_f32_16x16x32_bf16 v[34:37], v[170:173], v[194:197], v[34:37]
	v_mfma_f32_16x16x32_bf16 v[22:25], v[146:149], v[214:217], v[22:25]
	v_mfma_f32_16x16x32_bf16 v[18:21], v[170:173], v[214:217], v[18:21]
	v_mfma_f32_16x16x32_bf16 v[62:65], v[150:153], v[182:185], v[62:65]
	v_mfma_f32_16x16x32_bf16 v[58:61], v[174:177], v[182:185], v[58:61]
	v_mfma_f32_16x16x32_bf16 v[54:57], v[150:153], v[190:193], v[54:57]
	v_mfma_f32_16x16x32_bf16 v[50:53], v[174:177], v[190:193], v[50:53]
	v_mfma_f32_16x16x32_bf16 v[38:41], v[150:153], v[210:213], v[38:41]
	v_mfma_f32_16x16x32_bf16 v[34:37], v[174:177], v[210:213], v[34:37]
	v_mfma_f32_16x16x32_bf16 v[22:25], v[150:153], v[218:221], v[22:25]
	v_mfma_f32_16x16x32_bf16 v[18:21], v[174:177], v[218:221], v[18:21]
	s_barrier
; #define PG8_STAGE(bufoff, gbase, voff) do { _Pragma("unroll") for (int _i = 0; _i < 2; ++_i) \
;         __builtin_amdgcn_global_load_lds((const unsigned*)((const char*)(gbase) + (voff)[_i]), (LAS unsigned*)(lds + (bufoff) + ldsw + _i * 8192), 16, 0, 0); } while (0)
; #define PG8_LDA(dst, b, h) do { _Pragma("unroll") for (int m = 0; m < 4; ++m) _Pragma("unroll") for (int k = 0; k < 2; ++k) dst[m][k] = *(const LAS bf16x8*)(lds + PG8_SA(b, h) + aoff + m * 2048 + k * 1024); } while (0)
; #define PG8_LDB(dst, b, h) do { _Pragma("unroll") for (int n = 0; n < 2; ++n) _Pragma("unroll") for (int k = 0; k < 2; ++k) dst[n][k] = *(const LAS bf16x8*)(lds + PG8_SB(b, h) + boff + n * 2048 + k * 1024); } while (0)
; #define PG8_MMA(ai, bj, At, Bt) do { __builtin_amdgcn_s_setprio(1); _Pragma("unroll") for (int m = 0; m < 4; ++m) _Pragma("unroll") for (int n = 0; n < 2; ++n) _Pragma("unroll") for (int k = 0; k < 2; ++k) \
;         acc[ai][bj][m][n] = __builtin_amdgcn_mfma_f32_16x16x32_bf16(Bt[n][k], At[m][k], acc[ai][bj][m][n], 0, 0, 0); __builtin_amdgcn_s_setprio(0); } while (0)
; #define PG8_WAIT_V(n) asm volatile("s_waitcnt vmcnt(" #n ")" ::: "memory")
; #define PG8_WAIT_L(n) asm volatile("s_waitcnt lgkmcnt(" #n ")" ::: "memory")
; #define PG8_BAR __builtin_amdgcn_s_barrier()
; #define PG8_SCHED __builtin_amdgcn_sched_barrier(0)
; template <class Epi, class Sched>
; __device__ __forceinline__ void gemm_phase(LAS unsigned char* lds, const Gemm g, const Sched& S, const Epi& E) {
;     ...
;             PG8_STAGE(PG8_SB(0, 1), b2 + hstepB, voffB);
;             PG8_WAIT_V(6); PG8_BAR; PG8_MMA(1, 1, At, B1); PG8_BAR;
;             PG8_LDB(B0, 1, 0); PG8_SCHED; PG8_LDA(At, 1, 0); PG8_STAGE(PG8_SA(0, 1), a2 + hstepA, voffA);
;             PG8_WAIT_L(8); PG8_BAR; PG8_WAIT_L(0); PG8_MMA(0, 0, At, B0); PG8_BAR; PG8_SCHED;
;             PG8_LDB(B1, 1, 1); PG8_STAGE(PG8_SB(1, 0), b3, voffB);
	s_add_u32 s40, s44, 0x20000
	s_addc_u32 s41, s45, 0
	s_add_i32 s23, s25, s26
	v_lshl_add_u64 v[146:147], s[40:41], 0, v[134:135]
	s_mov_b32 m0, s23
	s_nop 0
	global_load_lds_dwordx4 v[146:147], off
	v_lshl_add_u64 v[146:147], s[40:41], 0, v[130:131]
	s_add_i32 m0, s23, 0x2000
	s_nop 0
	global_load_lds_dwordx4 v[146:147], off
	s_waitcnt vmcnt(6)
	s_barrier
	v_mfma_f32_16x16x32_bf16 v[46:49], v[222:225], v[178:181], v[46:49]
	v_mfma_f32_16x16x32_bf16 v[42:45], v[230:233], v[178:181], v[42:45]
	v_mfma_f32_16x16x32_bf16 v[30:33], v[222:225], v[186:189], v[30:33]
	v_mfma_f32_16x16x32_bf16 v[26:29], v[230:233], v[186:189], v[26:29]
	v_mfma_f32_16x16x32_bf16 v[14:17], v[222:225], v[194:197], v[14:17]
	v_mfma_f32_16x16x32_bf16 v[10:13], v[230:233], v[194:197], v[10:13]
	v_mfma_f32_16x16x32_bf16 v[6:9], v[222:225], v[214:217], v[6:9]
	v_mfma_f32_16x16x32_bf16 v[2:5], v[230:233], v[214:217], v[2:5]
	v_mfma_f32_16x16x32_bf16 v[46:49], v[226:229], v[182:185], v[46:49]
	v_mfma_f32_16x16x32_bf16 v[42:45], v[234:237], v[182:185], v[42:45]
	v_mfma_f32_16x16x32_bf16 v[30:33], v[226:229], v[190:193], v[30:33]
	v_mfma_f32_16x16x32_bf16 v[26:29], v[234:237], v[190:193], v[26:29]
	v_mfma_f32_16x16x32_bf16 v[14:17], v[226:229], v[210:213], v[14:17]
	v_mfma_f32_16x16x32_bf16 v[10:13], v[234:237], v[210:213], v[10:13]
	v_mfma_f32_16x16x32_bf16 v[6:9], v[226:229], v[218:221], v[6:9]
	v_mfma_f32_16x16x32_bf16 v[2:5], v[234:237], v[218:221], v[2:5]
	s_add_i32 s27, 0, 0x18000
	v_add_u32_e32 v162, s27, v144
	s_barrier
	ds_read_b128 v[146:149], v162
	ds_read_b128 v[150:153], v162 offset:1024
	ds_read_b128 v[170:173], v162 offset:2048
	ds_read_b128 v[174:177], v162 offset:3072
	s_add_u32 s40, s46, 0x30000
	s_addc_u32 s41, s47, 0
	s_mov_b32 m0, s35
	v_lshl_add_u64 v[222:223], s[40:41], 0, v[136:137]
	ds_read_b128 v[178:181], v145 offset:32768
	ds_read_b128 v[182:185], v145 offset:33792
	ds_read_b128 v[186:189], v145 offset:34816
	ds_read_b128 v[190:193], v145 offset:35840
	ds_read_b128 v[194:197], v145 offset:36864
	ds_read_b128 v[210:213], v145 offset:37888
	ds_read_b128 v[214:217], v145 offset:38912
	ds_read_b128 v[218:221], v145 offset:39936
	global_load_lds_dwordx4 v[222:223], off
	v_lshl_add_u64 v[222:223], s[40:41], 0, v[132:133]
	s_mov_b32 m0, s48
	s_nop 0
	global_load_lds_dwordx4 v[222:223], off
	s_waitcnt lgkmcnt(8)
	s_barrier
	s_waitcnt lgkmcnt(0)
	s_waitcnt lgkmcnt(0)
	v_mfma_f32_16x16x32_bf16 v[126:129], v[146:149], v[178:181], v[126:129]
	v_mfma_f32_16x16x32_bf16 v[122:125], v[170:173], v[178:181], v[122:125]
	v_mfma_f32_16x16x32_bf16 v[118:121], v[146:149], v[186:189], v[118:121]
	v_mfma_f32_16x16x32_bf16 v[114:117], v[170:173], v[186:189], v[114:117]
	v_mfma_f32_16x16x32_bf16 v[106:109], v[146:149], v[194:197], v[106:109]
	v_mfma_f32_16x16x32_bf16 v[98:101], v[170:173], v[194:197], v[98:101]
	v_mfma_f32_16x16x32_bf16 v[90:93], v[146:149], v[214:217], v[90:93]
	v_mfma_f32_16x16x32_bf16 v[82:85], v[170:173], v[214:217], v[82:85]
	v_mfma_f32_16x16x32_bf16 v[126:129], v[150:153], v[182:185], v[126:129]
	v_mfma_f32_16x16x32_bf16 v[122:125], v[174:177], v[182:185], v[122:125]
	v_mfma_f32_16x16x32_bf16 v[118:121], v[150:153], v[190:193], v[118:121]
	v_mfma_f32_16x16x32_bf16 v[114:117], v[174:177], v[190:193], v[114:117]
	v_mfma_f32_16x16x32_bf16 v[106:109], v[150:153], v[210:213], v[106:109]
	v_mfma_f32_16x16x32_bf16 v[98:101], v[174:177], v[210:213], v[98:101]
	v_mfma_f32_16x16x32_bf16 v[90:93], v[150:153], v[218:221], v[90:93]
	v_mfma_f32_16x16x32_bf16 v[82:85], v[174:177], v[218:221], v[82:85]
	s_barrier
	s_add_i32 s31, 0, 0x1c000
	s_add_i32 s23, s27, s26
	v_add_u32_e32 v162, s31, v144
	v_lshl_add_u64 v[198:199], v[198:199], 0, s[10:11]
	s_mov_b32 m0, s23
	ds_read_b128 v[222:225], v162
	ds_read_b128 v[226:229], v162 offset:1024
	ds_read_b128 v[230:233], v162 offset:2048
	ds_read_b128 v[234:237], v162 offset:3072
	global_load_lds_dwordx4 v[198:199], off
	v_lshl_add_u64 v[198:199], v[238:239], 0, s[10:11]
	s_add_i32 m0, s23, 0x2000
	s_nop 0
	global_load_lds_dwordx4 v[198:199], off
	s_barrier
; #define PG8_STAGE(bufoff, gbase, voff) do { _Pragma("unroll") for (int _i = 0; _i < 2; ++_i) \
;         __builtin_amdgcn_global_load_lds((const unsigned*)((const char*)(gbase) + (voff)[_i]), (LAS unsigned*)(lds + (bufoff) + ldsw + _i * 8192), 16, 0, 0); } while (0)
; #define PG8_LDA(dst, b, h) do { _Pragma("unroll") for (int m = 0; m < 4; ++m) _Pragma("unroll") for (int k = 0; k < 2; ++k) dst[m][k] = *(const LAS bf16x8*)(lds + PG8_SA(b, h) + aoff + m * 2048 + k * 1024); } while (0)
; #define PG8_MMA(ai, bj, At, Bt) do { __builtin_amdgcn_s_setprio(1); _Pragma("unroll") for (int m = 0; m < 4; ++m) _Pragma("unroll") for (int n = 0; n < 2; ++n) _Pragma("unroll") for (int k = 0; k < 2; ++k) \
;         acc[ai][bj][m][n] = __builtin_amdgcn_mfma_f32_16x16x32_bf16(Bt[n][k], At[m][k], acc[ai][bj][m][n], 0, 0, 0); __builtin_amdgcn_s_setprio(0); } while (0)
; #define PG8_WAIT_V(n) asm volatile("s_waitcnt vmcnt(" #n ")" ::: "memory")
; #define PG8_WAIT_L(n) asm volatile("s_waitcnt lgkmcnt(" #n ")" ::: "memory")
; #define PG8_BAR __builtin_amdgcn_s_barrier()
; #define PG8_SCHED __builtin_amdgcn_sched_barrier(0)
; template <class Epi, class Sched>
; __device__ __forceinline__ void gemm_phase(LAS unsigned char* lds, const Gemm g, const Sched& S, const Epi& E) {
;     ...
;             PG8_BAR; PG8_WAIT_L(0); PG8_MMA(0, 1, At, B1); PG8_BAR;
;             PG8_LDA(At, 1, 1); PG8_STAGE(PG8_SA(1, 0), a3, voffA);
;             PG8_BAR; PG8_WAIT_L(0); PG8_MMA(1, 0, At, B0); PG8_BAR; PG8_SCHED;
;             PG8_STAGE(PG8_SB(1, 1), b3 + hstepB, voffB);
;             PG8_WAIT_V(6); PG8_BAR; PG8_MMA(1, 1, At, B1); PG8_BAR;
;         }
	s_waitcnt lgkmcnt(0)
	s_waitcnt lgkmcnt(0)
	v_mfma_f32_16x16x32_bf16 v[110:113], v[222:225], v[178:181], v[110:113]
	v_mfma_f32_16x16x32_bf16 v[102:105], v[230:233], v[178:181], v[102:105]
	v_mfma_f32_16x16x32_bf16 v[94:97], v[222:225], v[186:189], v[94:97]
	v_mfma_f32_16x16x32_bf16 v[86:89], v[230:233], v[186:189], v[86:89]
	v_mfma_f32_16x16x32_bf16 v[78:81], v[222:225], v[194:197], v[78:81]
	v_mfma_f32_16x16x32_bf16 v[74:77], v[230:233], v[194:197], v[74:77]
	v_mfma_f32_16x16x32_bf16 v[70:73], v[222:225], v[214:217], v[70:73]
	v_mfma_f32_16x16x32_bf16 v[66:69], v[230:233], v[214:217], v[66:69]
	v_mfma_f32_16x16x32_bf16 v[110:113], v[226:229], v[182:185], v[110:113]
	v_mfma_f32_16x16x32_bf16 v[102:105], v[234:237], v[182:185], v[102:105]
	v_mfma_f32_16x16x32_bf16 v[94:97], v[226:229], v[190:193], v[94:97]
	v_mfma_f32_16x16x32_bf16 v[86:89], v[234:237], v[190:193], v[86:89]
	v_mfma_f32_16x16x32_bf16 v[78:81], v[226:229], v[210:213], v[78:81]
	v_mfma_f32_16x16x32_bf16 v[74:77], v[234:237], v[210:213], v[74:77]
	v_mfma_f32_16x16x32_bf16 v[70:73], v[226:229], v[218:221], v[70:73]
	v_mfma_f32_16x16x32_bf16 v[66:69], v[234:237], v[218:221], v[66:69]
	s_mov_b32 m0, s49
	v_lshl_add_u64 v[198:199], v[240:241], 0, s[10:11]
	s_barrier
	ds_read_b128 v[178:181], v145 offset:49152
	ds_read_b128 v[182:185], v145 offset:50176
	ds_read_b128 v[186:189], v145 offset:51200
	ds_read_b128 v[190:193], v145 offset:52224
	ds_read_b128 v[194:197], v145 offset:53248
	ds_read_b128 v[210:213], v145 offset:54272
	ds_read_b128 v[214:217], v145 offset:55296
	ds_read_b128 v[218:221], v145 offset:56320
	global_load_lds_dwordx4 v[198:199], off
	v_lshl_add_u64 v[198:199], v[242:243], 0, s[10:11]
	s_mov_b32 m0, s50
	s_nop 0
	global_load_lds_dwordx4 v[198:199], off
	s_barrier
	s_waitcnt lgkmcnt(0)
	s_waitcnt lgkmcnt(0)
	v_mfma_f32_16x16x32_bf16 v[62:65], v[146:149], v[178:181], v[62:65]
	v_mfma_f32_16x16x32_bf16 v[58:61], v[170:173], v[178:181], v[58:61]
	v_mfma_f32_16x16x32_bf16 v[54:57], v[146:149], v[186:189], v[54:57]
	v_mfma_f32_16x16x32_bf16 v[50:53], v[170:173], v[186:189], v[50:53]
	v_mfma_f32_16x16x32_bf16 v[38:41], v[146:149], v[194:197], v[38:41]
	v_mfma_f32_16x16x32_bf16 v[34:37], v[170:173], v[194:197], v[34:37]
	v_mfma_f32_16x16x32_bf16 v[22:25], v[146:149], v[214:217], v[22:25]
	v_mfma_f32_16x16x32_bf16 v[18:21], v[170:173], v[214:217], v[18:21]
	v_mfma_f32_16x16x32_bf16 v[62:65], v[150:153], v[182:185], v[62:65]
	v_mfma_f32_16x16x32_bf16 v[58:61], v[174:177], v[182:185], v[58:61]
	v_mfma_f32_16x16x32_bf16 v[54:57], v[150:153], v[190:193], v[54:57]
	v_mfma_f32_16x16x32_bf16 v[50:53], v[174:177], v[190:193], v[50:53]
	v_mfma_f32_16x16x32_bf16 v[38:41], v[150:153], v[210:213], v[38:41]
	v_mfma_f32_16x16x32_bf16 v[34:37], v[174:177], v[210:213], v[34:37]
	v_mfma_f32_16x16x32_bf16 v[22:25], v[150:153], v[218:221], v[22:25]
	v_mfma_f32_16x16x32_bf16 v[18:21], v[174:177], v[218:221], v[18:21]
	s_barrier
	s_add_u32 s40, s44, 0x20080
	s_addc_u32 s41, s45, 0
	s_add_i32 s23, s31, s26
	v_lshl_add_u64 v[146:147], s[40:41], 0, v[134:135]
	s_mov_b32 m0, s23
	s_nop 0
	global_load_lds_dwordx4 v[146:147], off
	v_lshl_add_u64 v[146:147], s[40:41], 0, v[130:131]
	s_add_i32 m0, s23, 0x2000
	s_nop 0
	global_load_lds_dwordx4 v[146:147], off
	s_waitcnt vmcnt(6)
	s_barrier
	v_mfma_f32_16x16x32_bf16 v[46:49], v[222:225], v[178:181], v[46:49]
	v_mfma_f32_16x16x32_bf16 v[42:45], v[230:233], v[178:181], v[42:45]
	v_mfma_f32_16x16x32_bf16 v[30:33], v[222:225], v[186:189], v[30:33]
	v_mfma_f32_16x16x32_bf16 v[26:29], v[230:233], v[186:189], v[26:29]
	v_mfma_f32_16x16x32_bf16 v[14:17], v[222:225], v[194:197], v[14:17]
	v_mfma_f32_16x16x32_bf16 v[10:13], v[230:233], v[194:197], v[10:13]
	v_mfma_f32_16x16x32_bf16 v[6:9], v[222:225], v[214:217], v[6:9]
	v_mfma_f32_16x16x32_bf16 v[2:5], v[230:233], v[214:217], v[2:5]
	v_mfma_f32_16x16x32_bf16 v[46:49], v[226:229], v[182:185], v[46:49]
	v_mfma_f32_16x16x32_bf16 v[42:45], v[234:237], v[182:185], v[42:45]
	v_mfma_f32_16x16x32_bf16 v[30:33], v[226:229], v[190:193], v[30:33]
	v_mfma_f32_16x16x32_bf16 v[26:29], v[234:237], v[190:193], v[26:29]
	v_mfma_f32_16x16x32_bf16 v[14:17], v[226:229], v[210:213], v[14:17]
	v_mfma_f32_16x16x32_bf16 v[10:13], v[234:237], v[210:213], v[10:13]
	v_mfma_f32_16x16x32_bf16 v[6:9], v[226:229], v[218:221], v[6:9]
	v_mfma_f32_16x16x32_bf16 v[2:5], v[234:237], v[218:221], v[2:5]
	s_add_i32 s58, s58, 2
	s_add_u32 s56, s56, 0x100
	s_addc_u32 s57, s57, 0
	s_cmp_gt_u32 s58, 5
	s_mov_b64 s[40:41], s[42:43]
	s_barrier
	s_cbranch_scc0 .LBB0_580
	s_mov_b32 s23, 0x20000
	s_mov_b64 s[40:41], 0x20000
	s_mov_b32 s53, s52
	s_mov_b32 s46, s52
	s_mov_b64 s[42:43], s[36:37]
	s_nop 0
	s_nop 1
	s_mov_b32 s23, 0x24000
	s_nop 0
	s_mov_b64 s[40:41], 0x24000
	s_nop 0
	s_mov_b32 s23, 0x28000
	s_nop 0
	s_mov_b64 s[40:41], 0x28000
	s_nop 0
	s_nop 0
	s_mov_b64 s[40:41], 0x2c000
	s_nop 0
	s_nop 0
	s_and_b64 vcc, exec, s[20:21]
	s_mov_b64 s[40:41], s[0:1]
	s_cbranch_vccz .LBB0_577
	s_waitcnt vmcnt(0)
	s_cmpk_gt_u32 s34, 0xff
	s_cbranch_scc1 .LBB0_584
	s_barrier

; #define PG8_STAGE(bufoff, gbase, voff) do { _Pragma("unroll") for (int _i = 0; _i < 2; ++_i) \
;         __builtin_amdgcn_global_load_lds((const unsigned*)((const char*)(gbase) + (voff)[_i]), (LAS unsigned*)(lds + (bufoff) + ldsw + _i * 8192), 16, 0, 0); } while (0)
; #define PG8_LDA(dst, b, h) do { _Pragma("unroll") for (int m = 0; m < 4; ++m) _Pragma("unroll") for (int k = 0; k < 2; ++k) dst[m][k] = *(const LAS bf16x8*)(lds + PG8_SA(b, h) + aoff + m * 2048 + k * 1024); } while (0)
; #define PG8_LDB(dst, b, h) do { _Pragma("unroll") for (int n = 0; n < 2; ++n) _Pragma("unroll") for (int k = 0; k < 2; ++k) dst[n][k] = *(const LAS bf16x8*)(lds + PG8_SB(b, h) + boff + n * 2048 + k * 1024); } while (0)
; #define PG8_MMA(ai, bj, At, Bt) do { __builtin_amdgcn_s_setprio(1); _Pragma("unroll") for (int m = 0; m < 4; ++m) _Pragma("unroll") for (int n = 0; n < 2; ++n) _Pragma("unroll") for (int k = 0; k < 2; ++k) \
;         acc[ai][bj][m][n] = __builtin_amdgcn_mfma_f32_16x16x32_bf16(Bt[n][k], At[m][k], acc[ai][bj][m][n], 0, 0, 0); __builtin_amdgcn_s_setprio(0); } while (0)
; #define PG8_WAIT_L(n) asm volatile("s_waitcnt lgkmcnt(" #n ")" ::: "memory")
; #define PG8_BAR __builtin_amdgcn_s_barrier()
; #define PG8_SCHED __builtin_amdgcn_sched_barrier(0)
; template <class Epi, class Sched>
; __device__ __forceinline__ void gemm_phase(LAS unsigned char* lds, const Gemm g, const Sched& S, const Epi& E) {
;     ...
;             PG8_LDB(B0, 0, 0); PG8_SCHED; PG8_LDA(At, 0, 0); PG8_STAGE(PG8_SA(1, 1), a1 + hstepA, voffA);
;             PG8_WAIT_L(8); PG8_BAR; PG8_WAIT_L(0); PG8_MMA(0, 0, At, B0); PG8_BAR; PG8_SCHED;
;             PG8_LDB(B1, 0, 1); PG8_STAGE(PG8_SB(0, 0), b2, voffB);
;             PG8_BAR; PG8_WAIT_L(0); PG8_MMA(0, 1, At, B1); PG8_BAR;
;             PG8_LDA(At, 0, 1); PG8_STAGE(PG8_SA(0, 0), a2, voffA);
;             PG8_BAR; PG8_WAIT_L(0); PG8_MMA(1, 0, At, B0); PG8_BAR; PG8_SCHED;
.LBB0_595:
	v_add_u32_e32 v144, s24, v1
	ds_read_b128 v[172:175], v144
	ds_read_b128 v[176:179], v144 offset:1024
	ds_read_b128 v[180:183], v144 offset:2048
	ds_read_b128 v[184:187], v144 offset:3072
	s_add_u32 s42, s36, 0x100
	s_addc_u32 s43, s37, 0
	s_cmp_eq_u32 s54, 8
	s_cselect_b32 s47, s21, s43
	s_cselect_b32 s46, s20, s42
	s_cselect_b32 s45, s1, s29
	s_cselect_b32 s44, s0, s28
	v_lshl_add_u64 v[144:145], s[36:37], 0, v[140:141]
	s_add_i32 m0, s34, 0xc000
	ds_read_b128 v[188:191], v170
	ds_read_b128 v[192:195], v170 offset:1024
	ds_read_b128 v[196:199], v170 offset:2048
	ds_read_b128 v[210:213], v170 offset:3072
	ds_read_b128 v[214:217], v170 offset:4096
	ds_read_b128 v[218:221], v170 offset:5120
	ds_read_b128 v[222:225], v170 offset:6144
	ds_read_b128 v[226:229], v170 offset:7168
	global_load_lds_dwordx4 v[144:145], off
	v_lshl_add_u64 v[144:145], s[36:37], 0, v[142:143]
	s_add_i32 m0, s34, 0xe000
	s_nop 0
	global_load_lds_dwordx4 v[144:145], off
	s_waitcnt lgkmcnt(8)
	s_barrier
	s_waitcnt lgkmcnt(0)
	s_waitcnt lgkmcnt(0)
	v_mfma_f32_16x16x32_bf16 v[126:129], v[172:175], v[188:191], v[126:129]
	v_mfma_f32_16x16x32_bf16 v[122:125], v[180:183], v[188:191], v[122:125]
	v_mfma_f32_16x16x32_bf16 v[110:113], v[172:175], v[196:199], v[110:113]
	v_mfma_f32_16x16x32_bf16 v[106:109], v[180:183], v[196:199], v[106:109]
	v_mfma_f32_16x16x32_bf16 v[94:97], v[172:175], v[214:217], v[94:97]
	v_mfma_f32_16x16x32_bf16 v[90:93], v[180:183], v[214:217], v[90:93]
	v_mfma_f32_16x16x32_bf16 v[78:81], v[172:175], v[222:225], v[78:81]
	v_mfma_f32_16x16x32_bf16 v[74:77], v[180:183], v[222:225], v[74:77]
	v_mfma_f32_16x16x32_bf16 v[126:129], v[176:179], v[192:195], v[126:129]
	v_mfma_f32_16x16x32_bf16 v[122:125], v[184:187], v[192:195], v[122:125]
	v_mfma_f32_16x16x32_bf16 v[110:113], v[176:179], v[210:213], v[110:113]
	v_mfma_f32_16x16x32_bf16 v[106:109], v[184:187], v[210:213], v[106:109]
	v_mfma_f32_16x16x32_bf16 v[94:97], v[176:179], v[218:221], v[94:97]
	v_mfma_f32_16x16x32_bf16 v[90:93], v[184:187], v[218:221], v[90:93]
	v_mfma_f32_16x16x32_bf16 v[78:81], v[176:179], v[226:229], v[78:81]
	v_mfma_f32_16x16x32_bf16 v[74:77], v[184:187], v[226:229], v[74:77]
	s_barrier
	v_add_u32_e32 v144, s25, v1
	s_add_i32 s23, s24, s13
	ds_read_b128 v[230:233], v144
	ds_read_b128 v[234:237], v144 offset:1024
	ds_read_b128 v[238:241], v144 offset:2048
	ds_read_b128 v[242:245], v144 offset:3072
	v_lshl_add_u64 v[144:145], s[44:45], 0, v[132:133]
	s_mov_b32 m0, s23
	v_lshl_add_u64 v[246:247], s[44:45], 0, v[136:137]
	global_load_lds_dwordx4 v[144:145], off
	s_add_i32 m0, s23, 0x2000
	s_nop 0
	global_load_lds_dwordx4 v[246:247], off
	s_barrier
	s_waitcnt lgkmcnt(0)
	s_waitcnt lgkmcnt(0)
	v_mfma_f32_16x16x32_bf16 v[118:121], v[230:233], v[188:191], v[118:121]
	v_mfma_f32_16x16x32_bf16 v[114:117], v[238:241], v[188:191], v[114:117]
	v_mfma_f32_16x16x32_bf16 v[102:105], v[230:233], v[196:199], v[102:105]
	v_mfma_f32_16x16x32_bf16 v[98:101], v[238:241], v[196:199], v[98:101]
	v_mfma_f32_16x16x32_bf16 v[86:89], v[230:233], v[214:217], v[86:89]
	v_mfma_f32_16x16x32_bf16 v[82:85], v[238:241], v[214:217], v[82:85]
	v_mfma_f32_16x16x32_bf16 v[70:73], v[230:233], v[222:225], v[70:73]
	v_mfma_f32_16x16x32_bf16 v[66:69], v[238:241], v[222:225], v[66:69]
	v_mfma_f32_16x16x32_bf16 v[118:121], v[234:237], v[192:195], v[118:121]
	v_mfma_f32_16x16x32_bf16 v[114:117], v[242:245], v[192:195], v[114:117]
	v_mfma_f32_16x16x32_bf16 v[102:105], v[234:237], v[210:213], v[102:105]
	v_mfma_f32_16x16x32_bf16 v[98:101], v[242:245], v[210:213], v[98:101]
	v_mfma_f32_16x16x32_bf16 v[86:89], v[234:237], v[218:221], v[86:89]
	v_mfma_f32_16x16x32_bf16 v[82:85], v[242:245], v[218:221], v[82:85]
	v_mfma_f32_16x16x32_bf16 v[70:73], v[234:237], v[226:229], v[70:73]
	v_mfma_f32_16x16x32_bf16 v[66:69], v[242:245], v[226:229], v[66:69]
	s_mov_b32 m0, s34
	v_lshl_add_u64 v[248:249], s[46:47], 0, v[130:131]
	s_barrier
	ds_read_b128 v[188:191], v170 offset:16384
	ds_read_b128 v[192:195], v170 offset:17408
	ds_read_b128 v[196:199], v170 offset:18432
	ds_read_b128 v[210:213], v170 offset:19456
	ds_read_b128 v[214:217], v170 offset:20480
	ds_read_b128 v[218:221], v170 offset:21504
	ds_read_b128 v[222:225], v170 offset:22528
	ds_read_b128 v[226:229], v170 offset:23552
	global_load_lds_dwordx4 v[248:249], off
	v_lshl_add_u64 v[250:251], s[46:47], 0, v[134:135]
	s_mov_b32 m0, s35
	s_nop 0
	global_load_lds_dwordx4 v[250:251], off
	s_barrier
	s_waitcnt lgkmcnt(0)
	s_waitcnt lgkmcnt(0)
	v_mfma_f32_16x16x32_bf16 v[62:65], v[172:175], v[188:191], v[62:65]
	v_mfma_f32_16x16x32_bf16 v[58:61], v[180:183], v[188:191], v[58:61]
	v_mfma_f32_16x16x32_bf16 v[46:49], v[172:175], v[196:199], v[46:49]
	v_mfma_f32_16x16x32_bf16 v[42:45], v[180:183], v[196:199], v[42:45]
	v_mfma_f32_16x16x32_bf16 v[30:33], v[172:175], v[214:217], v[30:33]
	v_mfma_f32_16x16x32_bf16 v[26:29], v[180:183], v[214:217], v[26:29]
	v_mfma_f32_16x16x32_bf16 v[14:17], v[172:175], v[222:225], v[14:17]
	v_mfma_f32_16x16x32_bf16 v[10:13], v[180:183], v[222:225], v[10:13]
	v_mfma_f32_16x16x32_bf16 v[62:65], v[176:179], v[192:195], v[62:65]
	v_mfma_f32_16x16x32_bf16 v[58:61], v[184:187], v[192:195], v[58:61]
	v_mfma_f32_16x16x32_bf16 v[46:49], v[176:179], v[210:213], v[46:49]
	v_mfma_f32_16x16x32_bf16 v[42:45], v[184:187], v[210:213], v[42:45]
	v_mfma_f32_16x16x32_bf16 v[30:33], v[176:179], v[218:221], v[30:33]
	v_mfma_f32_16x16x32_bf16 v[26:29], v[184:187], v[218:221], v[26:29]
	v_mfma_f32_16x16x32_bf16 v[14:17], v[176:179], v[226:229], v[14:17]
	v_mfma_f32_16x16x32_bf16 v[10:13], v[184:187], v[226:229], v[10:13]
	s_barrier
; #define PG8_STAGE(bufoff, gbase, voff) do { _Pragma("unroll") for (int _i = 0; _i < 2; ++_i) \
;         __builtin_amdgcn_global_load_lds((const unsigned*)((const char*)(gbase) + (voff)[_i]), (LAS unsigned*)(lds + (bufoff) + ldsw + _i * 8192), 16, 0, 0); } while (0)
; #define PG8_LDA(dst, b, h) do { _Pragma("unroll") for (int m = 0; m < 4; ++m) _Pragma("unroll") for (int k = 0; k < 2; ++k) dst[m][k] = *(const LAS bf16x8*)(lds + PG8_SA(b, h) + aoff + m * 2048 + k * 1024); } while (0)
; #define PG8_LDB(dst, b, h) do { _Pragma("unroll") for (int n = 0; n < 2; ++n) _Pragma("unroll") for (int k = 0; k < 2; ++k) dst[n][k] = *(const LAS bf16x8*)(lds + PG8_SB(b, h) + boff + n * 2048 + k * 1024); } while (0)
; #define PG8_MMA(ai, bj, At, Bt) do { __builtin_amdgcn_s_setprio(1); _Pragma("unroll") for (int m = 0; m < 4; ++m) _Pragma("unroll") for (int n = 0; n < 2; ++n) _Pragma("unroll") for (int k = 0; k < 2; ++k) \
;         acc[ai][bj][m][n] = __builtin_amdgcn_mfma_f32_16x16x32_bf16(Bt[n][k], At[m][k], acc[ai][bj][m][n], 0, 0, 0); __builtin_amdgcn_s_setprio(0); } while (0)
; #define PG8_WAIT_V(n) asm volatile("s_waitcnt vmcnt(" #n ")" ::: "memory")
; #define PG8_WAIT_L(n) asm volatile("s_waitcnt lgkmcnt(" #n ")" ::: "memory")
; #define PG8_BAR __builtin_amdgcn_s_barrier()
; #define PG8_SCHED __builtin_amdgcn_sched_barrier(0)
; template <class Epi, class Sched>
; __device__ __forceinline__ void gemm_phase(LAS unsigned char* lds, const Gemm g, const Sched& S, const Epi& E) {
;     ...
;             PG8_STAGE(PG8_SB(0, 1), b2 + hstepB, voffB);
;             PG8_WAIT_V(6); PG8_BAR; PG8_MMA(1, 1, At, B1); PG8_BAR;
;             PG8_LDB(B0, 1, 0); PG8_SCHED; PG8_LDA(At, 1, 0); PG8_STAGE(PG8_SA(0, 1), a2 + hstepA, voffA);
;             PG8_WAIT_L(8); PG8_BAR; PG8_WAIT_L(0); PG8_MMA(0, 0, At, B0); PG8_BAR; PG8_SCHED;
;             PG8_LDB(B1, 1, 1); PG8_STAGE(PG8_SB(1, 0), b3, voffB);
;             PG8_BAR; PG8_WAIT_L(0); PG8_MMA(0, 1, At, B1); PG8_BAR;
;             PG8_LDA(At, 1, 1); PG8_STAGE(PG8_SA(1, 0), a3, voffA);
	s_add_u32 s36, s44, 0x30000
	s_addc_u32 s37, s45, 0
	s_add_i32 s23, s25, s13
	v_lshl_add_u64 v[172:173], s[36:37], 0, v[132:133]
	s_mov_b32 m0, s23
	s_nop 0
	global_load_lds_dwordx4 v[172:173], off
	v_lshl_add_u64 v[172:173], s[36:37], 0, v[136:137]
	s_add_i32 m0, s23, 0x2000
	s_nop 0
	global_load_lds_dwordx4 v[172:173], off
	s_waitcnt vmcnt(6)
	s_barrier
	v_mfma_f32_16x16x32_bf16 v[54:57], v[230:233], v[188:191], v[54:57]
	v_mfma_f32_16x16x32_bf16 v[50:53], v[238:241], v[188:191], v[50:53]
	v_mfma_f32_16x16x32_bf16 v[38:41], v[230:233], v[196:199], v[38:41]
	v_mfma_f32_16x16x32_bf16 v[34:37], v[238:241], v[196:199], v[34:37]
	v_mfma_f32_16x16x32_bf16 v[22:25], v[230:233], v[214:217], v[22:25]
	v_mfma_f32_16x16x32_bf16 v[18:21], v[238:241], v[214:217], v[18:21]
	v_mfma_f32_16x16x32_bf16 v[6:9], v[230:233], v[222:225], v[6:9]
	v_mfma_f32_16x16x32_bf16 v[2:5], v[238:241], v[222:225], v[2:5]
	v_mfma_f32_16x16x32_bf16 v[54:57], v[234:237], v[192:195], v[54:57]
	v_mfma_f32_16x16x32_bf16 v[50:53], v[242:245], v[192:195], v[50:53]
	v_mfma_f32_16x16x32_bf16 v[38:41], v[234:237], v[210:213], v[38:41]
	v_mfma_f32_16x16x32_bf16 v[34:37], v[242:245], v[210:213], v[34:37]
	v_mfma_f32_16x16x32_bf16 v[22:25], v[234:237], v[218:221], v[22:25]
	v_mfma_f32_16x16x32_bf16 v[18:21], v[242:245], v[218:221], v[18:21]
	v_mfma_f32_16x16x32_bf16 v[6:9], v[234:237], v[226:229], v[6:9]
	v_mfma_f32_16x16x32_bf16 v[2:5], v[242:245], v[226:229], v[2:5]
	v_add_u32_e32 v171, s27, v1
	s_barrier
	ds_read_b128 v[172:175], v171
	ds_read_b128 v[176:179], v171 offset:1024
	ds_read_b128 v[180:183], v171 offset:2048
	ds_read_b128 v[184:187], v171 offset:3072
	s_add_u32 s36, s46, 0x30000
	s_addc_u32 s37, s47, 0
	s_mov_b32 m0, s48
	v_lshl_add_u64 v[230:231], s[36:37], 0, v[130:131]
	ds_read_b128 v[188:191], v170 offset:32768
	ds_read_b128 v[192:195], v170 offset:33792
	ds_read_b128 v[196:199], v170 offset:34816
	ds_read_b128 v[210:213], v170 offset:35840
	ds_read_b128 v[214:217], v170 offset:36864
	ds_read_b128 v[218:221], v170 offset:37888
	ds_read_b128 v[222:225], v170 offset:38912
	ds_read_b128 v[226:229], v170 offset:39936
	global_load_lds_dwordx4 v[230:231], off
	v_lshl_add_u64 v[230:231], s[36:37], 0, v[134:135]
	s_mov_b32 m0, s49
	s_nop 0
	global_load_lds_dwordx4 v[230:231], off
	s_waitcnt lgkmcnt(8)
	s_barrier
	s_waitcnt lgkmcnt(0)
	s_waitcnt lgkmcnt(0)
	v_mfma_f32_16x16x32_bf16 v[126:129], v[172:175], v[188:191], v[126:129]
	v_mfma_f32_16x16x32_bf16 v[122:125], v[180:183], v[188:191], v[122:125]
	v_mfma_f32_16x16x32_bf16 v[110:113], v[172:175], v[196:199], v[110:113]
	v_mfma_f32_16x16x32_bf16 v[106:109], v[180:183], v[196:199], v[106:109]
	v_mfma_f32_16x16x32_bf16 v[94:97], v[172:175], v[214:217], v[94:97]
	v_mfma_f32_16x16x32_bf16 v[90:93], v[180:183], v[214:217], v[90:93]
	v_mfma_f32_16x16x32_bf16 v[78:81], v[172:175], v[222:225], v[78:81]
	v_mfma_f32_16x16x32_bf16 v[74:77], v[180:183], v[222:225], v[74:77]
	v_mfma_f32_16x16x32_bf16 v[126:129], v[176:179], v[192:195], v[126:129]
	v_mfma_f32_16x16x32_bf16 v[122:125], v[184:187], v[192:195], v[122:125]
	v_mfma_f32_16x16x32_bf16 v[110:113], v[176:179], v[210:213], v[110:113]
	v_mfma_f32_16x16x32_bf16 v[106:109], v[184:187], v[210:213], v[106:109]
	v_mfma_f32_16x16x32_bf16 v[94:97], v[176:179], v[218:221], v[94:97]
	v_mfma_f32_16x16x32_bf16 v[90:93], v[184:187], v[218:221], v[90:93]
	v_mfma_f32_16x16x32_bf16 v[78:81], v[176:179], v[226:229], v[78:81]
	v_mfma_f32_16x16x32_bf16 v[74:77], v[184:187], v[226:229], v[74:77]
	s_barrier
	s_add_i32 s23, s27, s13
	v_add_u32_e32 v171, s31, v1
	v_lshl_add_u64 v[144:145], v[144:145], 0, s[10:11]
	s_mov_b32 m0, s23
	ds_read_b128 v[230:233], v171
	ds_read_b128 v[234:237], v171 offset:1024
	ds_read_b128 v[238:241], v171 offset:2048
	ds_read_b128 v[242:245], v171 offset:3072
	global_load_lds_dwordx4 v[144:145], off
	v_lshl_add_u64 v[144:145], v[246:247], 0, s[10:11]
	s_add_i32 m0, s23, 0x2000
	s_nop 0
	global_load_lds_dwordx4 v[144:145], off
	s_barrier
	s_waitcnt lgkmcnt(0)
	s_waitcnt lgkmcnt(0)
	v_mfma_f32_16x16x32_bf16 v[118:121], v[230:233], v[188:191], v[118:121]
	v_mfma_f32_16x16x32_bf16 v[114:117], v[238:241], v[188:191], v[114:117]
	v_mfma_f32_16x16x32_bf16 v[102:105], v[230:233], v[196:199], v[102:105]
	v_mfma_f32_16x16x32_bf16 v[98:101], v[238:241], v[196:199], v[98:101]
	v_mfma_f32_16x16x32_bf16 v[86:89], v[230:233], v[214:217], v[86:89]
	v_mfma_f32_16x16x32_bf16 v[82:85], v[238:241], v[214:217], v[82:85]
	v_mfma_f32_16x16x32_bf16 v[70:73], v[230:233], v[222:225], v[70:73]
	v_mfma_f32_16x16x32_bf16 v[66:69], v[238:241], v[222:225], v[66:69]
	v_mfma_f32_16x16x32_bf16 v[118:121], v[234:237], v[192:195], v[118:121]
	v_mfma_f32_16x16x32_bf16 v[114:117], v[242:245], v[192:195], v[114:117]
	v_mfma_f32_16x16x32_bf16 v[102:105], v[234:237], v[210:213], v[102:105]
	v_mfma_f32_16x16x32_bf16 v[98:101], v[242:245], v[210:213], v[98:101]
	v_mfma_f32_16x16x32_bf16 v[86:89], v[234:237], v[218:221], v[86:89]
	v_mfma_f32_16x16x32_bf16 v[82:85], v[242:245], v[218:221], v[82:85]
	v_mfma_f32_16x16x32_bf16 v[70:73], v[234:237], v[226:229], v[70:73]
	v_mfma_f32_16x16x32_bf16 v[66:69], v[242:245], v[226:229], v[66:69]
	s_mov_b32 m0, s50
	v_lshl_add_u64 v[144:145], v[248:249], 0, s[10:11]
	s_barrier
	ds_read_b128 v[188:191], v170 offset:49152
	ds_read_b128 v[192:195], v170 offset:50176
	ds_read_b128 v[196:199], v170 offset:51200
	ds_read_b128 v[210:213], v170 offset:52224
	ds_read_b128 v[214:217], v170 offset:53248
	ds_read_b128 v[218:221], v170 offset:54272
	ds_read_b128 v[222:225], v170 offset:55296
	ds_read_b128 v[226:229], v170 offset:56320
	global_load_lds_dwordx4 v[144:145], off
	v_lshl_add_u64 v[144:145], v[250:251], 0, s[10:11]
	s_mov_b32 m0, s51
	s_nop 0
	global_load_lds_dwordx4 v[144:145], off
	s_barrier
; #define LAS __attribute__((address_space(3)))
; __device__ __forceinline__ unsigned cvt_pk_bf16(float lo, float hi) { unsigned r; asm volatile("v_cvt_pk_bf16_f32 %0, %1, %2" : "=v"(r) : "v"(lo), "v"(hi)); return r; }
; __device__ __forceinline__ float gelu_tanh(float x) { const float z = 0.7978845608f * (x + 0.044715f * x * x * x); const float th = 1.0f - 2.0f / (__expf(2.0f * z) + 1.0f); return 0.5f * x * (1.0f + th); }
; #define PG8_STAGE(bufoff, gbase, voff) do { _Pragma("unroll") for (int _i = 0; _i < 2; ++_i) \
;         __builtin_amdgcn_global_load_lds((const unsigned*)((const char*)(gbase) + (voff)[_i]), (LAS unsigned*)(lds + (bufoff) + ldsw + _i * 8192), 16, 0, 0); } while (0)
; #define PG8_WAIT_V(n) asm volatile("s_waitcnt vmcnt(" #n ")" ::: "memory")
; #define PG8_WAIT_L(n) asm volatile("s_waitcnt lgkmcnt(" #n ")" ::: "memory")
; #define PG8_BAR __builtin_amdgcn_s_barrier()
; #define PG8_SCHED __builtin_amdgcn_sched_barrier(0)
;     __device__ __forceinline__ void operator()(const f32x4 (&acc)[2][2][4][2], const Unit& u, int ui, const LAS float* rtab, int wr, int wc, int fr, int fq) const {
;         const int g = u.pm; const int n0 = wr * 64 + fr; const int lc0 = (u.pn & 1) * 256 + wc * 32 + 8 * fq;
; #pragma unroll
;         for (int ai = 0; ai < 2; ++ai)
; #pragma unroll
;             for (int m = 0; m < 4; ++m) {
;                 const int n = n0 + ai * HALF + m * 16;
; #pragma unroll
;                 for (int bj = 0; bj < 2; ++bj) {
;                     const int lc = lc0 + bj * HALF, t = lc >> 4, co = lc & 15; const int token = n * 32 + t;
;                     const f32x4 a0 = acc[ai][bj][m][0], a1 = acc[ai][bj][m][1];
;                     u32x4 w; w.x = cvt_pk_bf16(gelu_tanh(a0[0]), gelu_tanh(a0[1])); w.y = cvt_pk_bf16(gelu_tanh(a0[2]), gelu_tanh(a0[3]));
;                     w.z = cvt_pk_bf16(gelu_tanh(a1[0]), gelu_tanh(a1[1])); w.w = cvt_pk_bf16(gelu_tanh(a1[2]), gelu_tanh(a1[3]));
;                     *(u32x4*)(Y + (size_t)token * 1024 + 16 * g + co) = w;
; template <class Epi, class Sched>
; __device__ __forceinline__ void gemm_phase(LAS unsigned char* lds, const Gemm g, const Sched& S, const Epi& E) {
;     ...
;             PG8_BAR; PG8_WAIT_L(0); PG8_MMA(1, 0, At, B0); PG8_BAR; PG8_SCHED;
;             PG8_STAGE(PG8_SB(1, 1), b3 + hstepB, voffB);
;             PG8_WAIT_V(6); PG8_BAR; PG8_MMA(1, 1, At, B1); PG8_BAR;
	s_waitcnt lgkmcnt(0)
	s_waitcnt lgkmcnt(0)
	v_mfma_f32_16x16x32_bf16 v[62:65], v[172:175], v[188:191], v[62:65]
	v_mfma_f32_16x16x32_bf16 v[58:61], v[180:183], v[188:191], v[58:61]
	v_mfma_f32_16x16x32_bf16 v[46:49], v[172:175], v[196:199], v[46:49]
	v_mfma_f32_16x16x32_bf16 v[42:45], v[180:183], v[196:199], v[42:45]
	v_mfma_f32_16x16x32_bf16 v[30:33], v[172:175], v[214:217], v[30:33]
	v_mfma_f32_16x16x32_bf16 v[26:29], v[180:183], v[214:217], v[26:29]
	v_mfma_f32_16x16x32_bf16 v[14:17], v[172:175], v[222:225], v[14:17]
	v_mfma_f32_16x16x32_bf16 v[10:13], v[180:183], v[222:225], v[10:13]
	v_mfma_f32_16x16x32_bf16 v[62:65], v[176:179], v[192:195], v[62:65]
	v_mfma_f32_16x16x32_bf16 v[58:61], v[184:187], v[192:195], v[58:61]
	v_mfma_f32_16x16x32_bf16 v[46:49], v[176:179], v[210:213], v[46:49]
	v_mfma_f32_16x16x32_bf16 v[42:45], v[184:187], v[210:213], v[42:45]
	v_mfma_f32_16x16x32_bf16 v[30:33], v[176:179], v[218:221], v[30:33]
	v_mfma_f32_16x16x32_bf16 v[26:29], v[184:187], v[218:221], v[26:29]
	v_mfma_f32_16x16x32_bf16 v[14:17], v[176:179], v[226:229], v[14:17]
	v_mfma_f32_16x16x32_bf16 v[10:13], v[184:187], v[226:229], v[10:13]
	s_barrier
	s_add_u32 s36, s44, 0x30080
	s_addc_u32 s37, s45, 0
	s_add_i32 s23, s31, s13
	v_lshl_add_u64 v[144:145], s[36:37], 0, v[132:133]
	s_mov_b32 m0, s23
	s_nop 0
	global_load_lds_dwordx4 v[144:145], off
	v_lshl_add_u64 v[144:145], s[36:37], 0, v[136:137]
	s_add_i32 m0, s23, 0x2000
	s_nop 0
	global_load_lds_dwordx4 v[144:145], off
	s_waitcnt vmcnt(6)
	s_barrier
	v_mfma_f32_16x16x32_bf16 v[54:57], v[230:233], v[188:191], v[54:57]
	v_mfma_f32_16x16x32_bf16 v[50:53], v[238:241], v[188:191], v[50:53]
	v_mfma_f32_16x16x32_bf16 v[38:41], v[230:233], v[196:199], v[38:41]
	v_mfma_f32_16x16x32_bf16 v[34:37], v[238:241], v[196:199], v[34:37]
	v_mfma_f32_16x16x32_bf16 v[22:25], v[230:233], v[214:217], v[22:25]
	v_mfma_f32_16x16x32_bf16 v[18:21], v[238:241], v[214:217], v[18:21]
	v_mfma_f32_16x16x32_bf16 v[6:9], v[230:233], v[222:225], v[6:9]
	v_mfma_f32_16x16x32_bf16 v[2:5], v[238:241], v[222:225], v[2:5]
	v_mfma_f32_16x16x32_bf16 v[54:57], v[234:237], v[192:195], v[54:57]
	v_mfma_f32_16x16x32_bf16 v[50:53], v[242:245], v[192:195], v[50:53]
	v_mfma_f32_16x16x32_bf16 v[38:41], v[234:237], v[210:213], v[38:41]
	v_mfma_f32_16x16x32_bf16 v[34:37], v[242:245], v[210:213], v[34:37]
	v_mfma_f32_16x16x32_bf16 v[22:25], v[234:237], v[218:221], v[22:25]
	v_mfma_f32_16x16x32_bf16 v[18:21], v[242:245], v[218:221], v[18:21]
	v_mfma_f32_16x16x32_bf16 v[6:9], v[234:237], v[226:229], v[6:9]
	v_mfma_f32_16x16x32_bf16 v[2:5], v[242:245], v[226:229], v[2:5]
	s_add_i32 s54, s54, 2
	s_add_u32 s28, s28, 0x100
	s_addc_u32 s29, s29, 0
	s_cmp_gt_u32 s54, 9
	s_mov_b64 s[36:37], s[42:43]
	s_barrier
	s_cbranch_scc0 .LBB0_595
	v_mul_f32_e32 v144, 0x3d372713, v126
	v_mul_f32_e32 v144, v126, v144
	v_fma_f32 v144, v126, v144, v126
	v_mul_f32_e32 v144, 0x3f4c422a, v144
	v_add_f32_e32 v144, v144, v144
	v_mul_f32_e32 v144, 0x3fb8aa3b, v144
	v_exp_f32_e32 v144, v144
	v_mul_f32_e32 v126, 0.5, v126
	s_lshl_b32 s23, s26, 8
	s_and_b32 s23, s23, 0x100
	v_add_f32_e32 v145, 1.0, v144
	v_div_scale_f32 v172, s[28:29], v145, v145, 2.0
	v_rcp_f32_e32 v173, v172
	v_or_b32_e32 v144, s23, v162
	v_lshrrev_b32_e32 v171, 4, v144
	v_or_b32_e32 v144, v171, v146
	v_fma_f32 v174, -v172, v173, 1.0
	v_fmac_f32_e32 v173, v174, v173
	v_div_scale_f32 v174, vcc, 2.0, v145, 2.0
	v_mul_f32_e32 v175, v174, v173
	v_fma_f32 v176, -v172, v175, v174
	v_fmac_f32_e32 v175, v176, v173
	v_fma_f32 v172, -v172, v175, v174
	v_mul_f32_e32 v174, 0x3d372713, v127
	v_mul_f32_e32 v174, v127, v174
	v_fma_f32 v174, v127, v174, v127
	v_mul_f32_e32 v174, 0x3f4c422a, v174
	v_add_f32_e32 v174, v174, v174
	v_mul_f32_e32 v174, 0x3fb8aa3b, v174
	v_exp_f32_e32 v174, v174
	v_div_fmas_f32 v172, v172, v173, v175
	v_div_fixup_f32 v145, v172, v145, 2.0
	v_sub_f32_e32 v145, 1.0, v145
	v_add_f32_e32 v172, 1.0, v174
	v_div_scale_f32 v173, s[28:29], v172, v172, 2.0
	v_rcp_f32_e32 v174, v173
	v_add_f32_e32 v145, 1.0, v145
	v_mul_f32_e32 v126, v126, v145
	v_mul_f32_e32 v127, 0.5, v127
	v_fma_f32 v145, -v173, v174, 1.0
	v_fmac_f32_e32 v174, v145, v174
	v_div_scale_f32 v145, vcc, 2.0, v172, 2.0
	v_mul_f32_e32 v175, v145, v174
	v_fma_f32 v176, -v173, v175, v145
	v_fmac_f32_e32 v175, v176, v174
	v_fma_f32 v145, -v173, v175, v145
	v_mul_f32_e32 v173, 0x3d372713, v128
	v_mul_f32_e32 v173, v128, v173
	v_fma_f32 v173, v128, v173, v128
	v_mul_f32_e32 v173, 0x3f4c422a, v173
	v_add_f32_e32 v173, v173, v173
	v_mul_f32_e32 v173, 0x3fb8aa3b, v173
	v_exp_f32_e32 v173, v173
	v_div_fmas_f32 v145, v145, v174, v175
	v_div_fixup_f32 v145, v145, v172, 2.0
	v_sub_f32_e32 v145, 1.0, v145
	v_add_f32_e32 v172, 1.0, v173
	v_div_scale_f32 v173, s[28:29], v172, v172, 2.0
	v_rcp_f32_e32 v174, v173
	v_add_f32_e32 v145, 1.0, v145
	v_mul_f32_e32 v127, v127, v145
	v_cvt_pk_bf16_f32 v126, v126, v127
	v_fma_f32 v127, -v173, v174, 1.0
	v_fmac_f32_e32 v174, v127, v174
	v_div_scale_f32 v127, vcc, 2.0, v172, 2.0
	v_mul_f32_e32 v145, v127, v174
	v_fma_f32 v175, -v173, v145, v127
	v_fmac_f32_e32 v145, v175, v174
	v_fma_f32 v127, -v173, v145, v127
	v_mul_f32_e32 v173, 0x3d372713, v129
	v_mul_f32_e32 v173, v129, v173
	v_fma_f32 v173, v129, v173, v129
	v_mul_f32_e32 v173, 0x3f4c422a, v173
	v_add_f32_e32 v173, v173, v173
	v_mul_f32_e32 v173, 0x3fb8aa3b, v173
	v_exp_f32_e32 v173, v173
	v_div_fmas_f32 v127, v127, v174, v145
	v_div_fixup_f32 v127, v127, v172, 2.0
	v_sub_f32_e32 v127, 1.0, v127
	v_add_f32_e32 v145, 1.0, v173
	v_div_scale_f32 v172, s[28:29], v145, v145, 2.0
	v_rcp_f32_e32 v173, v172
	v_mul_f32_e32 v128, 0.5, v128
	v_add_f32_e32 v127, 1.0, v127
; #define LAS __attribute__((address_space(3)))
; __device__ __forceinline__ unsigned cvt_pk_bf16(float lo, float hi) { unsigned r; asm volatile("v_cvt_pk_bf16_f32 %0, %1, %2" : "=v"(r) : "v"(lo), "v"(hi)); return r; }
; __device__ __forceinline__ float gelu_tanh(float x) { const float z = 0.7978845608f * (x + 0.044715f * x * x * x); const float th = 1.0f - 2.0f / (__expf(2.0f * z) + 1.0f); return 0.5f * x * (1.0f + th); }
;     __device__ __forceinline__ void operator()(const f32x4 (&acc)[2][2][4][2], const Unit& u, int ui, const LAS float* rtab, int wr, int wc, int fr, int fq) const {
;         const int g = u.pm; const int n0 = wr * 64 + fr; const int lc0 = (u.pn & 1) * 256 + wc * 32 + 8 * fq;
; #pragma unroll
;         for (int ai = 0; ai < 2; ++ai)
; #pragma unroll
;             for (int m = 0; m < 4; ++m) {
;                 const int n = n0 + ai * HALF + m * 16;
; #pragma unroll
;                 for (int bj = 0; bj < 2; ++bj) {
;                     const int lc = lc0 + bj * HALF, t = lc >> 4, co = lc & 15; const int token = n * 32 + t;
;                     const f32x4 a0 = acc[ai][bj][m][0], a1 = acc[ai][bj][m][1];
;                     u32x4 w; w.x = cvt_pk_bf16(gelu_tanh(a0[0]), gelu_tanh(a0[1])); w.y = cvt_pk_bf16(gelu_tanh(a0[2]), gelu_tanh(a0[3]));
;                     w.z = cvt_pk_bf16(gelu_tanh(a1[0]), gelu_tanh(a1[1])); w.w = cvt_pk_bf16(gelu_tanh(a1[2]), gelu_tanh(a1[3]));
;                     *(u32x4*)(Y + (size_t)token * 1024 + 16 * g + co) = w;
	v_mul_f32_e32 v127, v128, v127
	v_fma_f32 v128, -v172, v173, 1.0
	v_fmac_f32_e32 v173, v128, v173
	v_div_scale_f32 v128, vcc, 2.0, v145, 2.0
	v_mul_f32_e32 v174, v128, v173
	v_fma_f32 v175, -v172, v174, v128
	v_fmac_f32_e32 v174, v175, v173
	v_fma_f32 v128, -v172, v174, v128
	v_mul_f32_e32 v172, 0x3d372713, v122
	v_mul_f32_e32 v172, v122, v172
	v_fma_f32 v172, v122, v172, v122
	v_mul_f32_e32 v172, 0x3f4c422a, v172
	v_add_f32_e32 v172, v172, v172
	v_mul_f32_e32 v172, 0x3fb8aa3b, v172
	v_exp_f32_e32 v172, v172
	v_div_fmas_f32 v128, v128, v173, v174
	v_div_fixup_f32 v128, v128, v145, 2.0
	v_sub_f32_e32 v128, 1.0, v128
	v_add_f32_e32 v145, 1.0, v172
	v_div_scale_f32 v172, s[28:29], v145, v145, 2.0
	v_rcp_f32_e32 v173, v172
	v_mul_f32_e32 v129, 0.5, v129
	v_add_f32_e32 v128, 1.0, v128
	v_mul_f32_e32 v128, v129, v128
	v_cvt_pk_bf16_f32 v127, v127, v128
	v_fma_f32 v128, -v172, v173, 1.0
	v_fmac_f32_e32 v173, v128, v173
	v_div_scale_f32 v128, vcc, 2.0, v145, 2.0
	v_mul_f32_e32 v129, v128, v173
	v_fma_f32 v174, -v172, v129, v128
	v_fmac_f32_e32 v129, v174, v173
	v_fma_f32 v128, -v172, v129, v128
	v_mul_f32_e32 v172, 0x3d372713, v123
	v_mul_f32_e32 v172, v123, v172
	v_fma_f32 v172, v123, v172, v123
	v_mul_f32_e32 v172, 0x3f4c422a, v172
	v_add_f32_e32 v172, v172, v172
	v_mul_f32_e32 v172, 0x3fb8aa3b, v172
	v_exp_f32_e32 v172, v172
	v_div_fmas_f32 v128, v128, v173, v129
	v_div_fixup_f32 v128, v128, v145, 2.0
	v_sub_f32_e32 v128, 1.0, v128
	v_add_f32_e32 v129, 1.0, v172
	v_div_scale_f32 v145, s[28:29], v129, v129, 2.0
	v_rcp_f32_e32 v172, v145
	v_mul_f32_e32 v122, 0.5, v122
	v_add_f32_e32 v128, 1.0, v128
	v_mul_f32_e32 v122, v122, v128
	v_fma_f32 v128, -v145, v172, 1.0
	v_fmac_f32_e32 v172, v128, v172
	v_div_scale_f32 v128, vcc, 2.0, v129, 2.0
	v_mul_f32_e32 v173, v128, v172
	v_fma_f32 v174, -v145, v173, v128
	v_fmac_f32_e32 v173, v174, v172
	v_fma_f32 v128, -v145, v173, v128
	v_mul_f32_e32 v145, 0x3d372713, v124
	v_mul_f32_e32 v145, v124, v145
	v_fma_f32 v145, v124, v145, v124
	v_mul_f32_e32 v145, 0x3f4c422a, v145
	v_add_f32_e32 v145, v145, v145
	v_mul_f32_e32 v145, 0x3fb8aa3b, v145
	v_exp_f32_e32 v145, v145
	v_div_fmas_f32 v128, v128, v172, v173
	v_div_fixup_f32 v128, v128, v129, 2.0
	v_sub_f32_e32 v128, 1.0, v128
	v_add_f32_e32 v129, 1.0, v145
	v_div_scale_f32 v145, s[28:29], v129, v129, 2.0
	v_rcp_f32_e32 v172, v145
	v_mul_f32_e32 v123, 0.5, v123
	v_add_f32_e32 v128, 1.0, v128
	v_mul_f32_e32 v123, v123, v128
	v_cvt_pk_bf16_f32 v128, v122, v123
	v_fma_f32 v122, -v145, v172, 1.0
	v_fmac_f32_e32 v172, v122, v172
	v_div_scale_f32 v122, vcc, 2.0, v129, 2.0
	v_mul_f32_e32 v123, v122, v172
	v_fma_f32 v173, -v145, v123, v122
	v_fmac_f32_e32 v123, v173, v172
	v_fma_f32 v122, -v145, v123, v122
	v_mul_f32_e32 v145, 0x3d372713, v125
	v_mul_f32_e32 v145, v125, v145
	v_fma_f32 v145, v125, v145, v125
	v_mul_f32_e32 v145, 0x3f4c422a, v145
	v_add_f32_e32 v145, v145, v145
	v_mul_f32_e32 v145, 0x3fb8aa3b, v145
	v_exp_f32_e32 v145, v145
	v_div_fmas_f32 v122, v122, v172, v123
	v_div_fixup_f32 v122, v122, v129, 2.0
	v_sub_f32_e32 v122, 1.0, v122
	v_add_f32_e32 v123, 1.0, v145
	v_div_scale_f32 v129, s[28:29], v123, v123, 2.0
	v_rcp_f32_e32 v145, v129
	v_mul_f32_e32 v124, 0.5, v124
	v_add_f32_e32 v122, 1.0, v122
	v_mul_f32_e32 v122, v124, v122
	v_fma_f32 v124, -v129, v145, 1.0
	v_fmac_f32_e32 v145, v124, v145
	v_div_scale_f32 v124, vcc, 2.0, v123, 2.0
	v_mul_f32_e32 v172, v124, v145
	v_fma_f32 v173, -v129, v172, v124
	v_fmac_f32_e32 v172, v173, v145
	v_fma_f32 v124, -v129, v172, v124
	v_div_fmas_f32 v124, v124, v145, v172
	v_div_fixup_f32 v123, v124, v123, 2.0
	v_sub_f32_e32 v123, 1.0, v123
	v_mul_f32_e32 v124, 0.5, v125
	v_add_f32_e32 v123, 1.0, v123
	v_mul_f32_e32 v123, v124, v123
	v_cvt_pk_bf16_f32 v129, v122, v123
	v_mul_f32_e32 v122, 0x3d372713, v118
	v_mul_f32_e32 v122, v118, v122
	v_fma_f32 v122, v118, v122, v118
	v_mul_f32_e32 v122, 0x3f4c422a, v122
	v_add_f32_e32 v122, v122, v122
	v_mul_f32_e32 v122, 0x3fb8aa3b, v122
	v_exp_f32_e32 v124, v122
	v_ashrrev_i32_e32 v145, 31, v144
	v_lshlrev_b64 v[122:123], 11, v[144:145]
	v_lshl_add_u64 v[122:123], v[138:139], 0, v[122:123]
	v_add_f32_e32 v125, 1.0, v124
	v_div_scale_f32 v144, s[28:29], v125, v125, 2.0
	v_rcp_f32_e32 v145, v144
	global_store_dwordx4 v[122:123], v[126:129], off
	v_mul_f32_e32 v118, 0.5, v118
	v_or_b32_e32 v124, 8, v171
	v_fma_f32 v123, -v144, v145, 1.0
	v_fmac_f32_e32 v145, v123, v145
	v_div_scale_f32 v123, vcc, 2.0, v125, 2.0
	v_mul_f32_e32 v126, v123, v145
	v_fma_f32 v127, -v144, v126, v123
	v_fmac_f32_e32 v126, v127, v145
	v_mul_f32_e32 v127, 0x3d372713, v119
	v_mul_f32_e32 v127, v119, v127
	v_fma_f32 v127, v119, v127, v119
	v_mul_f32_e32 v127, 0x3f4c422a, v127
	v_add_f32_e32 v127, v127, v127
	v_mul_f32_e32 v127, 0x3fb8aa3b, v127
	v_exp_f32_e32 v127, v127
	v_fma_f32 v123, -v144, v126, v123
	v_div_fmas_f32 v123, v123, v145, v126
	v_div_fixup_f32 v123, v123, v125, 2.0
	v_add_f32_e32 v125, 1.0, v127
	v_div_scale_f32 v126, s[28:29], v125, v125, 2.0
	v_rcp_f32_e32 v127, v126
	v_sub_f32_e32 v123, 1.0, v123
	v_add_f32_e32 v123, 1.0, v123
	v_mul_f32_e32 v118, v118, v123
	v_fma_f32 v123, -v126, v127, 1.0
	v_fmac_f32_e32 v127, v123, v127
	v_div_scale_f32 v123, vcc, 2.0, v125, 2.0
	v_mul_f32_e32 v128, v123, v127
	v_fma_f32 v129, -v126, v128, v123
	v_fmac_f32_e32 v128, v129, v127
	v_fma_f32 v123, -v126, v128, v123
	v_mul_f32_e32 v126, 0x3d372713, v120
	v_mul_f32_e32 v126, v120, v126
	v_fma_f32 v126, v120, v126, v120
	v_mul_f32_e32 v126, 0x3f4c422a, v126
	v_add_f32_e32 v126, v126, v126
	v_mul_f32_e32 v126, 0x3fb8aa3b, v126
	v_exp_f32_e32 v126, v126
	v_div_fmas_f32 v123, v123, v127, v128
; #define LAS __attribute__((address_space(3)))
; __device__ __forceinline__ unsigned cvt_pk_bf16(float lo, float hi) { unsigned r; asm volatile("v_cvt_pk_bf16_f32 %0, %1, %2" : "=v"(r) : "v"(lo), "v"(hi)); return r; }
; __device__ __forceinline__ float gelu_tanh(float x) { const float z = 0.7978845608f * (x + 0.044715f * x * x * x); const float th = 1.0f - 2.0f / (__expf(2.0f * z) + 1.0f); return 0.5f * x * (1.0f + th); }
;     __device__ __forceinline__ void operator()(const f32x4 (&acc)[2][2][4][2], const Unit& u, int ui, const LAS float* rtab, int wr, int wc, int fr, int fq) const {
;         const int g = u.pm; const int n0 = wr * 64 + fr; const int lc0 = (u.pn & 1) * 256 + wc * 32 + 8 * fq;
; #pragma unroll
;         for (int ai = 0; ai < 2; ++ai)
; #pragma unroll
;             for (int m = 0; m < 4; ++m) {
;                 const int n = n0 + ai * HALF + m * 16;
; #pragma unroll
;                 for (int bj = 0; bj < 2; ++bj) {
;                     const int lc = lc0 + bj * HALF, t = lc >> 4, co = lc & 15; const int token = n * 32 + t;
;                     const f32x4 a0 = acc[ai][bj][m][0], a1 = acc[ai][bj][m][1];
;                     u32x4 w; w.x = cvt_pk_bf16(gelu_tanh(a0[0]), gelu_tanh(a0[1])); w.y = cvt_pk_bf16(gelu_tanh(a0[2]), gelu_tanh(a0[3]));
;                     w.z = cvt_pk_bf16(gelu_tanh(a1[0]), gelu_tanh(a1[1])); w.w = cvt_pk_bf16(gelu_tanh(a1[2]), gelu_tanh(a1[3]));
;                     *(u32x4*)(Y + (size_t)token * 1024 + 16 * g + co) = w;
	v_div_fixup_f32 v123, v123, v125, 2.0
	v_sub_f32_e32 v123, 1.0, v123
	v_add_f32_e32 v125, 1.0, v126
	v_div_scale_f32 v126, s[28:29], v125, v125, 2.0
	v_rcp_f32_e32 v127, v126
	v_mul_f32_e32 v119, 0.5, v119
	v_add_f32_e32 v123, 1.0, v123
	v_mul_f32_e32 v119, v119, v123
	v_cvt_pk_bf16_f32 v118, v118, v119
	v_fma_f32 v119, -v126, v127, 1.0
	v_fmac_f32_e32 v127, v119, v127
	v_div_scale_f32 v119, vcc, 2.0, v125, 2.0
	v_mul_f32_e32 v123, v119, v127
	v_fma_f32 v128, -v126, v123, v119
	v_fmac_f32_e32 v123, v128, v127
	v_fma_f32 v119, -v126, v123, v119
	v_mul_f32_e32 v126, 0x3d372713, v121
	v_mul_f32_e32 v126, v121, v126
	v_fma_f32 v126, v121, v126, v121
	v_mul_f32_e32 v126, 0x3f4c422a, v126
	v_add_f32_e32 v126, v126, v126
	v_mul_f32_e32 v126, 0x3fb8aa3b, v126
	v_exp_f32_e32 v126, v126
	v_div_fmas_f32 v119, v119, v127, v123
	v_div_fixup_f32 v119, v119, v125, 2.0
	v_sub_f32_e32 v119, 1.0, v119
	v_add_f32_e32 v123, 1.0, v126
	v_div_scale_f32 v125, s[28:29], v123, v123, 2.0
	v_rcp_f32_e32 v126, v125
	v_mul_f32_e32 v120, 0.5, v120
	v_add_f32_e32 v119, 1.0, v119
	v_mul_f32_e32 v119, v120, v119
	v_fma_f32 v120, -v125, v126, 1.0
	v_fmac_f32_e32 v126, v120, v126
	v_div_scale_f32 v120, vcc, 2.0, v123, 2.0
	v_mul_f32_e32 v127, v120, v126
	v_fma_f32 v128, -v125, v127, v120
	v_fmac_f32_e32 v127, v128, v126
	v_fma_f32 v120, -v125, v127, v120
	v_mul_f32_e32 v125, 0x3d372713, v114
	v_mul_f32_e32 v125, v114, v125
	v_fma_f32 v125, v114, v125, v114
	v_mul_f32_e32 v125, 0x3f4c422a, v125
	v_add_f32_e32 v125, v125, v125
	v_mul_f32_e32 v125, 0x3fb8aa3b, v125
	v_exp_f32_e32 v125, v125
	v_div_fmas_f32 v120, v120, v126, v127
	v_div_fixup_f32 v120, v120, v123, 2.0
	v_sub_f32_e32 v120, 1.0, v120
	v_add_f32_e32 v123, 1.0, v125
	v_div_scale_f32 v125, s[28:29], v123, v123, 2.0
	v_rcp_f32_e32 v126, v125
	v_mul_f32_e32 v121, 0.5, v121
	v_add_f32_e32 v120, 1.0, v120
	v_mul_f32_e32 v120, v121, v120
	v_cvt_pk_bf16_f32 v119, v119, v120
	v_fma_f32 v120, -v125, v126, 1.0
	v_fmac_f32_e32 v126, v120, v126
	v_div_scale_f32 v120, vcc, 2.0, v123, 2.0
	v_mul_f32_e32 v121, v120, v126
	v_fma_f32 v127, -v125, v121, v120
	v_fmac_f32_e32 v121, v127, v126
	v_fma_f32 v120, -v125, v121, v120
	v_mul_f32_e32 v125, 0x3d372713, v115
	v_mul_f32_e32 v125, v115, v125
	v_fma_f32 v125, v115, v125, v115
	v_mul_f32_e32 v125, 0x3f4c422a, v125
	v_add_f32_e32 v125, v125, v125
	v_mul_f32_e32 v125, 0x3fb8aa3b, v125
	v_exp_f32_e32 v125, v125
	v_div_fmas_f32 v120, v120, v126, v121
	v_div_fixup_f32 v120, v120, v123, 2.0
	v_sub_f32_e32 v120, 1.0, v120
	v_add_f32_e32 v121, 1.0, v125
	v_div_scale_f32 v123, s[28:29], v121, v121, 2.0
	v_rcp_f32_e32 v125, v123
	v_mul_f32_e32 v114, 0.5, v114
	v_add_f32_e32 v120, 1.0, v120
	v_mul_f32_e32 v114, v114, v120
	v_fma_f32 v120, -v123, v125, 1.0
	v_fmac_f32_e32 v125, v120, v125
	v_div_scale_f32 v120, vcc, 2.0, v121, 2.0
	v_mul_f32_e32 v126, v120, v125
	v_fma_f32 v127, -v123, v126, v120
	v_fmac_f32_e32 v126, v127, v125
	v_fma_f32 v120, -v123, v126, v120
	v_mul_f32_e32 v123, 0x3d372713, v116
	v_mul_f32_e32 v123, v116, v123
	v_fma_f32 v123, v116, v123, v116
	v_mul_f32_e32 v123, 0x3f4c422a, v123
	v_add_f32_e32 v123, v123, v123
	v_mul_f32_e32 v123, 0x3fb8aa3b, v123
	v_exp_f32_e32 v123, v123
	v_div_fmas_f32 v120, v120, v125, v126
	v_div_fixup_f32 v120, v120, v121, 2.0
	v_sub_f32_e32 v120, 1.0, v120
	v_add_f32_e32 v121, 1.0, v123
	v_div_scale_f32 v123, s[28:29], v121, v121, 2.0
	v_rcp_f32_e32 v125, v123
	v_mul_f32_e32 v115, 0.5, v115
	v_add_f32_e32 v120, 1.0, v120
	v_mul_f32_e32 v115, v115, v120
	v_cvt_pk_bf16_f32 v120, v114, v115
	v_fma_f32 v114, -v123, v125, 1.0
	v_fmac_f32_e32 v125, v114, v125
	v_div_scale_f32 v114, vcc, 2.0, v121, 2.0
	v_mul_f32_e32 v115, v114, v125
	v_fma_f32 v126, -v123, v115, v114
	v_fmac_f32_e32 v115, v126, v125
	v_fma_f32 v114, -v123, v115, v114
	v_mul_f32_e32 v123, 0x3d372713, v117
	v_mul_f32_e32 v123, v117, v123
	v_fma_f32 v123, v117, v123, v117
	v_mul_f32_e32 v123, 0x3f4c422a, v123
	v_add_f32_e32 v123, v123, v123
	v_mul_f32_e32 v123, 0x3fb8aa3b, v123
	v_exp_f32_e32 v123, v123
	v_div_fmas_f32 v114, v114, v125, v115
	v_div_fixup_f32 v114, v114, v121, 2.0
	v_sub_f32_e32 v114, 1.0, v114
	v_add_f32_e32 v115, 1.0, v123
	v_div_scale_f32 v121, s[28:29], v115, v115, 2.0
	v_rcp_f32_e32 v123, v121
	v_mul_f32_e32 v116, 0.5, v116
	v_add_f32_e32 v114, 1.0, v114
	v_mul_f32_e32 v114, v116, v114
	v_fma_f32 v116, -v121, v123, 1.0
	v_fmac_f32_e32 v123, v116, v123
	v_div_scale_f32 v116, vcc, 2.0, v115, 2.0
	v_mul_f32_e32 v125, v116, v123
	v_fma_f32 v126, -v121, v125, v116
	v_fmac_f32_e32 v125, v126, v123
	v_fma_f32 v116, -v121, v125, v116
	v_div_fmas_f32 v116, v116, v123, v125
	v_div_fixup_f32 v115, v116, v115, 2.0
	v_sub_f32_e32 v115, 1.0, v115
	v_mul_f32_e32 v116, 0.5, v117
	v_add_f32_e32 v115, 1.0, v115
	v_mul_f32_e32 v115, v116, v115
	v_mul_f32_e32 v116, 0x3d372713, v110
	v_mul_f32_e32 v116, v110, v116
	v_fma_f32 v116, v110, v116, v110
	v_mul_f32_e32 v116, 0x3f4c422a, v116
	v_add_f32_e32 v116, v116, v116
	v_mul_f32_e32 v116, 0x3fb8aa3b, v116
	v_exp_f32_e32 v116, v116
	v_or_b32_e32 v122, v124, v146
	v_ashrrev_i32_e32 v123, 31, v122
	v_cvt_pk_bf16_f32 v121, v114, v115
	v_add_f32_e32 v116, 1.0, v116
	v_div_scale_f32 v117, s[28:29], v116, v116, 2.0
	v_lshlrev_b64 v[114:115], 11, v[122:123]
	v_rcp_f32_e32 v122, v117
	v_lshl_add_u64 v[114:115], v[138:139], 0, v[114:115]
	global_store_dwordx4 v[114:115], v[118:121], off
	v_mul_f32_e32 v110, 0.5, v110
	v_fma_f32 v115, -v117, v122, 1.0
	v_fmac_f32_e32 v122, v115, v122
	v_div_scale_f32 v115, vcc, 2.0, v116, 2.0
	v_mul_f32_e32 v118, v115, v122
	v_fma_f32 v119, -v117, v118, v115
	v_fmac_f32_e32 v118, v119, v122
	v_fma_f32 v115, -v117, v118, v115
; #define LAS __attribute__((address_space(3)))
; __device__ __forceinline__ unsigned cvt_pk_bf16(float lo, float hi) { unsigned r; asm volatile("v_cvt_pk_bf16_f32 %0, %1, %2" : "=v"(r) : "v"(lo), "v"(hi)); return r; }
; __device__ __forceinline__ float gelu_tanh(float x) { const float z = 0.7978845608f * (x + 0.044715f * x * x * x); const float th = 1.0f - 2.0f / (__expf(2.0f * z) + 1.0f); return 0.5f * x * (1.0f + th); }
;     __device__ __forceinline__ void operator()(const f32x4 (&acc)[2][2][4][2], const Unit& u, int ui, const LAS float* rtab, int wr, int wc, int fr, int fq) const {
;         const int g = u.pm; const int n0 = wr * 64 + fr; const int lc0 = (u.pn & 1) * 256 + wc * 32 + 8 * fq;
; #pragma unroll
;         for (int ai = 0; ai < 2; ++ai)
; #pragma unroll
;             for (int m = 0; m < 4; ++m) {
;                 const int n = n0 + ai * HALF + m * 16;
; #pragma unroll
;                 for (int bj = 0; bj < 2; ++bj) {
;                     const int lc = lc0 + bj * HALF, t = lc >> 4, co = lc & 15; const int token = n * 32 + t;
;                     const f32x4 a0 = acc[ai][bj][m][0], a1 = acc[ai][bj][m][1];
;                     u32x4 w; w.x = cvt_pk_bf16(gelu_tanh(a0[0]), gelu_tanh(a0[1])); w.y = cvt_pk_bf16(gelu_tanh(a0[2]), gelu_tanh(a0[3]));
;                     w.z = cvt_pk_bf16(gelu_tanh(a1[0]), gelu_tanh(a1[1])); w.w = cvt_pk_bf16(gelu_tanh(a1[2]), gelu_tanh(a1[3]));
;                     *(u32x4*)(Y + (size_t)token * 1024 + 16 * g + co) = w;
	v_mul_f32_e32 v117, 0x3d372713, v111
	v_mul_f32_e32 v117, v111, v117
	v_fma_f32 v117, v111, v117, v111
	v_mul_f32_e32 v117, 0x3f4c422a, v117
	v_add_f32_e32 v117, v117, v117
	v_mul_f32_e32 v117, 0x3fb8aa3b, v117
	v_exp_f32_e32 v117, v117
	v_div_fmas_f32 v115, v115, v122, v118
	v_div_fixup_f32 v115, v115, v116, 2.0
	v_sub_f32_e32 v115, 1.0, v115
	v_add_f32_e32 v116, 1.0, v117
	v_div_scale_f32 v117, s[28:29], v116, v116, 2.0
	v_rcp_f32_e32 v118, v117
	v_add_f32_e32 v115, 1.0, v115
	v_mul_f32_e32 v110, v110, v115
	v_mul_f32_e32 v111, 0.5, v111
	v_fma_f32 v115, -v117, v118, 1.0
	v_fmac_f32_e32 v118, v115, v118
	v_div_scale_f32 v115, vcc, 2.0, v116, 2.0
	v_mul_f32_e32 v119, v115, v118
	v_fma_f32 v120, -v117, v119, v115
	v_fmac_f32_e32 v119, v120, v118
	v_fma_f32 v115, -v117, v119, v115
	v_mul_f32_e32 v117, 0x3d372713, v112
	v_mul_f32_e32 v117, v112, v117
	v_fma_f32 v117, v112, v117, v112
	v_mul_f32_e32 v117, 0x3f4c422a, v117
	v_add_f32_e32 v117, v117, v117
	v_mul_f32_e32 v117, 0x3fb8aa3b, v117
	v_exp_f32_e32 v117, v117
	v_div_fmas_f32 v115, v115, v118, v119
	v_div_fixup_f32 v115, v115, v116, 2.0
	v_sub_f32_e32 v115, 1.0, v115
	v_add_f32_e32 v116, 1.0, v117
	v_div_scale_f32 v117, s[28:29], v116, v116, 2.0
	v_rcp_f32_e32 v118, v117
	v_add_f32_e32 v115, 1.0, v115
	v_mul_f32_e32 v111, v111, v115
	v_cvt_pk_bf16_f32 v110, v110, v111
	v_fma_f32 v111, -v117, v118, 1.0
	v_fmac_f32_e32 v118, v111, v118
	v_div_scale_f32 v111, vcc, 2.0, v116, 2.0
	v_mul_f32_e32 v115, v111, v118
	v_fma_f32 v119, -v117, v115, v111
	v_fmac_f32_e32 v115, v119, v118
	v_fma_f32 v111, -v117, v115, v111
	v_mul_f32_e32 v117, 0x3d372713, v113
	v_mul_f32_e32 v117, v113, v117
	v_fma_f32 v117, v113, v117, v113
	v_mul_f32_e32 v117, 0x3f4c422a, v117
	v_add_f32_e32 v117, v117, v117
	v_mul_f32_e32 v117, 0x3fb8aa3b, v117
	v_exp_f32_e32 v117, v117
	v_div_fmas_f32 v111, v111, v118, v115
	v_div_fixup_f32 v111, v111, v116, 2.0
	v_sub_f32_e32 v111, 1.0, v111
	v_add_f32_e32 v115, 1.0, v117
	v_div_scale_f32 v116, s[28:29], v115, v115, 2.0
	v_rcp_f32_e32 v117, v116
	v_mul_f32_e32 v112, 0.5, v112
	v_add_f32_e32 v111, 1.0, v111
	v_mul_f32_e32 v111, v112, v111
	v_fma_f32 v112, -v116, v117, 1.0
	v_fmac_f32_e32 v117, v112, v117
	v_div_scale_f32 v112, vcc, 2.0, v115, 2.0
	v_mul_f32_e32 v118, v112, v117
	v_fma_f32 v119, -v116, v118, v112
	v_fmac_f32_e32 v118, v119, v117
	v_fma_f32 v112, -v116, v118, v112
	v_mul_f32_e32 v116, 0x3d372713, v106
	v_mul_f32_e32 v116, v106, v116
	v_fma_f32 v116, v106, v116, v106
	v_mul_f32_e32 v116, 0x3f4c422a, v116
	v_add_f32_e32 v116, v116, v116
	v_mul_f32_e32 v116, 0x3fb8aa3b, v116
	v_exp_f32_e32 v116, v116
	v_div_fmas_f32 v112, v112, v117, v118
	v_div_fixup_f32 v112, v112, v115, 2.0
	v_sub_f32_e32 v112, 1.0, v112
	v_add_f32_e32 v115, 1.0, v116
	v_div_scale_f32 v116, s[28:29], v115, v115, 2.0
	v_rcp_f32_e32 v117, v116
	v_mul_f32_e32 v113, 0.5, v113
	v_add_f32_e32 v112, 1.0, v112
	v_mul_f32_e32 v112, v113, v112
	v_cvt_pk_bf16_f32 v111, v111, v112
	v_fma_f32 v112, -v116, v117, 1.0
	v_fmac_f32_e32 v117, v112, v117
	v_div_scale_f32 v112, vcc, 2.0, v115, 2.0
	v_mul_f32_e32 v113, v112, v117
	v_fma_f32 v118, -v116, v113, v112
	v_fmac_f32_e32 v113, v118, v117
	v_fma_f32 v112, -v116, v113, v112
	v_mul_f32_e32 v116, 0x3d372713, v107
	v_mul_f32_e32 v116, v107, v116
	v_fma_f32 v116, v107, v116, v107
	v_mul_f32_e32 v116, 0x3f4c422a, v116
	v_add_f32_e32 v116, v116, v116
	v_mul_f32_e32 v116, 0x3fb8aa3b, v116
	v_exp_f32_e32 v116, v116
	v_div_fmas_f32 v112, v112, v117, v113
	v_div_fixup_f32 v112, v112, v115, 2.0
	v_sub_f32_e32 v112, 1.0, v112
	v_add_f32_e32 v113, 1.0, v116
	v_div_scale_f32 v115, s[28:29], v113, v113, 2.0
	v_rcp_f32_e32 v116, v115
	v_mul_f32_e32 v106, 0.5, v106
	v_add_f32_e32 v112, 1.0, v112
	v_mul_f32_e32 v106, v106, v112
	v_fma_f32 v112, -v115, v116, 1.0
	v_fmac_f32_e32 v116, v112, v116
	v_div_scale_f32 v112, vcc, 2.0, v113, 2.0
	v_mul_f32_e32 v117, v112, v116
	v_fma_f32 v118, -v115, v117, v112
	v_fmac_f32_e32 v117, v118, v116
	v_fma_f32 v112, -v115, v117, v112
	v_mul_f32_e32 v115, 0x3d372713, v108
	v_mul_f32_e32 v115, v108, v115
	v_fma_f32 v115, v108, v115, v108
	v_mul_f32_e32 v115, 0x3f4c422a, v115
	v_add_f32_e32 v115, v115, v115
	v_mul_f32_e32 v115, 0x3fb8aa3b, v115
	v_exp_f32_e32 v115, v115
	v_div_fmas_f32 v112, v112, v116, v117
	v_div_fixup_f32 v112, v112, v113, 2.0
	v_sub_f32_e32 v112, 1.0, v112
	v_add_f32_e32 v113, 1.0, v115
	v_div_scale_f32 v115, s[28:29], v113, v113, 2.0
	v_rcp_f32_e32 v116, v115
	v_mul_f32_e32 v107, 0.5, v107
	v_add_f32_e32 v112, 1.0, v112
	v_mul_f32_e32 v107, v107, v112
	v_cvt_pk_bf16_f32 v112, v106, v107
	v_fma_f32 v106, -v115, v116, 1.0
	v_fmac_f32_e32 v116, v106, v116
	v_div_scale_f32 v106, vcc, 2.0, v113, 2.0
	v_mul_f32_e32 v107, v106, v116
	v_fma_f32 v117, -v115, v107, v106
	v_fmac_f32_e32 v107, v117, v116
	v_fma_f32 v106, -v115, v107, v106
	v_mul_f32_e32 v115, 0x3d372713, v109
	v_mul_f32_e32 v115, v109, v115
	v_fma_f32 v115, v109, v115, v109
	v_mul_f32_e32 v115, 0x3f4c422a, v115
	v_add_f32_e32 v115, v115, v115
	v_mul_f32_e32 v115, 0x3fb8aa3b, v115
	v_exp_f32_e32 v115, v115
	v_div_fmas_f32 v106, v106, v116, v107
	v_div_fixup_f32 v106, v106, v113, 2.0
	v_sub_f32_e32 v106, 1.0, v106
	v_add_f32_e32 v107, 1.0, v115
	v_div_scale_f32 v113, s[28:29], v107, v107, 2.0
	v_rcp_f32_e32 v115, v113
	v_mul_f32_e32 v108, 0.5, v108
	v_add_f32_e32 v106, 1.0, v106
	v_mul_f32_e32 v106, v108, v106
	v_fma_f32 v108, -v113, v115, 1.0
	v_fmac_f32_e32 v115, v108, v115
	v_div_scale_f32 v108, vcc, 2.0, v107, 2.0
	v_mul_f32_e32 v116, v108, v115
	v_fma_f32 v117, -v113, v116, v108
	v_fmac_f32_e32 v116, v117, v115
	v_fma_f32 v108, -v113, v116, v108
; #define LAS __attribute__((address_space(3)))
; __device__ __forceinline__ unsigned cvt_pk_bf16(float lo, float hi) { unsigned r; asm volatile("v_cvt_pk_bf16_f32 %0, %1, %2" : "=v"(r) : "v"(lo), "v"(hi)); return r; }
; __device__ __forceinline__ float gelu_tanh(float x) { const float z = 0.7978845608f * (x + 0.044715f * x * x * x); const float th = 1.0f - 2.0f / (__expf(2.0f * z) + 1.0f); return 0.5f * x * (1.0f + th); }
;     __device__ __forceinline__ void operator()(const f32x4 (&acc)[2][2][4][2], const Unit& u, int ui, const LAS float* rtab, int wr, int wc, int fr, int fq) const {
;         const int g = u.pm; const int n0 = wr * 64 + fr; const int lc0 = (u.pn & 1) * 256 + wc * 32 + 8 * fq;
; #pragma unroll
;         for (int ai = 0; ai < 2; ++ai)
; #pragma unroll
;             for (int m = 0; m < 4; ++m) {
;                 const int n = n0 + ai * HALF + m * 16;
; #pragma unroll
;                 for (int bj = 0; bj < 2; ++bj) {
;                     const int lc = lc0 + bj * HALF, t = lc >> 4, co = lc & 15; const int token = n * 32 + t;
;                     const f32x4 a0 = acc[ai][bj][m][0], a1 = acc[ai][bj][m][1];
;                     u32x4 w; w.x = cvt_pk_bf16(gelu_tanh(a0[0]), gelu_tanh(a0[1])); w.y = cvt_pk_bf16(gelu_tanh(a0[2]), gelu_tanh(a0[3]));
;                     w.z = cvt_pk_bf16(gelu_tanh(a1[0]), gelu_tanh(a1[1])); w.w = cvt_pk_bf16(gelu_tanh(a1[2]), gelu_tanh(a1[3]));
;                     *(u32x4*)(Y + (size_t)token * 1024 + 16 * g + co) = w;
	v_div_fmas_f32 v108, v108, v115, v116
	v_div_fixup_f32 v107, v108, v107, 2.0
	v_sub_f32_e32 v107, 1.0, v107
	v_mul_f32_e32 v108, 0.5, v109
	v_add_f32_e32 v107, 1.0, v107
	v_mul_f32_e32 v107, v108, v107
	v_mul_f32_e32 v108, 0x3d372713, v102
	v_mul_f32_e32 v108, v102, v108
	v_fma_f32 v108, v102, v108, v102
	v_mul_f32_e32 v108, 0x3f4c422a, v108
	v_add_f32_e32 v108, v108, v108
	v_mul_f32_e32 v108, 0x3fb8aa3b, v108
	v_exp_f32_e32 v108, v108
	v_or_b32_e32 v114, v171, v147
	v_ashrrev_i32_e32 v115, 31, v114
	v_cvt_pk_bf16_f32 v113, v106, v107
	v_add_f32_e32 v108, 1.0, v108
	v_div_scale_f32 v109, s[28:29], v108, v108, 2.0
	v_lshlrev_b64 v[106:107], 11, v[114:115]
	v_rcp_f32_e32 v114, v109
	v_lshl_add_u64 v[106:107], v[138:139], 0, v[106:107]
	global_store_dwordx4 v[106:107], v[110:113], off
	v_mul_f32_e32 v102, 0.5, v102
	v_fma_f32 v107, -v109, v114, 1.0
	v_fmac_f32_e32 v114, v107, v114
	v_div_scale_f32 v107, vcc, 2.0, v108, 2.0
	v_mul_f32_e32 v110, v107, v114
	v_fma_f32 v111, -v109, v110, v107
	v_fmac_f32_e32 v110, v111, v114
	v_fma_f32 v107, -v109, v110, v107
	v_mul_f32_e32 v109, 0x3d372713, v103
	v_mul_f32_e32 v109, v103, v109
	v_fma_f32 v109, v103, v109, v103
	v_mul_f32_e32 v109, 0x3f4c422a, v109
	v_add_f32_e32 v109, v109, v109
	v_mul_f32_e32 v109, 0x3fb8aa3b, v109
	v_exp_f32_e32 v109, v109
	v_div_fmas_f32 v107, v107, v114, v110
	v_div_fixup_f32 v107, v107, v108, 2.0
	v_sub_f32_e32 v107, 1.0, v107
	v_add_f32_e32 v108, 1.0, v109
	v_div_scale_f32 v109, s[28:29], v108, v108, 2.0
	v_rcp_f32_e32 v110, v109
	v_add_f32_e32 v107, 1.0, v107
	v_mul_f32_e32 v102, v102, v107
	v_mul_f32_e32 v103, 0.5, v103
	v_fma_f32 v107, -v109, v110, 1.0
	v_fmac_f32_e32 v110, v107, v110
	v_div_scale_f32 v107, vcc, 2.0, v108, 2.0
	v_mul_f32_e32 v111, v107, v110
	v_fma_f32 v112, -v109, v111, v107
	v_fmac_f32_e32 v111, v112, v110
	v_fma_f32 v107, -v109, v111, v107
	v_mul_f32_e32 v109, 0x3d372713, v104
	v_mul_f32_e32 v109, v104, v109
	v_fma_f32 v109, v104, v109, v104
	v_mul_f32_e32 v109, 0x3f4c422a, v109
	v_add_f32_e32 v109, v109, v109
	v_mul_f32_e32 v109, 0x3fb8aa3b, v109
	v_exp_f32_e32 v109, v109
	v_div_fmas_f32 v107, v107, v110, v111
	v_div_fixup_f32 v107, v107, v108, 2.0
	v_sub_f32_e32 v107, 1.0, v107
	v_add_f32_e32 v108, 1.0, v109
	v_div_scale_f32 v109, s[28:29], v108, v108, 2.0
	v_rcp_f32_e32 v110, v109
	v_add_f32_e32 v107, 1.0, v107
	v_mul_f32_e32 v103, v103, v107
	v_cvt_pk_bf16_f32 v102, v102, v103
	v_fma_f32 v103, -v109, v110, 1.0
	v_fmac_f32_e32 v110, v103, v110
	v_div_scale_f32 v103, vcc, 2.0, v108, 2.0
	v_mul_f32_e32 v107, v103, v110
	v_fma_f32 v111, -v109, v107, v103
	v_fmac_f32_e32 v107, v111, v110
	v_fma_f32 v103, -v109, v107, v103
	v_mul_f32_e32 v109, 0x3d372713, v105
	v_mul_f32_e32 v109, v105, v109
	v_fma_f32 v109, v105, v109, v105
	v_mul_f32_e32 v109, 0x3f4c422a, v109
	v_add_f32_e32 v109, v109, v109
	v_mul_f32_e32 v109, 0x3fb8aa3b, v109
	v_exp_f32_e32 v109, v109
	v_div_fmas_f32 v103, v103, v110, v107
	v_div_fixup_f32 v103, v103, v108, 2.0
	v_sub_f32_e32 v103, 1.0, v103
	v_add_f32_e32 v107, 1.0, v109
	v_div_scale_f32 v108, s[28:29], v107, v107, 2.0
	v_rcp_f32_e32 v109, v108
	v_mul_f32_e32 v104, 0.5, v104
	v_add_f32_e32 v103, 1.0, v103
	v_mul_f32_e32 v103, v104, v103
	v_fma_f32 v104, -v108, v109, 1.0
	v_fmac_f32_e32 v109, v104, v109
	v_div_scale_f32 v104, vcc, 2.0, v107, 2.0
	v_mul_f32_e32 v110, v104, v109
	v_fma_f32 v111, -v108, v110, v104
	v_fmac_f32_e32 v110, v111, v109
	v_fma_f32 v104, -v108, v110, v104
	v_mul_f32_e32 v108, 0x3d372713, v98
	v_mul_f32_e32 v108, v98, v108
	v_fma_f32 v108, v98, v108, v98
	v_mul_f32_e32 v108, 0x3f4c422a, v108
	v_add_f32_e32 v108, v108, v108
	v_mul_f32_e32 v108, 0x3fb8aa3b, v108
	v_exp_f32_e32 v108, v108
	v_div_fmas_f32 v104, v104, v109, v110
	v_div_fixup_f32 v104, v104, v107, 2.0
	v_sub_f32_e32 v104, 1.0, v104
	v_add_f32_e32 v107, 1.0, v108
	v_div_scale_f32 v108, s[28:29], v107, v107, 2.0
	v_rcp_f32_e32 v109, v108
	v_mul_f32_e32 v105, 0.5, v105
	v_add_f32_e32 v104, 1.0, v104
	v_mul_f32_e32 v104, v105, v104
	v_cvt_pk_bf16_f32 v103, v103, v104
	v_fma_f32 v104, -v108, v109, 1.0
	v_fmac_f32_e32 v109, v104, v109
	v_div_scale_f32 v104, vcc, 2.0, v107, 2.0
	v_mul_f32_e32 v105, v104, v109
	v_fma_f32 v110, -v108, v105, v104
	v_fmac_f32_e32 v105, v110, v109
	v_fma_f32 v104, -v108, v105, v104
	v_mul_f32_e32 v108, 0x3d372713, v99
	v_mul_f32_e32 v108, v99, v108
	v_fma_f32 v108, v99, v108, v99
	v_mul_f32_e32 v108, 0x3f4c422a, v108
	v_add_f32_e32 v108, v108, v108
	v_mul_f32_e32 v108, 0x3fb8aa3b, v108
	v_exp_f32_e32 v108, v108
	v_div_fmas_f32 v104, v104, v109, v105
	v_div_fixup_f32 v104, v104, v107, 2.0
	v_sub_f32_e32 v104, 1.0, v104
	v_add_f32_e32 v105, 1.0, v108
	v_div_scale_f32 v107, s[28:29], v105, v105, 2.0
	v_rcp_f32_e32 v108, v107
	v_mul_f32_e32 v98, 0.5, v98
	v_add_f32_e32 v104, 1.0, v104
	v_mul_f32_e32 v98, v98, v104
	v_fma_f32 v104, -v107, v108, 1.0
	v_fmac_f32_e32 v108, v104, v108
	v_div_scale_f32 v104, vcc, 2.0, v105, 2.0
	v_mul_f32_e32 v109, v104, v108
	v_fma_f32 v110, -v107, v109, v104
	v_fmac_f32_e32 v109, v110, v108
	v_fma_f32 v104, -v107, v109, v104
	v_mul_f32_e32 v107, 0x3d372713, v100
	v_mul_f32_e32 v107, v100, v107
	v_fma_f32 v107, v100, v107, v100
	v_mul_f32_e32 v107, 0x3f4c422a, v107
	v_add_f32_e32 v107, v107, v107
	v_mul_f32_e32 v107, 0x3fb8aa3b, v107
	v_exp_f32_e32 v107, v107
	v_div_fmas_f32 v104, v104, v108, v109
	v_div_fixup_f32 v104, v104, v105, 2.0
	v_sub_f32_e32 v104, 1.0, v104
	v_add_f32_e32 v105, 1.0, v107
	v_div_scale_f32 v107, s[28:29], v105, v105, 2.0
	v_rcp_f32_e32 v108, v107
	v_mul_f32_e32 v99, 0.5, v99
	v_add_f32_e32 v104, 1.0, v104
	v_mul_f32_e32 v99, v99, v104
	v_cvt_pk_bf16_f32 v104, v98, v99
; #define LAS __attribute__((address_space(3)))
; __device__ __forceinline__ unsigned cvt_pk_bf16(float lo, float hi) { unsigned r; asm volatile("v_cvt_pk_bf16_f32 %0, %1, %2" : "=v"(r) : "v"(lo), "v"(hi)); return r; }
; __device__ __forceinline__ float gelu_tanh(float x) { const float z = 0.7978845608f * (x + 0.044715f * x * x * x); const float th = 1.0f - 2.0f / (__expf(2.0f * z) + 1.0f); return 0.5f * x * (1.0f + th); }
;     __device__ __forceinline__ void operator()(const f32x4 (&acc)[2][2][4][2], const Unit& u, int ui, const LAS float* rtab, int wr, int wc, int fr, int fq) const {
;         const int g = u.pm; const int n0 = wr * 64 + fr; const int lc0 = (u.pn & 1) * 256 + wc * 32 + 8 * fq;
; #pragma unroll
;         for (int ai = 0; ai < 2; ++ai)
; #pragma unroll
;             for (int m = 0; m < 4; ++m) {
;                 const int n = n0 + ai * HALF + m * 16;
; #pragma unroll
;                 for (int bj = 0; bj < 2; ++bj) {
;                     const int lc = lc0 + bj * HALF, t = lc >> 4, co = lc & 15; const int token = n * 32 + t;
;                     const f32x4 a0 = acc[ai][bj][m][0], a1 = acc[ai][bj][m][1];
;                     u32x4 w; w.x = cvt_pk_bf16(gelu_tanh(a0[0]), gelu_tanh(a0[1])); w.y = cvt_pk_bf16(gelu_tanh(a0[2]), gelu_tanh(a0[3]));
;                     w.z = cvt_pk_bf16(gelu_tanh(a1[0]), gelu_tanh(a1[1])); w.w = cvt_pk_bf16(gelu_tanh(a1[2]), gelu_tanh(a1[3]));
;                     *(u32x4*)(Y + (size_t)token * 1024 + 16 * g + co) = w;
	v_fma_f32 v98, -v107, v108, 1.0
	v_fmac_f32_e32 v108, v98, v108
	v_div_scale_f32 v98, vcc, 2.0, v105, 2.0
	v_mul_f32_e32 v99, v98, v108
	v_fma_f32 v109, -v107, v99, v98
	v_fmac_f32_e32 v99, v109, v108
	v_fma_f32 v98, -v107, v99, v98
	v_mul_f32_e32 v107, 0x3d372713, v101
	v_mul_f32_e32 v107, v101, v107
	v_fma_f32 v107, v101, v107, v101
	v_mul_f32_e32 v107, 0x3f4c422a, v107
	v_add_f32_e32 v107, v107, v107
	v_mul_f32_e32 v107, 0x3fb8aa3b, v107
	v_exp_f32_e32 v107, v107
	v_div_fmas_f32 v98, v98, v108, v99
	v_div_fixup_f32 v98, v98, v105, 2.0
	v_sub_f32_e32 v98, 1.0, v98
	v_add_f32_e32 v99, 1.0, v107
	v_div_scale_f32 v105, s[28:29], v99, v99, 2.0
	v_rcp_f32_e32 v107, v105
	v_mul_f32_e32 v100, 0.5, v100
	v_add_f32_e32 v98, 1.0, v98
	v_mul_f32_e32 v98, v100, v98
	v_fma_f32 v100, -v105, v107, 1.0
	v_fmac_f32_e32 v107, v100, v107
	v_div_scale_f32 v100, vcc, 2.0, v99, 2.0
	v_mul_f32_e32 v108, v100, v107
	v_fma_f32 v109, -v105, v108, v100
	v_fmac_f32_e32 v108, v109, v107
	v_fma_f32 v100, -v105, v108, v100
	v_div_fmas_f32 v100, v100, v107, v108
	v_div_fixup_f32 v99, v100, v99, 2.0
	v_sub_f32_e32 v99, 1.0, v99
	v_mul_f32_e32 v100, 0.5, v101
	v_add_f32_e32 v99, 1.0, v99
	v_mul_f32_e32 v99, v100, v99
	v_mul_f32_e32 v100, 0x3d372713, v94
	v_mul_f32_e32 v100, v94, v100
	v_fma_f32 v100, v94, v100, v94
	v_mul_f32_e32 v100, 0x3f4c422a, v100
	v_add_f32_e32 v100, v100, v100
	v_mul_f32_e32 v100, 0x3fb8aa3b, v100
	v_exp_f32_e32 v100, v100
	v_or_b32_e32 v106, v124, v147
	v_ashrrev_i32_e32 v107, 31, v106
	v_cvt_pk_bf16_f32 v105, v98, v99
	v_add_f32_e32 v100, 1.0, v100
	v_div_scale_f32 v101, s[28:29], v100, v100, 2.0
	v_lshlrev_b64 v[98:99], 11, v[106:107]
	v_rcp_f32_e32 v106, v101
	v_lshl_add_u64 v[98:99], v[138:139], 0, v[98:99]
	global_store_dwordx4 v[98:99], v[102:105], off
	v_mul_f32_e32 v94, 0.5, v94
	v_fma_f32 v99, -v101, v106, 1.0
	v_fmac_f32_e32 v106, v99, v106
	v_div_scale_f32 v99, vcc, 2.0, v100, 2.0
	v_mul_f32_e32 v102, v99, v106
	v_fma_f32 v103, -v101, v102, v99
	v_fmac_f32_e32 v102, v103, v106
	v_fma_f32 v99, -v101, v102, v99
	v_mul_f32_e32 v101, 0x3d372713, v95
	v_mul_f32_e32 v101, v95, v101
	v_fma_f32 v101, v95, v101, v95
	v_mul_f32_e32 v101, 0x3f4c422a, v101
	v_add_f32_e32 v101, v101, v101
	v_mul_f32_e32 v101, 0x3fb8aa3b, v101
	v_exp_f32_e32 v101, v101
	v_div_fmas_f32 v99, v99, v106, v102
	v_div_fixup_f32 v99, v99, v100, 2.0
	v_sub_f32_e32 v99, 1.0, v99
	v_add_f32_e32 v100, 1.0, v101
	v_div_scale_f32 v101, s[28:29], v100, v100, 2.0
	v_rcp_f32_e32 v102, v101
	v_add_f32_e32 v99, 1.0, v99
	v_mul_f32_e32 v94, v94, v99
	v_mul_f32_e32 v95, 0.5, v95
	v_fma_f32 v99, -v101, v102, 1.0
	v_fmac_f32_e32 v102, v99, v102
	v_div_scale_f32 v99, vcc, 2.0, v100, 2.0
	v_mul_f32_e32 v103, v99, v102
	v_fma_f32 v104, -v101, v103, v99
	v_fmac_f32_e32 v103, v104, v102
	v_fma_f32 v99, -v101, v103, v99
	v_mul_f32_e32 v101, 0x3d372713, v96
	v_mul_f32_e32 v101, v96, v101
	v_fma_f32 v101, v96, v101, v96
	v_mul_f32_e32 v101, 0x3f4c422a, v101
	v_add_f32_e32 v101, v101, v101
	v_mul_f32_e32 v101, 0x3fb8aa3b, v101
	v_exp_f32_e32 v101, v101
	v_div_fmas_f32 v99, v99, v102, v103
	v_div_fixup_f32 v99, v99, v100, 2.0
	v_sub_f32_e32 v99, 1.0, v99
	v_add_f32_e32 v100, 1.0, v101
	v_div_scale_f32 v101, s[28:29], v100, v100, 2.0
	v_rcp_f32_e32 v102, v101
	v_add_f32_e32 v99, 1.0, v99
	v_mul_f32_e32 v95, v95, v99
	v_cvt_pk_bf16_f32 v94, v94, v95
	v_fma_f32 v95, -v101, v102, 1.0
	v_fmac_f32_e32 v102, v95, v102
	v_div_scale_f32 v95, vcc, 2.0, v100, 2.0
	v_mul_f32_e32 v99, v95, v102
	v_fma_f32 v103, -v101, v99, v95
	v_fmac_f32_e32 v99, v103, v102
	v_fma_f32 v95, -v101, v99, v95
	v_mul_f32_e32 v101, 0x3d372713, v97
	v_mul_f32_e32 v101, v97, v101
	v_fma_f32 v101, v97, v101, v97
	v_mul_f32_e32 v101, 0x3f4c422a, v101
	v_add_f32_e32 v101, v101, v101
	v_mul_f32_e32 v101, 0x3fb8aa3b, v101
	v_exp_f32_e32 v101, v101
	v_div_fmas_f32 v95, v95, v102, v99
	v_div_fixup_f32 v95, v95, v100, 2.0
	v_sub_f32_e32 v95, 1.0, v95
	v_add_f32_e32 v99, 1.0, v101
	v_div_scale_f32 v100, s[28:29], v99, v99, 2.0
	v_rcp_f32_e32 v101, v100
	v_mul_f32_e32 v96, 0.5, v96
	v_add_f32_e32 v95, 1.0, v95
	v_mul_f32_e32 v95, v96, v95
	v_fma_f32 v96, -v100, v101, 1.0
	v_fmac_f32_e32 v101, v96, v101
	v_div_scale_f32 v96, vcc, 2.0, v99, 2.0
	v_mul_f32_e32 v102, v96, v101
	v_fma_f32 v103, -v100, v102, v96
	v_fmac_f32_e32 v102, v103, v101
	v_fma_f32 v96, -v100, v102, v96
	v_mul_f32_e32 v100, 0x3d372713, v90
	v_mul_f32_e32 v100, v90, v100
	v_fma_f32 v100, v90, v100, v90
	v_mul_f32_e32 v100, 0x3f4c422a, v100
	v_add_f32_e32 v100, v100, v100
	v_mul_f32_e32 v100, 0x3fb8aa3b, v100
	v_exp_f32_e32 v100, v100
	v_div_fmas_f32 v96, v96, v101, v102
	v_div_fixup_f32 v96, v96, v99, 2.0
	v_sub_f32_e32 v96, 1.0, v96
	v_add_f32_e32 v99, 1.0, v100
	v_div_scale_f32 v100, s[28:29], v99, v99, 2.0
	v_rcp_f32_e32 v101, v100
	v_mul_f32_e32 v97, 0.5, v97
	v_add_f32_e32 v96, 1.0, v96
	v_mul_f32_e32 v96, v97, v96
	v_cvt_pk_bf16_f32 v95, v95, v96
	v_fma_f32 v96, -v100, v101, 1.0
	v_fmac_f32_e32 v101, v96, v101
	v_div_scale_f32 v96, vcc, 2.0, v99, 2.0
	v_mul_f32_e32 v97, v96, v101
	v_fma_f32 v102, -v100, v97, v96
	v_fmac_f32_e32 v97, v102, v101
	v_fma_f32 v96, -v100, v97, v96
	v_mul_f32_e32 v100, 0x3d372713, v91
	v_mul_f32_e32 v100, v91, v100
	v_fma_f32 v100, v91, v100, v91
	v_mul_f32_e32 v100, 0x3f4c422a, v100
	v_add_f32_e32 v100, v100, v100
	v_mul_f32_e32 v100, 0x3fb8aa3b, v100
	v_exp_f32_e32 v100, v100
	v_div_fmas_f32 v96, v96, v101, v97
	v_div_fixup_f32 v96, v96, v99, 2.0
	v_sub_f32_e32 v96, 1.0, v96
	v_add_f32_e32 v97, 1.0, v100
	v_div_scale_f32 v99, s[28:29], v97, v97, 2.0
	v_rcp_f32_e32 v100, v99
	v_mul_f32_e32 v90, 0.5, v90
	v_add_f32_e32 v96, 1.0, v96
; #define LAS __attribute__((address_space(3)))
; __device__ __forceinline__ unsigned cvt_pk_bf16(float lo, float hi) { unsigned r; asm volatile("v_cvt_pk_bf16_f32 %0, %1, %2" : "=v"(r) : "v"(lo), "v"(hi)); return r; }
; __device__ __forceinline__ float gelu_tanh(float x) { const float z = 0.7978845608f * (x + 0.044715f * x * x * x); const float th = 1.0f - 2.0f / (__expf(2.0f * z) + 1.0f); return 0.5f * x * (1.0f + th); }
;     __device__ __forceinline__ void operator()(const f32x4 (&acc)[2][2][4][2], const Unit& u, int ui, const LAS float* rtab, int wr, int wc, int fr, int fq) const {
;         const int g = u.pm; const int n0 = wr * 64 + fr; const int lc0 = (u.pn & 1) * 256 + wc * 32 + 8 * fq;
; #pragma unroll
;         for (int ai = 0; ai < 2; ++ai)
; #pragma unroll
;             for (int m = 0; m < 4; ++m) {
;                 const int n = n0 + ai * HALF + m * 16;
; #pragma unroll
;                 for (int bj = 0; bj < 2; ++bj) {
;                     const int lc = lc0 + bj * HALF, t = lc >> 4, co = lc & 15; const int token = n * 32 + t;
;                     const f32x4 a0 = acc[ai][bj][m][0], a1 = acc[ai][bj][m][1];
;                     u32x4 w; w.x = cvt_pk_bf16(gelu_tanh(a0[0]), gelu_tanh(a0[1])); w.y = cvt_pk_bf16(gelu_tanh(a0[2]), gelu_tanh(a0[3]));
;                     w.z = cvt_pk_bf16(gelu_tanh(a1[0]), gelu_tanh(a1[1])); w.w = cvt_pk_bf16(gelu_tanh(a1[2]), gelu_tanh(a1[3]));
;                     *(u32x4*)(Y + (size_t)token * 1024 + 16 * g + co) = w;
	v_mul_f32_e32 v90, v90, v96
	v_fma_f32 v96, -v99, v100, 1.0
	v_fmac_f32_e32 v100, v96, v100
	v_div_scale_f32 v96, vcc, 2.0, v97, 2.0
	v_mul_f32_e32 v101, v96, v100
	v_fma_f32 v102, -v99, v101, v96
	v_fmac_f32_e32 v101, v102, v100
	v_fma_f32 v96, -v99, v101, v96
	v_mul_f32_e32 v99, 0x3d372713, v92
	v_mul_f32_e32 v99, v92, v99
	v_fma_f32 v99, v92, v99, v92
	v_mul_f32_e32 v99, 0x3f4c422a, v99
	v_add_f32_e32 v99, v99, v99
	v_mul_f32_e32 v99, 0x3fb8aa3b, v99
	v_exp_f32_e32 v99, v99
	v_div_fmas_f32 v96, v96, v100, v101
	v_div_fixup_f32 v96, v96, v97, 2.0
	v_sub_f32_e32 v96, 1.0, v96
	v_add_f32_e32 v97, 1.0, v99
	v_div_scale_f32 v99, s[28:29], v97, v97, 2.0
	v_rcp_f32_e32 v100, v99
	v_mul_f32_e32 v91, 0.5, v91
	v_add_f32_e32 v96, 1.0, v96
	v_mul_f32_e32 v91, v91, v96
	v_cvt_pk_bf16_f32 v96, v90, v91
	v_fma_f32 v90, -v99, v100, 1.0
	v_fmac_f32_e32 v100, v90, v100
	v_div_scale_f32 v90, vcc, 2.0, v97, 2.0
	v_mul_f32_e32 v91, v90, v100
	v_fma_f32 v101, -v99, v91, v90
	v_fmac_f32_e32 v91, v101, v100
	v_fma_f32 v90, -v99, v91, v90
	v_mul_f32_e32 v99, 0x3d372713, v93
	v_mul_f32_e32 v99, v93, v99
	v_fma_f32 v99, v93, v99, v93
	v_mul_f32_e32 v99, 0x3f4c422a, v99
	v_add_f32_e32 v99, v99, v99
	v_mul_f32_e32 v99, 0x3fb8aa3b, v99
	v_exp_f32_e32 v99, v99
	v_div_fmas_f32 v90, v90, v100, v91
	v_div_fixup_f32 v90, v90, v97, 2.0
	v_sub_f32_e32 v90, 1.0, v90
	v_add_f32_e32 v91, 1.0, v99
	v_div_scale_f32 v97, s[28:29], v91, v91, 2.0
	v_rcp_f32_e32 v99, v97
	v_mul_f32_e32 v92, 0.5, v92
	v_add_f32_e32 v90, 1.0, v90
	v_mul_f32_e32 v90, v92, v90
	v_fma_f32 v92, -v97, v99, 1.0
	v_fmac_f32_e32 v99, v92, v99
	v_div_scale_f32 v92, vcc, 2.0, v91, 2.0
	v_mul_f32_e32 v100, v92, v99
	v_fma_f32 v101, -v97, v100, v92
	v_fmac_f32_e32 v100, v101, v99
	v_fma_f32 v92, -v97, v100, v92
	v_div_fmas_f32 v92, v92, v99, v100
	v_div_fixup_f32 v91, v92, v91, 2.0
	v_sub_f32_e32 v91, 1.0, v91
	v_mul_f32_e32 v92, 0.5, v93
	v_add_f32_e32 v91, 1.0, v91
	v_mul_f32_e32 v91, v92, v91
	v_mul_f32_e32 v92, 0x3d372713, v86
	v_mul_f32_e32 v92, v86, v92
	v_fma_f32 v92, v86, v92, v86
	v_mul_f32_e32 v92, 0x3f4c422a, v92
	v_add_f32_e32 v92, v92, v92
	v_mul_f32_e32 v92, 0x3fb8aa3b, v92
	v_exp_f32_e32 v92, v92
	v_or_b32_e32 v98, v171, v148
	v_ashrrev_i32_e32 v99, 31, v98
	v_cvt_pk_bf16_f32 v97, v90, v91
	v_add_f32_e32 v92, 1.0, v92
	v_div_scale_f32 v93, s[28:29], v92, v92, 2.0
	v_lshlrev_b64 v[90:91], 11, v[98:99]
	v_rcp_f32_e32 v98, v93
	v_lshl_add_u64 v[90:91], v[138:139], 0, v[90:91]
	global_store_dwordx4 v[90:91], v[94:97], off
	v_mul_f32_e32 v86, 0.5, v86
	v_fma_f32 v91, -v93, v98, 1.0
	v_fmac_f32_e32 v98, v91, v98
	v_div_scale_f32 v91, vcc, 2.0, v92, 2.0
	v_mul_f32_e32 v94, v91, v98
	v_fma_f32 v95, -v93, v94, v91
	v_fmac_f32_e32 v94, v95, v98
	v_fma_f32 v91, -v93, v94, v91
	v_mul_f32_e32 v93, 0x3d372713, v87
	v_mul_f32_e32 v93, v87, v93
	v_fma_f32 v93, v87, v93, v87
	v_mul_f32_e32 v93, 0x3f4c422a, v93
	v_add_f32_e32 v93, v93, v93
	v_mul_f32_e32 v93, 0x3fb8aa3b, v93
	v_exp_f32_e32 v93, v93
	v_div_fmas_f32 v91, v91, v98, v94
	v_div_fixup_f32 v91, v91, v92, 2.0
	v_sub_f32_e32 v91, 1.0, v91
	v_add_f32_e32 v92, 1.0, v93
	v_div_scale_f32 v93, s[28:29], v92, v92, 2.0
	v_rcp_f32_e32 v94, v93
	v_add_f32_e32 v91, 1.0, v91
	v_mul_f32_e32 v86, v86, v91
	v_mul_f32_e32 v87, 0.5, v87
	v_fma_f32 v91, -v93, v94, 1.0
	v_fmac_f32_e32 v94, v91, v94
	v_div_scale_f32 v91, vcc, 2.0, v92, 2.0
	v_mul_f32_e32 v95, v91, v94
	v_fma_f32 v96, -v93, v95, v91
	v_fmac_f32_e32 v95, v96, v94
	v_fma_f32 v91, -v93, v95, v91
	v_mul_f32_e32 v93, 0x3d372713, v88
	v_mul_f32_e32 v93, v88, v93
	v_fma_f32 v93, v88, v93, v88
	v_mul_f32_e32 v93, 0x3f4c422a, v93
	v_add_f32_e32 v93, v93, v93
	v_mul_f32_e32 v93, 0x3fb8aa3b, v93
	v_exp_f32_e32 v93, v93
	v_div_fmas_f32 v91, v91, v94, v95
	v_div_fixup_f32 v91, v91, v92, 2.0
	v_sub_f32_e32 v91, 1.0, v91
	v_add_f32_e32 v92, 1.0, v93
	v_div_scale_f32 v93, s[28:29], v92, v92, 2.0
	v_rcp_f32_e32 v94, v93
	v_add_f32_e32 v91, 1.0, v91
	v_mul_f32_e32 v87, v87, v91
	v_cvt_pk_bf16_f32 v86, v86, v87
	v_fma_f32 v87, -v93, v94, 1.0
	v_fmac_f32_e32 v94, v87, v94
	v_div_scale_f32 v87, vcc, 2.0, v92, 2.0
	v_mul_f32_e32 v91, v87, v94
	v_fma_f32 v95, -v93, v91, v87
	v_fmac_f32_e32 v91, v95, v94
	v_fma_f32 v87, -v93, v91, v87
	v_mul_f32_e32 v93, 0x3d372713, v89
	v_mul_f32_e32 v93, v89, v93
	v_fma_f32 v93, v89, v93, v89
	v_mul_f32_e32 v93, 0x3f4c422a, v93
	v_add_f32_e32 v93, v93, v93
	v_mul_f32_e32 v93, 0x3fb8aa3b, v93
	v_exp_f32_e32 v93, v93
	v_div_fmas_f32 v87, v87, v94, v91
	v_div_fixup_f32 v87, v87, v92, 2.0
	v_sub_f32_e32 v87, 1.0, v87
	v_add_f32_e32 v91, 1.0, v93
	v_div_scale_f32 v92, s[28:29], v91, v91, 2.0
	v_rcp_f32_e32 v93, v92
	v_mul_f32_e32 v88, 0.5, v88
	v_add_f32_e32 v87, 1.0, v87
	v_mul_f32_e32 v87, v88, v87
	v_fma_f32 v88, -v92, v93, 1.0
	v_fmac_f32_e32 v93, v88, v93
	v_div_scale_f32 v88, vcc, 2.0, v91, 2.0
	v_mul_f32_e32 v94, v88, v93
	v_fma_f32 v95, -v92, v94, v88
	v_fmac_f32_e32 v94, v95, v93
	v_fma_f32 v88, -v92, v94, v88
	v_mul_f32_e32 v92, 0x3d372713, v82
	v_mul_f32_e32 v92, v82, v92
	v_fma_f32 v92, v82, v92, v82
	v_mul_f32_e32 v92, 0x3f4c422a, v92
	v_add_f32_e32 v92, v92, v92
	v_mul_f32_e32 v92, 0x3fb8aa3b, v92
	v_exp_f32_e32 v92, v92
	v_div_fmas_f32 v88, v88, v93, v94
	v_div_fixup_f32 v88, v88, v91, 2.0
	v_sub_f32_e32 v88, 1.0, v88
	v_add_f32_e32 v91, 1.0, v92
	v_div_scale_f32 v92, s[28:29], v91, v91, 2.0
	v_rcp_f32_e32 v93, v92
	v_mul_f32_e32 v89, 0.5, v89
	v_add_f32_e32 v88, 1.0, v88
	v_mul_f32_e32 v88, v89, v88
	v_cvt_pk_bf16_f32 v87, v87, v88
	v_fma_f32 v88, -v92, v93, 1.0
	v_fmac_f32_e32 v93, v88, v93
	v_div_scale_f32 v88, vcc, 2.0, v91, 2.0
	v_mul_f32_e32 v89, v88, v93
	v_fma_f32 v94, -v92, v89, v88
; #define LAS __attribute__((address_space(3)))
; __device__ __forceinline__ unsigned cvt_pk_bf16(float lo, float hi) { unsigned r; asm volatile("v_cvt_pk_bf16_f32 %0, %1, %2" : "=v"(r) : "v"(lo), "v"(hi)); return r; }
; __device__ __forceinline__ float gelu_tanh(float x) { const float z = 0.7978845608f * (x + 0.044715f * x * x * x); const float th = 1.0f - 2.0f / (__expf(2.0f * z) + 1.0f); return 0.5f * x * (1.0f + th); }
;     __device__ __forceinline__ void operator()(const f32x4 (&acc)[2][2][4][2], const Unit& u, int ui, const LAS float* rtab, int wr, int wc, int fr, int fq) const {
;         const int g = u.pm; const int n0 = wr * 64 + fr; const int lc0 = (u.pn & 1) * 256 + wc * 32 + 8 * fq;
; #pragma unroll
;         for (int ai = 0; ai < 2; ++ai)
; #pragma unroll
;             for (int m = 0; m < 4; ++m) {
;                 const int n = n0 + ai * HALF + m * 16;
; #pragma unroll
;                 for (int bj = 0; bj < 2; ++bj) {
;                     const int lc = lc0 + bj * HALF, t = lc >> 4, co = lc & 15; const int token = n * 32 + t;
;                     const f32x4 a0 = acc[ai][bj][m][0], a1 = acc[ai][bj][m][1];
;                     u32x4 w; w.x = cvt_pk_bf16(gelu_tanh(a0[0]), gelu_tanh(a0[1])); w.y = cvt_pk_bf16(gelu_tanh(a0[2]), gelu_tanh(a0[3]));
;                     w.z = cvt_pk_bf16(gelu_tanh(a1[0]), gelu_tanh(a1[1])); w.w = cvt_pk_bf16(gelu_tanh(a1[2]), gelu_tanh(a1[3]));
;                     *(u32x4*)(Y + (size_t)token * 1024 + 16 * g + co) = w;
	v_fmac_f32_e32 v89, v94, v93
	v_fma_f32 v88, -v92, v89, v88
	v_mul_f32_e32 v92, 0x3d372713, v83
	v_mul_f32_e32 v92, v83, v92
	v_fma_f32 v92, v83, v92, v83
	v_mul_f32_e32 v92, 0x3f4c422a, v92
	v_add_f32_e32 v92, v92, v92
	v_mul_f32_e32 v92, 0x3fb8aa3b, v92
	v_exp_f32_e32 v92, v92
	v_div_fmas_f32 v88, v88, v93, v89
	v_div_fixup_f32 v88, v88, v91, 2.0
	v_sub_f32_e32 v88, 1.0, v88
	v_add_f32_e32 v89, 1.0, v92
	v_div_scale_f32 v91, s[28:29], v89, v89, 2.0
	v_rcp_f32_e32 v92, v91
	v_mul_f32_e32 v82, 0.5, v82
	v_add_f32_e32 v88, 1.0, v88
	v_mul_f32_e32 v82, v82, v88
	v_fma_f32 v88, -v91, v92, 1.0
	v_fmac_f32_e32 v92, v88, v92
	v_div_scale_f32 v88, vcc, 2.0, v89, 2.0
	v_mul_f32_e32 v93, v88, v92
	v_fma_f32 v94, -v91, v93, v88
	v_fmac_f32_e32 v93, v94, v92
	v_fma_f32 v88, -v91, v93, v88
	v_mul_f32_e32 v91, 0x3d372713, v84
	v_mul_f32_e32 v91, v84, v91
	v_fma_f32 v91, v84, v91, v84
	v_mul_f32_e32 v91, 0x3f4c422a, v91
	v_add_f32_e32 v91, v91, v91
	v_mul_f32_e32 v91, 0x3fb8aa3b, v91
	v_exp_f32_e32 v91, v91
	v_div_fmas_f32 v88, v88, v92, v93
	v_div_fixup_f32 v88, v88, v89, 2.0
	v_sub_f32_e32 v88, 1.0, v88
	v_add_f32_e32 v89, 1.0, v91
	v_div_scale_f32 v91, s[28:29], v89, v89, 2.0
	v_rcp_f32_e32 v92, v91
	v_mul_f32_e32 v83, 0.5, v83
	v_add_f32_e32 v88, 1.0, v88
	v_mul_f32_e32 v83, v83, v88
	v_cvt_pk_bf16_f32 v88, v82, v83
	v_fma_f32 v82, -v91, v92, 1.0
	v_fmac_f32_e32 v92, v82, v92
	v_div_scale_f32 v82, vcc, 2.0, v89, 2.0
	v_mul_f32_e32 v83, v82, v92
	v_fma_f32 v93, -v91, v83, v82
	v_fmac_f32_e32 v83, v93, v92
	v_fma_f32 v82, -v91, v83, v82
	v_mul_f32_e32 v91, 0x3d372713, v85
	v_mul_f32_e32 v91, v85, v91
	v_fma_f32 v91, v85, v91, v85
	v_mul_f32_e32 v91, 0x3f4c422a, v91
	v_add_f32_e32 v91, v91, v91
	v_mul_f32_e32 v91, 0x3fb8aa3b, v91
	v_exp_f32_e32 v91, v91
	v_div_fmas_f32 v82, v82, v92, v83
	v_div_fixup_f32 v82, v82, v89, 2.0
	v_sub_f32_e32 v82, 1.0, v82
	v_add_f32_e32 v83, 1.0, v91
	v_div_scale_f32 v89, s[28:29], v83, v83, 2.0
	v_rcp_f32_e32 v91, v89
	v_mul_f32_e32 v84, 0.5, v84
	v_add_f32_e32 v82, 1.0, v82
	v_mul_f32_e32 v82, v84, v82
	v_fma_f32 v84, -v89, v91, 1.0
	v_fmac_f32_e32 v91, v84, v91
	v_div_scale_f32 v84, vcc, 2.0, v83, 2.0
	v_mul_f32_e32 v92, v84, v91
	v_fma_f32 v93, -v89, v92, v84
	v_fmac_f32_e32 v92, v93, v91
	v_fma_f32 v84, -v89, v92, v84
	v_div_fmas_f32 v84, v84, v91, v92
	v_div_fixup_f32 v83, v84, v83, 2.0
	v_sub_f32_e32 v83, 1.0, v83
	v_mul_f32_e32 v84, 0.5, v85
	v_add_f32_e32 v83, 1.0, v83
	v_mul_f32_e32 v83, v84, v83
	v_mul_f32_e32 v84, 0x3d372713, v78
	v_mul_f32_e32 v84, v78, v84
	v_fma_f32 v84, v78, v84, v78
	v_mul_f32_e32 v84, 0x3f4c422a, v84
	v_add_f32_e32 v84, v84, v84
	v_mul_f32_e32 v84, 0x3fb8aa3b, v84
	v_exp_f32_e32 v84, v84
	v_or_b32_e32 v90, v124, v148
	v_ashrrev_i32_e32 v91, 31, v90
	v_cvt_pk_bf16_f32 v89, v82, v83
	v_add_f32_e32 v84, 1.0, v84
	v_div_scale_f32 v85, s[28:29], v84, v84, 2.0
	v_lshlrev_b64 v[82:83], 11, v[90:91]
	v_rcp_f32_e32 v90, v85
	v_lshl_add_u64 v[82:83], v[138:139], 0, v[82:83]
	global_store_dwordx4 v[82:83], v[86:89], off
	v_mul_f32_e32 v78, 0.5, v78
	v_fma_f32 v83, -v85, v90, 1.0
	v_fmac_f32_e32 v90, v83, v90
	v_div_scale_f32 v83, vcc, 2.0, v84, 2.0
	v_mul_f32_e32 v86, v83, v90
	v_fma_f32 v87, -v85, v86, v83
	v_fmac_f32_e32 v86, v87, v90
	v_fma_f32 v83, -v85, v86, v83
	v_mul_f32_e32 v85, 0x3d372713, v79
	v_mul_f32_e32 v85, v79, v85
	v_fma_f32 v85, v79, v85, v79
	v_mul_f32_e32 v85, 0x3f4c422a, v85
	v_add_f32_e32 v85, v85, v85
	v_mul_f32_e32 v85, 0x3fb8aa3b, v85
	v_exp_f32_e32 v85, v85
	v_div_fmas_f32 v83, v83, v90, v86
	v_div_fixup_f32 v83, v83, v84, 2.0
	v_sub_f32_e32 v83, 1.0, v83
	v_add_f32_e32 v84, 1.0, v85
	v_div_scale_f32 v85, s[28:29], v84, v84, 2.0
	v_rcp_f32_e32 v86, v85
	v_add_f32_e32 v83, 1.0, v83
	v_mul_f32_e32 v78, v78, v83
	v_mul_f32_e32 v79, 0.5, v79
	v_fma_f32 v83, -v85, v86, 1.0
	v_fmac_f32_e32 v86, v83, v86
	v_div_scale_f32 v83, vcc, 2.0, v84, 2.0
	v_mul_f32_e32 v87, v83, v86
	v_fma_f32 v88, -v85, v87, v83
	v_fmac_f32_e32 v87, v88, v86
	v_fma_f32 v83, -v85, v87, v83
	v_mul_f32_e32 v85, 0x3d372713, v80
	v_mul_f32_e32 v85, v80, v85
	v_fma_f32 v85, v80, v85, v80
	v_mul_f32_e32 v85, 0x3f4c422a, v85
	v_add_f32_e32 v85, v85, v85
	v_mul_f32_e32 v85, 0x3fb8aa3b, v85
	v_exp_f32_e32 v85, v85
	v_div_fmas_f32 v83, v83, v86, v87
	v_div_fixup_f32 v83, v83, v84, 2.0
	v_sub_f32_e32 v83, 1.0, v83
	v_add_f32_e32 v84, 1.0, v85
	v_div_scale_f32 v85, s[28:29], v84, v84, 2.0
	v_rcp_f32_e32 v86, v85
	v_add_f32_e32 v83, 1.0, v83
	v_mul_f32_e32 v79, v79, v83
	v_cvt_pk_bf16_f32 v78, v78, v79
	v_fma_f32 v79, -v85, v86, 1.0
	v_fmac_f32_e32 v86, v79, v86
	v_div_scale_f32 v79, vcc, 2.0, v84, 2.0
	v_mul_f32_e32 v83, v79, v86
	v_fma_f32 v87, -v85, v83, v79
	v_fmac_f32_e32 v83, v87, v86
	v_fma_f32 v79, -v85, v83, v79
	v_mul_f32_e32 v85, 0x3d372713, v81
	v_mul_f32_e32 v85, v81, v85
	v_fma_f32 v85, v81, v85, v81
	v_mul_f32_e32 v85, 0x3f4c422a, v85
	v_add_f32_e32 v85, v85, v85
	v_mul_f32_e32 v85, 0x3fb8aa3b, v85
	v_exp_f32_e32 v85, v85
	v_div_fmas_f32 v79, v79, v86, v83
	v_div_fixup_f32 v79, v79, v84, 2.0
	v_sub_f32_e32 v79, 1.0, v79
	v_add_f32_e32 v83, 1.0, v85
	v_div_scale_f32 v84, s[28:29], v83, v83, 2.0
	v_rcp_f32_e32 v85, v84
	v_mul_f32_e32 v80, 0.5, v80
	v_add_f32_e32 v79, 1.0, v79
	v_mul_f32_e32 v79, v80, v79
	v_fma_f32 v80, -v84, v85, 1.0
	v_fmac_f32_e32 v85, v80, v85
	v_div_scale_f32 v80, vcc, 2.0, v83, 2.0
	v_mul_f32_e32 v86, v80, v85
	v_fma_f32 v87, -v84, v86, v80
	v_fmac_f32_e32 v86, v87, v85
	v_fma_f32 v80, -v84, v86, v80
	v_mul_f32_e32 v84, 0x3d372713, v74
	v_mul_f32_e32 v84, v74, v84
	v_fma_f32 v84, v74, v84, v74
	v_mul_f32_e32 v84, 0x3f4c422a, v84
	v_add_f32_e32 v84, v84, v84
	v_mul_f32_e32 v84, 0x3fb8aa3b, v84
; #define LAS __attribute__((address_space(3)))
; __device__ __forceinline__ unsigned cvt_pk_bf16(float lo, float hi) { unsigned r; asm volatile("v_cvt_pk_bf16_f32 %0, %1, %2" : "=v"(r) : "v"(lo), "v"(hi)); return r; }
; __device__ __forceinline__ float gelu_tanh(float x) { const float z = 0.7978845608f * (x + 0.044715f * x * x * x); const float th = 1.0f - 2.0f / (__expf(2.0f * z) + 1.0f); return 0.5f * x * (1.0f + th); }
;     __device__ __forceinline__ void operator()(const f32x4 (&acc)[2][2][4][2], const Unit& u, int ui, const LAS float* rtab, int wr, int wc, int fr, int fq) const {
;         const int g = u.pm; const int n0 = wr * 64 + fr; const int lc0 = (u.pn & 1) * 256 + wc * 32 + 8 * fq;
; #pragma unroll
;         for (int ai = 0; ai < 2; ++ai)
; #pragma unroll
;             for (int m = 0; m < 4; ++m) {
;                 const int n = n0 + ai * HALF + m * 16;
; #pragma unroll
;                 for (int bj = 0; bj < 2; ++bj) {
;                     const int lc = lc0 + bj * HALF, t = lc >> 4, co = lc & 15; const int token = n * 32 + t;
;                     const f32x4 a0 = acc[ai][bj][m][0], a1 = acc[ai][bj][m][1];
;                     u32x4 w; w.x = cvt_pk_bf16(gelu_tanh(a0[0]), gelu_tanh(a0[1])); w.y = cvt_pk_bf16(gelu_tanh(a0[2]), gelu_tanh(a0[3]));
;                     w.z = cvt_pk_bf16(gelu_tanh(a1[0]), gelu_tanh(a1[1])); w.w = cvt_pk_bf16(gelu_tanh(a1[2]), gelu_tanh(a1[3]));
;                     *(u32x4*)(Y + (size_t)token * 1024 + 16 * g + co) = w;
	v_exp_f32_e32 v84, v84
	v_div_fmas_f32 v80, v80, v85, v86
	v_div_fixup_f32 v80, v80, v83, 2.0
	v_sub_f32_e32 v80, 1.0, v80
	v_add_f32_e32 v83, 1.0, v84
	v_div_scale_f32 v84, s[28:29], v83, v83, 2.0
	v_rcp_f32_e32 v85, v84
	v_mul_f32_e32 v81, 0.5, v81
	v_add_f32_e32 v80, 1.0, v80
	v_mul_f32_e32 v80, v81, v80
	v_cvt_pk_bf16_f32 v79, v79, v80
	v_fma_f32 v80, -v84, v85, 1.0
	v_fmac_f32_e32 v85, v80, v85
	v_div_scale_f32 v80, vcc, 2.0, v83, 2.0
	v_mul_f32_e32 v81, v80, v85
	v_fma_f32 v86, -v84, v81, v80
	v_fmac_f32_e32 v81, v86, v85
	v_fma_f32 v80, -v84, v81, v80
	v_mul_f32_e32 v84, 0x3d372713, v75
	v_mul_f32_e32 v84, v75, v84
	v_fma_f32 v84, v75, v84, v75
	v_mul_f32_e32 v84, 0x3f4c422a, v84
	v_add_f32_e32 v84, v84, v84
	v_mul_f32_e32 v84, 0x3fb8aa3b, v84
	v_exp_f32_e32 v84, v84
	v_div_fmas_f32 v80, v80, v85, v81
	v_div_fixup_f32 v80, v80, v83, 2.0
	v_sub_f32_e32 v80, 1.0, v80
	v_add_f32_e32 v81, 1.0, v84
	v_div_scale_f32 v83, s[28:29], v81, v81, 2.0
	v_rcp_f32_e32 v84, v83
	v_mul_f32_e32 v74, 0.5, v74
	v_add_f32_e32 v80, 1.0, v80
	v_mul_f32_e32 v74, v74, v80
	v_fma_f32 v80, -v83, v84, 1.0
	v_fmac_f32_e32 v84, v80, v84
	v_div_scale_f32 v80, vcc, 2.0, v81, 2.0
	v_mul_f32_e32 v85, v80, v84
	v_fma_f32 v86, -v83, v85, v80
	v_fmac_f32_e32 v85, v86, v84
	v_fma_f32 v80, -v83, v85, v80
	v_mul_f32_e32 v83, 0x3d372713, v76
	v_mul_f32_e32 v83, v76, v83
	v_fma_f32 v83, v76, v83, v76
	v_mul_f32_e32 v83, 0x3f4c422a, v83
	v_add_f32_e32 v83, v83, v83
	v_mul_f32_e32 v83, 0x3fb8aa3b, v83
	v_exp_f32_e32 v83, v83
	v_div_fmas_f32 v80, v80, v84, v85
	v_div_fixup_f32 v80, v80, v81, 2.0
	v_sub_f32_e32 v80, 1.0, v80
	v_add_f32_e32 v81, 1.0, v83
	v_div_scale_f32 v83, s[28:29], v81, v81, 2.0
	v_rcp_f32_e32 v84, v83
	v_mul_f32_e32 v75, 0.5, v75
	v_add_f32_e32 v80, 1.0, v80
	v_mul_f32_e32 v75, v75, v80
	v_cvt_pk_bf16_f32 v80, v74, v75
	v_fma_f32 v74, -v83, v84, 1.0
	v_fmac_f32_e32 v84, v74, v84
	v_div_scale_f32 v74, vcc, 2.0, v81, 2.0
	v_mul_f32_e32 v75, v74, v84
	v_fma_f32 v85, -v83, v75, v74
	v_fmac_f32_e32 v75, v85, v84
	v_fma_f32 v74, -v83, v75, v74
	v_mul_f32_e32 v83, 0x3d372713, v77
	v_mul_f32_e32 v83, v77, v83
	v_fma_f32 v83, v77, v83, v77
	v_mul_f32_e32 v83, 0x3f4c422a, v83
	v_add_f32_e32 v83, v83, v83
	v_mul_f32_e32 v83, 0x3fb8aa3b, v83
	v_exp_f32_e32 v83, v83
	v_div_fmas_f32 v74, v74, v84, v75
	v_div_fixup_f32 v74, v74, v81, 2.0
	v_sub_f32_e32 v74, 1.0, v74
	v_add_f32_e32 v75, 1.0, v83
	v_div_scale_f32 v81, s[28:29], v75, v75, 2.0
	v_rcp_f32_e32 v83, v81
	v_mul_f32_e32 v76, 0.5, v76
	v_add_f32_e32 v74, 1.0, v74
	v_mul_f32_e32 v74, v76, v74
	v_fma_f32 v76, -v81, v83, 1.0
	v_fmac_f32_e32 v83, v76, v83
	v_div_scale_f32 v76, vcc, 2.0, v75, 2.0
	v_mul_f32_e32 v84, v76, v83
	v_fma_f32 v85, -v81, v84, v76
	v_fmac_f32_e32 v84, v85, v83
	v_fma_f32 v76, -v81, v84, v76
	v_div_fmas_f32 v76, v76, v83, v84
	v_div_fixup_f32 v75, v76, v75, 2.0
	v_sub_f32_e32 v75, 1.0, v75
	v_mul_f32_e32 v76, 0.5, v77
	v_add_f32_e32 v75, 1.0, v75
	v_mul_f32_e32 v75, v76, v75
	v_mul_f32_e32 v76, 0x3d372713, v70
	v_mul_f32_e32 v76, v70, v76
	v_fma_f32 v76, v70, v76, v70
	v_mul_f32_e32 v76, 0x3f4c422a, v76
	v_add_f32_e32 v76, v76, v76
	v_mul_f32_e32 v76, 0x3fb8aa3b, v76
	v_exp_f32_e32 v76, v76
	v_or_b32_e32 v82, v171, v149
	v_ashrrev_i32_e32 v83, 31, v82
	v_cvt_pk_bf16_f32 v81, v74, v75
	v_add_f32_e32 v76, 1.0, v76
	v_div_scale_f32 v77, s[28:29], v76, v76, 2.0
	v_lshlrev_b64 v[74:75], 11, v[82:83]
	v_rcp_f32_e32 v82, v77
	v_lshl_add_u64 v[74:75], v[138:139], 0, v[74:75]
	global_store_dwordx4 v[74:75], v[78:81], off
	v_mul_f32_e32 v70, 0.5, v70
	v_fma_f32 v75, -v77, v82, 1.0
	v_fmac_f32_e32 v82, v75, v82
	v_div_scale_f32 v75, vcc, 2.0, v76, 2.0
	v_mul_f32_e32 v78, v75, v82
	v_fma_f32 v79, -v77, v78, v75
	v_fmac_f32_e32 v78, v79, v82
	v_fma_f32 v75, -v77, v78, v75
	v_mul_f32_e32 v77, 0x3d372713, v71
	v_mul_f32_e32 v77, v71, v77
	v_fma_f32 v77, v71, v77, v71
	v_mul_f32_e32 v77, 0x3f4c422a, v77
	v_add_f32_e32 v77, v77, v77
	v_mul_f32_e32 v77, 0x3fb8aa3b, v77
	v_exp_f32_e32 v77, v77
	v_div_fmas_f32 v75, v75, v82, v78
	v_div_fixup_f32 v75, v75, v76, 2.0
	v_sub_f32_e32 v75, 1.0, v75
	v_add_f32_e32 v76, 1.0, v77
	v_div_scale_f32 v77, s[28:29], v76, v76, 2.0
	v_rcp_f32_e32 v78, v77
	v_add_f32_e32 v75, 1.0, v75
	v_mul_f32_e32 v70, v70, v75
	v_mul_f32_e32 v71, 0.5, v71
	v_fma_f32 v75, -v77, v78, 1.0
	v_fmac_f32_e32 v78, v75, v78
	v_div_scale_f32 v75, vcc, 2.0, v76, 2.0
	v_mul_f32_e32 v79, v75, v78
	v_fma_f32 v80, -v77, v79, v75
	v_fmac_f32_e32 v79, v80, v78
	v_fma_f32 v75, -v77, v79, v75
	v_mul_f32_e32 v77, 0x3d372713, v72
	v_mul_f32_e32 v77, v72, v77
	v_fma_f32 v77, v72, v77, v72
	v_mul_f32_e32 v77, 0x3f4c422a, v77
	v_add_f32_e32 v77, v77, v77
	v_mul_f32_e32 v77, 0x3fb8aa3b, v77
	v_exp_f32_e32 v77, v77
	v_div_fmas_f32 v75, v75, v78, v79
	v_div_fixup_f32 v75, v75, v76, 2.0
	v_sub_f32_e32 v75, 1.0, v75
	v_add_f32_e32 v76, 1.0, v77
	v_div_scale_f32 v77, s[28:29], v76, v76, 2.0
	v_rcp_f32_e32 v78, v77
	v_add_f32_e32 v75, 1.0, v75
	v_mul_f32_e32 v71, v71, v75
	v_cvt_pk_bf16_f32 v70, v70, v71
	v_fma_f32 v71, -v77, v78, 1.0
	v_fmac_f32_e32 v78, v71, v78
	v_div_scale_f32 v71, vcc, 2.0, v76, 2.0
	v_mul_f32_e32 v75, v71, v78
	v_fma_f32 v79, -v77, v75, v71
	v_fmac_f32_e32 v75, v79, v78
	v_fma_f32 v71, -v77, v75, v71
	v_mul_f32_e32 v77, 0x3d372713, v73
	v_mul_f32_e32 v77, v73, v77
	v_fma_f32 v77, v73, v77, v73
	v_mul_f32_e32 v77, 0x3f4c422a, v77
	v_add_f32_e32 v77, v77, v77
	v_mul_f32_e32 v77, 0x3fb8aa3b, v77
	v_exp_f32_e32 v77, v77
	v_div_fmas_f32 v71, v71, v78, v75
	v_div_fixup_f32 v71, v71, v76, 2.0
	v_sub_f32_e32 v71, 1.0, v71
	v_add_f32_e32 v75, 1.0, v77
	v_div_scale_f32 v76, s[28:29], v75, v75, 2.0
; #define LAS __attribute__((address_space(3)))
; __device__ __forceinline__ unsigned cvt_pk_bf16(float lo, float hi) { unsigned r; asm volatile("v_cvt_pk_bf16_f32 %0, %1, %2" : "=v"(r) : "v"(lo), "v"(hi)); return r; }
; __device__ __forceinline__ float gelu_tanh(float x) { const float z = 0.7978845608f * (x + 0.044715f * x * x * x); const float th = 1.0f - 2.0f / (__expf(2.0f * z) + 1.0f); return 0.5f * x * (1.0f + th); }
;     __device__ __forceinline__ void operator()(const f32x4 (&acc)[2][2][4][2], const Unit& u, int ui, const LAS float* rtab, int wr, int wc, int fr, int fq) const {
;         const int g = u.pm; const int n0 = wr * 64 + fr; const int lc0 = (u.pn & 1) * 256 + wc * 32 + 8 * fq;
; #pragma unroll
;         for (int ai = 0; ai < 2; ++ai)
; #pragma unroll
;             for (int m = 0; m < 4; ++m) {
;                 const int n = n0 + ai * HALF + m * 16;
; #pragma unroll
;                 for (int bj = 0; bj < 2; ++bj) {
;                     const int lc = lc0 + bj * HALF, t = lc >> 4, co = lc & 15; const int token = n * 32 + t;
;                     const f32x4 a0 = acc[ai][bj][m][0], a1 = acc[ai][bj][m][1];
;                     u32x4 w; w.x = cvt_pk_bf16(gelu_tanh(a0[0]), gelu_tanh(a0[1])); w.y = cvt_pk_bf16(gelu_tanh(a0[2]), gelu_tanh(a0[3]));
;                     w.z = cvt_pk_bf16(gelu_tanh(a1[0]), gelu_tanh(a1[1])); w.w = cvt_pk_bf16(gelu_tanh(a1[2]), gelu_tanh(a1[3]));
;                     *(u32x4*)(Y + (size_t)token * 1024 + 16 * g + co) = w;
	v_rcp_f32_e32 v77, v76
	v_mul_f32_e32 v72, 0.5, v72
	v_add_f32_e32 v71, 1.0, v71
	v_mul_f32_e32 v71, v72, v71
	v_fma_f32 v72, -v76, v77, 1.0
	v_fmac_f32_e32 v77, v72, v77
	v_div_scale_f32 v72, vcc, 2.0, v75, 2.0
	v_mul_f32_e32 v78, v72, v77
	v_fma_f32 v79, -v76, v78, v72
	v_fmac_f32_e32 v78, v79, v77
	v_fma_f32 v72, -v76, v78, v72
	v_mul_f32_e32 v76, 0x3d372713, v66
	v_mul_f32_e32 v76, v66, v76
	v_fma_f32 v76, v66, v76, v66
	v_mul_f32_e32 v76, 0x3f4c422a, v76
	v_add_f32_e32 v76, v76, v76
	v_mul_f32_e32 v76, 0x3fb8aa3b, v76
	v_exp_f32_e32 v76, v76
	v_div_fmas_f32 v72, v72, v77, v78
	v_div_fixup_f32 v72, v72, v75, 2.0
	v_sub_f32_e32 v72, 1.0, v72
	v_add_f32_e32 v75, 1.0, v76
	v_div_scale_f32 v76, s[28:29], v75, v75, 2.0
	v_rcp_f32_e32 v77, v76
	v_mul_f32_e32 v73, 0.5, v73
	v_add_f32_e32 v72, 1.0, v72
	v_mul_f32_e32 v72, v73, v72
	v_cvt_pk_bf16_f32 v71, v71, v72
	v_fma_f32 v72, -v76, v77, 1.0
	v_fmac_f32_e32 v77, v72, v77
	v_div_scale_f32 v72, vcc, 2.0, v75, 2.0
	v_mul_f32_e32 v73, v72, v77
	v_fma_f32 v78, -v76, v73, v72
	v_fmac_f32_e32 v73, v78, v77
	v_fma_f32 v72, -v76, v73, v72
	v_mul_f32_e32 v76, 0x3d372713, v67
	v_mul_f32_e32 v76, v67, v76
	v_fma_f32 v76, v67, v76, v67
	v_mul_f32_e32 v76, 0x3f4c422a, v76
	v_add_f32_e32 v76, v76, v76
	v_mul_f32_e32 v76, 0x3fb8aa3b, v76
	v_exp_f32_e32 v76, v76
	v_div_fmas_f32 v72, v72, v77, v73
	v_div_fixup_f32 v72, v72, v75, 2.0
	v_sub_f32_e32 v72, 1.0, v72
	v_add_f32_e32 v73, 1.0, v76
	v_div_scale_f32 v75, s[28:29], v73, v73, 2.0
	v_rcp_f32_e32 v76, v75
	v_mul_f32_e32 v66, 0.5, v66
	v_add_f32_e32 v72, 1.0, v72
	v_mul_f32_e32 v66, v66, v72
	v_fma_f32 v72, -v75, v76, 1.0
	v_fmac_f32_e32 v76, v72, v76
	v_div_scale_f32 v72, vcc, 2.0, v73, 2.0
	v_mul_f32_e32 v77, v72, v76
	v_fma_f32 v78, -v75, v77, v72
	v_fmac_f32_e32 v77, v78, v76
	v_fma_f32 v72, -v75, v77, v72
	v_mul_f32_e32 v75, 0x3d372713, v68
	v_mul_f32_e32 v75, v68, v75
	v_fma_f32 v75, v68, v75, v68
	v_mul_f32_e32 v75, 0x3f4c422a, v75
	v_add_f32_e32 v75, v75, v75
	v_mul_f32_e32 v75, 0x3fb8aa3b, v75
	v_exp_f32_e32 v75, v75
	v_div_fmas_f32 v72, v72, v76, v77
	v_div_fixup_f32 v72, v72, v73, 2.0
	v_sub_f32_e32 v72, 1.0, v72
	v_add_f32_e32 v73, 1.0, v75
	v_div_scale_f32 v75, s[28:29], v73, v73, 2.0
	v_rcp_f32_e32 v76, v75
	v_mul_f32_e32 v67, 0.5, v67
	v_add_f32_e32 v72, 1.0, v72
	v_mul_f32_e32 v67, v67, v72
	v_cvt_pk_bf16_f32 v72, v66, v67
	v_fma_f32 v66, -v75, v76, 1.0
	v_fmac_f32_e32 v76, v66, v76
	v_div_scale_f32 v66, vcc, 2.0, v73, 2.0
	v_mul_f32_e32 v67, v66, v76
	v_fma_f32 v77, -v75, v67, v66
	v_fmac_f32_e32 v67, v77, v76
	v_fma_f32 v66, -v75, v67, v66
	v_mul_f32_e32 v75, 0x3d372713, v69
	v_mul_f32_e32 v75, v69, v75
	v_fma_f32 v75, v69, v75, v69
	v_mul_f32_e32 v75, 0x3f4c422a, v75
	v_add_f32_e32 v75, v75, v75
	v_mul_f32_e32 v75, 0x3fb8aa3b, v75
	v_exp_f32_e32 v75, v75
	v_div_fmas_f32 v66, v66, v76, v67
	v_div_fixup_f32 v66, v66, v73, 2.0
	v_sub_f32_e32 v66, 1.0, v66
	v_add_f32_e32 v67, 1.0, v75
	v_div_scale_f32 v73, s[28:29], v67, v67, 2.0
	v_rcp_f32_e32 v75, v73
	v_mul_f32_e32 v68, 0.5, v68
	v_add_f32_e32 v66, 1.0, v66
	v_mul_f32_e32 v66, v68, v66
	v_fma_f32 v68, -v73, v75, 1.0
	v_fmac_f32_e32 v75, v68, v75
	v_div_scale_f32 v68, vcc, 2.0, v67, 2.0
	v_mul_f32_e32 v76, v68, v75
	v_fma_f32 v77, -v73, v76, v68
	v_fmac_f32_e32 v76, v77, v75
	v_fma_f32 v68, -v73, v76, v68
	v_div_fmas_f32 v68, v68, v75, v76
	v_div_fixup_f32 v67, v68, v67, 2.0
	v_sub_f32_e32 v67, 1.0, v67
	v_mul_f32_e32 v68, 0.5, v69
	v_add_f32_e32 v67, 1.0, v67
	v_mul_f32_e32 v67, v68, v67
	v_mul_f32_e32 v68, 0x3d372713, v62
	v_mul_f32_e32 v68, v62, v68
	v_fma_f32 v68, v62, v68, v62
	v_mul_f32_e32 v68, 0x3f4c422a, v68
	v_add_f32_e32 v68, v68, v68
	v_mul_f32_e32 v68, 0x3fb8aa3b, v68
	v_exp_f32_e32 v68, v68
	v_or_b32_e32 v74, v124, v149
	v_ashrrev_i32_e32 v75, 31, v74
	v_cvt_pk_bf16_f32 v73, v66, v67
	v_add_f32_e32 v68, 1.0, v68
	v_div_scale_f32 v69, s[28:29], v68, v68, 2.0
	v_lshlrev_b64 v[66:67], 11, v[74:75]
	v_rcp_f32_e32 v74, v69
	v_lshl_add_u64 v[66:67], v[138:139], 0, v[66:67]
	global_store_dwordx4 v[66:67], v[70:73], off
	v_mul_f32_e32 v62, 0.5, v62
	v_fma_f32 v67, -v69, v74, 1.0
	v_fmac_f32_e32 v74, v67, v74
	v_div_scale_f32 v67, vcc, 2.0, v68, 2.0
	v_mul_f32_e32 v70, v67, v74
	v_fma_f32 v71, -v69, v70, v67
	v_fmac_f32_e32 v70, v71, v74
	v_fma_f32 v67, -v69, v70, v67
	v_mul_f32_e32 v69, 0x3d372713, v63
	v_mul_f32_e32 v69, v63, v69
	v_fma_f32 v69, v63, v69, v63
	v_mul_f32_e32 v69, 0x3f4c422a, v69
	v_add_f32_e32 v69, v69, v69
	v_mul_f32_e32 v69, 0x3fb8aa3b, v69
	v_exp_f32_e32 v69, v69
	v_div_fmas_f32 v67, v67, v74, v70
	v_div_fixup_f32 v67, v67, v68, 2.0
	v_sub_f32_e32 v67, 1.0, v67
	v_add_f32_e32 v68, 1.0, v69
	v_div_scale_f32 v69, s[28:29], v68, v68, 2.0
	v_rcp_f32_e32 v70, v69
	v_add_f32_e32 v67, 1.0, v67
	v_mul_f32_e32 v62, v62, v67
	v_mul_f32_e32 v63, 0.5, v63
	v_fma_f32 v67, -v69, v70, 1.0
	v_fmac_f32_e32 v70, v67, v70
	v_div_scale_f32 v67, vcc, 2.0, v68, 2.0
	v_mul_f32_e32 v71, v67, v70
	v_fma_f32 v72, -v69, v71, v67
	v_fmac_f32_e32 v71, v72, v70
	v_fma_f32 v67, -v69, v71, v67
	v_mul_f32_e32 v69, 0x3d372713, v64
	v_mul_f32_e32 v69, v64, v69
	v_fma_f32 v69, v64, v69, v64
	v_mul_f32_e32 v69, 0x3f4c422a, v69
	v_add_f32_e32 v69, v69, v69
	v_mul_f32_e32 v69, 0x3fb8aa3b, v69
	v_exp_f32_e32 v69, v69
	v_div_fmas_f32 v67, v67, v70, v71
	v_div_fixup_f32 v67, v67, v68, 2.0
	v_sub_f32_e32 v67, 1.0, v67
	v_add_f32_e32 v68, 1.0, v69
	v_div_scale_f32 v69, s[28:29], v68, v68, 2.0
	v_rcp_f32_e32 v70, v69
	v_add_f32_e32 v67, 1.0, v67
	v_mul_f32_e32 v63, v63, v67
	v_cvt_pk_bf16_f32 v62, v62, v63
	v_fma_f32 v63, -v69, v70, 1.0
	v_fmac_f32_e32 v70, v63, v70
	v_div_scale_f32 v63, vcc, 2.0, v68, 2.0
; #define LAS __attribute__((address_space(3)))
; __device__ __forceinline__ unsigned cvt_pk_bf16(float lo, float hi) { unsigned r; asm volatile("v_cvt_pk_bf16_f32 %0, %1, %2" : "=v"(r) : "v"(lo), "v"(hi)); return r; }
; __device__ __forceinline__ float gelu_tanh(float x) { const float z = 0.7978845608f * (x + 0.044715f * x * x * x); const float th = 1.0f - 2.0f / (__expf(2.0f * z) + 1.0f); return 0.5f * x * (1.0f + th); }
;     __device__ __forceinline__ void operator()(const f32x4 (&acc)[2][2][4][2], const Unit& u, int ui, const LAS float* rtab, int wr, int wc, int fr, int fq) const {
;         const int g = u.pm; const int n0 = wr * 64 + fr; const int lc0 = (u.pn & 1) * 256 + wc * 32 + 8 * fq;
; #pragma unroll
;         for (int ai = 0; ai < 2; ++ai)
; #pragma unroll
;             for (int m = 0; m < 4; ++m) {
;                 const int n = n0 + ai * HALF + m * 16;
; #pragma unroll
;                 for (int bj = 0; bj < 2; ++bj) {
;                     const int lc = lc0 + bj * HALF, t = lc >> 4, co = lc & 15; const int token = n * 32 + t;
;                     const f32x4 a0 = acc[ai][bj][m][0], a1 = acc[ai][bj][m][1];
;                     u32x4 w; w.x = cvt_pk_bf16(gelu_tanh(a0[0]), gelu_tanh(a0[1])); w.y = cvt_pk_bf16(gelu_tanh(a0[2]), gelu_tanh(a0[3]));
;                     w.z = cvt_pk_bf16(gelu_tanh(a1[0]), gelu_tanh(a1[1])); w.w = cvt_pk_bf16(gelu_tanh(a1[2]), gelu_tanh(a1[3]));
;                     *(u32x4*)(Y + (size_t)token * 1024 + 16 * g + co) = w;
	v_mul_f32_e32 v67, v63, v70
	v_fma_f32 v71, -v69, v67, v63
	v_fmac_f32_e32 v67, v71, v70
	v_fma_f32 v63, -v69, v67, v63
	v_mul_f32_e32 v69, 0x3d372713, v65
	v_mul_f32_e32 v69, v65, v69
	v_fma_f32 v69, v65, v69, v65
	v_mul_f32_e32 v69, 0x3f4c422a, v69
	v_add_f32_e32 v69, v69, v69
	v_mul_f32_e32 v69, 0x3fb8aa3b, v69
	v_exp_f32_e32 v69, v69
	v_div_fmas_f32 v63, v63, v70, v67
	v_div_fixup_f32 v63, v63, v68, 2.0
	v_sub_f32_e32 v63, 1.0, v63
	v_add_f32_e32 v67, 1.0, v69
	v_div_scale_f32 v68, s[28:29], v67, v67, 2.0
	v_rcp_f32_e32 v69, v68
	v_mul_f32_e32 v64, 0.5, v64
	v_add_f32_e32 v63, 1.0, v63
	v_mul_f32_e32 v63, v64, v63
	v_fma_f32 v64, -v68, v69, 1.0
	v_fmac_f32_e32 v69, v64, v69
	v_div_scale_f32 v64, vcc, 2.0, v67, 2.0
	v_mul_f32_e32 v70, v64, v69
	v_fma_f32 v71, -v68, v70, v64
	v_fmac_f32_e32 v70, v71, v69
	v_fma_f32 v64, -v68, v70, v64
	v_mul_f32_e32 v68, 0x3d372713, v58
	v_mul_f32_e32 v68, v58, v68
	v_fma_f32 v68, v58, v68, v58
	v_mul_f32_e32 v68, 0x3f4c422a, v68
	v_add_f32_e32 v68, v68, v68
	v_mul_f32_e32 v68, 0x3fb8aa3b, v68
	v_exp_f32_e32 v68, v68
	v_div_fmas_f32 v64, v64, v69, v70
	v_div_fixup_f32 v64, v64, v67, 2.0
	v_sub_f32_e32 v64, 1.0, v64
	v_add_f32_e32 v67, 1.0, v68
	v_div_scale_f32 v68, s[28:29], v67, v67, 2.0
	v_rcp_f32_e32 v69, v68
	v_mul_f32_e32 v65, 0.5, v65
	v_add_f32_e32 v64, 1.0, v64
	v_mul_f32_e32 v64, v65, v64
	v_cvt_pk_bf16_f32 v63, v63, v64
	v_fma_f32 v64, -v68, v69, 1.0
	v_fmac_f32_e32 v69, v64, v69
	v_div_scale_f32 v64, vcc, 2.0, v67, 2.0
	v_mul_f32_e32 v65, v64, v69
	v_fma_f32 v70, -v68, v65, v64
	v_fmac_f32_e32 v65, v70, v69
	v_fma_f32 v64, -v68, v65, v64
	v_mul_f32_e32 v68, 0x3d372713, v59
	v_mul_f32_e32 v68, v59, v68
	v_fma_f32 v68, v59, v68, v59
	v_mul_f32_e32 v68, 0x3f4c422a, v68
	v_add_f32_e32 v68, v68, v68
	v_mul_f32_e32 v68, 0x3fb8aa3b, v68
	v_exp_f32_e32 v68, v68
	v_div_fmas_f32 v64, v64, v69, v65
	v_div_fixup_f32 v64, v64, v67, 2.0
	v_sub_f32_e32 v64, 1.0, v64
	v_add_f32_e32 v65, 1.0, v68
	v_div_scale_f32 v67, s[28:29], v65, v65, 2.0
	v_rcp_f32_e32 v68, v67
	v_mul_f32_e32 v58, 0.5, v58
	v_add_f32_e32 v64, 1.0, v64
	v_mul_f32_e32 v58, v58, v64
	v_fma_f32 v64, -v67, v68, 1.0
	v_fmac_f32_e32 v68, v64, v68
	v_div_scale_f32 v64, vcc, 2.0, v65, 2.0
	v_mul_f32_e32 v69, v64, v68
	v_fma_f32 v70, -v67, v69, v64
	v_fmac_f32_e32 v69, v70, v68
	v_fma_f32 v64, -v67, v69, v64
	v_mul_f32_e32 v67, 0x3d372713, v60
	v_mul_f32_e32 v67, v60, v67
	v_fma_f32 v67, v60, v67, v60
	v_mul_f32_e32 v67, 0x3f4c422a, v67
	v_add_f32_e32 v67, v67, v67
	v_mul_f32_e32 v67, 0x3fb8aa3b, v67
	v_exp_f32_e32 v67, v67
	v_div_fmas_f32 v64, v64, v68, v69
	v_div_fixup_f32 v64, v64, v65, 2.0
	v_sub_f32_e32 v64, 1.0, v64
	v_add_f32_e32 v65, 1.0, v67
	v_div_scale_f32 v67, s[28:29], v65, v65, 2.0
	v_rcp_f32_e32 v68, v67
	v_mul_f32_e32 v59, 0.5, v59
	v_add_f32_e32 v64, 1.0, v64
	v_mul_f32_e32 v59, v59, v64
	v_cvt_pk_bf16_f32 v64, v58, v59
	v_fma_f32 v58, -v67, v68, 1.0
	v_fmac_f32_e32 v68, v58, v68
	v_div_scale_f32 v58, vcc, 2.0, v65, 2.0
	v_mul_f32_e32 v59, v58, v68
	v_fma_f32 v69, -v67, v59, v58
	v_fmac_f32_e32 v59, v69, v68
	v_fma_f32 v58, -v67, v59, v58
	v_mul_f32_e32 v67, 0x3d372713, v61
	v_mul_f32_e32 v67, v61, v67
	v_fma_f32 v67, v61, v67, v61
	v_mul_f32_e32 v67, 0x3f4c422a, v67
	v_add_f32_e32 v67, v67, v67
	v_mul_f32_e32 v67, 0x3fb8aa3b, v67
	v_exp_f32_e32 v67, v67
	v_div_fmas_f32 v58, v58, v68, v59
	v_div_fixup_f32 v58, v58, v65, 2.0
	v_sub_f32_e32 v58, 1.0, v58
	v_add_f32_e32 v59, 1.0, v67
	v_div_scale_f32 v65, s[28:29], v59, v59, 2.0
	v_rcp_f32_e32 v67, v65
	v_mul_f32_e32 v60, 0.5, v60
	v_add_f32_e32 v58, 1.0, v58
	v_mul_f32_e32 v58, v60, v58
	v_fma_f32 v60, -v65, v67, 1.0
	v_fmac_f32_e32 v67, v60, v67
	v_div_scale_f32 v60, vcc, 2.0, v59, 2.0
	v_mul_f32_e32 v68, v60, v67
	v_fma_f32 v69, -v65, v68, v60
	v_fmac_f32_e32 v68, v69, v67
	v_fma_f32 v60, -v65, v68, v60
	v_div_fmas_f32 v60, v60, v67, v68
	v_div_fixup_f32 v59, v60, v59, 2.0
	v_sub_f32_e32 v59, 1.0, v59
	v_mul_f32_e32 v60, 0.5, v61
	v_add_f32_e32 v59, 1.0, v59
	v_mul_f32_e32 v59, v60, v59
	v_mul_f32_e32 v60, 0x3d372713, v54
	v_mul_f32_e32 v60, v54, v60
	v_fma_f32 v60, v54, v60, v54
	v_mul_f32_e32 v60, 0x3f4c422a, v60
	v_add_f32_e32 v60, v60, v60
	v_mul_f32_e32 v60, 0x3fb8aa3b, v60
	v_exp_f32_e32 v60, v60
	v_or_b32_e32 v66, v171, v150
	v_ashrrev_i32_e32 v67, 31, v66
	v_cvt_pk_bf16_f32 v65, v58, v59
	v_add_f32_e32 v60, 1.0, v60
	v_div_scale_f32 v61, s[28:29], v60, v60, 2.0
	v_lshlrev_b64 v[58:59], 11, v[66:67]
	v_rcp_f32_e32 v66, v61
	v_lshl_add_u64 v[58:59], v[138:139], 0, v[58:59]
	global_store_dwordx4 v[58:59], v[62:65], off
	v_mul_f32_e32 v54, 0.5, v54
	v_fma_f32 v59, -v61, v66, 1.0
	v_fmac_f32_e32 v66, v59, v66
	v_div_scale_f32 v59, vcc, 2.0, v60, 2.0
	v_mul_f32_e32 v62, v59, v66
	v_fma_f32 v63, -v61, v62, v59
	v_fmac_f32_e32 v62, v63, v66
	v_fma_f32 v59, -v61, v62, v59
	v_mul_f32_e32 v61, 0x3d372713, v55
	v_mul_f32_e32 v61, v55, v61
	v_fma_f32 v61, v55, v61, v55
	v_mul_f32_e32 v61, 0x3f4c422a, v61
	v_add_f32_e32 v61, v61, v61
	v_mul_f32_e32 v61, 0x3fb8aa3b, v61
	v_exp_f32_e32 v61, v61
	v_div_fmas_f32 v59, v59, v66, v62
	v_div_fixup_f32 v59, v59, v60, 2.0
	v_sub_f32_e32 v59, 1.0, v59
	v_add_f32_e32 v60, 1.0, v61
	v_div_scale_f32 v61, s[28:29], v60, v60, 2.0
	v_rcp_f32_e32 v62, v61
	v_add_f32_e32 v59, 1.0, v59
	v_mul_f32_e32 v54, v54, v59
	v_mul_f32_e32 v55, 0.5, v55
	v_fma_f32 v59, -v61, v62, 1.0
	v_fmac_f32_e32 v62, v59, v62
	v_div_scale_f32 v59, vcc, 2.0, v60, 2.0
	v_mul_f32_e32 v63, v59, v62
	v_fma_f32 v64, -v61, v63, v59
	v_fmac_f32_e32 v63, v64, v62
	v_fma_f32 v59, -v61, v63, v59
	v_mul_f32_e32 v61, 0x3d372713, v56
	v_mul_f32_e32 v61, v56, v61
	v_fma_f32 v61, v56, v61, v56
; #define LAS __attribute__((address_space(3)))
; __device__ __forceinline__ unsigned cvt_pk_bf16(float lo, float hi) { unsigned r; asm volatile("v_cvt_pk_bf16_f32 %0, %1, %2" : "=v"(r) : "v"(lo), "v"(hi)); return r; }
; __device__ __forceinline__ float gelu_tanh(float x) { const float z = 0.7978845608f * (x + 0.044715f * x * x * x); const float th = 1.0f - 2.0f / (__expf(2.0f * z) + 1.0f); return 0.5f * x * (1.0f + th); }
;     __device__ __forceinline__ void operator()(const f32x4 (&acc)[2][2][4][2], const Unit& u, int ui, const LAS float* rtab, int wr, int wc, int fr, int fq) const {
;         const int g = u.pm; const int n0 = wr * 64 + fr; const int lc0 = (u.pn & 1) * 256 + wc * 32 + 8 * fq;
; #pragma unroll
;         for (int ai = 0; ai < 2; ++ai)
; #pragma unroll
;             for (int m = 0; m < 4; ++m) {
;                 const int n = n0 + ai * HALF + m * 16;
; #pragma unroll
;                 for (int bj = 0; bj < 2; ++bj) {
;                     const int lc = lc0 + bj * HALF, t = lc >> 4, co = lc & 15; const int token = n * 32 + t;
;                     const f32x4 a0 = acc[ai][bj][m][0], a1 = acc[ai][bj][m][1];
;                     u32x4 w; w.x = cvt_pk_bf16(gelu_tanh(a0[0]), gelu_tanh(a0[1])); w.y = cvt_pk_bf16(gelu_tanh(a0[2]), gelu_tanh(a0[3]));
;                     w.z = cvt_pk_bf16(gelu_tanh(a1[0]), gelu_tanh(a1[1])); w.w = cvt_pk_bf16(gelu_tanh(a1[2]), gelu_tanh(a1[3]));
;                     *(u32x4*)(Y + (size_t)token * 1024 + 16 * g + co) = w;
	v_mul_f32_e32 v61, 0x3f4c422a, v61
	v_add_f32_e32 v61, v61, v61
	v_mul_f32_e32 v61, 0x3fb8aa3b, v61
	v_exp_f32_e32 v61, v61
	v_div_fmas_f32 v59, v59, v62, v63
	v_div_fixup_f32 v59, v59, v60, 2.0
	v_sub_f32_e32 v59, 1.0, v59
	v_add_f32_e32 v60, 1.0, v61
	v_div_scale_f32 v61, s[28:29], v60, v60, 2.0
	v_rcp_f32_e32 v62, v61
	v_add_f32_e32 v59, 1.0, v59
	v_mul_f32_e32 v55, v55, v59
	v_cvt_pk_bf16_f32 v54, v54, v55
	v_fma_f32 v55, -v61, v62, 1.0
	v_fmac_f32_e32 v62, v55, v62
	v_div_scale_f32 v55, vcc, 2.0, v60, 2.0
	v_mul_f32_e32 v59, v55, v62
	v_fma_f32 v63, -v61, v59, v55
	v_fmac_f32_e32 v59, v63, v62
	v_fma_f32 v55, -v61, v59, v55
	v_mul_f32_e32 v61, 0x3d372713, v57
	v_mul_f32_e32 v61, v57, v61
	v_fma_f32 v61, v57, v61, v57
	v_mul_f32_e32 v61, 0x3f4c422a, v61
	v_add_f32_e32 v61, v61, v61
	v_mul_f32_e32 v61, 0x3fb8aa3b, v61
	v_exp_f32_e32 v61, v61
	v_div_fmas_f32 v55, v55, v62, v59
	v_div_fixup_f32 v55, v55, v60, 2.0
	v_sub_f32_e32 v55, 1.0, v55
	v_add_f32_e32 v59, 1.0, v61
	v_div_scale_f32 v60, s[28:29], v59, v59, 2.0
	v_rcp_f32_e32 v61, v60
	v_mul_f32_e32 v56, 0.5, v56
	v_add_f32_e32 v55, 1.0, v55
	v_mul_f32_e32 v55, v56, v55
	v_fma_f32 v56, -v60, v61, 1.0
	v_fmac_f32_e32 v61, v56, v61
	v_div_scale_f32 v56, vcc, 2.0, v59, 2.0
	v_mul_f32_e32 v62, v56, v61
	v_fma_f32 v63, -v60, v62, v56
	v_fmac_f32_e32 v62, v63, v61
	v_fma_f32 v56, -v60, v62, v56
	v_mul_f32_e32 v60, 0x3d372713, v50
	v_mul_f32_e32 v60, v50, v60
	v_fma_f32 v60, v50, v60, v50
	v_mul_f32_e32 v60, 0x3f4c422a, v60
	v_add_f32_e32 v60, v60, v60
	v_mul_f32_e32 v60, 0x3fb8aa3b, v60
	v_exp_f32_e32 v60, v60
	v_div_fmas_f32 v56, v56, v61, v62
	v_div_fixup_f32 v56, v56, v59, 2.0
	v_sub_f32_e32 v56, 1.0, v56
	v_add_f32_e32 v59, 1.0, v60
	v_div_scale_f32 v60, s[28:29], v59, v59, 2.0
	v_rcp_f32_e32 v61, v60
	v_mul_f32_e32 v57, 0.5, v57
	v_add_f32_e32 v56, 1.0, v56
	v_mul_f32_e32 v56, v57, v56
	v_cvt_pk_bf16_f32 v55, v55, v56
	v_fma_f32 v56, -v60, v61, 1.0
	v_fmac_f32_e32 v61, v56, v61
	v_div_scale_f32 v56, vcc, 2.0, v59, 2.0
	v_mul_f32_e32 v57, v56, v61
	v_fma_f32 v62, -v60, v57, v56
	v_fmac_f32_e32 v57, v62, v61
	v_fma_f32 v56, -v60, v57, v56
	v_mul_f32_e32 v60, 0x3d372713, v51
	v_mul_f32_e32 v60, v51, v60
	v_fma_f32 v60, v51, v60, v51
	v_mul_f32_e32 v60, 0x3f4c422a, v60
	v_add_f32_e32 v60, v60, v60
	v_mul_f32_e32 v60, 0x3fb8aa3b, v60
	v_exp_f32_e32 v60, v60
	v_div_fmas_f32 v56, v56, v61, v57
	v_div_fixup_f32 v56, v56, v59, 2.0
	v_sub_f32_e32 v56, 1.0, v56
	v_add_f32_e32 v57, 1.0, v60
	v_div_scale_f32 v59, s[28:29], v57, v57, 2.0
	v_rcp_f32_e32 v60, v59
	v_mul_f32_e32 v50, 0.5, v50
	v_add_f32_e32 v56, 1.0, v56
	v_mul_f32_e32 v50, v50, v56
	v_fma_f32 v56, -v59, v60, 1.0
	v_fmac_f32_e32 v60, v56, v60
	v_div_scale_f32 v56, vcc, 2.0, v57, 2.0
	v_mul_f32_e32 v61, v56, v60
	v_fma_f32 v62, -v59, v61, v56
	v_fmac_f32_e32 v61, v62, v60
	v_fma_f32 v56, -v59, v61, v56
	v_mul_f32_e32 v59, 0x3d372713, v52
	v_mul_f32_e32 v59, v52, v59
	v_fma_f32 v59, v52, v59, v52
	v_mul_f32_e32 v59, 0x3f4c422a, v59
	v_add_f32_e32 v59, v59, v59
	v_mul_f32_e32 v59, 0x3fb8aa3b, v59
	v_exp_f32_e32 v59, v59
	v_div_fmas_f32 v56, v56, v60, v61
	v_div_fixup_f32 v56, v56, v57, 2.0
	v_sub_f32_e32 v56, 1.0, v56
	v_add_f32_e32 v57, 1.0, v59
	v_div_scale_f32 v59, s[28:29], v57, v57, 2.0
	v_rcp_f32_e32 v60, v59
	v_mul_f32_e32 v51, 0.5, v51
	v_add_f32_e32 v56, 1.0, v56
	v_mul_f32_e32 v51, v51, v56
	v_cvt_pk_bf16_f32 v56, v50, v51
	v_fma_f32 v50, -v59, v60, 1.0
	v_fmac_f32_e32 v60, v50, v60
	v_div_scale_f32 v50, vcc, 2.0, v57, 2.0
	v_mul_f32_e32 v51, v50, v60
	v_fma_f32 v61, -v59, v51, v50
	v_fmac_f32_e32 v51, v61, v60
	v_fma_f32 v50, -v59, v51, v50
	v_mul_f32_e32 v59, 0x3d372713, v53
	v_mul_f32_e32 v59, v53, v59
	v_fma_f32 v59, v53, v59, v53
	v_mul_f32_e32 v59, 0x3f4c422a, v59
	v_add_f32_e32 v59, v59, v59
	v_mul_f32_e32 v59, 0x3fb8aa3b, v59
	v_exp_f32_e32 v59, v59
	v_div_fmas_f32 v50, v50, v60, v51
	v_div_fixup_f32 v50, v50, v57, 2.0
	v_sub_f32_e32 v50, 1.0, v50
	v_add_f32_e32 v51, 1.0, v59
	v_div_scale_f32 v57, s[28:29], v51, v51, 2.0
	v_rcp_f32_e32 v59, v57
	v_mul_f32_e32 v52, 0.5, v52
	v_add_f32_e32 v50, 1.0, v50
	v_mul_f32_e32 v50, v52, v50
	v_fma_f32 v52, -v57, v59, 1.0
	v_fmac_f32_e32 v59, v52, v59
	v_div_scale_f32 v52, vcc, 2.0, v51, 2.0
	v_mul_f32_e32 v60, v52, v59
	v_fma_f32 v61, -v57, v60, v52
	v_fmac_f32_e32 v60, v61, v59
	v_fma_f32 v52, -v57, v60, v52
	v_div_fmas_f32 v52, v52, v59, v60
	v_div_fixup_f32 v51, v52, v51, 2.0
	v_sub_f32_e32 v51, 1.0, v51
	v_mul_f32_e32 v52, 0.5, v53
	v_add_f32_e32 v51, 1.0, v51
	v_mul_f32_e32 v51, v52, v51
	v_mul_f32_e32 v52, 0x3d372713, v46
	v_mul_f32_e32 v52, v46, v52
	v_fma_f32 v52, v46, v52, v46
	v_mul_f32_e32 v52, 0x3f4c422a, v52
	v_add_f32_e32 v52, v52, v52
	v_mul_f32_e32 v52, 0x3fb8aa3b, v52
	v_exp_f32_e32 v52, v52
	v_or_b32_e32 v58, v124, v150
	v_ashrrev_i32_e32 v59, 31, v58
	v_cvt_pk_bf16_f32 v57, v50, v51
	v_add_f32_e32 v52, 1.0, v52
	v_div_scale_f32 v53, s[28:29], v52, v52, 2.0
	v_lshlrev_b64 v[50:51], 11, v[58:59]
	v_rcp_f32_e32 v58, v53
	v_lshl_add_u64 v[50:51], v[138:139], 0, v[50:51]
	global_store_dwordx4 v[50:51], v[54:57], off
	v_mul_f32_e32 v46, 0.5, v46
	v_fma_f32 v51, -v53, v58, 1.0
	v_fmac_f32_e32 v58, v51, v58
	v_div_scale_f32 v51, vcc, 2.0, v52, 2.0
	v_mul_f32_e32 v54, v51, v58
	v_fma_f32 v55, -v53, v54, v51
	v_fmac_f32_e32 v54, v55, v58
	v_fma_f32 v51, -v53, v54, v51
	v_mul_f32_e32 v53, 0x3d372713, v47
	v_mul_f32_e32 v53, v47, v53
	v_fma_f32 v53, v47, v53, v47
	v_mul_f32_e32 v53, 0x3f4c422a, v53
	v_add_f32_e32 v53, v53, v53
	v_mul_f32_e32 v53, 0x3fb8aa3b, v53
	v_exp_f32_e32 v53, v53
	v_div_fmas_f32 v51, v51, v58, v54
	v_div_fixup_f32 v51, v51, v52, 2.0
; #define LAS __attribute__((address_space(3)))
; __device__ __forceinline__ unsigned cvt_pk_bf16(float lo, float hi) { unsigned r; asm volatile("v_cvt_pk_bf16_f32 %0, %1, %2" : "=v"(r) : "v"(lo), "v"(hi)); return r; }
; __device__ __forceinline__ float gelu_tanh(float x) { const float z = 0.7978845608f * (x + 0.044715f * x * x * x); const float th = 1.0f - 2.0f / (__expf(2.0f * z) + 1.0f); return 0.5f * x * (1.0f + th); }
;     __device__ __forceinline__ void operator()(const f32x4 (&acc)[2][2][4][2], const Unit& u, int ui, const LAS float* rtab, int wr, int wc, int fr, int fq) const {
;         const int g = u.pm; const int n0 = wr * 64 + fr; const int lc0 = (u.pn & 1) * 256 + wc * 32 + 8 * fq;
; #pragma unroll
;         for (int ai = 0; ai < 2; ++ai)
; #pragma unroll
;             for (int m = 0; m < 4; ++m) {
;                 const int n = n0 + ai * HALF + m * 16;
; #pragma unroll
;                 for (int bj = 0; bj < 2; ++bj) {
;                     const int lc = lc0 + bj * HALF, t = lc >> 4, co = lc & 15; const int token = n * 32 + t;
;                     const f32x4 a0 = acc[ai][bj][m][0], a1 = acc[ai][bj][m][1];
;                     u32x4 w; w.x = cvt_pk_bf16(gelu_tanh(a0[0]), gelu_tanh(a0[1])); w.y = cvt_pk_bf16(gelu_tanh(a0[2]), gelu_tanh(a0[3]));
;                     w.z = cvt_pk_bf16(gelu_tanh(a1[0]), gelu_tanh(a1[1])); w.w = cvt_pk_bf16(gelu_tanh(a1[2]), gelu_tanh(a1[3]));
;                     *(u32x4*)(Y + (size_t)token * 1024 + 16 * g + co) = w;
	v_sub_f32_e32 v51, 1.0, v51
	v_add_f32_e32 v52, 1.0, v53
	v_div_scale_f32 v53, s[28:29], v52, v52, 2.0
	v_rcp_f32_e32 v54, v53
	v_add_f32_e32 v51, 1.0, v51
	v_mul_f32_e32 v46, v46, v51
	v_mul_f32_e32 v47, 0.5, v47
	v_fma_f32 v51, -v53, v54, 1.0
	v_fmac_f32_e32 v54, v51, v54
	v_div_scale_f32 v51, vcc, 2.0, v52, 2.0
	v_mul_f32_e32 v55, v51, v54
	v_fma_f32 v56, -v53, v55, v51
	v_fmac_f32_e32 v55, v56, v54
	v_fma_f32 v51, -v53, v55, v51
	v_mul_f32_e32 v53, 0x3d372713, v48
	v_mul_f32_e32 v53, v48, v53
	v_fma_f32 v53, v48, v53, v48
	v_mul_f32_e32 v53, 0x3f4c422a, v53
	v_add_f32_e32 v53, v53, v53
	v_mul_f32_e32 v53, 0x3fb8aa3b, v53
	v_exp_f32_e32 v53, v53
	v_div_fmas_f32 v51, v51, v54, v55
	v_div_fixup_f32 v51, v51, v52, 2.0
	v_sub_f32_e32 v51, 1.0, v51
	v_add_f32_e32 v52, 1.0, v53
	v_div_scale_f32 v53, s[28:29], v52, v52, 2.0
	v_rcp_f32_e32 v54, v53
	v_add_f32_e32 v51, 1.0, v51
	v_mul_f32_e32 v47, v47, v51
	v_cvt_pk_bf16_f32 v46, v46, v47
	v_fma_f32 v47, -v53, v54, 1.0
	v_fmac_f32_e32 v54, v47, v54
	v_div_scale_f32 v47, vcc, 2.0, v52, 2.0
	v_mul_f32_e32 v51, v47, v54
	v_fma_f32 v55, -v53, v51, v47
	v_fmac_f32_e32 v51, v55, v54
	v_fma_f32 v47, -v53, v51, v47
	v_mul_f32_e32 v53, 0x3d372713, v49
	v_mul_f32_e32 v53, v49, v53
	v_fma_f32 v53, v49, v53, v49
	v_mul_f32_e32 v53, 0x3f4c422a, v53
	v_add_f32_e32 v53, v53, v53
	v_mul_f32_e32 v53, 0x3fb8aa3b, v53
	v_exp_f32_e32 v53, v53
	v_div_fmas_f32 v47, v47, v54, v51
	v_div_fixup_f32 v47, v47, v52, 2.0
	v_sub_f32_e32 v47, 1.0, v47
	v_add_f32_e32 v51, 1.0, v53
	v_div_scale_f32 v52, s[28:29], v51, v51, 2.0
	v_rcp_f32_e32 v53, v52
	v_mul_f32_e32 v48, 0.5, v48
	v_add_f32_e32 v47, 1.0, v47
	v_mul_f32_e32 v47, v48, v47
	v_fma_f32 v48, -v52, v53, 1.0
	v_fmac_f32_e32 v53, v48, v53
	v_div_scale_f32 v48, vcc, 2.0, v51, 2.0
	v_mul_f32_e32 v54, v48, v53
	v_fma_f32 v55, -v52, v54, v48
	v_fmac_f32_e32 v54, v55, v53
	v_fma_f32 v48, -v52, v54, v48
	v_mul_f32_e32 v52, 0x3d372713, v42
	v_mul_f32_e32 v52, v42, v52
	v_fma_f32 v52, v42, v52, v42
	v_mul_f32_e32 v52, 0x3f4c422a, v52
	v_add_f32_e32 v52, v52, v52
	v_mul_f32_e32 v52, 0x3fb8aa3b, v52
	v_exp_f32_e32 v52, v52
	v_div_fmas_f32 v48, v48, v53, v54
	v_div_fixup_f32 v48, v48, v51, 2.0
	v_sub_f32_e32 v48, 1.0, v48
	v_add_f32_e32 v51, 1.0, v52
	v_div_scale_f32 v52, s[28:29], v51, v51, 2.0
	v_rcp_f32_e32 v53, v52
	v_mul_f32_e32 v49, 0.5, v49
	v_add_f32_e32 v48, 1.0, v48
	v_mul_f32_e32 v48, v49, v48
	v_cvt_pk_bf16_f32 v47, v47, v48
	v_fma_f32 v48, -v52, v53, 1.0
	v_fmac_f32_e32 v53, v48, v53
	v_div_scale_f32 v48, vcc, 2.0, v51, 2.0
	v_mul_f32_e32 v49, v48, v53
	v_fma_f32 v54, -v52, v49, v48
	v_fmac_f32_e32 v49, v54, v53
	v_fma_f32 v48, -v52, v49, v48
	v_mul_f32_e32 v52, 0x3d372713, v43
	v_mul_f32_e32 v52, v43, v52
	v_fma_f32 v52, v43, v52, v43
	v_mul_f32_e32 v52, 0x3f4c422a, v52
	v_add_f32_e32 v52, v52, v52
	v_mul_f32_e32 v52, 0x3fb8aa3b, v52
	v_exp_f32_e32 v52, v52
	v_div_fmas_f32 v48, v48, v53, v49
	v_div_fixup_f32 v48, v48, v51, 2.0
	v_sub_f32_e32 v48, 1.0, v48
	v_add_f32_e32 v49, 1.0, v52
	v_div_scale_f32 v51, s[28:29], v49, v49, 2.0
	v_rcp_f32_e32 v52, v51
	v_mul_f32_e32 v42, 0.5, v42
	v_add_f32_e32 v48, 1.0, v48
	v_mul_f32_e32 v42, v42, v48
	v_fma_f32 v48, -v51, v52, 1.0
	v_fmac_f32_e32 v52, v48, v52
	v_div_scale_f32 v48, vcc, 2.0, v49, 2.0
	v_mul_f32_e32 v53, v48, v52
	v_fma_f32 v54, -v51, v53, v48
	v_fmac_f32_e32 v53, v54, v52
	v_fma_f32 v48, -v51, v53, v48
	v_mul_f32_e32 v51, 0x3d372713, v44
	v_mul_f32_e32 v51, v44, v51
	v_fma_f32 v51, v44, v51, v44
	v_mul_f32_e32 v51, 0x3f4c422a, v51
	v_add_f32_e32 v51, v51, v51
	v_mul_f32_e32 v51, 0x3fb8aa3b, v51
	v_exp_f32_e32 v51, v51
	v_div_fmas_f32 v48, v48, v52, v53
	v_div_fixup_f32 v48, v48, v49, 2.0
	v_sub_f32_e32 v48, 1.0, v48
	v_add_f32_e32 v49, 1.0, v51
	v_div_scale_f32 v51, s[28:29], v49, v49, 2.0
	v_rcp_f32_e32 v52, v51
	v_mul_f32_e32 v43, 0.5, v43
	v_add_f32_e32 v48, 1.0, v48
	v_mul_f32_e32 v43, v43, v48
	v_cvt_pk_bf16_f32 v48, v42, v43
	v_fma_f32 v42, -v51, v52, 1.0
	v_fmac_f32_e32 v52, v42, v52
	v_div_scale_f32 v42, vcc, 2.0, v49, 2.0
	v_mul_f32_e32 v43, v42, v52
	v_fma_f32 v53, -v51, v43, v42
	v_fmac_f32_e32 v43, v53, v52
	v_fma_f32 v42, -v51, v43, v42
	v_mul_f32_e32 v51, 0x3d372713, v45
	v_mul_f32_e32 v51, v45, v51
	v_fma_f32 v51, v45, v51, v45
	v_mul_f32_e32 v51, 0x3f4c422a, v51
	v_add_f32_e32 v51, v51, v51
	v_mul_f32_e32 v51, 0x3fb8aa3b, v51
	v_exp_f32_e32 v51, v51
	v_div_fmas_f32 v42, v42, v52, v43
	v_div_fixup_f32 v42, v42, v49, 2.0
	v_sub_f32_e32 v42, 1.0, v42
	v_add_f32_e32 v43, 1.0, v51
	v_div_scale_f32 v49, s[28:29], v43, v43, 2.0
	v_rcp_f32_e32 v51, v49
	v_mul_f32_e32 v44, 0.5, v44
	v_add_f32_e32 v42, 1.0, v42
	v_mul_f32_e32 v42, v44, v42
	v_fma_f32 v44, -v49, v51, 1.0
	v_fmac_f32_e32 v51, v44, v51
	v_div_scale_f32 v44, vcc, 2.0, v43, 2.0
	v_mul_f32_e32 v52, v44, v51
	v_fma_f32 v53, -v49, v52, v44
	v_fmac_f32_e32 v52, v53, v51
	v_fma_f32 v44, -v49, v52, v44
	v_div_fmas_f32 v44, v44, v51, v52
	v_div_fixup_f32 v43, v44, v43, 2.0
	v_sub_f32_e32 v43, 1.0, v43
	v_mul_f32_e32 v44, 0.5, v45
	v_add_f32_e32 v43, 1.0, v43
	v_mul_f32_e32 v43, v44, v43
	v_mul_f32_e32 v44, 0x3d372713, v38
	v_mul_f32_e32 v44, v38, v44
	v_fma_f32 v44, v38, v44, v38
	v_mul_f32_e32 v44, 0x3f4c422a, v44
	v_add_f32_e32 v44, v44, v44
	v_mul_f32_e32 v44, 0x3fb8aa3b, v44
	v_exp_f32_e32 v44, v44
	v_or_b32_e32 v50, v171, v151
	v_ashrrev_i32_e32 v51, 31, v50
	v_cvt_pk_bf16_f32 v49, v42, v43
	v_add_f32_e32 v44, 1.0, v44
	v_div_scale_f32 v45, s[28:29], v44, v44, 2.0
	v_lshlrev_b64 v[42:43], 11, v[50:51]
	v_rcp_f32_e32 v50, v45
	v_lshl_add_u64 v[42:43], v[138:139], 0, v[42:43]
	global_store_dwordx4 v[42:43], v[46:49], off
	v_mul_f32_e32 v38, 0.5, v38
; #define LAS __attribute__((address_space(3)))
; __device__ __forceinline__ unsigned cvt_pk_bf16(float lo, float hi) { unsigned r; asm volatile("v_cvt_pk_bf16_f32 %0, %1, %2" : "=v"(r) : "v"(lo), "v"(hi)); return r; }
; __device__ __forceinline__ float gelu_tanh(float x) { const float z = 0.7978845608f * (x + 0.044715f * x * x * x); const float th = 1.0f - 2.0f / (__expf(2.0f * z) + 1.0f); return 0.5f * x * (1.0f + th); }
;     __device__ __forceinline__ void operator()(const f32x4 (&acc)[2][2][4][2], const Unit& u, int ui, const LAS float* rtab, int wr, int wc, int fr, int fq) const {
;         const int g = u.pm; const int n0 = wr * 64 + fr; const int lc0 = (u.pn & 1) * 256 + wc * 32 + 8 * fq;
; #pragma unroll
;         for (int ai = 0; ai < 2; ++ai)
; #pragma unroll
;             for (int m = 0; m < 4; ++m) {
;                 const int n = n0 + ai * HALF + m * 16;
; #pragma unroll
;                 for (int bj = 0; bj < 2; ++bj) {
;                     const int lc = lc0 + bj * HALF, t = lc >> 4, co = lc & 15; const int token = n * 32 + t;
;                     const f32x4 a0 = acc[ai][bj][m][0], a1 = acc[ai][bj][m][1];
;                     u32x4 w; w.x = cvt_pk_bf16(gelu_tanh(a0[0]), gelu_tanh(a0[1])); w.y = cvt_pk_bf16(gelu_tanh(a0[2]), gelu_tanh(a0[3]));
;                     w.z = cvt_pk_bf16(gelu_tanh(a1[0]), gelu_tanh(a1[1])); w.w = cvt_pk_bf16(gelu_tanh(a1[2]), gelu_tanh(a1[3]));
;                     *(u32x4*)(Y + (size_t)token * 1024 + 16 * g + co) = w;
	v_fma_f32 v43, -v45, v50, 1.0
	v_fmac_f32_e32 v50, v43, v50
	v_div_scale_f32 v43, vcc, 2.0, v44, 2.0
	v_mul_f32_e32 v46, v43, v50
	v_fma_f32 v47, -v45, v46, v43
	v_fmac_f32_e32 v46, v47, v50
	v_fma_f32 v43, -v45, v46, v43
	v_mul_f32_e32 v45, 0x3d372713, v39
	v_mul_f32_e32 v45, v39, v45
	v_fma_f32 v45, v39, v45, v39
	v_mul_f32_e32 v45, 0x3f4c422a, v45
	v_add_f32_e32 v45, v45, v45
	v_mul_f32_e32 v45, 0x3fb8aa3b, v45
	v_exp_f32_e32 v45, v45
	v_div_fmas_f32 v43, v43, v50, v46
	v_div_fixup_f32 v43, v43, v44, 2.0
	v_sub_f32_e32 v43, 1.0, v43
	v_add_f32_e32 v44, 1.0, v45
	v_div_scale_f32 v45, s[28:29], v44, v44, 2.0
	v_rcp_f32_e32 v46, v45
	v_add_f32_e32 v43, 1.0, v43
	v_mul_f32_e32 v38, v38, v43
	v_mul_f32_e32 v39, 0.5, v39
	v_fma_f32 v43, -v45, v46, 1.0
	v_fmac_f32_e32 v46, v43, v46
	v_div_scale_f32 v43, vcc, 2.0, v44, 2.0
	v_mul_f32_e32 v47, v43, v46
	v_fma_f32 v48, -v45, v47, v43
	v_fmac_f32_e32 v47, v48, v46
	v_fma_f32 v43, -v45, v47, v43
	v_mul_f32_e32 v45, 0x3d372713, v40
	v_mul_f32_e32 v45, v40, v45
	v_fma_f32 v45, v40, v45, v40
	v_mul_f32_e32 v45, 0x3f4c422a, v45
	v_add_f32_e32 v45, v45, v45
	v_mul_f32_e32 v45, 0x3fb8aa3b, v45
	v_exp_f32_e32 v45, v45
	v_div_fmas_f32 v43, v43, v46, v47
	v_div_fixup_f32 v43, v43, v44, 2.0
	v_sub_f32_e32 v43, 1.0, v43
	v_add_f32_e32 v44, 1.0, v45
	v_div_scale_f32 v45, s[28:29], v44, v44, 2.0
	v_rcp_f32_e32 v46, v45
	v_add_f32_e32 v43, 1.0, v43
	v_mul_f32_e32 v39, v39, v43
	v_cvt_pk_bf16_f32 v38, v38, v39
	v_fma_f32 v39, -v45, v46, 1.0
	v_fmac_f32_e32 v46, v39, v46
	v_div_scale_f32 v39, vcc, 2.0, v44, 2.0
	v_mul_f32_e32 v43, v39, v46
	v_fma_f32 v47, -v45, v43, v39
	v_fmac_f32_e32 v43, v47, v46
	v_fma_f32 v39, -v45, v43, v39
	v_mul_f32_e32 v45, 0x3d372713, v41
	v_mul_f32_e32 v45, v41, v45
	v_fma_f32 v45, v41, v45, v41
	v_mul_f32_e32 v45, 0x3f4c422a, v45
	v_add_f32_e32 v45, v45, v45
	v_mul_f32_e32 v45, 0x3fb8aa3b, v45
	v_exp_f32_e32 v45, v45
	v_div_fmas_f32 v39, v39, v46, v43
	v_div_fixup_f32 v39, v39, v44, 2.0
	v_sub_f32_e32 v39, 1.0, v39
	v_add_f32_e32 v43, 1.0, v45
	v_div_scale_f32 v44, s[28:29], v43, v43, 2.0
	v_rcp_f32_e32 v45, v44
	v_mul_f32_e32 v40, 0.5, v40
	v_add_f32_e32 v39, 1.0, v39
	v_mul_f32_e32 v39, v40, v39
	v_fma_f32 v40, -v44, v45, 1.0
	v_fmac_f32_e32 v45, v40, v45
	v_div_scale_f32 v40, vcc, 2.0, v43, 2.0
	v_mul_f32_e32 v46, v40, v45
	v_fma_f32 v47, -v44, v46, v40
	v_fmac_f32_e32 v46, v47, v45
	v_fma_f32 v40, -v44, v46, v40
	v_mul_f32_e32 v44, 0x3d372713, v34
	v_mul_f32_e32 v44, v34, v44
	v_fma_f32 v44, v34, v44, v34
	v_mul_f32_e32 v44, 0x3f4c422a, v44
	v_add_f32_e32 v44, v44, v44
	v_mul_f32_e32 v44, 0x3fb8aa3b, v44
	v_exp_f32_e32 v44, v44
	v_div_fmas_f32 v40, v40, v45, v46
	v_div_fixup_f32 v40, v40, v43, 2.0
	v_sub_f32_e32 v40, 1.0, v40
	v_add_f32_e32 v43, 1.0, v44
	v_div_scale_f32 v44, s[28:29], v43, v43, 2.0
	v_rcp_f32_e32 v45, v44
	v_mul_f32_e32 v41, 0.5, v41
	v_add_f32_e32 v40, 1.0, v40
	v_mul_f32_e32 v40, v41, v40
	v_cvt_pk_bf16_f32 v39, v39, v40
	v_fma_f32 v40, -v44, v45, 1.0
	v_fmac_f32_e32 v45, v40, v45
	v_div_scale_f32 v40, vcc, 2.0, v43, 2.0
	v_mul_f32_e32 v41, v40, v45
	v_fma_f32 v46, -v44, v41, v40
	v_fmac_f32_e32 v41, v46, v45
	v_fma_f32 v40, -v44, v41, v40
	v_mul_f32_e32 v44, 0x3d372713, v35
	v_mul_f32_e32 v44, v35, v44
	v_fma_f32 v44, v35, v44, v35
	v_mul_f32_e32 v44, 0x3f4c422a, v44
	v_add_f32_e32 v44, v44, v44
	v_mul_f32_e32 v44, 0x3fb8aa3b, v44
	v_exp_f32_e32 v44, v44
	v_div_fmas_f32 v40, v40, v45, v41
	v_div_fixup_f32 v40, v40, v43, 2.0
	v_sub_f32_e32 v40, 1.0, v40
	v_add_f32_e32 v41, 1.0, v44
	v_div_scale_f32 v43, s[28:29], v41, v41, 2.0
	v_rcp_f32_e32 v44, v43
	v_mul_f32_e32 v34, 0.5, v34
	v_add_f32_e32 v40, 1.0, v40
	v_mul_f32_e32 v34, v34, v40
	v_fma_f32 v40, -v43, v44, 1.0
	v_fmac_f32_e32 v44, v40, v44
	v_div_scale_f32 v40, vcc, 2.0, v41, 2.0
	v_mul_f32_e32 v45, v40, v44
	v_fma_f32 v46, -v43, v45, v40
	v_fmac_f32_e32 v45, v46, v44
	v_fma_f32 v40, -v43, v45, v40
	v_mul_f32_e32 v43, 0x3d372713, v36
	v_mul_f32_e32 v43, v36, v43
	v_fma_f32 v43, v36, v43, v36
	v_mul_f32_e32 v43, 0x3f4c422a, v43
	v_add_f32_e32 v43, v43, v43
	v_mul_f32_e32 v43, 0x3fb8aa3b, v43
	v_exp_f32_e32 v43, v43
	v_div_fmas_f32 v40, v40, v44, v45
	v_div_fixup_f32 v40, v40, v41, 2.0
	v_sub_f32_e32 v40, 1.0, v40
	v_add_f32_e32 v41, 1.0, v43
	v_div_scale_f32 v43, s[28:29], v41, v41, 2.0
	v_rcp_f32_e32 v44, v43
	v_mul_f32_e32 v35, 0.5, v35
	v_add_f32_e32 v40, 1.0, v40
	v_mul_f32_e32 v35, v35, v40
	v_cvt_pk_bf16_f32 v40, v34, v35
	v_fma_f32 v34, -v43, v44, 1.0
	v_fmac_f32_e32 v44, v34, v44
	v_div_scale_f32 v34, vcc, 2.0, v41, 2.0
	v_mul_f32_e32 v35, v34, v44
	v_fma_f32 v45, -v43, v35, v34
	v_fmac_f32_e32 v35, v45, v44
	v_fma_f32 v34, -v43, v35, v34
	v_mul_f32_e32 v43, 0x3d372713, v37
	v_mul_f32_e32 v43, v37, v43
	v_fma_f32 v43, v37, v43, v37
	v_mul_f32_e32 v43, 0x3f4c422a, v43
	v_add_f32_e32 v43, v43, v43
	v_mul_f32_e32 v43, 0x3fb8aa3b, v43
	v_exp_f32_e32 v43, v43
	v_div_fmas_f32 v34, v34, v44, v35
	v_div_fixup_f32 v34, v34, v41, 2.0
	v_sub_f32_e32 v34, 1.0, v34
	v_add_f32_e32 v35, 1.0, v43
	v_div_scale_f32 v41, s[28:29], v35, v35, 2.0
	v_rcp_f32_e32 v43, v41
	v_mul_f32_e32 v36, 0.5, v36
	v_add_f32_e32 v34, 1.0, v34
	v_mul_f32_e32 v34, v36, v34
	v_fma_f32 v36, -v41, v43, 1.0
	v_fmac_f32_e32 v43, v36, v43
	v_div_scale_f32 v36, vcc, 2.0, v35, 2.0
	v_mul_f32_e32 v44, v36, v43
	v_fma_f32 v45, -v41, v44, v36
	v_fmac_f32_e32 v44, v45, v43
	v_fma_f32 v36, -v41, v44, v36
	v_div_fmas_f32 v36, v36, v43, v44
	v_div_fixup_f32 v35, v36, v35, 2.0
	v_sub_f32_e32 v35, 1.0, v35
	v_mul_f32_e32 v36, 0.5, v37
	v_add_f32_e32 v35, 1.0, v35
	v_mul_f32_e32 v35, v36, v35
	v_mul_f32_e32 v36, 0x3d372713, v30
	v_mul_f32_e32 v36, v30, v36
; #define LAS __attribute__((address_space(3)))
; __device__ __forceinline__ unsigned cvt_pk_bf16(float lo, float hi) { unsigned r; asm volatile("v_cvt_pk_bf16_f32 %0, %1, %2" : "=v"(r) : "v"(lo), "v"(hi)); return r; }
; __device__ __forceinline__ float gelu_tanh(float x) { const float z = 0.7978845608f * (x + 0.044715f * x * x * x); const float th = 1.0f - 2.0f / (__expf(2.0f * z) + 1.0f); return 0.5f * x * (1.0f + th); }
;     __device__ __forceinline__ void operator()(const f32x4 (&acc)[2][2][4][2], const Unit& u, int ui, const LAS float* rtab, int wr, int wc, int fr, int fq) const {
;         const int g = u.pm; const int n0 = wr * 64 + fr; const int lc0 = (u.pn & 1) * 256 + wc * 32 + 8 * fq;
; #pragma unroll
;         for (int ai = 0; ai < 2; ++ai)
; #pragma unroll
;             for (int m = 0; m < 4; ++m) {
;                 const int n = n0 + ai * HALF + m * 16;
; #pragma unroll
;                 for (int bj = 0; bj < 2; ++bj) {
;                     const int lc = lc0 + bj * HALF, t = lc >> 4, co = lc & 15; const int token = n * 32 + t;
;                     const f32x4 a0 = acc[ai][bj][m][0], a1 = acc[ai][bj][m][1];
;                     u32x4 w; w.x = cvt_pk_bf16(gelu_tanh(a0[0]), gelu_tanh(a0[1])); w.y = cvt_pk_bf16(gelu_tanh(a0[2]), gelu_tanh(a0[3]));
;                     w.z = cvt_pk_bf16(gelu_tanh(a1[0]), gelu_tanh(a1[1])); w.w = cvt_pk_bf16(gelu_tanh(a1[2]), gelu_tanh(a1[3]));
;                     *(u32x4*)(Y + (size_t)token * 1024 + 16 * g + co) = w;
	v_fma_f32 v36, v30, v36, v30
	v_mul_f32_e32 v36, 0x3f4c422a, v36
	v_add_f32_e32 v36, v36, v36
	v_mul_f32_e32 v36, 0x3fb8aa3b, v36
	v_exp_f32_e32 v36, v36
	v_or_b32_e32 v42, v124, v151
	v_ashrrev_i32_e32 v43, 31, v42
	v_cvt_pk_bf16_f32 v41, v34, v35
	v_add_f32_e32 v36, 1.0, v36
	v_div_scale_f32 v37, s[28:29], v36, v36, 2.0
	v_lshlrev_b64 v[34:35], 11, v[42:43]
	v_rcp_f32_e32 v42, v37
	v_lshl_add_u64 v[34:35], v[138:139], 0, v[34:35]
	global_store_dwordx4 v[34:35], v[38:41], off
	v_mul_f32_e32 v30, 0.5, v30
	v_fma_f32 v35, -v37, v42, 1.0
	v_fmac_f32_e32 v42, v35, v42
	v_div_scale_f32 v35, vcc, 2.0, v36, 2.0
	v_mul_f32_e32 v38, v35, v42
	v_fma_f32 v39, -v37, v38, v35
	v_fmac_f32_e32 v38, v39, v42
	v_fma_f32 v35, -v37, v38, v35
	v_mul_f32_e32 v37, 0x3d372713, v31
	v_mul_f32_e32 v37, v31, v37
	v_fma_f32 v37, v31, v37, v31
	v_mul_f32_e32 v37, 0x3f4c422a, v37
	v_add_f32_e32 v37, v37, v37
	v_mul_f32_e32 v37, 0x3fb8aa3b, v37
	v_exp_f32_e32 v37, v37
	v_div_fmas_f32 v35, v35, v42, v38
	v_div_fixup_f32 v35, v35, v36, 2.0
	v_sub_f32_e32 v35, 1.0, v35
	v_add_f32_e32 v36, 1.0, v37
	v_div_scale_f32 v37, s[28:29], v36, v36, 2.0
	v_rcp_f32_e32 v38, v37
	v_add_f32_e32 v35, 1.0, v35
	v_mul_f32_e32 v30, v30, v35
	v_mul_f32_e32 v31, 0.5, v31
	v_fma_f32 v35, -v37, v38, 1.0
	v_fmac_f32_e32 v38, v35, v38
	v_div_scale_f32 v35, vcc, 2.0, v36, 2.0
	v_mul_f32_e32 v39, v35, v38
	v_fma_f32 v40, -v37, v39, v35
	v_fmac_f32_e32 v39, v40, v38
	v_fma_f32 v35, -v37, v39, v35
	v_mul_f32_e32 v37, 0x3d372713, v32
	v_mul_f32_e32 v37, v32, v37
	v_fma_f32 v37, v32, v37, v32
	v_mul_f32_e32 v37, 0x3f4c422a, v37
	v_add_f32_e32 v37, v37, v37
	v_mul_f32_e32 v37, 0x3fb8aa3b, v37
	v_exp_f32_e32 v37, v37
	v_div_fmas_f32 v35, v35, v38, v39
	v_div_fixup_f32 v35, v35, v36, 2.0
	v_sub_f32_e32 v35, 1.0, v35
	v_add_f32_e32 v36, 1.0, v37
	v_div_scale_f32 v37, s[28:29], v36, v36, 2.0
	v_rcp_f32_e32 v38, v37
	v_add_f32_e32 v35, 1.0, v35
	v_mul_f32_e32 v31, v31, v35
	v_cvt_pk_bf16_f32 v30, v30, v31
	v_fma_f32 v31, -v37, v38, 1.0
	v_fmac_f32_e32 v38, v31, v38
	v_div_scale_f32 v31, vcc, 2.0, v36, 2.0
	v_mul_f32_e32 v35, v31, v38
	v_fma_f32 v39, -v37, v35, v31
	v_fmac_f32_e32 v35, v39, v38
	v_fma_f32 v31, -v37, v35, v31
	v_mul_f32_e32 v37, 0x3d372713, v33
	v_mul_f32_e32 v37, v33, v37
	v_fma_f32 v37, v33, v37, v33
	v_mul_f32_e32 v37, 0x3f4c422a, v37
	v_add_f32_e32 v37, v37, v37
	v_mul_f32_e32 v37, 0x3fb8aa3b, v37
	v_exp_f32_e32 v37, v37
	v_div_fmas_f32 v31, v31, v38, v35
	v_div_fixup_f32 v31, v31, v36, 2.0
	v_sub_f32_e32 v31, 1.0, v31
	v_add_f32_e32 v35, 1.0, v37
	v_div_scale_f32 v36, s[28:29], v35, v35, 2.0
	v_rcp_f32_e32 v37, v36
	v_mul_f32_e32 v32, 0.5, v32
	v_add_f32_e32 v31, 1.0, v31
	v_mul_f32_e32 v31, v32, v31
	v_fma_f32 v32, -v36, v37, 1.0
	v_fmac_f32_e32 v37, v32, v37
	v_div_scale_f32 v32, vcc, 2.0, v35, 2.0
	v_mul_f32_e32 v38, v32, v37
	v_fma_f32 v39, -v36, v38, v32
	v_fmac_f32_e32 v38, v39, v37
	v_fma_f32 v32, -v36, v38, v32
	v_mul_f32_e32 v36, 0x3d372713, v26
	v_mul_f32_e32 v36, v26, v36
	v_fma_f32 v36, v26, v36, v26
	v_mul_f32_e32 v36, 0x3f4c422a, v36
	v_add_f32_e32 v36, v36, v36
	v_mul_f32_e32 v36, 0x3fb8aa3b, v36
	v_exp_f32_e32 v36, v36
	v_div_fmas_f32 v32, v32, v37, v38
	v_div_fixup_f32 v32, v32, v35, 2.0
	v_sub_f32_e32 v32, 1.0, v32
	v_add_f32_e32 v35, 1.0, v36
	v_div_scale_f32 v36, s[28:29], v35, v35, 2.0
	v_rcp_f32_e32 v37, v36
	v_mul_f32_e32 v33, 0.5, v33
	v_add_f32_e32 v32, 1.0, v32
	v_mul_f32_e32 v32, v33, v32
	v_cvt_pk_bf16_f32 v31, v31, v32
	v_fma_f32 v32, -v36, v37, 1.0
	v_fmac_f32_e32 v37, v32, v37
	v_div_scale_f32 v32, vcc, 2.0, v35, 2.0
	v_mul_f32_e32 v33, v32, v37
	v_fma_f32 v38, -v36, v33, v32
	v_fmac_f32_e32 v33, v38, v37
	v_fma_f32 v32, -v36, v33, v32
	v_mul_f32_e32 v36, 0x3d372713, v27
	v_mul_f32_e32 v36, v27, v36
	v_fma_f32 v36, v27, v36, v27
	v_mul_f32_e32 v36, 0x3f4c422a, v36
	v_add_f32_e32 v36, v36, v36
	v_mul_f32_e32 v36, 0x3fb8aa3b, v36
	v_exp_f32_e32 v36, v36
	v_div_fmas_f32 v32, v32, v37, v33
	v_div_fixup_f32 v32, v32, v35, 2.0
	v_sub_f32_e32 v32, 1.0, v32
	v_add_f32_e32 v33, 1.0, v36
	v_div_scale_f32 v35, s[28:29], v33, v33, 2.0
	v_rcp_f32_e32 v36, v35
	v_mul_f32_e32 v26, 0.5, v26
	v_add_f32_e32 v32, 1.0, v32
	v_mul_f32_e32 v26, v26, v32
	v_fma_f32 v32, -v35, v36, 1.0
	v_fmac_f32_e32 v36, v32, v36
	v_div_scale_f32 v32, vcc, 2.0, v33, 2.0
	v_mul_f32_e32 v37, v32, v36
	v_fma_f32 v38, -v35, v37, v32
	v_fmac_f32_e32 v37, v38, v36
	v_fma_f32 v32, -v35, v37, v32
	v_mul_f32_e32 v35, 0x3d372713, v28
	v_mul_f32_e32 v35, v28, v35
	v_fma_f32 v35, v28, v35, v28
	v_mul_f32_e32 v35, 0x3f4c422a, v35
	v_add_f32_e32 v35, v35, v35
	v_mul_f32_e32 v35, 0x3fb8aa3b, v35
	v_exp_f32_e32 v35, v35
	v_div_fmas_f32 v32, v32, v36, v37
	v_div_fixup_f32 v32, v32, v33, 2.0
	v_sub_f32_e32 v32, 1.0, v32
	v_add_f32_e32 v33, 1.0, v35
	v_div_scale_f32 v35, s[28:29], v33, v33, 2.0
	v_rcp_f32_e32 v36, v35
	v_mul_f32_e32 v27, 0.5, v27
	v_add_f32_e32 v32, 1.0, v32
	v_mul_f32_e32 v27, v27, v32
	v_cvt_pk_bf16_f32 v32, v26, v27
	v_fma_f32 v26, -v35, v36, 1.0
	v_fmac_f32_e32 v36, v26, v36
	v_div_scale_f32 v26, vcc, 2.0, v33, 2.0
	v_mul_f32_e32 v27, v26, v36
	v_fma_f32 v37, -v35, v27, v26
	v_fmac_f32_e32 v27, v37, v36
	v_fma_f32 v26, -v35, v27, v26
	v_mul_f32_e32 v35, 0x3d372713, v29
	v_mul_f32_e32 v35, v29, v35
	v_fma_f32 v35, v29, v35, v29
	v_mul_f32_e32 v35, 0x3f4c422a, v35
	v_add_f32_e32 v35, v35, v35
	v_mul_f32_e32 v35, 0x3fb8aa3b, v35
	v_exp_f32_e32 v35, v35
	v_div_fmas_f32 v26, v26, v36, v27
	v_div_fixup_f32 v26, v26, v33, 2.0
	v_sub_f32_e32 v26, 1.0, v26
	v_add_f32_e32 v27, 1.0, v35
	v_div_scale_f32 v33, s[28:29], v27, v27, 2.0
	v_rcp_f32_e32 v35, v33
	v_mul_f32_e32 v28, 0.5, v28
; #define LAS __attribute__((address_space(3)))
; __device__ __forceinline__ unsigned cvt_pk_bf16(float lo, float hi) { unsigned r; asm volatile("v_cvt_pk_bf16_f32 %0, %1, %2" : "=v"(r) : "v"(lo), "v"(hi)); return r; }
; __device__ __forceinline__ float gelu_tanh(float x) { const float z = 0.7978845608f * (x + 0.044715f * x * x * x); const float th = 1.0f - 2.0f / (__expf(2.0f * z) + 1.0f); return 0.5f * x * (1.0f + th); }
;     __device__ __forceinline__ void operator()(const f32x4 (&acc)[2][2][4][2], const Unit& u, int ui, const LAS float* rtab, int wr, int wc, int fr, int fq) const {
;         const int g = u.pm; const int n0 = wr * 64 + fr; const int lc0 = (u.pn & 1) * 256 + wc * 32 + 8 * fq;
; #pragma unroll
;         for (int ai = 0; ai < 2; ++ai)
; #pragma unroll
;             for (int m = 0; m < 4; ++m) {
;                 const int n = n0 + ai * HALF + m * 16;
; #pragma unroll
;                 for (int bj = 0; bj < 2; ++bj) {
;                     const int lc = lc0 + bj * HALF, t = lc >> 4, co = lc & 15; const int token = n * 32 + t;
;                     const f32x4 a0 = acc[ai][bj][m][0], a1 = acc[ai][bj][m][1];
;                     u32x4 w; w.x = cvt_pk_bf16(gelu_tanh(a0[0]), gelu_tanh(a0[1])); w.y = cvt_pk_bf16(gelu_tanh(a0[2]), gelu_tanh(a0[3]));
;                     w.z = cvt_pk_bf16(gelu_tanh(a1[0]), gelu_tanh(a1[1])); w.w = cvt_pk_bf16(gelu_tanh(a1[2]), gelu_tanh(a1[3]));
;                     *(u32x4*)(Y + (size_t)token * 1024 + 16 * g + co) = w;
	v_add_f32_e32 v26, 1.0, v26
	v_mul_f32_e32 v26, v28, v26
	v_fma_f32 v28, -v33, v35, 1.0
	v_fmac_f32_e32 v35, v28, v35
	v_div_scale_f32 v28, vcc, 2.0, v27, 2.0
	v_mul_f32_e32 v36, v28, v35
	v_fma_f32 v37, -v33, v36, v28
	v_fmac_f32_e32 v36, v37, v35
	v_fma_f32 v28, -v33, v36, v28
	v_div_fmas_f32 v28, v28, v35, v36
	v_div_fixup_f32 v27, v28, v27, 2.0
	v_sub_f32_e32 v27, 1.0, v27
	v_mul_f32_e32 v28, 0.5, v29
	v_add_f32_e32 v27, 1.0, v27
	v_mul_f32_e32 v27, v28, v27
	v_mul_f32_e32 v28, 0x3d372713, v22
	v_mul_f32_e32 v28, v22, v28
	v_fma_f32 v28, v22, v28, v22
	v_mul_f32_e32 v28, 0x3f4c422a, v28
	v_add_f32_e32 v28, v28, v28
	v_mul_f32_e32 v28, 0x3fb8aa3b, v28
	v_exp_f32_e32 v28, v28
	v_or_b32_e32 v34, v171, v152
	v_ashrrev_i32_e32 v35, 31, v34
	v_cvt_pk_bf16_f32 v33, v26, v27
	v_add_f32_e32 v28, 1.0, v28
	v_div_scale_f32 v29, s[28:29], v28, v28, 2.0
	v_lshlrev_b64 v[26:27], 11, v[34:35]
	v_rcp_f32_e32 v34, v29
	v_lshl_add_u64 v[26:27], v[138:139], 0, v[26:27]
	global_store_dwordx4 v[26:27], v[30:33], off
	v_mul_f32_e32 v22, 0.5, v22
	v_fma_f32 v27, -v29, v34, 1.0
	v_fmac_f32_e32 v34, v27, v34
	v_div_scale_f32 v27, vcc, 2.0, v28, 2.0
	v_mul_f32_e32 v30, v27, v34
	v_fma_f32 v31, -v29, v30, v27
	v_fmac_f32_e32 v30, v31, v34
	v_fma_f32 v27, -v29, v30, v27
	v_mul_f32_e32 v29, 0x3d372713, v23
	v_mul_f32_e32 v29, v23, v29
	v_fma_f32 v29, v23, v29, v23
	v_mul_f32_e32 v29, 0x3f4c422a, v29
	v_add_f32_e32 v29, v29, v29
	v_mul_f32_e32 v29, 0x3fb8aa3b, v29
	v_exp_f32_e32 v29, v29
	v_div_fmas_f32 v27, v27, v34, v30
	v_div_fixup_f32 v27, v27, v28, 2.0
	v_sub_f32_e32 v27, 1.0, v27
	v_add_f32_e32 v28, 1.0, v29
	v_div_scale_f32 v29, s[28:29], v28, v28, 2.0
	v_rcp_f32_e32 v30, v29
	v_add_f32_e32 v27, 1.0, v27
	v_mul_f32_e32 v22, v22, v27
	v_mul_f32_e32 v23, 0.5, v23
	v_fma_f32 v27, -v29, v30, 1.0
	v_fmac_f32_e32 v30, v27, v30
	v_div_scale_f32 v27, vcc, 2.0, v28, 2.0
	v_mul_f32_e32 v31, v27, v30
	v_fma_f32 v32, -v29, v31, v27
	v_fmac_f32_e32 v31, v32, v30
	v_fma_f32 v27, -v29, v31, v27
	v_mul_f32_e32 v29, 0x3d372713, v24
	v_mul_f32_e32 v29, v24, v29
	v_fma_f32 v29, v24, v29, v24
	v_mul_f32_e32 v29, 0x3f4c422a, v29
	v_add_f32_e32 v29, v29, v29
	v_mul_f32_e32 v29, 0x3fb8aa3b, v29
	v_exp_f32_e32 v29, v29
	v_div_fmas_f32 v27, v27, v30, v31
	v_div_fixup_f32 v27, v27, v28, 2.0
	v_sub_f32_e32 v27, 1.0, v27
	v_add_f32_e32 v28, 1.0, v29
	v_div_scale_f32 v29, s[28:29], v28, v28, 2.0
	v_rcp_f32_e32 v30, v29
	v_add_f32_e32 v27, 1.0, v27
	v_mul_f32_e32 v23, v23, v27
	v_cvt_pk_bf16_f32 v22, v22, v23
	v_fma_f32 v23, -v29, v30, 1.0
	v_fmac_f32_e32 v30, v23, v30
	v_div_scale_f32 v23, vcc, 2.0, v28, 2.0
	v_mul_f32_e32 v27, v23, v30
	v_fma_f32 v31, -v29, v27, v23
	v_fmac_f32_e32 v27, v31, v30
	v_fma_f32 v23, -v29, v27, v23
	v_mul_f32_e32 v29, 0x3d372713, v25
	v_mul_f32_e32 v29, v25, v29
	v_fma_f32 v29, v25, v29, v25
	v_mul_f32_e32 v29, 0x3f4c422a, v29
	v_add_f32_e32 v29, v29, v29
	v_mul_f32_e32 v29, 0x3fb8aa3b, v29
	v_exp_f32_e32 v29, v29
	v_div_fmas_f32 v23, v23, v30, v27
	v_div_fixup_f32 v23, v23, v28, 2.0
	v_sub_f32_e32 v23, 1.0, v23
	v_add_f32_e32 v27, 1.0, v29
	v_div_scale_f32 v28, s[28:29], v27, v27, 2.0
	v_rcp_f32_e32 v29, v28
	v_mul_f32_e32 v24, 0.5, v24
	v_add_f32_e32 v23, 1.0, v23
	v_mul_f32_e32 v23, v24, v23
	v_fma_f32 v24, -v28, v29, 1.0
	v_fmac_f32_e32 v29, v24, v29
	v_div_scale_f32 v24, vcc, 2.0, v27, 2.0
	v_mul_f32_e32 v30, v24, v29
	v_fma_f32 v31, -v28, v30, v24
	v_fmac_f32_e32 v30, v31, v29
	v_fma_f32 v24, -v28, v30, v24
	v_mul_f32_e32 v28, 0x3d372713, v18
	v_mul_f32_e32 v28, v18, v28
	v_fma_f32 v28, v18, v28, v18
	v_mul_f32_e32 v28, 0x3f4c422a, v28
	v_add_f32_e32 v28, v28, v28
	v_mul_f32_e32 v28, 0x3fb8aa3b, v28
	v_exp_f32_e32 v28, v28
	v_div_fmas_f32 v24, v24, v29, v30
	v_div_fixup_f32 v24, v24, v27, 2.0
	v_sub_f32_e32 v24, 1.0, v24
	v_add_f32_e32 v27, 1.0, v28
	v_div_scale_f32 v28, s[28:29], v27, v27, 2.0
	v_rcp_f32_e32 v29, v28
	v_mul_f32_e32 v25, 0.5, v25
	v_add_f32_e32 v24, 1.0, v24
	v_mul_f32_e32 v24, v25, v24
	v_cvt_pk_bf16_f32 v23, v23, v24
	v_fma_f32 v24, -v28, v29, 1.0
	v_fmac_f32_e32 v29, v24, v29
	v_div_scale_f32 v24, vcc, 2.0, v27, 2.0
	v_mul_f32_e32 v25, v24, v29
	v_fma_f32 v30, -v28, v25, v24
	v_fmac_f32_e32 v25, v30, v29
	v_fma_f32 v24, -v28, v25, v24
	v_mul_f32_e32 v28, 0x3d372713, v19
	v_mul_f32_e32 v28, v19, v28
	v_fma_f32 v28, v19, v28, v19
	v_mul_f32_e32 v28, 0x3f4c422a, v28
	v_add_f32_e32 v28, v28, v28
	v_mul_f32_e32 v28, 0x3fb8aa3b, v28
	v_exp_f32_e32 v28, v28
	v_div_fmas_f32 v24, v24, v29, v25
	v_div_fixup_f32 v24, v24, v27, 2.0
	v_sub_f32_e32 v24, 1.0, v24
	v_add_f32_e32 v25, 1.0, v28
	v_div_scale_f32 v27, s[28:29], v25, v25, 2.0
	v_rcp_f32_e32 v28, v27
	v_mul_f32_e32 v18, 0.5, v18
	v_add_f32_e32 v24, 1.0, v24
	v_mul_f32_e32 v18, v18, v24
	v_fma_f32 v24, -v27, v28, 1.0
	v_fmac_f32_e32 v28, v24, v28
	v_div_scale_f32 v24, vcc, 2.0, v25, 2.0
	v_mul_f32_e32 v29, v24, v28
	v_fma_f32 v30, -v27, v29, v24
	v_fmac_f32_e32 v29, v30, v28
	v_fma_f32 v24, -v27, v29, v24
	v_mul_f32_e32 v27, 0x3d372713, v20
	v_mul_f32_e32 v27, v20, v27
	v_fma_f32 v27, v20, v27, v20
	v_mul_f32_e32 v27, 0x3f4c422a, v27
	v_add_f32_e32 v27, v27, v27
	v_mul_f32_e32 v27, 0x3fb8aa3b, v27
	v_exp_f32_e32 v27, v27
	v_div_fmas_f32 v24, v24, v28, v29
	v_div_fixup_f32 v24, v24, v25, 2.0
	v_sub_f32_e32 v24, 1.0, v24
	v_add_f32_e32 v25, 1.0, v27
	v_div_scale_f32 v27, s[28:29], v25, v25, 2.0
	v_rcp_f32_e32 v28, v27
	v_mul_f32_e32 v19, 0.5, v19
	v_add_f32_e32 v24, 1.0, v24
	v_mul_f32_e32 v19, v19, v24
	v_cvt_pk_bf16_f32 v24, v18, v19
	v_fma_f32 v18, -v27, v28, 1.0
	v_fmac_f32_e32 v28, v18, v28
	v_div_scale_f32 v18, vcc, 2.0, v25, 2.0
	v_mul_f32_e32 v19, v18, v28
	v_fma_f32 v29, -v27, v19, v18
; #define LAS __attribute__((address_space(3)))
; __device__ __forceinline__ unsigned cvt_pk_bf16(float lo, float hi) { unsigned r; asm volatile("v_cvt_pk_bf16_f32 %0, %1, %2" : "=v"(r) : "v"(lo), "v"(hi)); return r; }
; __device__ __forceinline__ float gelu_tanh(float x) { const float z = 0.7978845608f * (x + 0.044715f * x * x * x); const float th = 1.0f - 2.0f / (__expf(2.0f * z) + 1.0f); return 0.5f * x * (1.0f + th); }
;     __device__ __forceinline__ void operator()(const f32x4 (&acc)[2][2][4][2], const Unit& u, int ui, const LAS float* rtab, int wr, int wc, int fr, int fq) const {
;         const int g = u.pm; const int n0 = wr * 64 + fr; const int lc0 = (u.pn & 1) * 256 + wc * 32 + 8 * fq;
; #pragma unroll
;         for (int ai = 0; ai < 2; ++ai)
; #pragma unroll
;             for (int m = 0; m < 4; ++m) {
;                 const int n = n0 + ai * HALF + m * 16;
; #pragma unroll
;                 for (int bj = 0; bj < 2; ++bj) {
;                     const int lc = lc0 + bj * HALF, t = lc >> 4, co = lc & 15; const int token = n * 32 + t;
;                     const f32x4 a0 = acc[ai][bj][m][0], a1 = acc[ai][bj][m][1];
;                     u32x4 w; w.x = cvt_pk_bf16(gelu_tanh(a0[0]), gelu_tanh(a0[1])); w.y = cvt_pk_bf16(gelu_tanh(a0[2]), gelu_tanh(a0[3]));
;                     w.z = cvt_pk_bf16(gelu_tanh(a1[0]), gelu_tanh(a1[1])); w.w = cvt_pk_bf16(gelu_tanh(a1[2]), gelu_tanh(a1[3]));
;                     *(u32x4*)(Y + (size_t)token * 1024 + 16 * g + co) = w;
	v_fmac_f32_e32 v19, v29, v28
	v_fma_f32 v18, -v27, v19, v18
	v_mul_f32_e32 v27, 0x3d372713, v21
	v_mul_f32_e32 v27, v21, v27
	v_fma_f32 v27, v21, v27, v21
	v_mul_f32_e32 v27, 0x3f4c422a, v27
	v_add_f32_e32 v27, v27, v27
	v_mul_f32_e32 v27, 0x3fb8aa3b, v27
	v_exp_f32_e32 v27, v27
	v_div_fmas_f32 v18, v18, v28, v19
	v_div_fixup_f32 v18, v18, v25, 2.0
	v_sub_f32_e32 v18, 1.0, v18
	v_add_f32_e32 v19, 1.0, v27
	v_div_scale_f32 v25, s[28:29], v19, v19, 2.0
	v_rcp_f32_e32 v27, v25
	v_mul_f32_e32 v20, 0.5, v20
	v_add_f32_e32 v18, 1.0, v18
	v_mul_f32_e32 v18, v20, v18
	v_fma_f32 v20, -v25, v27, 1.0
	v_fmac_f32_e32 v27, v20, v27
	v_div_scale_f32 v20, vcc, 2.0, v19, 2.0
	v_mul_f32_e32 v28, v20, v27
	v_fma_f32 v29, -v25, v28, v20
	v_fmac_f32_e32 v28, v29, v27
	v_fma_f32 v20, -v25, v28, v20
	v_div_fmas_f32 v20, v20, v27, v28
	v_div_fixup_f32 v19, v20, v19, 2.0
	v_sub_f32_e32 v19, 1.0, v19
	v_mul_f32_e32 v20, 0.5, v21
	v_add_f32_e32 v19, 1.0, v19
	v_mul_f32_e32 v19, v20, v19
	v_mul_f32_e32 v20, 0x3d372713, v14
	v_mul_f32_e32 v20, v14, v20
	v_fma_f32 v20, v14, v20, v14
	v_mul_f32_e32 v20, 0x3f4c422a, v20
	v_add_f32_e32 v20, v20, v20
	v_mul_f32_e32 v20, 0x3fb8aa3b, v20
	v_exp_f32_e32 v20, v20
	v_or_b32_e32 v26, v124, v152
	v_ashrrev_i32_e32 v27, 31, v26
	v_cvt_pk_bf16_f32 v25, v18, v19
	v_add_f32_e32 v20, 1.0, v20
	v_div_scale_f32 v21, s[28:29], v20, v20, 2.0
	v_lshlrev_b64 v[18:19], 11, v[26:27]
	v_rcp_f32_e32 v26, v21
	v_lshl_add_u64 v[18:19], v[138:139], 0, v[18:19]
	global_store_dwordx4 v[18:19], v[22:25], off
	v_mul_f32_e32 v14, 0.5, v14
	v_fma_f32 v19, -v21, v26, 1.0
	v_fmac_f32_e32 v26, v19, v26
	v_div_scale_f32 v19, vcc, 2.0, v20, 2.0
	v_mul_f32_e32 v22, v19, v26
	v_fma_f32 v23, -v21, v22, v19
	v_fmac_f32_e32 v22, v23, v26
	v_fma_f32 v19, -v21, v22, v19
	v_mul_f32_e32 v21, 0x3d372713, v15
	v_mul_f32_e32 v21, v15, v21
	v_fma_f32 v21, v15, v21, v15
	v_mul_f32_e32 v21, 0x3f4c422a, v21
	v_add_f32_e32 v21, v21, v21
	v_mul_f32_e32 v21, 0x3fb8aa3b, v21
	v_exp_f32_e32 v21, v21
	v_div_fmas_f32 v19, v19, v26, v22
	v_div_fixup_f32 v19, v19, v20, 2.0
	v_sub_f32_e32 v19, 1.0, v19
	v_add_f32_e32 v20, 1.0, v21
	v_div_scale_f32 v21, s[28:29], v20, v20, 2.0
	v_rcp_f32_e32 v22, v21
	v_add_f32_e32 v19, 1.0, v19
	v_mul_f32_e32 v14, v14, v19
	v_mul_f32_e32 v15, 0.5, v15
	v_fma_f32 v19, -v21, v22, 1.0
	v_fmac_f32_e32 v22, v19, v22
	v_div_scale_f32 v19, vcc, 2.0, v20, 2.0
	v_mul_f32_e32 v23, v19, v22
	v_fma_f32 v24, -v21, v23, v19
	v_fmac_f32_e32 v23, v24, v22
	v_fma_f32 v19, -v21, v23, v19
	v_mul_f32_e32 v21, 0x3d372713, v16
	v_mul_f32_e32 v21, v16, v21
	v_fma_f32 v21, v16, v21, v16
	v_mul_f32_e32 v21, 0x3f4c422a, v21
	v_add_f32_e32 v21, v21, v21
	v_mul_f32_e32 v21, 0x3fb8aa3b, v21
	v_exp_f32_e32 v21, v21
	v_div_fmas_f32 v19, v19, v22, v23
	v_div_fixup_f32 v19, v19, v20, 2.0
	v_sub_f32_e32 v19, 1.0, v19
	v_add_f32_e32 v20, 1.0, v21
	v_div_scale_f32 v21, s[28:29], v20, v20, 2.0
	v_rcp_f32_e32 v22, v21
	v_add_f32_e32 v19, 1.0, v19
	v_mul_f32_e32 v15, v15, v19
	v_cvt_pk_bf16_f32 v14, v14, v15
	v_fma_f32 v15, -v21, v22, 1.0
	v_fmac_f32_e32 v22, v15, v22
	v_div_scale_f32 v15, vcc, 2.0, v20, 2.0
	v_mul_f32_e32 v19, v15, v22
	v_fma_f32 v23, -v21, v19, v15
	v_fmac_f32_e32 v19, v23, v22
	v_fma_f32 v15, -v21, v19, v15
	v_mul_f32_e32 v21, 0x3d372713, v17
	v_mul_f32_e32 v21, v17, v21
	v_fma_f32 v21, v17, v21, v17
	v_mul_f32_e32 v21, 0x3f4c422a, v21
	v_add_f32_e32 v21, v21, v21
	v_mul_f32_e32 v21, 0x3fb8aa3b, v21
	v_exp_f32_e32 v21, v21
	v_div_fmas_f32 v15, v15, v22, v19
	v_div_fixup_f32 v15, v15, v20, 2.0
	v_sub_f32_e32 v15, 1.0, v15
	v_add_f32_e32 v19, 1.0, v21
	v_div_scale_f32 v20, s[28:29], v19, v19, 2.0
	v_rcp_f32_e32 v21, v20
	v_mul_f32_e32 v16, 0.5, v16
	v_add_f32_e32 v15, 1.0, v15
	v_mul_f32_e32 v15, v16, v15
	v_fma_f32 v16, -v20, v21, 1.0
	v_fmac_f32_e32 v21, v16, v21
	v_div_scale_f32 v16, vcc, 2.0, v19, 2.0
	v_mul_f32_e32 v22, v16, v21
	v_fma_f32 v23, -v20, v22, v16
	v_fmac_f32_e32 v22, v23, v21
	v_fma_f32 v16, -v20, v22, v16
	v_mul_f32_e32 v20, 0x3d372713, v10
	v_mul_f32_e32 v20, v10, v20
	v_fma_f32 v20, v10, v20, v10
	v_mul_f32_e32 v20, 0x3f4c422a, v20
	v_add_f32_e32 v20, v20, v20
	v_mul_f32_e32 v20, 0x3fb8aa3b, v20
	v_exp_f32_e32 v20, v20
	v_div_fmas_f32 v16, v16, v21, v22
	v_div_fixup_f32 v16, v16, v19, 2.0
	v_sub_f32_e32 v16, 1.0, v16
	v_add_f32_e32 v19, 1.0, v20
	v_div_scale_f32 v20, s[28:29], v19, v19, 2.0
	v_rcp_f32_e32 v21, v20
	v_mul_f32_e32 v17, 0.5, v17
	v_add_f32_e32 v16, 1.0, v16
	v_mul_f32_e32 v16, v17, v16
	v_cvt_pk_bf16_f32 v15, v15, v16
	v_fma_f32 v16, -v20, v21, 1.0
	v_fmac_f32_e32 v21, v16, v21
	v_div_scale_f32 v16, vcc, 2.0, v19, 2.0
	v_mul_f32_e32 v17, v16, v21
	v_fma_f32 v22, -v20, v17, v16
	v_fmac_f32_e32 v17, v22, v21
	v_fma_f32 v16, -v20, v17, v16
	v_mul_f32_e32 v20, 0x3d372713, v11
	v_mul_f32_e32 v20, v11, v20
	v_fma_f32 v20, v11, v20, v11
	v_mul_f32_e32 v20, 0x3f4c422a, v20
	v_add_f32_e32 v20, v20, v20
	v_mul_f32_e32 v20, 0x3fb8aa3b, v20
	v_exp_f32_e32 v20, v20
	v_div_fmas_f32 v16, v16, v21, v17
	v_div_fixup_f32 v16, v16, v19, 2.0
	v_sub_f32_e32 v16, 1.0, v16
	v_add_f32_e32 v17, 1.0, v20
	v_div_scale_f32 v19, s[28:29], v17, v17, 2.0
	v_rcp_f32_e32 v20, v19
	v_mul_f32_e32 v10, 0.5, v10
	v_add_f32_e32 v16, 1.0, v16
	v_mul_f32_e32 v10, v10, v16
	v_fma_f32 v16, -v19, v20, 1.0
	v_fmac_f32_e32 v20, v16, v20
	v_div_scale_f32 v16, vcc, 2.0, v17, 2.0
	v_mul_f32_e32 v21, v16, v20
	v_fma_f32 v22, -v19, v21, v16
	v_fmac_f32_e32 v21, v22, v20
	v_fma_f32 v16, -v19, v21, v16
	v_mul_f32_e32 v19, 0x3d372713, v12
	v_mul_f32_e32 v19, v12, v19
	v_fma_f32 v19, v12, v19, v12
	v_mul_f32_e32 v19, 0x3f4c422a, v19
	v_add_f32_e32 v19, v19, v19
	v_mul_f32_e32 v19, 0x3fb8aa3b, v19
; #define LAS __attribute__((address_space(3)))
; __device__ __forceinline__ unsigned cvt_pk_bf16(float lo, float hi) { unsigned r; asm volatile("v_cvt_pk_bf16_f32 %0, %1, %2" : "=v"(r) : "v"(lo), "v"(hi)); return r; }
; __device__ __forceinline__ float gelu_tanh(float x) { const float z = 0.7978845608f * (x + 0.044715f * x * x * x); const float th = 1.0f - 2.0f / (__expf(2.0f * z) + 1.0f); return 0.5f * x * (1.0f + th); }
;     __device__ __forceinline__ void operator()(const f32x4 (&acc)[2][2][4][2], const Unit& u, int ui, const LAS float* rtab, int wr, int wc, int fr, int fq) const {
;         const int g = u.pm; const int n0 = wr * 64 + fr; const int lc0 = (u.pn & 1) * 256 + wc * 32 + 8 * fq;
; #pragma unroll
;         for (int ai = 0; ai < 2; ++ai)
; #pragma unroll
;             for (int m = 0; m < 4; ++m) {
;                 const int n = n0 + ai * HALF + m * 16;
; #pragma unroll
;                 for (int bj = 0; bj < 2; ++bj) {
;                     const int lc = lc0 + bj * HALF, t = lc >> 4, co = lc & 15; const int token = n * 32 + t;
;                     const f32x4 a0 = acc[ai][bj][m][0], a1 = acc[ai][bj][m][1];
;                     u32x4 w; w.x = cvt_pk_bf16(gelu_tanh(a0[0]), gelu_tanh(a0[1])); w.y = cvt_pk_bf16(gelu_tanh(a0[2]), gelu_tanh(a0[3]));
;                     w.z = cvt_pk_bf16(gelu_tanh(a1[0]), gelu_tanh(a1[1])); w.w = cvt_pk_bf16(gelu_tanh(a1[2]), gelu_tanh(a1[3]));
;                     *(u32x4*)(Y + (size_t)token * 1024 + 16 * g + co) = w;
	v_exp_f32_e32 v19, v19
	v_div_fmas_f32 v16, v16, v20, v21
	v_div_fixup_f32 v16, v16, v17, 2.0
	v_sub_f32_e32 v16, 1.0, v16
	v_add_f32_e32 v17, 1.0, v19
	v_div_scale_f32 v19, s[28:29], v17, v17, 2.0
	v_rcp_f32_e32 v20, v19
	v_mul_f32_e32 v11, 0.5, v11
	v_add_f32_e32 v16, 1.0, v16
	v_mul_f32_e32 v11, v11, v16
	v_cvt_pk_bf16_f32 v16, v10, v11
	v_fma_f32 v10, -v19, v20, 1.0
	v_fmac_f32_e32 v20, v10, v20
	v_div_scale_f32 v10, vcc, 2.0, v17, 2.0
	v_mul_f32_e32 v11, v10, v20
	v_fma_f32 v21, -v19, v11, v10
	v_fmac_f32_e32 v11, v21, v20
	v_fma_f32 v10, -v19, v11, v10
	v_mul_f32_e32 v19, 0x3d372713, v13
	v_mul_f32_e32 v19, v13, v19
	v_fma_f32 v19, v13, v19, v13
	v_mul_f32_e32 v19, 0x3f4c422a, v19
	v_add_f32_e32 v19, v19, v19
	v_mul_f32_e32 v19, 0x3fb8aa3b, v19
	v_exp_f32_e32 v19, v19
	v_div_fmas_f32 v10, v10, v20, v11
	v_div_fixup_f32 v10, v10, v17, 2.0
	v_sub_f32_e32 v10, 1.0, v10
	v_add_f32_e32 v11, 1.0, v19
	v_div_scale_f32 v17, s[28:29], v11, v11, 2.0
	v_rcp_f32_e32 v19, v17
	v_mul_f32_e32 v12, 0.5, v12
	v_add_f32_e32 v10, 1.0, v10
	v_mul_f32_e32 v10, v12, v10
	v_fma_f32 v12, -v17, v19, 1.0
	v_fmac_f32_e32 v19, v12, v19
	v_div_scale_f32 v12, vcc, 2.0, v11, 2.0
	v_mul_f32_e32 v20, v12, v19
	v_fma_f32 v21, -v17, v20, v12
	v_fmac_f32_e32 v20, v21, v19
	v_fma_f32 v12, -v17, v20, v12
	v_div_fmas_f32 v12, v12, v19, v20
	v_div_fixup_f32 v11, v12, v11, 2.0
	v_sub_f32_e32 v11, 1.0, v11
	v_mul_f32_e32 v12, 0.5, v13
	v_add_f32_e32 v11, 1.0, v11
	v_mul_f32_e32 v11, v12, v11
	v_mul_f32_e32 v12, 0x3d372713, v6
	v_mul_f32_e32 v12, v6, v12
	v_fma_f32 v12, v6, v12, v6
	v_mul_f32_e32 v12, 0x3f4c422a, v12
	v_add_f32_e32 v12, v12, v12
	v_mul_f32_e32 v12, 0x3fb8aa3b, v12
	v_exp_f32_e32 v12, v12
	v_or_b32_e32 v18, v171, v153
	v_ashrrev_i32_e32 v19, 31, v18
	v_cvt_pk_bf16_f32 v17, v10, v11
	v_add_f32_e32 v12, 1.0, v12
	v_div_scale_f32 v13, s[28:29], v12, v12, 2.0
	v_lshlrev_b64 v[10:11], 11, v[18:19]
	v_rcp_f32_e32 v18, v13
	v_lshl_add_u64 v[10:11], v[138:139], 0, v[10:11]
	global_store_dwordx4 v[10:11], v[14:17], off
	v_mul_f32_e32 v6, 0.5, v6
	v_fma_f32 v11, -v13, v18, 1.0
	v_fmac_f32_e32 v18, v11, v18
	v_div_scale_f32 v11, vcc, 2.0, v12, 2.0
	v_mul_f32_e32 v14, v11, v18
	v_fma_f32 v15, -v13, v14, v11
	v_fmac_f32_e32 v14, v15, v18
	v_fma_f32 v11, -v13, v14, v11
	v_mul_f32_e32 v13, 0x3d372713, v7
	v_mul_f32_e32 v13, v7, v13
	v_fma_f32 v13, v7, v13, v7
	v_mul_f32_e32 v13, 0x3f4c422a, v13
	v_add_f32_e32 v13, v13, v13
	v_mul_f32_e32 v13, 0x3fb8aa3b, v13
	v_exp_f32_e32 v13, v13
	v_div_fmas_f32 v11, v11, v18, v14
	v_div_fixup_f32 v11, v11, v12, 2.0
	v_sub_f32_e32 v11, 1.0, v11
	v_add_f32_e32 v12, 1.0, v13
	v_div_scale_f32 v13, s[28:29], v12, v12, 2.0
	v_rcp_f32_e32 v14, v13
	v_add_f32_e32 v11, 1.0, v11
	v_mul_f32_e32 v6, v6, v11
	v_mul_f32_e32 v7, 0.5, v7
	v_fma_f32 v11, -v13, v14, 1.0
	v_fmac_f32_e32 v14, v11, v14
	v_div_scale_f32 v11, vcc, 2.0, v12, 2.0
	v_mul_f32_e32 v15, v11, v14
	v_fma_f32 v16, -v13, v15, v11
	v_fmac_f32_e32 v15, v16, v14
	v_fma_f32 v11, -v13, v15, v11
	v_mul_f32_e32 v13, 0x3d372713, v8
	v_mul_f32_e32 v13, v8, v13
	v_fma_f32 v13, v8, v13, v8
	v_mul_f32_e32 v13, 0x3f4c422a, v13
	v_add_f32_e32 v13, v13, v13
	v_mul_f32_e32 v13, 0x3fb8aa3b, v13
	v_exp_f32_e32 v13, v13
	v_div_fmas_f32 v11, v11, v14, v15
	v_div_fixup_f32 v11, v11, v12, 2.0
	v_sub_f32_e32 v11, 1.0, v11
	v_add_f32_e32 v12, 1.0, v13
	v_div_scale_f32 v13, s[28:29], v12, v12, 2.0
	v_rcp_f32_e32 v14, v13
	v_add_f32_e32 v11, 1.0, v11
	v_mul_f32_e32 v7, v7, v11
	v_cvt_pk_bf16_f32 v6, v6, v7
	v_fma_f32 v7, -v13, v14, 1.0
	v_fmac_f32_e32 v14, v7, v14
	v_div_scale_f32 v7, vcc, 2.0, v12, 2.0
	v_mul_f32_e32 v11, v7, v14
	v_fma_f32 v15, -v13, v11, v7
	v_fmac_f32_e32 v11, v15, v14
	v_fma_f32 v7, -v13, v11, v7
	v_mul_f32_e32 v13, 0x3d372713, v9
	v_mul_f32_e32 v13, v9, v13
	v_fma_f32 v13, v9, v13, v9
	v_mul_f32_e32 v13, 0x3f4c422a, v13
	v_add_f32_e32 v13, v13, v13
	v_mul_f32_e32 v13, 0x3fb8aa3b, v13
	v_exp_f32_e32 v13, v13
; #define LAS __attribute__((address_space(3)))
; __device__ __forceinline__ unsigned cvt_pk_bf16(float lo, float hi) { unsigned r; asm volatile("v_cvt_pk_bf16_f32 %0, %1, %2" : "=v"(r) : "v"(lo), "v"(hi)); return r; }
; __device__ __forceinline__ float gelu_tanh(float x) { const float z = 0.7978845608f * (x + 0.044715f * x * x * x); const float th = 1.0f - 2.0f / (__expf(2.0f * z) + 1.0f); return 0.5f * x * (1.0f + th); }
; #define PG8_WAIT_V(n) asm volatile("s_waitcnt vmcnt(" #n ")" ::: "memory")
; #define PG8_BAR __builtin_amdgcn_s_barrier()
;     __device__ __forceinline__ void operator()(const f32x4 (&acc)[2][2][4][2], const Unit& u, int ui, const LAS float* rtab, int wr, int wc, int fr, int fq) const {
;         const int g = u.pm; const int n0 = wr * 64 + fr; const int lc0 = (u.pn & 1) * 256 + wc * 32 + 8 * fq;
; #pragma unroll
;         for (int ai = 0; ai < 2; ++ai)
; #pragma unroll
;             for (int m = 0; m < 4; ++m) {
;                 const int n = n0 + ai * HALF + m * 16;
; #pragma unroll
;                 for (int bj = 0; bj < 2; ++bj) {
;                     const int lc = lc0 + bj * HALF, t = lc >> 4, co = lc & 15; const int token = n * 32 + t;
;                     const f32x4 a0 = acc[ai][bj][m][0], a1 = acc[ai][bj][m][1];
;                     u32x4 w; w.x = cvt_pk_bf16(gelu_tanh(a0[0]), gelu_tanh(a0[1])); w.y = cvt_pk_bf16(gelu_tanh(a0[2]), gelu_tanh(a0[3]));
;                     w.z = cvt_pk_bf16(gelu_tanh(a1[0]), gelu_tanh(a1[1])); w.w = cvt_pk_bf16(gelu_tanh(a1[2]), gelu_tanh(a1[3]));
;                     *(u32x4*)(Y + (size_t)token * 1024 + 16 * g + co) = w;
; template <class Epi, class Sched>
; __device__ __forceinline__ void gemm_phase(LAS unsigned char* lds, const Gemm g, const Sched& S, const Epi& E) {
;     ...
;         if (!has_next) break;
; #pragma unroll
;         for (int a = 0; a < 2; ++a)
; #pragma unroll
;             for (int b = 0; b < 2; ++b)
; #pragma unroll
;                 for (int m = 0; m < 4; ++m)
; #pragma unroll
;                     for (int n = 0; n < 2; ++n) acc[a][b][m][n] = (f32x4){0.f, 0.f, 0.f, 0.f};
;         cur = nxt; cA = nA; cB = nB; ++ui;
;     }
;     PG8_WAIT_V(0);
;     if (wr == 0) PG8_BAR;
	v_div_fmas_f32 v7, v7, v14, v11
	v_div_fixup_f32 v7, v7, v12, 2.0
	v_sub_f32_e32 v7, 1.0, v7
	v_add_f32_e32 v11, 1.0, v13
	v_div_scale_f32 v12, s[28:29], v11, v11, 2.0
	v_rcp_f32_e32 v13, v12
	v_mul_f32_e32 v8, 0.5, v8
	v_add_f32_e32 v7, 1.0, v7
	v_mul_f32_e32 v7, v8, v7
	v_fma_f32 v8, -v12, v13, 1.0
	v_fmac_f32_e32 v13, v8, v13
	v_div_scale_f32 v8, vcc, 2.0, v11, 2.0
	v_mul_f32_e32 v14, v8, v13
	v_fma_f32 v15, -v12, v14, v8
	v_fmac_f32_e32 v14, v15, v13
	v_fma_f32 v8, -v12, v14, v8
	v_mul_f32_e32 v12, 0x3d372713, v2
	v_mul_f32_e32 v12, v2, v12
	v_fma_f32 v12, v2, v12, v2
	v_mul_f32_e32 v12, 0x3f4c422a, v12
	v_add_f32_e32 v12, v12, v12
	v_mul_f32_e32 v12, 0x3fb8aa3b, v12
	v_exp_f32_e32 v12, v12
	v_div_fmas_f32 v8, v8, v13, v14
	v_div_fixup_f32 v8, v8, v11, 2.0
	v_sub_f32_e32 v8, 1.0, v8
	v_add_f32_e32 v11, 1.0, v12
	v_div_scale_f32 v12, s[28:29], v11, v11, 2.0
	v_rcp_f32_e32 v13, v12
	v_mul_f32_e32 v9, 0.5, v9
	v_add_f32_e32 v8, 1.0, v8
	v_mul_f32_e32 v8, v9, v8
	v_cvt_pk_bf16_f32 v7, v7, v8
	v_fma_f32 v8, -v12, v13, 1.0
	v_fmac_f32_e32 v13, v8, v13
	v_div_scale_f32 v8, vcc, 2.0, v11, 2.0
	v_mul_f32_e32 v9, v8, v13
	v_fma_f32 v14, -v12, v9, v8
	v_fmac_f32_e32 v9, v14, v13
	v_fma_f32 v8, -v12, v9, v8
	v_mul_f32_e32 v12, 0x3d372713, v3
	v_mul_f32_e32 v12, v3, v12
	v_fma_f32 v12, v3, v12, v3
	v_mul_f32_e32 v12, 0x3f4c422a, v12
	v_add_f32_e32 v12, v12, v12
	v_mul_f32_e32 v12, 0x3fb8aa3b, v12
	v_exp_f32_e32 v12, v12
	v_div_fmas_f32 v8, v8, v13, v9
	v_div_fixup_f32 v8, v8, v11, 2.0
	v_sub_f32_e32 v8, 1.0, v8
	v_add_f32_e32 v9, 1.0, v12
	v_div_scale_f32 v11, s[28:29], v9, v9, 2.0
	v_rcp_f32_e32 v12, v11
	v_mul_f32_e32 v2, 0.5, v2
	v_add_f32_e32 v8, 1.0, v8
	v_mul_f32_e32 v2, v2, v8
	v_fma_f32 v8, -v11, v12, 1.0
	v_fmac_f32_e32 v12, v8, v12
	v_div_scale_f32 v8, vcc, 2.0, v9, 2.0
	v_mul_f32_e32 v13, v8, v12
	v_fma_f32 v14, -v11, v13, v8
	v_fmac_f32_e32 v13, v14, v12
	v_fma_f32 v8, -v11, v13, v8
	v_mul_f32_e32 v11, 0x3d372713, v4
	v_mul_f32_e32 v11, v4, v11
	v_fma_f32 v11, v4, v11, v4
	v_mul_f32_e32 v11, 0x3f4c422a, v11
	v_add_f32_e32 v11, v11, v11
	v_mul_f32_e32 v11, 0x3fb8aa3b, v11
	v_exp_f32_e32 v11, v11
	v_div_fmas_f32 v8, v8, v12, v13
	v_div_fixup_f32 v8, v8, v9, 2.0
	v_sub_f32_e32 v8, 1.0, v8
	v_add_f32_e32 v9, 1.0, v11
	v_div_scale_f32 v11, s[28:29], v9, v9, 2.0
	v_rcp_f32_e32 v12, v11
	v_mul_f32_e32 v3, 0.5, v3
	v_add_f32_e32 v8, 1.0, v8
	v_mul_f32_e32 v3, v3, v8
	v_cvt_pk_bf16_f32 v8, v2, v3
	v_fma_f32 v2, -v11, v12, 1.0
	v_fmac_f32_e32 v12, v2, v12
	v_div_scale_f32 v2, vcc, 2.0, v9, 2.0
	v_mul_f32_e32 v3, v2, v12
	v_fma_f32 v13, -v11, v3, v2
	v_fmac_f32_e32 v3, v13, v12
	v_fma_f32 v2, -v11, v3, v2
	v_mul_f32_e32 v11, 0x3d372713, v5
	v_mul_f32_e32 v11, v5, v11
	v_fma_f32 v11, v5, v11, v5
	v_mul_f32_e32 v11, 0x3f4c422a, v11
	v_add_f32_e32 v11, v11, v11
	v_mul_f32_e32 v11, 0x3fb8aa3b, v11
	v_exp_f32_e32 v11, v11
	v_div_fmas_f32 v2, v2, v12, v3
	v_div_fixup_f32 v2, v2, v9, 2.0
	v_sub_f32_e32 v2, 1.0, v2
	v_add_f32_e32 v3, 1.0, v11
	v_div_scale_f32 v9, s[28:29], v3, v3, 2.0
	v_rcp_f32_e32 v11, v9
	v_mul_f32_e32 v4, 0.5, v4
	v_add_f32_e32 v2, 1.0, v2
	v_mul_f32_e32 v2, v4, v2
	v_fma_f32 v4, -v9, v11, 1.0
	v_fmac_f32_e32 v11, v4, v11
	v_div_scale_f32 v4, vcc, 2.0, v3, 2.0
	v_mul_f32_e32 v12, v4, v11
	v_fma_f32 v13, -v9, v12, v4
	v_fmac_f32_e32 v12, v13, v11
	v_fma_f32 v4, -v9, v12, v4
	v_div_fmas_f32 v4, v4, v11, v12
	v_div_fixup_f32 v3, v4, v3, 2.0
	v_sub_f32_e32 v3, 1.0, v3
	v_or_b32_e32 v10, v124, v153
	v_mul_f32_e32 v4, 0.5, v5
	v_add_f32_e32 v3, 1.0, v3
	v_mul_f32_e32 v3, v4, v3
	v_ashrrev_i32_e32 v11, 31, v10
	v_cvt_pk_bf16_f32 v9, v2, v3
	v_lshlrev_b64 v[2:3], 11, v[10:11]
	v_lshl_add_u64 v[2:3], v[138:139], 0, v[2:3]
	s_mov_b64 s[42:43], 0
	s_and_b64 vcc, exec, s[40:41]
	v_readlane_b32 s26, v254, 32
	global_store_dwordx4 v[2:3], v[6:9], off
	s_cbranch_vccz .LBB0_594
	s_waitcnt vmcnt(0)
	s_cmpk_gt_u32 s12, 0xff
	s_cbranch_scc1 .LBB0_599
	s_barrier

; #define PG8_STAGE(bufoff, gbase, voff) do { _Pragma("unroll") for (int _i = 0; _i < 2; ++_i) \
;         __builtin_amdgcn_global_load_lds((const unsigned*)((const char*)(gbase) + (voff)[_i]), (LAS unsigned*)(lds + (bufoff) + ldsw + _i * 8192), 16, 0, 0); } while (0)
; #define PG8_LDA(dst, b, h) do { _Pragma("unroll") for (int m = 0; m < 4; ++m) _Pragma("unroll") for (int k = 0; k < 2; ++k) dst[m][k] = *(const LAS bf16x8*)(lds + PG8_SA(b, h) + aoff + m * 2048 + k * 1024); } while (0)
; #define PG8_LDB(dst, b, h) do { _Pragma("unroll") for (int n = 0; n < 2; ++n) _Pragma("unroll") for (int k = 0; k < 2; ++k) dst[n][k] = *(const LAS bf16x8*)(lds + PG8_SB(b, h) + boff + n * 2048 + k * 1024); } while (0)
; #define PG8_WAIT_V(n) asm volatile("s_waitcnt vmcnt(" #n ")" ::: "memory")
; #define PG8_WAIT_L(n) asm volatile("s_waitcnt lgkmcnt(" #n ")" ::: "memory")
; #define PG8_BAR __builtin_amdgcn_s_barrier()
; #define PG8_SCHED __builtin_amdgcn_sched_barrier(0)
; template <class Epi, class Sched>
; __device__ __forceinline__ void gemm_phase(LAS unsigned char* lds, const Gemm g, const Sched& S, const Epi& E) {
;     ...
;             PG8_LDB(B0, 0, 0); PG8_SCHED; PG8_LDA(At, 0, 0); PG8_STAGE(PG8_SA(1, 1), a1 + hstepA, voffA);
;             PG8_WAIT_L(8); PG8_BAR; PG8_WAIT_L(0); PG8_MMA(0, 0, At, B0); PG8_BAR; PG8_SCHED;
;             PG8_LDB(B1, 0, 1); PG8_STAGE(PG8_SB(0, 0), b2, voffB);
;             PG8_BAR; PG8_WAIT_L(0); PG8_MMA(0, 1, At, B1); PG8_BAR;
;             PG8_LDA(At, 0, 1); PG8_STAGE(PG8_SA(0, 0), a2, voffA);
;             PG8_BAR; PG8_WAIT_L(0); PG8_MMA(1, 0, At, B0); PG8_BAR; PG8_SCHED;
;             PG8_STAGE(PG8_SB(0, 1), b2 + hstepB, voffB);
;             PG8_WAIT_V(6); PG8_BAR; PG8_MMA(1, 1, At, B1); PG8_BAR;
;             PG8_LDB(B0, 1, 0); PG8_SCHED; PG8_LDA(At, 1, 0); PG8_STAGE(PG8_SA(0, 1), a2 + hstepA, voffA);
;             PG8_WAIT_L(8); PG8_BAR; PG8_WAIT_L(0); PG8_MMA(0, 0, At, B0); PG8_BAR; PG8_SCHED;
;             PG8_LDB(B1, 1, 1); PG8_STAGE(PG8_SB(1, 0), b3, voffB);
;             PG8_BAR; PG8_WAIT_L(0); PG8_MMA(0, 1, At, B1); PG8_BAR;
;             PG8_LDA(At, 1, 1); PG8_STAGE(PG8_SA(1, 0), a3, voffA);
;             PG8_BAR; PG8_WAIT_L(0); PG8_MMA(1, 0, At, B0); PG8_BAR; PG8_SCHED;
;             PG8_STAGE(PG8_SB(1, 1), b3 + hstepB, voffB);
;             PG8_WAIT_V(6); PG8_BAR; PG8_MMA(1, 1, At, B1); PG8_BAR;
;         }
.LBB0_668:
	s_add_u32 s23, s20, 0xfffc0080
	s_addc_u32 s34, s21, -1
	s_add_i32 s43, 0, 0x10000
	v_add_u32_e32 v153, s43, v150
	ds_read_b128 v[142:145], v153
	ds_read_b128 v[146:149], v153 offset:1024
	ds_read_b128 v[170:173], v153 offset:2048
	ds_read_b128 v[174:177], v153 offset:3072
	s_cmp_eq_u32 s31, 12
	s_cselect_b32 s49, s24, s34
	s_cselect_b32 s48, s25, s23
	s_cselect_b32 s37, s1, s29
	s_cselect_b32 s36, s26, s28
	v_lshl_add_u64 v[198:199], s[20:21], 0, v[138:139]
	s_add_i32 m0, s52, 0xc000
	ds_read_b128 v[178:181], v152
	ds_read_b128 v[182:185], v152 offset:1024
	ds_read_b128 v[186:189], v152 offset:2048
	ds_read_b128 v[190:193], v152 offset:3072
	ds_read_b128 v[194:197], v152 offset:4096
	ds_read_b128 v[210:213], v152 offset:5120
	ds_read_b128 v[214:217], v152 offset:6144
	ds_read_b128 v[218:221], v152 offset:7168
	global_load_lds_dwordx4 v[198:199], off
	v_lshl_add_u64 v[198:199], s[20:21], 0, v[140:141]
	s_add_i32 m0, s52, 0xe000
	s_nop 0
	global_load_lds_dwordx4 v[198:199], off
	s_waitcnt lgkmcnt(8)
	s_barrier
	s_waitcnt lgkmcnt(0)
	s_waitcnt lgkmcnt(0)
	v_mfma_f32_16x16x32_bf16 v[126:129], v[142:145], v[178:181], v[126:129]
	v_mfma_f32_16x16x32_bf16 v[122:125], v[170:173], v[178:181], v[122:125]
	v_mfma_f32_16x16x32_bf16 v[110:113], v[142:145], v[186:189], v[110:113]
	v_mfma_f32_16x16x32_bf16 v[106:109], v[170:173], v[186:189], v[106:109]
	v_mfma_f32_16x16x32_bf16 v[94:97], v[142:145], v[194:197], v[94:97]
	v_mfma_f32_16x16x32_bf16 v[90:93], v[170:173], v[194:197], v[90:93]
	v_mfma_f32_16x16x32_bf16 v[78:81], v[142:145], v[214:217], v[78:81]
	v_mfma_f32_16x16x32_bf16 v[74:77], v[170:173], v[214:217], v[74:77]
	v_mfma_f32_16x16x32_bf16 v[126:129], v[146:149], v[182:185], v[126:129]
	v_mfma_f32_16x16x32_bf16 v[122:125], v[174:177], v[182:185], v[122:125]
	v_mfma_f32_16x16x32_bf16 v[110:113], v[146:149], v[190:193], v[110:113]
	v_mfma_f32_16x16x32_bf16 v[106:109], v[174:177], v[190:193], v[106:109]
	v_mfma_f32_16x16x32_bf16 v[94:97], v[146:149], v[210:213], v[94:97]
	v_mfma_f32_16x16x32_bf16 v[90:93], v[174:177], v[210:213], v[90:93]
	v_mfma_f32_16x16x32_bf16 v[78:81], v[146:149], v[218:221], v[78:81]
	v_mfma_f32_16x16x32_bf16 v[74:77], v[174:177], v[218:221], v[74:77]
	s_barrier
	s_add_i32 s23, 0, 0x14000
	s_add_i32 s34, s43, s51
	v_add_u32_e32 v153, s23, v150
	v_lshl_add_u64 v[198:199], s[36:37], 0, v[134:135]
	s_mov_b32 m0, s34
	ds_read_b128 v[222:225], v153
	ds_read_b128 v[226:229], v153 offset:1024
	ds_read_b128 v[230:233], v153 offset:2048
	ds_read_b128 v[234:237], v153 offset:3072
	global_load_lds_dwordx4 v[198:199], off
	v_lshl_add_u64 v[238:239], s[36:37], 0, v[130:131]
	s_add_i32 m0, s34, 0x2000
	s_nop 0
	global_load_lds_dwordx4 v[238:239], off
	s_barrier
	s_waitcnt lgkmcnt(0)
	s_waitcnt lgkmcnt(0)
	v_mfma_f32_16x16x32_bf16 v[118:121], v[222:225], v[178:181], v[118:121]
	v_mfma_f32_16x16x32_bf16 v[114:117], v[230:233], v[178:181], v[114:117]
	v_mfma_f32_16x16x32_bf16 v[102:105], v[222:225], v[186:189], v[102:105]
	v_mfma_f32_16x16x32_bf16 v[98:101], v[230:233], v[186:189], v[98:101]
	v_mfma_f32_16x16x32_bf16 v[86:89], v[222:225], v[194:197], v[86:89]
	v_mfma_f32_16x16x32_bf16 v[82:85], v[230:233], v[194:197], v[82:85]
	v_mfma_f32_16x16x32_bf16 v[70:73], v[222:225], v[214:217], v[70:73]
	v_mfma_f32_16x16x32_bf16 v[66:69], v[230:233], v[214:217], v[66:69]
	v_mfma_f32_16x16x32_bf16 v[118:121], v[226:229], v[182:185], v[118:121]
	v_mfma_f32_16x16x32_bf16 v[114:117], v[234:237], v[182:185], v[114:117]
	v_mfma_f32_16x16x32_bf16 v[102:105], v[226:229], v[190:193], v[102:105]
	v_mfma_f32_16x16x32_bf16 v[98:101], v[234:237], v[190:193], v[98:101]
	v_mfma_f32_16x16x32_bf16 v[86:89], v[226:229], v[210:213], v[86:89]
	v_mfma_f32_16x16x32_bf16 v[82:85], v[234:237], v[210:213], v[82:85]
	v_mfma_f32_16x16x32_bf16 v[70:73], v[226:229], v[218:221], v[70:73]
	v_mfma_f32_16x16x32_bf16 v[66:69], v[234:237], v[218:221], v[66:69]
	s_mov_b32 m0, s52
	v_lshl_add_u64 v[240:241], s[48:49], 0, v[136:137]
	s_barrier
	ds_read_b128 v[178:181], v152 offset:16384
	ds_read_b128 v[182:185], v152 offset:17408
	ds_read_b128 v[186:189], v152 offset:18432
	ds_read_b128 v[190:193], v152 offset:19456
	ds_read_b128 v[194:197], v152 offset:20480
	ds_read_b128 v[210:213], v152 offset:21504
	ds_read_b128 v[214:217], v152 offset:22528
	ds_read_b128 v[218:221], v152 offset:23552
	global_load_lds_dwordx4 v[240:241], off
	v_lshl_add_u64 v[242:243], s[48:49], 0, v[132:133]
	s_mov_b32 m0, s53
	s_nop 0
	global_load_lds_dwordx4 v[242:243], off
	s_barrier
	s_waitcnt lgkmcnt(0)
	s_waitcnt lgkmcnt(0)
	v_mfma_f32_16x16x32_bf16 v[62:65], v[142:145], v[178:181], v[62:65]
	v_mfma_f32_16x16x32_bf16 v[58:61], v[170:173], v[178:181], v[58:61]
	v_mfma_f32_16x16x32_bf16 v[46:49], v[142:145], v[186:189], v[46:49]
	v_mfma_f32_16x16x32_bf16 v[42:45], v[170:173], v[186:189], v[42:45]
	v_mfma_f32_16x16x32_bf16 v[30:33], v[142:145], v[194:197], v[30:33]
	v_mfma_f32_16x16x32_bf16 v[26:29], v[170:173], v[194:197], v[26:29]
	v_mfma_f32_16x16x32_bf16 v[14:17], v[142:145], v[214:217], v[14:17]
	v_mfma_f32_16x16x32_bf16 v[10:13], v[170:173], v[214:217], v[10:13]
	v_mfma_f32_16x16x32_bf16 v[62:65], v[146:149], v[182:185], v[62:65]
	v_mfma_f32_16x16x32_bf16 v[58:61], v[174:177], v[182:185], v[58:61]
	v_mfma_f32_16x16x32_bf16 v[46:49], v[146:149], v[190:193], v[46:49]
	v_mfma_f32_16x16x32_bf16 v[42:45], v[174:177], v[190:193], v[42:45]
	v_mfma_f32_16x16x32_bf16 v[30:33], v[146:149], v[210:213], v[30:33]
	v_mfma_f32_16x16x32_bf16 v[26:29], v[174:177], v[210:213], v[26:29]
	v_mfma_f32_16x16x32_bf16 v[14:17], v[146:149], v[218:221], v[14:17]
	v_mfma_f32_16x16x32_bf16 v[10:13], v[174:177], v[218:221], v[10:13]
	s_barrier
; #define PG8_STAGE(bufoff, gbase, voff) do { _Pragma("unroll") for (int _i = 0; _i < 2; ++_i) \
;         __builtin_amdgcn_global_load_lds((const unsigned*)((const char*)(gbase) + (voff)[_i]), (LAS unsigned*)(lds + (bufoff) + ldsw + _i * 8192), 16, 0, 0); } while (0)
; #define PG8_LDA(dst, b, h) do { _Pragma("unroll") for (int m = 0; m < 4; ++m) _Pragma("unroll") for (int k = 0; k < 2; ++k) dst[m][k] = *(const LAS bf16x8*)(lds + PG8_SA(b, h) + aoff + m * 2048 + k * 1024); } while (0)
; #define PG8_LDB(dst, b, h) do { _Pragma("unroll") for (int n = 0; n < 2; ++n) _Pragma("unroll") for (int k = 0; k < 2; ++k) dst[n][k] = *(const LAS bf16x8*)(lds + PG8_SB(b, h) + boff + n * 2048 + k * 1024); } while (0)
; #define PG8_WAIT_V(n) asm volatile("s_waitcnt vmcnt(" #n ")" ::: "memory")
; #define PG8_WAIT_L(n) asm volatile("s_waitcnt lgkmcnt(" #n ")" ::: "memory")
; #define PG8_BAR __builtin_amdgcn_s_barrier()
; #define PG8_SCHED __builtin_amdgcn_sched_barrier(0)
; template <class Epi, class Sched>
; __device__ __forceinline__ void gemm_phase(LAS unsigned char* lds, const Gemm g, const Sched& S, const Epi& E) {
;     ...
;             PG8_LDB(B0, 0, 0); PG8_SCHED; PG8_LDA(At, 0, 0); PG8_STAGE(PG8_SA(1, 1), a1 + hstepA, voffA);
;             PG8_WAIT_L(8); PG8_BAR; PG8_WAIT_L(0); PG8_MMA(0, 0, At, B0); PG8_BAR; PG8_SCHED;
;             PG8_LDB(B1, 0, 1); PG8_STAGE(PG8_SB(0, 0), b2, voffB);
;             PG8_BAR; PG8_WAIT_L(0); PG8_MMA(0, 1, At, B1); PG8_BAR;
;             PG8_LDA(At, 0, 1); PG8_STAGE(PG8_SA(0, 0), a2, voffA);
;             PG8_BAR; PG8_WAIT_L(0); PG8_MMA(1, 0, At, B0); PG8_BAR; PG8_SCHED;
;             PG8_STAGE(PG8_SB(0, 1), b2 + hstepB, voffB);
;             PG8_WAIT_V(6); PG8_BAR; PG8_MMA(1, 1, At, B1); PG8_BAR;
;             PG8_LDB(B0, 1, 0); PG8_SCHED; PG8_LDA(At, 1, 0); PG8_STAGE(PG8_SA(0, 1), a2 + hstepA, voffA);
;             PG8_WAIT_L(8); PG8_BAR; PG8_WAIT_L(0); PG8_MMA(0, 0, At, B0); PG8_BAR; PG8_SCHED;
;             PG8_LDB(B1, 1, 1); PG8_STAGE(PG8_SB(1, 0), b3, voffB);
;             PG8_BAR; PG8_WAIT_L(0); PG8_MMA(0, 1, At, B1); PG8_BAR;
;             PG8_LDA(At, 1, 1); PG8_STAGE(PG8_SA(1, 0), a3, voffA);
;             PG8_BAR; PG8_WAIT_L(0); PG8_MMA(1, 0, At, B0); PG8_BAR; PG8_SCHED;
;             PG8_STAGE(PG8_SB(1, 1), b3 + hstepB, voffB);
;             PG8_WAIT_V(6); PG8_BAR; PG8_MMA(1, 1, At, B1); PG8_BAR;
;         }
	s_add_u32 s66, s36, 0x40000
	s_addc_u32 s67, s37, 0
	s_add_i32 s23, s23, s51
	v_lshl_add_u64 v[142:143], s[66:67], 0, v[134:135]
	s_mov_b32 m0, s23
	s_nop 0
	global_load_lds_dwordx4 v[142:143], off
	v_lshl_add_u64 v[142:143], s[66:67], 0, v[130:131]
	s_add_i32 m0, s23, 0x2000
	s_nop 0
	global_load_lds_dwordx4 v[142:143], off
	s_waitcnt vmcnt(6)
	s_barrier
	v_mfma_f32_16x16x32_bf16 v[54:57], v[222:225], v[178:181], v[54:57]
	v_mfma_f32_16x16x32_bf16 v[50:53], v[230:233], v[178:181], v[50:53]
	v_mfma_f32_16x16x32_bf16 v[38:41], v[222:225], v[186:189], v[38:41]
	v_mfma_f32_16x16x32_bf16 v[34:37], v[230:233], v[186:189], v[34:37]
	v_mfma_f32_16x16x32_bf16 v[22:25], v[222:225], v[194:197], v[22:25]
	v_mfma_f32_16x16x32_bf16 v[18:21], v[230:233], v[194:197], v[18:21]
	v_mfma_f32_16x16x32_bf16 v[6:9], v[222:225], v[214:217], v[6:9]
	v_mfma_f32_16x16x32_bf16 v[2:5], v[230:233], v[214:217], v[2:5]
	v_mfma_f32_16x16x32_bf16 v[54:57], v[226:229], v[182:185], v[54:57]
	v_mfma_f32_16x16x32_bf16 v[50:53], v[234:237], v[182:185], v[50:53]
	v_mfma_f32_16x16x32_bf16 v[38:41], v[226:229], v[190:193], v[38:41]
	v_mfma_f32_16x16x32_bf16 v[34:37], v[234:237], v[190:193], v[34:37]
	v_mfma_f32_16x16x32_bf16 v[22:25], v[226:229], v[210:213], v[22:25]
	v_mfma_f32_16x16x32_bf16 v[18:21], v[234:237], v[210:213], v[18:21]
	v_mfma_f32_16x16x32_bf16 v[6:9], v[226:229], v[218:221], v[6:9]
	v_mfma_f32_16x16x32_bf16 v[2:5], v[234:237], v[218:221], v[2:5]
	s_add_i32 s23, 0, 0x18000
	v_add_u32_e32 v153, s23, v150
	s_barrier
	ds_read_b128 v[142:145], v153
	ds_read_b128 v[146:149], v153 offset:1024
	ds_read_b128 v[170:173], v153 offset:2048
	ds_read_b128 v[174:177], v153 offset:3072
	s_add_u32 s48, s48, 0x40000
	s_addc_u32 s49, s49, 0
	s_mov_b32 m0, s54
	v_lshl_add_u64 v[222:223], s[48:49], 0, v[136:137]
	ds_read_b128 v[178:181], v152 offset:32768
	ds_read_b128 v[182:185], v152 offset:33792
	ds_read_b128 v[186:189], v152 offset:34816
	ds_read_b128 v[190:193], v152 offset:35840
	ds_read_b128 v[194:197], v152 offset:36864
	ds_read_b128 v[210:213], v152 offset:37888
	ds_read_b128 v[214:217], v152 offset:38912
	ds_read_b128 v[218:221], v152 offset:39936
	global_load_lds_dwordx4 v[222:223], off
	v_lshl_add_u64 v[222:223], s[48:49], 0, v[132:133]
	s_mov_b32 m0, s55
	s_nop 0
	global_load_lds_dwordx4 v[222:223], off
	s_waitcnt lgkmcnt(8)
	s_barrier
	s_waitcnt lgkmcnt(0)
	s_waitcnt lgkmcnt(0)
	v_mfma_f32_16x16x32_bf16 v[126:129], v[142:145], v[178:181], v[126:129]
	v_mfma_f32_16x16x32_bf16 v[122:125], v[170:173], v[178:181], v[122:125]
	v_mfma_f32_16x16x32_bf16 v[110:113], v[142:145], v[186:189], v[110:113]
	v_mfma_f32_16x16x32_bf16 v[106:109], v[170:173], v[186:189], v[106:109]
	v_mfma_f32_16x16x32_bf16 v[94:97], v[142:145], v[194:197], v[94:97]
	v_mfma_f32_16x16x32_bf16 v[90:93], v[170:173], v[194:197], v[90:93]
	v_mfma_f32_16x16x32_bf16 v[78:81], v[142:145], v[214:217], v[78:81]
	v_mfma_f32_16x16x32_bf16 v[74:77], v[170:173], v[214:217], v[74:77]
	v_mfma_f32_16x16x32_bf16 v[126:129], v[146:149], v[182:185], v[126:129]
	v_mfma_f32_16x16x32_bf16 v[122:125], v[174:177], v[182:185], v[122:125]
	v_mfma_f32_16x16x32_bf16 v[110:113], v[146:149], v[190:193], v[110:113]
	v_mfma_f32_16x16x32_bf16 v[106:109], v[174:177], v[190:193], v[106:109]
	v_mfma_f32_16x16x32_bf16 v[94:97], v[146:149], v[210:213], v[94:97]
	v_mfma_f32_16x16x32_bf16 v[90:93], v[174:177], v[210:213], v[90:93]
	v_mfma_f32_16x16x32_bf16 v[78:81], v[146:149], v[218:221], v[78:81]
	v_mfma_f32_16x16x32_bf16 v[74:77], v[174:177], v[218:221], v[74:77]
	s_barrier
	s_add_i32 s34, 0, 0x1c000
	s_add_i32 s23, s23, s51
	v_add_u32_e32 v153, s34, v150
	v_lshl_add_u64 v[198:199], v[198:199], 0, s[10:11]
	s_mov_b32 m0, s23
	ds_read_b128 v[222:225], v153
	ds_read_b128 v[226:229], v153 offset:1024
	ds_read_b128 v[230:233], v153 offset:2048
	ds_read_b128 v[234:237], v153 offset:3072
	global_load_lds_dwordx4 v[198:199], off
	v_lshl_add_u64 v[198:199], v[238:239], 0, s[10:11]
	s_add_i32 m0, s23, 0x2000
	s_nop 0
	global_load_lds_dwordx4 v[198:199], off
	s_barrier
	s_waitcnt lgkmcnt(0)
	s_waitcnt lgkmcnt(0)
	v_mfma_f32_16x16x32_bf16 v[118:121], v[222:225], v[178:181], v[118:121]
	v_mfma_f32_16x16x32_bf16 v[114:117], v[230:233], v[178:181], v[114:117]
	v_mfma_f32_16x16x32_bf16 v[102:105], v[222:225], v[186:189], v[102:105]
	v_mfma_f32_16x16x32_bf16 v[98:101], v[230:233], v[186:189], v[98:101]
	v_mfma_f32_16x16x32_bf16 v[86:89], v[222:225], v[194:197], v[86:89]
	v_mfma_f32_16x16x32_bf16 v[82:85], v[230:233], v[194:197], v[82:85]
	v_mfma_f32_16x16x32_bf16 v[70:73], v[222:225], v[214:217], v[70:73]
	v_mfma_f32_16x16x32_bf16 v[66:69], v[230:233], v[214:217], v[66:69]
	v_mfma_f32_16x16x32_bf16 v[118:121], v[226:229], v[182:185], v[118:121]
	v_mfma_f32_16x16x32_bf16 v[114:117], v[234:237], v[182:185], v[114:117]
	v_mfma_f32_16x16x32_bf16 v[102:105], v[226:229], v[190:193], v[102:105]
	v_mfma_f32_16x16x32_bf16 v[98:101], v[234:237], v[190:193], v[98:101]
	v_mfma_f32_16x16x32_bf16 v[86:89], v[226:229], v[210:213], v[86:89]
	v_mfma_f32_16x16x32_bf16 v[82:85], v[234:237], v[210:213], v[82:85]
	v_mfma_f32_16x16x32_bf16 v[70:73], v[226:229], v[218:221], v[70:73]
	v_mfma_f32_16x16x32_bf16 v[66:69], v[234:237], v[218:221], v[66:69]
	s_mov_b32 m0, s56
	v_lshl_add_u64 v[198:199], v[240:241], 0, s[10:11]
	s_barrier
	ds_read_b128 v[178:181], v152 offset:49152
	ds_read_b128 v[182:185], v152 offset:50176
	ds_read_b128 v[186:189], v152 offset:51200
	ds_read_b128 v[190:193], v152 offset:52224
	ds_read_b128 v[194:197], v152 offset:53248
	ds_read_b128 v[210:213], v152 offset:54272
	ds_read_b128 v[214:217], v152 offset:55296
	ds_read_b128 v[218:221], v152 offset:56320
	global_load_lds_dwordx4 v[198:199], off
	v_lshl_add_u64 v[198:199], v[242:243], 0, s[10:11]
	s_mov_b32 m0, s57
	s_nop 0
	global_load_lds_dwordx4 v[198:199], off
	s_barrier
; __device__ __forceinline__ float bf_lo(unsigned w) { return __uint_as_float(w << 16); }
; __device__ __forceinline__ float bf_hi(unsigned w) { return __uint_as_float(w & 0xffff0000u); }
; #define PG8_WAIT_V(n) asm volatile("s_waitcnt vmcnt(" #n ")" ::: "memory")
;     __device__ __forceinline__ void operator()(const f32x4 (&acc)[2][2][4][2], const Unit& u, int ui, const LAS float* rtab, int wr, int wc, int fr, int fq) const {
;     ...
;                     const int col = col0 + bj * HALF; const u32x4 yv = *(const u32x4*)(Y + (size_t)row * 1024 + col);
;                     const f32x4 a0 = acc[ai][bj][m][0], a1 = acc[ai][bj][m][1]; float o[8];
;                     const float yy[8] = {bf_lo(yv.x), bf_hi(yv.x), bf_lo(yv.y), bf_hi(yv.y), bf_lo(yv.z), bf_hi(yv.z), bf_lo(yv.w), bf_hi(yv.w)};
; #pragma unroll
;                     for (int e = 0; e < 4; ++e) { o[e] = yy[e] / (1.0f + __expf(-a0[e])); o[4 + e] = yy[4 + e] / (1.0f + __expf(-a1[e])); }
; template <class Epi, class Sched>
; __device__ __forceinline__ void gemm_phase(LAS unsigned char* lds, const Gemm g, const Sched& S, const Epi& E) {
;     ...
;             PG8_LDB(B0, 0, 0); PG8_SCHED; PG8_LDA(At, 0, 0); PG8_STAGE(PG8_SA(1, 1), a1 + hstepA, voffA);
;             PG8_WAIT_L(8); PG8_BAR; PG8_WAIT_L(0); PG8_MMA(0, 0, At, B0); PG8_BAR; PG8_SCHED;
;             PG8_LDB(B1, 0, 1); PG8_STAGE(PG8_SB(0, 0), b2, voffB);
;             PG8_BAR; PG8_WAIT_L(0); PG8_MMA(0, 1, At, B1); PG8_BAR;
;             PG8_LDA(At, 0, 1); PG8_STAGE(PG8_SA(0, 0), a2, voffA);
;             PG8_BAR; PG8_WAIT_L(0); PG8_MMA(1, 0, At, B0); PG8_BAR; PG8_SCHED;
;             PG8_STAGE(PG8_SB(0, 1), b2 + hstepB, voffB);
;             PG8_WAIT_V(6); PG8_BAR; PG8_MMA(1, 1, At, B1); PG8_BAR;
;             PG8_LDB(B0, 1, 0); PG8_SCHED; PG8_LDA(At, 1, 0); PG8_STAGE(PG8_SA(0, 1), a2 + hstepA, voffA);
;             PG8_WAIT_L(8); PG8_BAR; PG8_WAIT_L(0); PG8_MMA(0, 0, At, B0); PG8_BAR; PG8_SCHED;
;             PG8_LDB(B1, 1, 1); PG8_STAGE(PG8_SB(1, 0), b3, voffB);
;             PG8_BAR; PG8_WAIT_L(0); PG8_MMA(0, 1, At, B1); PG8_BAR;
;             PG8_LDA(At, 1, 1); PG8_STAGE(PG8_SA(1, 0), a3, voffA);
;             PG8_BAR; PG8_WAIT_L(0); PG8_MMA(1, 0, At, B0); PG8_BAR; PG8_SCHED;
;             PG8_STAGE(PG8_SB(1, 1), b3 + hstepB, voffB);
;             PG8_WAIT_V(6); PG8_BAR; PG8_MMA(1, 1, At, B1); PG8_BAR;
;         }
	s_waitcnt lgkmcnt(0)
	s_waitcnt lgkmcnt(0)
	v_mfma_f32_16x16x32_bf16 v[62:65], v[142:145], v[178:181], v[62:65]
	v_mfma_f32_16x16x32_bf16 v[58:61], v[170:173], v[178:181], v[58:61]
	v_mfma_f32_16x16x32_bf16 v[46:49], v[142:145], v[186:189], v[46:49]
	v_mfma_f32_16x16x32_bf16 v[42:45], v[170:173], v[186:189], v[42:45]
	v_mfma_f32_16x16x32_bf16 v[30:33], v[142:145], v[194:197], v[30:33]
	v_mfma_f32_16x16x32_bf16 v[26:29], v[170:173], v[194:197], v[26:29]
	v_mfma_f32_16x16x32_bf16 v[14:17], v[142:145], v[214:217], v[14:17]
	v_mfma_f32_16x16x32_bf16 v[10:13], v[170:173], v[214:217], v[10:13]
	v_mfma_f32_16x16x32_bf16 v[62:65], v[146:149], v[182:185], v[62:65]
	v_mfma_f32_16x16x32_bf16 v[58:61], v[174:177], v[182:185], v[58:61]
	v_mfma_f32_16x16x32_bf16 v[46:49], v[146:149], v[190:193], v[46:49]
	v_mfma_f32_16x16x32_bf16 v[42:45], v[174:177], v[190:193], v[42:45]
	v_mfma_f32_16x16x32_bf16 v[30:33], v[146:149], v[210:213], v[30:33]
	v_mfma_f32_16x16x32_bf16 v[26:29], v[174:177], v[210:213], v[26:29]
	v_mfma_f32_16x16x32_bf16 v[14:17], v[146:149], v[218:221], v[14:17]
	v_mfma_f32_16x16x32_bf16 v[10:13], v[174:177], v[218:221], v[10:13]
	s_barrier
	s_add_u32 s36, s36, 0x40080
	s_addc_u32 s37, s37, 0
	s_add_i32 s23, s34, s51
	v_lshl_add_u64 v[142:143], s[36:37], 0, v[134:135]
	s_mov_b32 m0, s23
	s_nop 0
	global_load_lds_dwordx4 v[142:143], off
	v_lshl_add_u64 v[142:143], s[36:37], 0, v[130:131]
	s_add_i32 m0, s23, 0x2000
	s_nop 0
	global_load_lds_dwordx4 v[142:143], off
	s_waitcnt vmcnt(6)
	s_barrier
	v_mfma_f32_16x16x32_bf16 v[54:57], v[222:225], v[178:181], v[54:57]
	v_mfma_f32_16x16x32_bf16 v[50:53], v[230:233], v[178:181], v[50:53]
	v_mfma_f32_16x16x32_bf16 v[38:41], v[222:225], v[186:189], v[38:41]
	v_mfma_f32_16x16x32_bf16 v[34:37], v[230:233], v[186:189], v[34:37]
	v_mfma_f32_16x16x32_bf16 v[22:25], v[222:225], v[194:197], v[22:25]
	v_mfma_f32_16x16x32_bf16 v[18:21], v[230:233], v[194:197], v[18:21]
	v_mfma_f32_16x16x32_bf16 v[6:9], v[222:225], v[214:217], v[6:9]
	v_mfma_f32_16x16x32_bf16 v[2:5], v[230:233], v[214:217], v[2:5]
	v_mfma_f32_16x16x32_bf16 v[54:57], v[226:229], v[182:185], v[54:57]
	v_mfma_f32_16x16x32_bf16 v[50:53], v[234:237], v[182:185], v[50:53]
	v_mfma_f32_16x16x32_bf16 v[38:41], v[226:229], v[190:193], v[38:41]
	v_mfma_f32_16x16x32_bf16 v[34:37], v[234:237], v[190:193], v[34:37]
	v_mfma_f32_16x16x32_bf16 v[22:25], v[226:229], v[210:213], v[22:25]
	v_mfma_f32_16x16x32_bf16 v[18:21], v[234:237], v[210:213], v[18:21]
	v_mfma_f32_16x16x32_bf16 v[6:9], v[226:229], v[218:221], v[6:9]
	v_mfma_f32_16x16x32_bf16 v[2:5], v[234:237], v[218:221], v[2:5]
	s_add_i32 s31, s31, 2
	s_add_u32 s20, s20, 0x100
	s_addc_u32 s21, s21, 0
	s_add_u32 s28, s28, 0x100
	s_addc_u32 s29, s29, 0
	s_cmp_gt_u32 s31, 13
	s_barrier
	s_cbranch_scc0 .LBB0_668
	v_lshl_add_u32 v144, s13, 8, v1
	v_lshl_or_b32 v142, s12, 8, v151
	v_ashrrev_i32_e32 v145, 31, v144
	v_lshlrev_b64 v[146:147], 11, v[144:145]
	v_ashrrev_i32_e32 v143, 31, v142
	v_lshl_add_u64 v[146:147], s[86:87], 0, v[146:147]
	v_lshlrev_b64 v[142:143], 1, v[142:143]
	v_lshl_add_u64 v[146:147], v[146:147], 0, v[142:143]
	global_load_dwordx4 v[170:173], v[146:147], off
	v_mul_f32_e32 v126, 0xbfb8aa3b, v126
	v_exp_f32_e32 v126, v126
	v_lshlrev_b64 v[148:149], 12, v[144:145]
	v_mul_f32_e32 v122, 0xbfb8aa3b, v122
	v_exp_f32_e32 v122, v122
	v_add_f32_e32 v126, 1.0, v126
	v_mul_f32_e32 v127, 0xbfb8aa3b, v127
	v_exp_f32_e32 v127, v127
	v_add_f32_e32 v122, 1.0, v122
	v_mul_f32_e32 v123, 0xbfb8aa3b, v123
	v_exp_f32_e32 v123, v123
	v_add_f32_e32 v127, 1.0, v127
	v_mul_f32_e32 v128, 0xbfb8aa3b, v128
	v_exp_f32_e32 v128, v128
	v_add_f32_e32 v123, 1.0, v123
	v_mul_f32_e32 v124, 0xbfb8aa3b, v124
	v_exp_f32_e32 v124, v124
	v_add_f32_e32 v128, 1.0, v128
	v_mul_f32_e32 v118, 0xbfb8aa3b, v118
	v_exp_f32_e32 v118, v118
	v_add_f32_e32 v124, 1.0, v124
	v_mul_f32_e32 v114, 0xbfb8aa3b, v114
	v_exp_f32_e32 v114, v114
	v_add_f32_e32 v118, 1.0, v118
	v_mul_f32_e32 v119, 0xbfb8aa3b, v119
	v_exp_f32_e32 v119, v119
	v_add_f32_e32 v114, 1.0, v114
	v_mul_f32_e32 v115, 0xbfb8aa3b, v115
	v_exp_f32_e32 v115, v115
	v_add_f32_e32 v119, 1.0, v119
	v_mul_f32_e32 v120, 0xbfb8aa3b, v120
	v_exp_f32_e32 v120, v120
	v_add_f32_e32 v115, 1.0, v115
	v_mul_f32_e32 v116, 0xbfb8aa3b, v116
	v_exp_f32_e32 v116, v116
	v_add_f32_e32 v120, 1.0, v120
	v_mul_f32_e32 v110, 0xbfb8aa3b, v110
	v_exp_f32_e32 v110, v110
	v_add_f32_e32 v116, 1.0, v116
	v_mul_f32_e32 v106, 0xbfb8aa3b, v106
	v_exp_f32_e32 v106, v106
	v_add_f32_e32 v110, 1.0, v110
	v_mul_f32_e32 v111, 0xbfb8aa3b, v111
	v_exp_f32_e32 v111, v111
	v_add_f32_e32 v106, 1.0, v106
	v_mul_f32_e32 v107, 0xbfb8aa3b, v107
	v_exp_f32_e32 v107, v107
	v_add_f32_e32 v111, 1.0, v111
	v_mul_f32_e32 v112, 0xbfb8aa3b, v112
	v_exp_f32_e32 v112, v112
	v_add_f32_e32 v107, 1.0, v107
	v_mul_f32_e32 v108, 0xbfb8aa3b, v108
	v_exp_f32_e32 v108, v108
	v_add_f32_e32 v112, 1.0, v112
	v_mul_f32_e32 v102, 0xbfb8aa3b, v102
	v_exp_f32_e32 v102, v102
	v_add_f32_e32 v108, 1.0, v108
	v_mul_f32_e32 v98, 0xbfb8aa3b, v98
	v_exp_f32_e32 v98, v98
	v_add_f32_e32 v102, 1.0, v102
	v_mul_f32_e32 v99, 0xbfb8aa3b, v99
	v_exp_f32_e32 v99, v99
	v_add_f32_e32 v98, 1.0, v98
	v_mul_f32_e32 v100, 0xbfb8aa3b, v100
	v_exp_f32_e32 v100, v100
	v_add_f32_e32 v99, 1.0, v99
	v_mul_f32_e32 v101, 0xbfb8aa3b, v101
	v_exp_f32_e32 v101, v101
	v_add_f32_e32 v100, 1.0, v100
	v_mul_f32_e32 v94, 0xbfb8aa3b, v94
	v_exp_f32_e32 v94, v94
	v_add_f32_e32 v101, 1.0, v101
	v_mul_f32_e32 v90, 0xbfb8aa3b, v90
	v_exp_f32_e32 v90, v90
	v_add_f32_e32 v94, 1.0, v94
	v_mul_f32_e32 v95, 0xbfb8aa3b, v95
	v_exp_f32_e32 v95, v95
	v_add_f32_e32 v90, 1.0, v90
	v_mul_f32_e32 v91, 0xbfb8aa3b, v91
	s_waitcnt vmcnt(0)
; __device__ __forceinline__ unsigned cvt_pk_bf16(float lo, float hi) { unsigned r; asm volatile("v_cvt_pk_bf16_f32 %0, %1, %2" : "=v"(r) : "v"(lo), "v"(hi)); return r; }
; __device__ __forceinline__ float bf_lo(unsigned w) { return __uint_as_float(w << 16); }
; __device__ __forceinline__ float bf_hi(unsigned w) { return __uint_as_float(w & 0xffff0000u); }
;     __device__ __forceinline__ void operator()(const f32x4 (&acc)[2][2][4][2], const Unit& u, int ui, const LAS float* rtab, int wr, int wc, int fr, int fq) const {
;     ...
;                     const int col = col0 + bj * HALF; const u32x4 yv = *(const u32x4*)(Y + (size_t)row * 1024 + col);
;                     const f32x4 a0 = acc[ai][bj][m][0], a1 = acc[ai][bj][m][1]; float o[8];
;                     const float yy[8] = {bf_lo(yv.x), bf_hi(yv.x), bf_lo(yv.y), bf_hi(yv.y), bf_lo(yv.z), bf_hi(yv.z), bf_lo(yv.w), bf_hi(yv.w)};
; #pragma unroll
;                     for (int e = 0; e < 4; ++e) { o[e] = yy[e] / (1.0f + __expf(-a0[e])); o[4 + e] = yy[4 + e] / (1.0f + __expf(-a1[e])); }
;                     u32x4 w; w.x = cvt_pk_bf16(o[0], o[1]); w.y = cvt_pk_bf16(o[2], o[3]); w.z = cvt_pk_bf16(o[4], o[5]); w.w = cvt_pk_bf16(o[6], o[7]);
;                     *(u32x4*)(MG + (size_t)row * DM + 1024 + col) = w;
	v_lshlrev_b32_e32 v174, 16, v170
	v_lshlrev_b32_e32 v162, 16, v173
	v_and_b32_e32 v145, 0xffff0000, v173
	v_div_scale_f32 v173, s[12:13], v126, v126, v174
	v_rcp_f32_e32 v176, v173
	v_lshlrev_b32_e32 v175, 16, v171
	v_and_b32_e32 v153, 0xffff0000, v171
	v_lshlrev_b32_e32 v171, 16, v172
	v_fma_f32 v177, -v173, v176, 1.0
	v_fmac_f32_e32 v176, v177, v176
	v_div_scale_f32 v177, vcc, v174, v126, v174
	v_mul_f32_e32 v178, v177, v176
	v_fma_f32 v179, -v173, v178, v177
	v_fmac_f32_e32 v178, v179, v176
	v_fma_f32 v173, -v173, v178, v177
	v_div_fmas_f32 v173, v173, v176, v178
	v_div_fixup_f32 v126, v173, v126, v174
	v_div_scale_f32 v173, s[12:13], v122, v122, v171
	v_rcp_f32_e32 v174, v173
	v_and_b32_e32 v170, 0xffff0000, v170
	v_and_b32_e32 v172, 0xffff0000, v172
	v_add_f32_e32 v95, 1.0, v95
	v_fma_f32 v176, -v173, v174, 1.0
	v_fmac_f32_e32 v174, v176, v174
	v_div_scale_f32 v176, vcc, v171, v122, v171
	v_mul_f32_e32 v177, v176, v174
	v_fma_f32 v178, -v173, v177, v176
	v_fmac_f32_e32 v177, v178, v174
	v_fma_f32 v173, -v173, v177, v176
	v_div_fmas_f32 v173, v173, v174, v177
	v_div_fixup_f32 v122, v173, v122, v171
	v_div_scale_f32 v171, s[12:13], v127, v127, v170
	v_rcp_f32_e32 v173, v171
	v_exp_f32_e32 v91, v91
	v_mul_f32_e32 v96, 0xbfb8aa3b, v96
	v_exp_f32_e32 v96, v96
	v_fma_f32 v174, -v171, v173, 1.0
	v_fmac_f32_e32 v173, v174, v173
	v_div_scale_f32 v174, vcc, v170, v127, v170
	v_mul_f32_e32 v176, v174, v173
	v_fma_f32 v177, -v171, v176, v174
	v_fmac_f32_e32 v176, v177, v173
	v_fma_f32 v171, -v171, v176, v174
	v_div_fmas_f32 v171, v171, v173, v176
	v_div_fixup_f32 v127, v171, v127, v170
	v_div_scale_f32 v170, s[12:13], v123, v123, v172
	v_rcp_f32_e32 v171, v170
	v_add_f32_e32 v91, 1.0, v91
	v_add_f32_e32 v96, 1.0, v96
	v_mul_f32_e32 v92, 0xbfb8aa3b, v92
	v_fma_f32 v173, -v170, v171, 1.0
	v_fmac_f32_e32 v171, v173, v171
	v_div_scale_f32 v173, vcc, v172, v123, v172
	v_mul_f32_e32 v174, v173, v171
	v_fma_f32 v176, -v170, v174, v173
	v_fmac_f32_e32 v174, v176, v171
	v_fma_f32 v170, -v170, v174, v173
	v_div_fmas_f32 v170, v170, v171, v174
	v_div_fixup_f32 v123, v170, v123, v172
	v_div_scale_f32 v170, s[12:13], v128, v128, v175
	v_rcp_f32_e32 v171, v170
	v_exp_f32_e32 v92, v92
	v_mul_f32_e32 v86, 0xbfb8aa3b, v86
	v_exp_f32_e32 v86, v86
	v_fma_f32 v172, -v170, v171, 1.0
	v_fmac_f32_e32 v171, v172, v171
	v_div_scale_f32 v172, vcc, v175, v128, v175
	v_mul_f32_e32 v173, v172, v171
	v_fma_f32 v174, -v170, v173, v172
	v_fmac_f32_e32 v173, v174, v171
	v_fma_f32 v170, -v170, v173, v172
	v_div_fmas_f32 v170, v170, v171, v173
	v_div_fixup_f32 v128, v170, v128, v175
	v_div_scale_f32 v170, s[12:13], v124, v124, v162
	v_rcp_f32_e32 v171, v170
	v_add_f32_e32 v92, 1.0, v92
	v_add_f32_e32 v86, 1.0, v86
	v_mul_f32_e32 v82, 0xbfb8aa3b, v82
	v_fma_f32 v172, -v170, v171, 1.0
	v_fmac_f32_e32 v171, v172, v171
	v_div_scale_f32 v172, vcc, v162, v124, v162
	v_mul_f32_e32 v173, v172, v171
	v_fma_f32 v174, -v170, v173, v172
	v_fmac_f32_e32 v173, v174, v171
	v_fma_f32 v170, -v170, v173, v172
	v_div_fmas_f32 v170, v170, v171, v173
	v_div_fixup_f32 v162, v170, v124, v162
	v_mul_f32_e32 v124, 0xbfb8aa3b, v129
	v_exp_f32_e32 v124, v124
	v_exp_f32_e32 v82, v82
	v_mul_f32_e32 v83, 0xbfb8aa3b, v83
	v_exp_f32_e32 v83, v83
	v_add_f32_e32 v124, 1.0, v124
	v_div_scale_f32 v129, s[12:13], v124, v124, v153
	v_rcp_f32_e32 v170, v129
	v_add_f32_e32 v82, 1.0, v82
	v_add_f32_e32 v83, 1.0, v83
	v_mul_f32_e32 v84, 0xbfb8aa3b, v84
	v_fma_f32 v171, -v129, v170, 1.0
	v_fmac_f32_e32 v170, v171, v170
	v_div_scale_f32 v171, vcc, v153, v124, v153
	v_mul_f32_e32 v172, v171, v170
	v_fma_f32 v173, -v129, v172, v171
	v_fmac_f32_e32 v172, v173, v170
	v_fma_f32 v129, -v129, v172, v171
	v_div_fmas_f32 v129, v129, v170, v172
	v_div_fixup_f32 v129, v129, v124, v153
	v_mul_f32_e32 v124, 0xbfb8aa3b, v125
	v_exp_f32_e32 v124, v124
	v_exp_f32_e32 v84, v84
	v_mul_f32_e32 v85, 0xbfb8aa3b, v85
	v_exp_f32_e32 v85, v85
	v_add_f32_e32 v124, 1.0, v124
	v_div_scale_f32 v125, s[12:13], v124, v124, v145
	v_rcp_f32_e32 v153, v125
	v_add_f32_e32 v84, 1.0, v84
	v_add_f32_e32 v85, 1.0, v85
	v_mul_f32_e32 v78, 0xbfb8aa3b, v78
	v_fma_f32 v170, -v125, v153, 1.0
	v_fmac_f32_e32 v153, v170, v153
	v_div_scale_f32 v170, vcc, v145, v124, v145
	v_mul_f32_e32 v171, v170, v153
	v_fma_f32 v172, -v125, v171, v170
	v_fmac_f32_e32 v171, v172, v153
	v_fma_f32 v125, -v125, v171, v170
	v_div_fmas_f32 v125, v125, v153, v171
	v_div_fixup_f32 v145, v125, v124, v145
	v_cvt_pk_bf16_f32 v124, v126, v127
	v_cvt_pk_bf16_f32 v125, v128, v129
	v_cvt_pk_bf16_f32 v126, v122, v123
	v_lshl_add_u64 v[122:123], s[88:89], 0, v[148:149]
	v_cvt_pk_bf16_f32 v127, v162, v145
	v_lshl_add_u64 v[122:123], v[122:123], 0, v[142:143]
	global_store_dwordx4 v[122:123], v[124:127], off offset:2048
	global_load_dwordx4 v[124:127], v[146:147], off offset:256
	v_exp_f32_e32 v78, v78
	v_mul_f32_e32 v74, 0xbfb8aa3b, v74
	v_exp_f32_e32 v74, v74
	v_mul_f32_e32 v79, 0xbfb8aa3b, v79
	v_add_f32_e32 v78, 1.0, v78
	v_exp_f32_e32 v79, v79
	v_add_f32_e32 v74, 1.0, v74
	v_mul_f32_e32 v75, 0xbfb8aa3b, v75
	v_exp_f32_e32 v75, v75
	v_add_f32_e32 v79, 1.0, v79
	v_mul_f32_e32 v80, 0xbfb8aa3b, v80
	v_exp_f32_e32 v80, v80
	v_add_f32_e32 v75, 1.0, v75
	v_mul_f32_e32 v76, 0xbfb8aa3b, v76
	v_exp_f32_e32 v76, v76
	v_add_f32_e32 v80, 1.0, v80
	v_mul_f32_e32 v70, 0xbfb8aa3b, v70
	v_exp_f32_e32 v70, v70
	v_add_f32_e32 v76, 1.0, v76
	v_mul_f32_e32 v66, 0xbfb8aa3b, v66
	v_exp_f32_e32 v66, v66
	v_add_f32_e32 v70, 1.0, v70
	v_mul_f32_e32 v67, 0xbfb8aa3b, v67
	v_exp_f32_e32 v67, v67
	v_add_f32_e32 v66, 1.0, v66
	v_mul_f32_e32 v68, 0xbfb8aa3b, v68
	v_exp_f32_e32 v68, v68
	v_add_f32_e32 v67, 1.0, v67
; #define LAS __attribute__((address_space(3)))
; __device__ __forceinline__ unsigned cvt_pk_bf16(float lo, float hi) { unsigned r; asm volatile("v_cvt_pk_bf16_f32 %0, %1, %2" : "=v"(r) : "v"(lo), "v"(hi)); return r; }
; __device__ __forceinline__ float bf_lo(unsigned w) { return __uint_as_float(w << 16); }
; __device__ __forceinline__ float bf_hi(unsigned w) { return __uint_as_float(w & 0xffff0000u); }
;     __device__ __forceinline__ void operator()(const f32x4 (&acc)[2][2][4][2], const Unit& u, int ui, const LAS float* rtab, int wr, int wc, int fr, int fq) const {
;         const int row0 = u.pm * BM + wr * 64 + fr, col0 = u.pn * BM + wc * 32 + 8 * fq;
; #pragma unroll
;         for (int ai = 0; ai < 2; ++ai)
; #pragma unroll
;             for (int m = 0; m < 4; ++m) {
;                 const int row = row0 + ai * HALF + m * 16;
; #pragma unroll
;                 for (int bj = 0; bj < 2; ++bj) {
;                     const int col = col0 + bj * HALF; const u32x4 yv = *(const u32x4*)(Y + (size_t)row * 1024 + col);
;                     const f32x4 a0 = acc[ai][bj][m][0], a1 = acc[ai][bj][m][1]; float o[8];
;                     const float yy[8] = {bf_lo(yv.x), bf_hi(yv.x), bf_lo(yv.y), bf_hi(yv.y), bf_lo(yv.z), bf_hi(yv.z), bf_lo(yv.w), bf_hi(yv.w)};
; #pragma unroll
;                     for (int e = 0; e < 4; ++e) { o[e] = yy[e] / (1.0f + __expf(-a0[e])); o[4 + e] = yy[4 + e] / (1.0f + __expf(-a1[e])); }
;                     u32x4 w; w.x = cvt_pk_bf16(o[0], o[1]); w.y = cvt_pk_bf16(o[2], o[3]); w.z = cvt_pk_bf16(o[4], o[5]); w.w = cvt_pk_bf16(o[6], o[7]);
;                     *(u32x4*)(MG + (size_t)row * DM + 1024 + col) = w;
	v_mul_f32_e32 v69, 0xbfb8aa3b, v69
	v_exp_f32_e32 v69, v69
	v_add_f32_e32 v68, 1.0, v68
	v_mul_f32_e32 v62, 0xbfb8aa3b, v62
	v_exp_f32_e32 v62, v62
	v_add_f32_e32 v69, 1.0, v69
	v_mul_f32_e32 v58, 0xbfb8aa3b, v58
	v_exp_f32_e32 v58, v58
	v_add_f32_e32 v62, 1.0, v62
	v_mul_f32_e32 v63, 0xbfb8aa3b, v63
	v_exp_f32_e32 v63, v63
	v_add_f32_e32 v58, 1.0, v58
	v_mul_f32_e32 v59, 0xbfb8aa3b, v59
	v_exp_f32_e32 v59, v59
	v_add_f32_e32 v63, 1.0, v63
	v_mul_f32_e32 v64, 0xbfb8aa3b, v64
	v_exp_f32_e32 v64, v64
	v_add_f32_e32 v59, 1.0, v59
	v_mul_f32_e32 v60, 0xbfb8aa3b, v60
	v_exp_f32_e32 v60, v60
	v_add_f32_e32 v64, 1.0, v64
	v_mul_f32_e32 v54, 0xbfb8aa3b, v54
	v_exp_f32_e32 v54, v54
	v_add_f32_e32 v60, 1.0, v60
	v_mul_f32_e32 v50, 0xbfb8aa3b, v50
	v_exp_f32_e32 v50, v50
	v_add_f32_e32 v54, 1.0, v54
	v_mul_f32_e32 v51, 0xbfb8aa3b, v51
	v_exp_f32_e32 v51, v51
	v_add_f32_e32 v50, 1.0, v50
	v_mul_f32_e32 v52, 0xbfb8aa3b, v52
	v_exp_f32_e32 v52, v52
	v_add_f32_e32 v51, 1.0, v51
	v_mul_f32_e32 v53, 0xbfb8aa3b, v53
	v_exp_f32_e32 v53, v53
	v_add_f32_e32 v52, 1.0, v52
	v_mul_f32_e32 v46, 0xbfb8aa3b, v46
	v_exp_f32_e32 v46, v46
	v_add_f32_e32 v53, 1.0, v53
	v_mul_f32_e32 v42, 0xbfb8aa3b, v42
	v_exp_f32_e32 v42, v42
	v_add_f32_e32 v46, 1.0, v46
	v_mul_f32_e32 v47, 0xbfb8aa3b, v47
	v_exp_f32_e32 v47, v47
	v_add_f32_e32 v42, 1.0, v42
	v_mul_f32_e32 v43, 0xbfb8aa3b, v43
	v_exp_f32_e32 v43, v43
	v_add_f32_e32 v47, 1.0, v47
	v_mul_f32_e32 v48, 0xbfb8aa3b, v48
	v_exp_f32_e32 v48, v48
	v_add_f32_e32 v43, 1.0, v43
	s_waitcnt vmcnt(0)
	v_lshlrev_b32_e32 v128, 16, v124
	v_and_b32_e32 v129, 0xffff0000, v124
	v_lshlrev_b32_e32 v146, 16, v126
	v_and_b32_e32 v147, 0xffff0000, v126
	v_lshlrev_b32_e32 v126, 16, v127
	v_and_b32_e32 v124, 0xffff0000, v127
	v_div_scale_f32 v127, s[12:13], v118, v118, v128
	v_rcp_f32_e32 v148, v127
	v_lshlrev_b32_e32 v145, 16, v125
	v_and_b32_e32 v125, 0xffff0000, v125
	v_add_f32_e32 v48, 1.0, v48
	v_fma_f32 v149, -v127, v148, 1.0
	v_fmac_f32_e32 v148, v149, v148
	v_div_scale_f32 v149, vcc, v128, v118, v128
	v_mul_f32_e32 v153, v149, v148
	v_fma_f32 v162, -v127, v153, v149
	v_fmac_f32_e32 v153, v162, v148
	v_fma_f32 v127, -v127, v153, v149
	v_div_fmas_f32 v127, v127, v148, v153
	v_div_fixup_f32 v118, v127, v118, v128
	v_div_scale_f32 v127, s[12:13], v114, v114, v146
	v_rcp_f32_e32 v128, v127
	v_mul_f32_e32 v44, 0xbfb8aa3b, v44
	v_exp_f32_e32 v44, v44
	v_mul_f32_e32 v38, 0xbfb8aa3b, v38
	v_fma_f32 v148, -v127, v128, 1.0
	v_fmac_f32_e32 v128, v148, v128
	v_div_scale_f32 v148, vcc, v146, v114, v146
	v_mul_f32_e32 v149, v148, v128
	v_fma_f32 v153, -v127, v149, v148
	v_fmac_f32_e32 v149, v153, v128
	v_fma_f32 v127, -v127, v149, v148
	v_div_fmas_f32 v127, v127, v128, v149
	v_div_fixup_f32 v114, v127, v114, v146
	v_div_scale_f32 v127, s[12:13], v119, v119, v129
	v_rcp_f32_e32 v128, v127
	v_add_f32_e32 v44, 1.0, v44
	v_exp_f32_e32 v38, v38
	v_mul_f32_e32 v34, 0xbfb8aa3b, v34
	v_fma_f32 v146, -v127, v128, 1.0
	v_fmac_f32_e32 v128, v146, v128
	v_div_scale_f32 v146, vcc, v129, v119, v129
	v_mul_f32_e32 v148, v146, v128
	v_fma_f32 v149, -v127, v148, v146
	v_fmac_f32_e32 v148, v149, v128
	v_fma_f32 v127, -v127, v148, v146
	v_div_fmas_f32 v127, v127, v128, v148
	v_div_fixup_f32 v119, v127, v119, v129
	v_div_scale_f32 v127, s[12:13], v115, v115, v147
	v_rcp_f32_e32 v128, v127
	v_add_f32_e32 v38, 1.0, v38
	v_exp_f32_e32 v34, v34
	v_mul_f32_e32 v35, 0xbfb8aa3b, v35
	v_fma_f32 v129, -v127, v128, 1.0
	v_fmac_f32_e32 v128, v129, v128
	v_div_scale_f32 v129, vcc, v147, v115, v147
	v_mul_f32_e32 v146, v129, v128
	v_fma_f32 v148, -v127, v146, v129
	v_fmac_f32_e32 v146, v148, v128
	v_fma_f32 v127, -v127, v146, v129
	v_div_fmas_f32 v127, v127, v128, v146
	v_div_fixup_f32 v115, v127, v115, v147
	v_div_scale_f32 v127, s[12:13], v120, v120, v145
	v_rcp_f32_e32 v128, v127
	v_add_f32_e32 v34, 1.0, v34
	v_exp_f32_e32 v35, v35
	v_mul_f32_e32 v36, 0xbfb8aa3b, v36
	v_fma_f32 v129, -v127, v128, 1.0
	v_fmac_f32_e32 v128, v129, v128
	v_div_scale_f32 v129, vcc, v145, v120, v145
	v_mul_f32_e32 v146, v129, v128
	v_fma_f32 v147, -v127, v146, v129
	v_fmac_f32_e32 v146, v147, v128
	v_fma_f32 v127, -v127, v146, v129
	v_div_fmas_f32 v127, v127, v128, v146
	v_div_fixup_f32 v120, v127, v120, v145
	v_div_scale_f32 v127, s[12:13], v116, v116, v126
	v_rcp_f32_e32 v128, v127
	v_add_f32_e32 v35, 1.0, v35
	v_exp_f32_e32 v36, v36
	v_mul_f32_e32 v37, 0xbfb8aa3b, v37
	v_fma_f32 v129, -v127, v128, 1.0
	v_fmac_f32_e32 v128, v129, v128
	v_div_scale_f32 v129, vcc, v126, v116, v126
	v_mul_f32_e32 v145, v129, v128
	v_fma_f32 v146, -v127, v145, v129
	v_fmac_f32_e32 v145, v146, v128
	v_fma_f32 v127, -v127, v145, v129
	v_div_fmas_f32 v127, v127, v128, v145
	v_div_fixup_f32 v126, v127, v116, v126
	v_mul_f32_e32 v116, 0xbfb8aa3b, v121
	v_exp_f32_e32 v116, v116
	v_add_f32_e32 v36, 1.0, v36
	v_exp_f32_e32 v37, v37
	v_mul_f32_e32 v30, 0xbfb8aa3b, v30
	v_add_f32_e32 v116, 1.0, v116
	v_div_scale_f32 v121, s[12:13], v116, v116, v125
	v_rcp_f32_e32 v127, v121
	v_add_f32_e32 v37, 1.0, v37
	v_exp_f32_e32 v30, v30
	v_mul_f32_e32 v26, 0xbfb8aa3b, v26
	v_fma_f32 v128, -v121, v127, 1.0
	v_fmac_f32_e32 v127, v128, v127
	v_div_scale_f32 v128, vcc, v125, v116, v125
	v_mul_f32_e32 v129, v128, v127
	v_fma_f32 v145, -v121, v129, v128
	v_fmac_f32_e32 v129, v145, v127
	v_fma_f32 v121, -v121, v129, v128
	v_div_fmas_f32 v121, v121, v127, v129
	v_div_fixup_f32 v121, v121, v116, v125
	v_mul_f32_e32 v116, 0xbfb8aa3b, v117
	v_exp_f32_e32 v116, v116
	v_add_f32_e32 v30, 1.0, v30
	v_exp_f32_e32 v26, v26
	v_mul_f32_e32 v31, 0xbfb8aa3b, v31
	v_add_f32_e32 v116, 1.0, v116
	v_div_scale_f32 v117, s[12:13], v116, v116, v124
	v_rcp_f32_e32 v125, v117
; __device__ __forceinline__ unsigned cvt_pk_bf16(float lo, float hi) { unsigned r; asm volatile("v_cvt_pk_bf16_f32 %0, %1, %2" : "=v"(r) : "v"(lo), "v"(hi)); return r; }
; __device__ __forceinline__ float bf_lo(unsigned w) { return __uint_as_float(w << 16); }
; __device__ __forceinline__ float bf_hi(unsigned w) { return __uint_as_float(w & 0xffff0000u); }
;     __device__ __forceinline__ void operator()(const f32x4 (&acc)[2][2][4][2], const Unit& u, int ui, const LAS float* rtab, int wr, int wc, int fr, int fq) const {
;     ...
;                 for (int bj = 0; bj < 2; ++bj) {
;                     const int col = col0 + bj * HALF; const u32x4 yv = *(const u32x4*)(Y + (size_t)row * 1024 + col);
;                     const f32x4 a0 = acc[ai][bj][m][0], a1 = acc[ai][bj][m][1]; float o[8];
;                     const float yy[8] = {bf_lo(yv.x), bf_hi(yv.x), bf_lo(yv.y), bf_hi(yv.y), bf_lo(yv.z), bf_hi(yv.z), bf_lo(yv.w), bf_hi(yv.w)};
; #pragma unroll
;                     for (int e = 0; e < 4; ++e) { o[e] = yy[e] / (1.0f + __expf(-a0[e])); o[4 + e] = yy[4 + e] / (1.0f + __expf(-a1[e])); }
;                     u32x4 w; w.x = cvt_pk_bf16(o[0], o[1]); w.y = cvt_pk_bf16(o[2], o[3]); w.z = cvt_pk_bf16(o[4], o[5]); w.w = cvt_pk_bf16(o[6], o[7]);
;                     *(u32x4*)(MG + (size_t)row * DM + 1024 + col) = w;
	v_add_f32_e32 v26, 1.0, v26
	v_exp_f32_e32 v31, v31
	v_mul_f32_e32 v27, 0xbfb8aa3b, v27
	v_fma_f32 v127, -v117, v125, 1.0
	v_fmac_f32_e32 v125, v127, v125
	v_div_scale_f32 v127, vcc, v124, v116, v124
	v_mul_f32_e32 v128, v127, v125
	v_fma_f32 v129, -v117, v128, v127
	v_fmac_f32_e32 v128, v129, v125
	v_fma_f32 v117, -v117, v128, v127
	v_div_fmas_f32 v117, v117, v125, v128
	v_div_fixup_f32 v124, v117, v116, v124
	v_cvt_pk_bf16_f32 v116, v118, v119
	v_cvt_pk_bf16_f32 v117, v120, v121
	v_cvt_pk_bf16_f32 v118, v114, v115
	v_or_b32_e32 v114, 16, v144
	v_cvt_pk_bf16_f32 v119, v126, v124
	v_ashrrev_i32_e32 v115, 31, v114
	global_store_dwordx4 v[122:123], v[116:119], off offset:2304
	v_add_f32_e32 v31, 1.0, v31
	v_exp_f32_e32 v27, v27
	v_lshlrev_b64 v[118:119], 11, v[114:115]
	v_lshlrev_b64 v[116:117], 12, v[114:115]
	v_lshl_add_u64 v[114:115], s[86:87], 0, v[118:119]
	v_lshl_add_u64 v[114:115], v[114:115], 0, v[142:143]
	global_load_dwordx4 v[118:121], v[114:115], off
	v_add_f32_e32 v27, 1.0, v27
	v_mul_f32_e32 v32, 0xbfb8aa3b, v32
	v_exp_f32_e32 v32, v32
	v_mul_f32_e32 v28, 0xbfb8aa3b, v28
	v_exp_f32_e32 v28, v28
	v_mul_f32_e32 v22, 0xbfb8aa3b, v22
	v_add_f32_e32 v32, 1.0, v32
	v_exp_f32_e32 v22, v22
	v_add_f32_e32 v28, 1.0, v28
	v_mul_f32_e32 v18, 0xbfb8aa3b, v18
	v_exp_f32_e32 v18, v18
	v_add_f32_e32 v22, 1.0, v22
	v_mul_f32_e32 v19, 0xbfb8aa3b, v19
	v_exp_f32_e32 v19, v19
	v_add_f32_e32 v18, 1.0, v18
	v_mul_f32_e32 v20, 0xbfb8aa3b, v20
	v_exp_f32_e32 v20, v20
	v_add_f32_e32 v19, 1.0, v19
	v_mul_f32_e32 v21, 0xbfb8aa3b, v21
	v_exp_f32_e32 v21, v21
	v_add_f32_e32 v20, 1.0, v20
	v_mul_f32_e32 v14, 0xbfb8aa3b, v14
	v_exp_f32_e32 v14, v14
	v_add_f32_e32 v21, 1.0, v21
	v_mul_f32_e32 v10, 0xbfb8aa3b, v10
	v_exp_f32_e32 v10, v10
	v_add_f32_e32 v14, 1.0, v14
	v_mul_f32_e32 v15, 0xbfb8aa3b, v15
	v_exp_f32_e32 v15, v15
	v_add_f32_e32 v10, 1.0, v10
	v_mul_f32_e32 v11, 0xbfb8aa3b, v11
	v_exp_f32_e32 v11, v11
	v_add_f32_e32 v15, 1.0, v15
	v_mul_f32_e32 v16, 0xbfb8aa3b, v16
	v_exp_f32_e32 v16, v16
	v_add_f32_e32 v11, 1.0, v11
	v_mul_f32_e32 v12, 0xbfb8aa3b, v12
	v_exp_f32_e32 v12, v12
	v_add_f32_e32 v16, 1.0, v16
	v_mul_f32_e32 v6, 0xbfb8aa3b, v6
	v_exp_f32_e32 v6, v6
	v_add_f32_e32 v12, 1.0, v12
	v_mul_f32_e32 v2, 0xbfb8aa3b, v2
	v_exp_f32_e32 v2, v2
	v_add_f32_e32 v6, 1.0, v6
	v_mul_f32_e32 v3, 0xbfb8aa3b, v3
	v_exp_f32_e32 v3, v3
	v_add_f32_e32 v2, 1.0, v2
	v_mul_f32_e32 v4, 0xbfb8aa3b, v4
	v_exp_f32_e32 v4, v4
	v_add_f32_e32 v3, 1.0, v3
	v_mul_f32_e32 v5, 0xbfb8aa3b, v5
	v_exp_f32_e32 v5, v5
	v_add_f32_e32 v4, 1.0, v4
	s_mov_b64 s[36:37], s[46:47]
	s_mov_b64 s[20:21], s[44:45]
	v_add_f32_e32 v5, 1.0, v5
	s_waitcnt vmcnt(0)
	v_lshlrev_b32_e32 v122, 16, v118
	v_and_b32_e32 v123, 0xffff0000, v118
	v_lshlrev_b32_e32 v126, 16, v121
	v_and_b32_e32 v118, 0xffff0000, v121
	v_div_scale_f32 v121, s[12:13], v110, v110, v122
	v_rcp_f32_e32 v127, v121
	v_lshlrev_b32_e32 v125, 16, v120
	v_and_b32_e32 v120, 0xffff0000, v120
	v_lshlrev_b32_e32 v124, 16, v119
	v_fma_f32 v128, -v121, v127, 1.0
	v_fmac_f32_e32 v127, v128, v127
	v_div_scale_f32 v128, vcc, v122, v110, v122
	v_mul_f32_e32 v129, v128, v127
	v_fma_f32 v145, -v121, v129, v128
	v_fmac_f32_e32 v129, v145, v127
	v_fma_f32 v121, -v121, v129, v128
	v_div_fmas_f32 v121, v121, v127, v129
	v_div_fixup_f32 v110, v121, v110, v122
	v_div_scale_f32 v121, s[12:13], v106, v106, v125
	v_rcp_f32_e32 v122, v121
	v_and_b32_e32 v119, 0xffff0000, v119
	v_fma_f32 v127, -v121, v122, 1.0
	v_fmac_f32_e32 v122, v127, v122
	v_div_scale_f32 v127, vcc, v125, v106, v125
	v_mul_f32_e32 v128, v127, v122
	v_fma_f32 v129, -v121, v128, v127
	v_fmac_f32_e32 v128, v129, v122
	v_fma_f32 v121, -v121, v128, v127
	v_div_fmas_f32 v121, v121, v122, v128
	v_div_fixup_f32 v106, v121, v106, v125
	v_div_scale_f32 v121, s[12:13], v111, v111, v123
	v_rcp_f32_e32 v122, v121
	s_nop 0
	v_fma_f32 v125, -v121, v122, 1.0
	v_fmac_f32_e32 v122, v125, v122
	v_div_scale_f32 v125, vcc, v123, v111, v123
	v_mul_f32_e32 v127, v125, v122
	v_fma_f32 v128, -v121, v127, v125
	v_fmac_f32_e32 v127, v128, v122
	v_fma_f32 v121, -v121, v127, v125
	v_div_fmas_f32 v121, v121, v122, v127
	v_div_fixup_f32 v111, v121, v111, v123
	v_div_scale_f32 v121, s[12:13], v107, v107, v120
	v_rcp_f32_e32 v122, v121
	s_nop 0
	v_fma_f32 v123, -v121, v122, 1.0
	v_fmac_f32_e32 v122, v123, v122
	v_div_scale_f32 v123, vcc, v120, v107, v120
	v_mul_f32_e32 v125, v123, v122
	v_fma_f32 v127, -v121, v125, v123
	v_fmac_f32_e32 v125, v127, v122
	v_fma_f32 v121, -v121, v125, v123
	v_div_fmas_f32 v121, v121, v122, v125
	v_div_fixup_f32 v107, v121, v107, v120
	v_div_scale_f32 v120, s[12:13], v112, v112, v124
	v_rcp_f32_e32 v121, v120
	s_nop 0
	v_fma_f32 v122, -v120, v121, 1.0
	v_fmac_f32_e32 v121, v122, v121
	v_div_scale_f32 v122, vcc, v124, v112, v124
	v_mul_f32_e32 v123, v122, v121
	v_fma_f32 v125, -v120, v123, v122
	v_fmac_f32_e32 v123, v125, v121
	v_fma_f32 v120, -v120, v123, v122
	v_div_fmas_f32 v120, v120, v121, v123
	v_div_fixup_f32 v112, v120, v112, v124
	v_div_scale_f32 v120, s[12:13], v108, v108, v126
	v_rcp_f32_e32 v121, v120
	s_nop 0
	v_fma_f32 v122, -v120, v121, 1.0
	v_fmac_f32_e32 v121, v122, v121
	v_div_scale_f32 v122, vcc, v126, v108, v126
	v_mul_f32_e32 v123, v122, v121
	v_fma_f32 v124, -v120, v123, v122
	v_fmac_f32_e32 v123, v124, v121
	v_fma_f32 v120, -v120, v123, v122
	v_div_fmas_f32 v120, v120, v121, v123
	v_div_fixup_f32 v120, v120, v108, v126
	v_mul_f32_e32 v108, 0xbfb8aa3b, v113
	v_exp_f32_e32 v108, v108
	s_nop 0
	v_add_f32_e32 v108, 1.0, v108
	v_div_scale_f32 v113, s[12:13], v108, v108, v119
	v_rcp_f32_e32 v121, v113
	s_nop 0
	v_fma_f32 v122, -v113, v121, 1.0
	v_fmac_f32_e32 v121, v122, v121
	v_div_scale_f32 v122, vcc, v119, v108, v119
	v_mul_f32_e32 v123, v122, v121
	v_fma_f32 v124, -v113, v123, v122
	v_fmac_f32_e32 v123, v124, v121
	v_fma_f32 v113, -v113, v123, v122
	v_div_fmas_f32 v113, v113, v121, v123
	v_div_fixup_f32 v113, v113, v108, v119
	v_mul_f32_e32 v108, 0xbfb8aa3b, v109
	v_exp_f32_e32 v108, v108
	s_nop 0
	v_add_f32_e32 v108, 1.0, v108
	v_div_scale_f32 v109, s[12:13], v108, v108, v118
	v_rcp_f32_e32 v119, v109
	s_nop 0
	v_fma_f32 v121, -v109, v119, 1.0
	v_fmac_f32_e32 v119, v121, v119
	v_div_scale_f32 v121, vcc, v118, v108, v118
	v_mul_f32_e32 v122, v121, v119
	v_fma_f32 v123, -v109, v122, v121
	v_fmac_f32_e32 v122, v123, v119
	v_fma_f32 v109, -v109, v122, v121
	v_div_fmas_f32 v109, v109, v119, v122
	v_div_fixup_f32 v118, v109, v108, v118
	v_cvt_pk_bf16_f32 v108, v110, v111
	v_cvt_pk_bf16_f32 v109, v112, v113
	v_cvt_pk_bf16_f32 v110, v106, v107
	v_lshl_add_u64 v[106:107], s[88:89], 0, v[116:117]
	v_cvt_pk_bf16_f32 v111, v120, v118
	v_lshl_add_u64 v[106:107], v[106:107], 0, v[142:143]
	global_store_dwordx4 v[106:107], v[108:111], off offset:2048
	global_load_dwordx4 v[108:111], v[114:115], off offset:256
	s_waitcnt vmcnt(0)
; __device__ __forceinline__ unsigned cvt_pk_bf16(float lo, float hi) { unsigned r; asm volatile("v_cvt_pk_bf16_f32 %0, %1, %2" : "=v"(r) : "v"(lo), "v"(hi)); return r; }
; __device__ __forceinline__ float bf_lo(unsigned w) { return __uint_as_float(w << 16); }
; __device__ __forceinline__ float bf_hi(unsigned w) { return __uint_as_float(w & 0xffff0000u); }
;     __device__ __forceinline__ void operator()(const f32x4 (&acc)[2][2][4][2], const Unit& u, int ui, const LAS float* rtab, int wr, int wc, int fr, int fq) const {
;     ...
;                 for (int bj = 0; bj < 2; ++bj) {
;                     const int col = col0 + bj * HALF; const u32x4 yv = *(const u32x4*)(Y + (size_t)row * 1024 + col);
;                     const f32x4 a0 = acc[ai][bj][m][0], a1 = acc[ai][bj][m][1]; float o[8];
;                     const float yy[8] = {bf_lo(yv.x), bf_hi(yv.x), bf_lo(yv.y), bf_hi(yv.y), bf_lo(yv.z), bf_hi(yv.z), bf_lo(yv.w), bf_hi(yv.w)};
; #pragma unroll
;                     for (int e = 0; e < 4; ++e) { o[e] = yy[e] / (1.0f + __expf(-a0[e])); o[4 + e] = yy[4 + e] / (1.0f + __expf(-a1[e])); }
;                     u32x4 w; w.x = cvt_pk_bf16(o[0], o[1]); w.y = cvt_pk_bf16(o[2], o[3]); w.z = cvt_pk_bf16(o[4], o[5]); w.w = cvt_pk_bf16(o[6], o[7]);
;                     *(u32x4*)(MG + (size_t)row * DM + 1024 + col) = w;
	v_lshlrev_b32_e32 v112, 16, v108
	v_and_b32_e32 v113, 0xffff0000, v108
	v_lshlrev_b32_e32 v116, 16, v111
	v_and_b32_e32 v108, 0xffff0000, v111
	v_div_scale_f32 v111, s[12:13], v102, v102, v112
	v_rcp_f32_e32 v117, v111
	v_lshlrev_b32_e32 v115, 16, v110
	v_and_b32_e32 v110, 0xffff0000, v110
	v_lshlrev_b32_e32 v114, 16, v109
	v_fma_f32 v118, -v111, v117, 1.0
	v_fmac_f32_e32 v117, v118, v117
	v_div_scale_f32 v118, vcc, v112, v102, v112
	v_mul_f32_e32 v119, v118, v117
	v_fma_f32 v120, -v111, v119, v118
	v_fmac_f32_e32 v119, v120, v117
	v_fma_f32 v111, -v111, v119, v118
	v_div_fmas_f32 v111, v111, v117, v119
	v_div_fixup_f32 v102, v111, v102, v112
	v_div_scale_f32 v111, s[12:13], v98, v98, v115
	v_rcp_f32_e32 v112, v111
	v_and_b32_e32 v109, 0xffff0000, v109
	v_fma_f32 v117, -v111, v112, 1.0
	v_fmac_f32_e32 v112, v117, v112
	v_div_scale_f32 v117, vcc, v115, v98, v115
	v_mul_f32_e32 v118, v117, v112
	v_fma_f32 v119, -v111, v118, v117
	v_fmac_f32_e32 v118, v119, v112
	v_fma_f32 v111, -v111, v118, v117
	v_div_fmas_f32 v111, v111, v112, v118
	v_div_fixup_f32 v111, v111, v98, v115
	v_mul_f32_e32 v98, 0xbfb8aa3b, v103
	v_exp_f32_e32 v98, v98
	s_nop 0
	v_add_f32_e32 v98, 1.0, v98
	v_div_scale_f32 v103, s[12:13], v98, v98, v113
	v_rcp_f32_e32 v112, v103
	s_nop 0
	v_fma_f32 v115, -v103, v112, 1.0
	v_fmac_f32_e32 v112, v115, v112
	v_div_scale_f32 v115, vcc, v113, v98, v113
	v_mul_f32_e32 v117, v115, v112
	v_fma_f32 v118, -v103, v117, v115
	v_fmac_f32_e32 v117, v118, v112
	v_fma_f32 v103, -v103, v117, v115
	v_div_fmas_f32 v103, v103, v112, v117
	v_div_fixup_f32 v98, v103, v98, v113
	v_div_scale_f32 v103, s[12:13], v99, v99, v110
	v_rcp_f32_e32 v112, v103
	v_cvt_pk_bf16_f32 v98, v102, v98
	s_nop 0
	v_fma_f32 v113, -v103, v112, 1.0
	v_fmac_f32_e32 v112, v113, v112
	v_div_scale_f32 v113, vcc, v110, v99, v110
	v_mul_f32_e32 v115, v113, v112
	v_fma_f32 v117, -v103, v115, v113
	v_fmac_f32_e32 v115, v117, v112
	v_fma_f32 v103, -v103, v115, v113
	v_div_fmas_f32 v103, v103, v112, v115
	v_div_fixup_f32 v103, v103, v99, v110
	v_mul_f32_e32 v99, 0xbfb8aa3b, v104
	v_exp_f32_e32 v99, v99
	s_nop 0
	v_add_f32_e32 v99, 1.0, v99
	v_div_scale_f32 v104, s[12:13], v99, v99, v114
	v_rcp_f32_e32 v110, v104
	s_nop 0
	v_fma_f32 v112, -v104, v110, 1.0
	v_fmac_f32_e32 v110, v112, v110
	v_div_scale_f32 v112, vcc, v114, v99, v114
	v_mul_f32_e32 v113, v112, v110
	v_fma_f32 v115, -v104, v113, v112
	v_fmac_f32_e32 v113, v115, v110
	v_fma_f32 v104, -v104, v113, v112
	v_div_fmas_f32 v104, v104, v110, v113
	v_div_fixup_f32 v99, v104, v99, v114
	v_div_scale_f32 v104, s[12:13], v100, v100, v116
	v_rcp_f32_e32 v110, v104
	s_nop 0
	v_fma_f32 v112, -v104, v110, 1.0
	v_fmac_f32_e32 v110, v112, v110
	v_div_scale_f32 v112, vcc, v116, v100, v116
	v_mul_f32_e32 v113, v112, v110
	v_fma_f32 v114, -v104, v113, v112
	v_fmac_f32_e32 v113, v114, v110
	v_fma_f32 v104, -v104, v113, v112
	v_div_fmas_f32 v104, v104, v110, v113
	v_div_fixup_f32 v104, v104, v100, v116
	v_mul_f32_e32 v100, 0xbfb8aa3b, v105
	v_exp_f32_e32 v100, v100
	s_nop 0
	v_add_f32_e32 v100, 1.0, v100
	v_div_scale_f32 v105, s[12:13], v100, v100, v109
	v_rcp_f32_e32 v110, v105
	s_nop 0
	v_fma_f32 v112, -v105, v110, 1.0
	v_fmac_f32_e32 v110, v112, v110
	v_div_scale_f32 v112, vcc, v109, v100, v109
	v_mul_f32_e32 v113, v112, v110
	v_fma_f32 v114, -v105, v113, v112
	v_fmac_f32_e32 v113, v114, v110
	v_fma_f32 v105, -v105, v113, v112
	v_div_fmas_f32 v105, v105, v110, v113
	v_div_fixup_f32 v100, v105, v100, v109
	v_div_scale_f32 v105, s[12:13], v101, v101, v108
	v_rcp_f32_e32 v109, v105
	v_cvt_pk_bf16_f32 v99, v99, v100
	v_cvt_pk_bf16_f32 v100, v111, v103
	s_nop 0
	v_fma_f32 v110, -v105, v109, 1.0
	v_fmac_f32_e32 v109, v110, v109
	v_div_scale_f32 v110, vcc, v108, v101, v108
	v_mul_f32_e32 v112, v110, v109
	v_fma_f32 v113, -v105, v112, v110
	v_fmac_f32_e32 v112, v113, v109
	v_fma_f32 v105, -v105, v112, v110
	v_div_fmas_f32 v105, v105, v109, v112
	v_div_fixup_f32 v101, v105, v101, v108
	v_cvt_pk_bf16_f32 v101, v104, v101
	global_store_dwordx4 v[106:107], v[98:101], off offset:2304
	s_nop 1
	v_or_b32_e32 v98, 32, v144
	v_ashrrev_i32_e32 v99, 31, v98
	v_lshlrev_b64 v[102:103], 11, v[98:99]
	v_lshlrev_b64 v[100:101], 12, v[98:99]
	v_lshl_add_u64 v[98:99], s[86:87], 0, v[102:103]
	v_lshl_add_u64 v[98:99], v[98:99], 0, v[142:143]
	global_load_dwordx4 v[102:105], v[98:99], off
	s_waitcnt vmcnt(0)
; __device__ __forceinline__ unsigned cvt_pk_bf16(float lo, float hi) { unsigned r; asm volatile("v_cvt_pk_bf16_f32 %0, %1, %2" : "=v"(r) : "v"(lo), "v"(hi)); return r; }
; __device__ __forceinline__ float bf_lo(unsigned w) { return __uint_as_float(w << 16); }
; __device__ __forceinline__ float bf_hi(unsigned w) { return __uint_as_float(w & 0xffff0000u); }
;     __device__ __forceinline__ void operator()(const f32x4 (&acc)[2][2][4][2], const Unit& u, int ui, const LAS float* rtab, int wr, int wc, int fr, int fq) const {
;     ...
;                 for (int bj = 0; bj < 2; ++bj) {
;                     const int col = col0 + bj * HALF; const u32x4 yv = *(const u32x4*)(Y + (size_t)row * 1024 + col);
;                     const f32x4 a0 = acc[ai][bj][m][0], a1 = acc[ai][bj][m][1]; float o[8];
;                     const float yy[8] = {bf_lo(yv.x), bf_hi(yv.x), bf_lo(yv.y), bf_hi(yv.y), bf_lo(yv.z), bf_hi(yv.z), bf_lo(yv.w), bf_hi(yv.w)};
; #pragma unroll
;                     for (int e = 0; e < 4; ++e) { o[e] = yy[e] / (1.0f + __expf(-a0[e])); o[4 + e] = yy[4 + e] / (1.0f + __expf(-a1[e])); }
;                     u32x4 w; w.x = cvt_pk_bf16(o[0], o[1]); w.y = cvt_pk_bf16(o[2], o[3]); w.z = cvt_pk_bf16(o[4], o[5]); w.w = cvt_pk_bf16(o[6], o[7]);
;                     *(u32x4*)(MG + (size_t)row * DM + 1024 + col) = w;
	v_lshlrev_b32_e32 v106, 16, v102
	v_and_b32_e32 v107, 0xffff0000, v102
	v_lshlrev_b32_e32 v110, 16, v105
	v_and_b32_e32 v102, 0xffff0000, v105
	v_div_scale_f32 v105, s[12:13], v94, v94, v106
	v_rcp_f32_e32 v111, v105
	v_lshlrev_b32_e32 v109, 16, v104
	v_and_b32_e32 v104, 0xffff0000, v104
	v_lshlrev_b32_e32 v108, 16, v103
	v_fma_f32 v112, -v105, v111, 1.0
	v_fmac_f32_e32 v111, v112, v111
	v_div_scale_f32 v112, vcc, v106, v94, v106
	v_mul_f32_e32 v113, v112, v111
	v_fma_f32 v114, -v105, v113, v112
	v_fmac_f32_e32 v113, v114, v111
	v_fma_f32 v105, -v105, v113, v112
	v_div_fmas_f32 v105, v105, v111, v113
	v_div_fixup_f32 v94, v105, v94, v106
	v_div_scale_f32 v105, s[12:13], v90, v90, v109
	v_rcp_f32_e32 v106, v105
	v_and_b32_e32 v103, 0xffff0000, v103
	v_fma_f32 v111, -v105, v106, 1.0
	v_fmac_f32_e32 v106, v111, v106
	v_div_scale_f32 v111, vcc, v109, v90, v109
	v_mul_f32_e32 v112, v111, v106
	v_fma_f32 v113, -v105, v112, v111
	v_fmac_f32_e32 v112, v113, v106
	v_fma_f32 v105, -v105, v112, v111
	v_div_fmas_f32 v105, v105, v106, v112
	v_div_fixup_f32 v90, v105, v90, v109
	v_div_scale_f32 v105, s[12:13], v95, v95, v107
	v_rcp_f32_e32 v106, v105
	s_nop 0
	v_fma_f32 v109, -v105, v106, 1.0
	v_fmac_f32_e32 v106, v109, v106
	v_div_scale_f32 v109, vcc, v107, v95, v107
	v_mul_f32_e32 v111, v109, v106
	v_fma_f32 v112, -v105, v111, v109
	v_fmac_f32_e32 v111, v112, v106
	v_fma_f32 v105, -v105, v111, v109
	v_div_fmas_f32 v105, v105, v106, v111
	v_div_fixup_f32 v95, v105, v95, v107
	v_div_scale_f32 v105, s[12:13], v91, v91, v104
	v_rcp_f32_e32 v106, v105
	s_nop 0
	v_fma_f32 v107, -v105, v106, 1.0
	v_fmac_f32_e32 v106, v107, v106
	v_div_scale_f32 v107, vcc, v104, v91, v104
	v_mul_f32_e32 v109, v107, v106
	v_fma_f32 v111, -v105, v109, v107
	v_fmac_f32_e32 v109, v111, v106
	v_fma_f32 v105, -v105, v109, v107
	v_div_fmas_f32 v105, v105, v106, v109
	v_div_fixup_f32 v91, v105, v91, v104
	v_div_scale_f32 v104, s[12:13], v96, v96, v108
	v_rcp_f32_e32 v105, v104
	s_nop 0
	v_fma_f32 v106, -v104, v105, 1.0
	v_fmac_f32_e32 v105, v106, v105
	v_div_scale_f32 v106, vcc, v108, v96, v108
	v_mul_f32_e32 v107, v106, v105
	v_fma_f32 v109, -v104, v107, v106
	v_fmac_f32_e32 v107, v109, v105
	v_fma_f32 v104, -v104, v107, v106
	v_div_fmas_f32 v104, v104, v105, v107
	v_div_fixup_f32 v96, v104, v96, v108
	v_div_scale_f32 v104, s[12:13], v92, v92, v110
	v_rcp_f32_e32 v105, v104
	s_nop 0
	v_fma_f32 v106, -v104, v105, 1.0
	v_fmac_f32_e32 v105, v106, v105
	v_div_scale_f32 v106, vcc, v110, v92, v110
	v_mul_f32_e32 v107, v106, v105
	v_fma_f32 v108, -v104, v107, v106
	v_fmac_f32_e32 v107, v108, v105
	v_fma_f32 v104, -v104, v107, v106
	v_div_fmas_f32 v104, v104, v105, v107
	v_div_fixup_f32 v104, v104, v92, v110
	v_mul_f32_e32 v92, 0xbfb8aa3b, v97
	v_exp_f32_e32 v92, v92
	s_nop 0
	v_add_f32_e32 v92, 1.0, v92
	v_div_scale_f32 v97, s[12:13], v92, v92, v103
	v_rcp_f32_e32 v105, v97
	s_nop 0
	v_fma_f32 v106, -v97, v105, 1.0
	v_fmac_f32_e32 v105, v106, v105
	v_div_scale_f32 v106, vcc, v103, v92, v103
	v_mul_f32_e32 v107, v106, v105
	v_fma_f32 v108, -v97, v107, v106
	v_fmac_f32_e32 v107, v108, v105
	v_fma_f32 v97, -v97, v107, v106
	v_div_fmas_f32 v97, v97, v105, v107
	v_div_fixup_f32 v97, v97, v92, v103
	v_mul_f32_e32 v92, 0xbfb8aa3b, v93
	v_exp_f32_e32 v92, v92
	s_nop 0
	v_add_f32_e32 v92, 1.0, v92
	v_div_scale_f32 v93, s[12:13], v92, v92, v102
	v_rcp_f32_e32 v103, v93
	s_nop 0
	v_fma_f32 v105, -v93, v103, 1.0
	v_fmac_f32_e32 v103, v105, v103
	v_div_scale_f32 v105, vcc, v102, v92, v102
	v_mul_f32_e32 v106, v105, v103
	v_fma_f32 v107, -v93, v106, v105
	v_fmac_f32_e32 v106, v107, v103
	v_fma_f32 v93, -v93, v106, v105
	v_div_fmas_f32 v93, v93, v103, v106
	v_div_fixup_f32 v102, v93, v92, v102
	v_cvt_pk_bf16_f32 v92, v94, v95
	v_cvt_pk_bf16_f32 v93, v96, v97
	v_cvt_pk_bf16_f32 v94, v90, v91
	v_lshl_add_u64 v[90:91], s[88:89], 0, v[100:101]
	v_cvt_pk_bf16_f32 v95, v104, v102
	v_lshl_add_u64 v[90:91], v[90:91], 0, v[142:143]
	global_store_dwordx4 v[90:91], v[92:95], off offset:2048
	global_load_dwordx4 v[92:95], v[98:99], off offset:256
	s_waitcnt vmcnt(0)
	v_lshlrev_b32_e32 v96, 16, v92
	v_and_b32_e32 v97, 0xffff0000, v92
	v_lshlrev_b32_e32 v100, 16, v95
	v_and_b32_e32 v92, 0xffff0000, v95
	v_div_scale_f32 v95, s[12:13], v86, v86, v96
	v_rcp_f32_e32 v101, v95
	v_lshlrev_b32_e32 v99, 16, v94
	v_and_b32_e32 v94, 0xffff0000, v94
	v_lshlrev_b32_e32 v98, 16, v93
	v_fma_f32 v102, -v95, v101, 1.0
	v_fmac_f32_e32 v101, v102, v101
	v_div_scale_f32 v102, vcc, v96, v86, v96
	v_mul_f32_e32 v103, v102, v101
	v_fma_f32 v104, -v95, v103, v102
	v_fmac_f32_e32 v103, v104, v101
	v_fma_f32 v95, -v95, v103, v102
	v_div_fmas_f32 v95, v95, v101, v103
	v_div_fixup_f32 v86, v95, v86, v96
	v_div_scale_f32 v95, s[12:13], v82, v82, v99
	v_rcp_f32_e32 v96, v95
	v_and_b32_e32 v93, 0xffff0000, v93
	v_fma_f32 v101, -v95, v96, 1.0
	v_fmac_f32_e32 v96, v101, v96
	v_div_scale_f32 v101, vcc, v99, v82, v99
	v_mul_f32_e32 v102, v101, v96
	v_fma_f32 v103, -v95, v102, v101
	v_fmac_f32_e32 v102, v103, v96
	v_fma_f32 v95, -v95, v102, v101
	v_div_fmas_f32 v95, v95, v96, v102
	v_div_fixup_f32 v95, v95, v82, v99
	v_mul_f32_e32 v82, 0xbfb8aa3b, v87
	v_exp_f32_e32 v82, v82
	s_nop 0
	v_add_f32_e32 v82, 1.0, v82
	v_div_scale_f32 v87, s[12:13], v82, v82, v97
	v_rcp_f32_e32 v96, v87
	s_nop 0
	v_fma_f32 v99, -v87, v96, 1.0
	v_fmac_f32_e32 v96, v99, v96
	v_div_scale_f32 v99, vcc, v97, v82, v97
	v_mul_f32_e32 v101, v99, v96
	v_fma_f32 v102, -v87, v101, v99
	v_fmac_f32_e32 v101, v102, v96
	v_fma_f32 v87, -v87, v101, v99
	v_div_fmas_f32 v87, v87, v96, v101
	v_div_fixup_f32 v82, v87, v82, v97
	v_div_scale_f32 v87, s[12:13], v83, v83, v94
	v_rcp_f32_e32 v96, v87
; __device__ __forceinline__ unsigned cvt_pk_bf16(float lo, float hi) { unsigned r; asm volatile("v_cvt_pk_bf16_f32 %0, %1, %2" : "=v"(r) : "v"(lo), "v"(hi)); return r; }
; __device__ __forceinline__ float bf_lo(unsigned w) { return __uint_as_float(w << 16); }
; __device__ __forceinline__ float bf_hi(unsigned w) { return __uint_as_float(w & 0xffff0000u); }
;     __device__ __forceinline__ void operator()(const f32x4 (&acc)[2][2][4][2], const Unit& u, int ui, const LAS float* rtab, int wr, int wc, int fr, int fq) const {
;     ...
;                 for (int bj = 0; bj < 2; ++bj) {
;                     const int col = col0 + bj * HALF; const u32x4 yv = *(const u32x4*)(Y + (size_t)row * 1024 + col);
;                     const f32x4 a0 = acc[ai][bj][m][0], a1 = acc[ai][bj][m][1]; float o[8];
;                     const float yy[8] = {bf_lo(yv.x), bf_hi(yv.x), bf_lo(yv.y), bf_hi(yv.y), bf_lo(yv.z), bf_hi(yv.z), bf_lo(yv.w), bf_hi(yv.w)};
; #pragma unroll
;                     for (int e = 0; e < 4; ++e) { o[e] = yy[e] / (1.0f + __expf(-a0[e])); o[4 + e] = yy[4 + e] / (1.0f + __expf(-a1[e])); }
;                     u32x4 w; w.x = cvt_pk_bf16(o[0], o[1]); w.y = cvt_pk_bf16(o[2], o[3]); w.z = cvt_pk_bf16(o[4], o[5]); w.w = cvt_pk_bf16(o[6], o[7]);
;                     *(u32x4*)(MG + (size_t)row * DM + 1024 + col) = w;
	v_cvt_pk_bf16_f32 v82, v86, v82
	s_nop 0
	v_fma_f32 v97, -v87, v96, 1.0
	v_fmac_f32_e32 v96, v97, v96
	v_div_scale_f32 v97, vcc, v94, v83, v94
	v_mul_f32_e32 v99, v97, v96
	v_fma_f32 v101, -v87, v99, v97
	v_fmac_f32_e32 v99, v101, v96
	v_fma_f32 v87, -v87, v99, v97
	v_div_fmas_f32 v87, v87, v96, v99
	v_div_fixup_f32 v87, v87, v83, v94
	v_mul_f32_e32 v83, 0xbfb8aa3b, v88
	v_exp_f32_e32 v83, v83
	s_nop 0
	v_add_f32_e32 v83, 1.0, v83
	v_div_scale_f32 v88, s[12:13], v83, v83, v98
	v_rcp_f32_e32 v94, v88
	s_nop 0
	v_fma_f32 v96, -v88, v94, 1.0
	v_fmac_f32_e32 v94, v96, v94
	v_div_scale_f32 v96, vcc, v98, v83, v98
	v_mul_f32_e32 v97, v96, v94
	v_fma_f32 v99, -v88, v97, v96
	v_fmac_f32_e32 v97, v99, v94
	v_fma_f32 v88, -v88, v97, v96
	v_div_fmas_f32 v88, v88, v94, v97
	v_div_fixup_f32 v83, v88, v83, v98
	v_div_scale_f32 v88, s[12:13], v84, v84, v100
	v_rcp_f32_e32 v94, v88
	s_nop 0
	v_fma_f32 v96, -v88, v94, 1.0
	v_fmac_f32_e32 v94, v96, v94
	v_div_scale_f32 v96, vcc, v100, v84, v100
	v_mul_f32_e32 v97, v96, v94
	v_fma_f32 v98, -v88, v97, v96
	v_fmac_f32_e32 v97, v98, v94
	v_fma_f32 v88, -v88, v97, v96
	v_div_fmas_f32 v88, v88, v94, v97
	v_div_fixup_f32 v88, v88, v84, v100
	v_mul_f32_e32 v84, 0xbfb8aa3b, v89
	v_exp_f32_e32 v84, v84
	s_nop 0
	v_add_f32_e32 v84, 1.0, v84
	v_div_scale_f32 v89, s[12:13], v84, v84, v93
	v_rcp_f32_e32 v94, v89
	s_nop 0
	v_fma_f32 v96, -v89, v94, 1.0
	v_fmac_f32_e32 v94, v96, v94
	v_div_scale_f32 v96, vcc, v93, v84, v93
	v_mul_f32_e32 v97, v96, v94
	v_fma_f32 v98, -v89, v97, v96
	v_fmac_f32_e32 v97, v98, v94
	v_fma_f32 v89, -v89, v97, v96
	v_div_fmas_f32 v89, v89, v94, v97
	v_div_fixup_f32 v84, v89, v84, v93
	v_div_scale_f32 v89, s[12:13], v85, v85, v92
	v_rcp_f32_e32 v93, v89
	v_cvt_pk_bf16_f32 v83, v83, v84
	v_cvt_pk_bf16_f32 v84, v95, v87
	s_nop 0
	v_fma_f32 v94, -v89, v93, 1.0
	v_fmac_f32_e32 v93, v94, v93
	v_div_scale_f32 v94, vcc, v92, v85, v92
	v_mul_f32_e32 v96, v94, v93
	v_fma_f32 v97, -v89, v96, v94
	v_fmac_f32_e32 v96, v97, v93
	v_fma_f32 v89, -v89, v96, v94
	v_div_fmas_f32 v89, v89, v93, v96
	v_div_fixup_f32 v85, v89, v85, v92
	v_cvt_pk_bf16_f32 v85, v88, v85
	global_store_dwordx4 v[90:91], v[82:85], off offset:2304
	s_nop 1
	v_or_b32_e32 v82, 48, v144
	v_ashrrev_i32_e32 v83, 31, v82
	v_lshlrev_b64 v[86:87], 11, v[82:83]
	v_lshlrev_b64 v[84:85], 12, v[82:83]
	v_lshl_add_u64 v[82:83], s[86:87], 0, v[86:87]
	v_lshl_add_u64 v[82:83], v[82:83], 0, v[142:143]
	global_load_dwordx4 v[86:89], v[82:83], off
	s_waitcnt vmcnt(0)
	v_lshlrev_b32_e32 v90, 16, v86
	v_and_b32_e32 v91, 0xffff0000, v86
	v_lshlrev_b32_e32 v94, 16, v89
	v_and_b32_e32 v86, 0xffff0000, v89
	v_div_scale_f32 v89, s[12:13], v78, v78, v90
	v_rcp_f32_e32 v95, v89
	v_lshlrev_b32_e32 v93, 16, v88
	v_and_b32_e32 v88, 0xffff0000, v88
	v_lshlrev_b32_e32 v92, 16, v87
	v_fma_f32 v96, -v89, v95, 1.0
	v_fmac_f32_e32 v95, v96, v95
	v_div_scale_f32 v96, vcc, v90, v78, v90
	v_mul_f32_e32 v97, v96, v95
	v_fma_f32 v98, -v89, v97, v96
	v_fmac_f32_e32 v97, v98, v95
	v_fma_f32 v89, -v89, v97, v96
	v_div_fmas_f32 v89, v89, v95, v97
	v_div_fixup_f32 v78, v89, v78, v90
	v_div_scale_f32 v89, s[12:13], v74, v74, v93
	v_rcp_f32_e32 v90, v89
	v_and_b32_e32 v87, 0xffff0000, v87
	v_fma_f32 v95, -v89, v90, 1.0
	v_fmac_f32_e32 v90, v95, v90
	v_div_scale_f32 v95, vcc, v93, v74, v93
	v_mul_f32_e32 v96, v95, v90
	v_fma_f32 v97, -v89, v96, v95
	v_fmac_f32_e32 v96, v97, v90
	v_fma_f32 v89, -v89, v96, v95
	v_div_fmas_f32 v89, v89, v90, v96
	v_div_fixup_f32 v74, v89, v74, v93
	v_div_scale_f32 v89, s[12:13], v79, v79, v91
	v_rcp_f32_e32 v90, v89
	s_nop 0
	v_fma_f32 v93, -v89, v90, 1.0
	v_fmac_f32_e32 v90, v93, v90
	v_div_scale_f32 v93, vcc, v91, v79, v91
	v_mul_f32_e32 v95, v93, v90
	v_fma_f32 v96, -v89, v95, v93
	v_fmac_f32_e32 v95, v96, v90
	v_fma_f32 v89, -v89, v95, v93
	v_div_fmas_f32 v89, v89, v90, v95
	v_div_fixup_f32 v79, v89, v79, v91
	v_div_scale_f32 v89, s[12:13], v75, v75, v88
	v_rcp_f32_e32 v90, v89
	s_nop 0
	v_fma_f32 v91, -v89, v90, 1.0
	v_fmac_f32_e32 v90, v91, v90
	v_div_scale_f32 v91, vcc, v88, v75, v88
	v_mul_f32_e32 v93, v91, v90
	v_fma_f32 v95, -v89, v93, v91
	v_fmac_f32_e32 v93, v95, v90
	v_fma_f32 v89, -v89, v93, v91
	v_div_fmas_f32 v89, v89, v90, v93
	v_div_fixup_f32 v75, v89, v75, v88
	v_div_scale_f32 v88, s[12:13], v80, v80, v92
	v_rcp_f32_e32 v89, v88
	s_nop 0
	v_fma_f32 v90, -v88, v89, 1.0
	v_fmac_f32_e32 v89, v90, v89
	v_div_scale_f32 v90, vcc, v92, v80, v92
	v_mul_f32_e32 v91, v90, v89
	v_fma_f32 v93, -v88, v91, v90
	v_fmac_f32_e32 v91, v93, v89
	v_fma_f32 v88, -v88, v91, v90
	v_div_fmas_f32 v88, v88, v89, v91
	v_div_fixup_f32 v80, v88, v80, v92
	v_div_scale_f32 v88, s[12:13], v76, v76, v94
	v_rcp_f32_e32 v89, v88
	s_nop 0
	v_fma_f32 v90, -v88, v89, 1.0
	v_fmac_f32_e32 v89, v90, v89
	v_div_scale_f32 v90, vcc, v94, v76, v94
	v_mul_f32_e32 v91, v90, v89
	v_fma_f32 v92, -v88, v91, v90
	v_fmac_f32_e32 v91, v92, v89
	v_fma_f32 v88, -v88, v91, v90
	v_div_fmas_f32 v88, v88, v89, v91
	v_div_fixup_f32 v88, v88, v76, v94
	v_mul_f32_e32 v76, 0xbfb8aa3b, v81
	v_exp_f32_e32 v76, v76
	s_nop 0
	v_add_f32_e32 v76, 1.0, v76
	v_div_scale_f32 v81, s[12:13], v76, v76, v87
	v_rcp_f32_e32 v89, v81
	s_nop 0
	v_fma_f32 v90, -v81, v89, 1.0
	v_fmac_f32_e32 v89, v90, v89
	v_div_scale_f32 v90, vcc, v87, v76, v87
	v_mul_f32_e32 v91, v90, v89
	v_fma_f32 v92, -v81, v91, v90
	v_fmac_f32_e32 v91, v92, v89
	v_fma_f32 v81, -v81, v91, v90
	v_div_fmas_f32 v81, v81, v89, v91
	v_div_fixup_f32 v81, v81, v76, v87
	v_mul_f32_e32 v76, 0xbfb8aa3b, v77
	v_exp_f32_e32 v76, v76
	s_nop 0
	v_add_f32_e32 v76, 1.0, v76
	v_div_scale_f32 v77, s[12:13], v76, v76, v86
	v_rcp_f32_e32 v87, v77
	s_nop 0
	v_fma_f32 v89, -v77, v87, 1.0
	v_fmac_f32_e32 v87, v89, v87
	v_div_scale_f32 v89, vcc, v86, v76, v86
	v_mul_f32_e32 v90, v89, v87
	v_fma_f32 v91, -v77, v90, v89
	v_fmac_f32_e32 v90, v91, v87
	v_fma_f32 v77, -v77, v90, v89
	v_div_fmas_f32 v77, v77, v87, v90
	v_div_fixup_f32 v86, v77, v76, v86
	v_cvt_pk_bf16_f32 v76, v78, v79
	v_cvt_pk_bf16_f32 v77, v80, v81
	v_cvt_pk_bf16_f32 v78, v74, v75
	v_lshl_add_u64 v[74:75], s[88:89], 0, v[84:85]
	v_cvt_pk_bf16_f32 v79, v88, v86
	v_lshl_add_u64 v[74:75], v[74:75], 0, v[142:143]
	global_store_dwordx4 v[74:75], v[76:79], off offset:2048
	global_load_dwordx4 v[76:79], v[82:83], off offset:256
	s_waitcnt vmcnt(0)
; __device__ __forceinline__ unsigned cvt_pk_bf16(float lo, float hi) { unsigned r; asm volatile("v_cvt_pk_bf16_f32 %0, %1, %2" : "=v"(r) : "v"(lo), "v"(hi)); return r; }
; __device__ __forceinline__ float bf_lo(unsigned w) { return __uint_as_float(w << 16); }
; __device__ __forceinline__ float bf_hi(unsigned w) { return __uint_as_float(w & 0xffff0000u); }
;     __device__ __forceinline__ void operator()(const f32x4 (&acc)[2][2][4][2], const Unit& u, int ui, const LAS float* rtab, int wr, int wc, int fr, int fq) const {
;     ...
; #pragma unroll
;         for (int ai = 0; ai < 2; ++ai)
; #pragma unroll
;             for (int m = 0; m < 4; ++m) {
;                 const int row = row0 + ai * HALF + m * 16;
; #pragma unroll
;                 for (int bj = 0; bj < 2; ++bj) {
;                     const int col = col0 + bj * HALF; const u32x4 yv = *(const u32x4*)(Y + (size_t)row * 1024 + col);
;                     const f32x4 a0 = acc[ai][bj][m][0], a1 = acc[ai][bj][m][1]; float o[8];
;                     const float yy[8] = {bf_lo(yv.x), bf_hi(yv.x), bf_lo(yv.y), bf_hi(yv.y), bf_lo(yv.z), bf_hi(yv.z), bf_lo(yv.w), bf_hi(yv.w)};
; #pragma unroll
;                     for (int e = 0; e < 4; ++e) { o[e] = yy[e] / (1.0f + __expf(-a0[e])); o[4 + e] = yy[4 + e] / (1.0f + __expf(-a1[e])); }
;                     u32x4 w; w.x = cvt_pk_bf16(o[0], o[1]); w.y = cvt_pk_bf16(o[2], o[3]); w.z = cvt_pk_bf16(o[4], o[5]); w.w = cvt_pk_bf16(o[6], o[7]);
;                     *(u32x4*)(MG + (size_t)row * DM + 1024 + col) = w;
	v_lshlrev_b32_e32 v80, 16, v76
	v_and_b32_e32 v81, 0xffff0000, v76
	v_lshlrev_b32_e32 v84, 16, v79
	v_and_b32_e32 v76, 0xffff0000, v79
	v_div_scale_f32 v79, s[12:13], v70, v70, v80
	v_rcp_f32_e32 v85, v79
	v_lshlrev_b32_e32 v83, 16, v78
	v_and_b32_e32 v78, 0xffff0000, v78
	v_lshlrev_b32_e32 v82, 16, v77
	v_fma_f32 v86, -v79, v85, 1.0
	v_fmac_f32_e32 v85, v86, v85
	v_div_scale_f32 v86, vcc, v80, v70, v80
	v_mul_f32_e32 v87, v86, v85
	v_fma_f32 v88, -v79, v87, v86
	v_fmac_f32_e32 v87, v88, v85
	v_fma_f32 v79, -v79, v87, v86
	v_div_fmas_f32 v79, v79, v85, v87
	v_div_fixup_f32 v70, v79, v70, v80
	v_div_scale_f32 v79, s[12:13], v66, v66, v83
	v_rcp_f32_e32 v80, v79
	v_and_b32_e32 v77, 0xffff0000, v77
	v_fma_f32 v85, -v79, v80, 1.0
	v_fmac_f32_e32 v80, v85, v80
	v_div_scale_f32 v85, vcc, v83, v66, v83
	v_mul_f32_e32 v86, v85, v80
	v_fma_f32 v87, -v79, v86, v85
	v_fmac_f32_e32 v86, v87, v80
	v_fma_f32 v79, -v79, v86, v85
	v_div_fmas_f32 v79, v79, v80, v86
	v_div_fixup_f32 v79, v79, v66, v83
	v_mul_f32_e32 v66, 0xbfb8aa3b, v71
	v_exp_f32_e32 v66, v66
	s_nop 0
	v_add_f32_e32 v66, 1.0, v66
	v_div_scale_f32 v71, s[12:13], v66, v66, v81
	v_rcp_f32_e32 v80, v71
	s_nop 0
	v_fma_f32 v83, -v71, v80, 1.0
	v_fmac_f32_e32 v80, v83, v80
	v_div_scale_f32 v83, vcc, v81, v66, v81
	v_mul_f32_e32 v85, v83, v80
	v_fma_f32 v86, -v71, v85, v83
	v_fmac_f32_e32 v85, v86, v80
	v_fma_f32 v71, -v71, v85, v83
	v_div_fmas_f32 v71, v71, v80, v85
	v_div_fixup_f32 v66, v71, v66, v81
	v_div_scale_f32 v71, s[12:13], v67, v67, v78
	v_rcp_f32_e32 v80, v71
	v_cvt_pk_bf16_f32 v66, v70, v66
	s_nop 0
	v_fma_f32 v81, -v71, v80, 1.0
	v_fmac_f32_e32 v80, v81, v80
	v_div_scale_f32 v81, vcc, v78, v67, v78
	v_mul_f32_e32 v83, v81, v80
	v_fma_f32 v85, -v71, v83, v81
	v_fmac_f32_e32 v83, v85, v80
	v_fma_f32 v71, -v71, v83, v81
	v_div_fmas_f32 v71, v71, v80, v83
	v_div_fixup_f32 v71, v71, v67, v78
	v_mul_f32_e32 v67, 0xbfb8aa3b, v72
	v_exp_f32_e32 v67, v67
	s_nop 0
	v_add_f32_e32 v67, 1.0, v67
	v_div_scale_f32 v72, s[12:13], v67, v67, v82
	v_rcp_f32_e32 v78, v72
	s_nop 0
	v_fma_f32 v80, -v72, v78, 1.0
	v_fmac_f32_e32 v78, v80, v78
	v_div_scale_f32 v80, vcc, v82, v67, v82
	v_mul_f32_e32 v81, v80, v78
	v_fma_f32 v83, -v72, v81, v80
	v_fmac_f32_e32 v81, v83, v78
	v_fma_f32 v72, -v72, v81, v80
	v_div_fmas_f32 v72, v72, v78, v81
	v_div_fixup_f32 v67, v72, v67, v82
	v_div_scale_f32 v72, s[12:13], v68, v68, v84
	v_rcp_f32_e32 v78, v72
	s_nop 0
	v_fma_f32 v80, -v72, v78, 1.0
	v_fmac_f32_e32 v78, v80, v78
	v_div_scale_f32 v80, vcc, v84, v68, v84
	v_mul_f32_e32 v81, v80, v78
	v_fma_f32 v82, -v72, v81, v80
	v_fmac_f32_e32 v81, v82, v78
	v_fma_f32 v72, -v72, v81, v80
	v_div_fmas_f32 v72, v72, v78, v81
	v_div_fixup_f32 v72, v72, v68, v84
	v_mul_f32_e32 v68, 0xbfb8aa3b, v73
	v_exp_f32_e32 v68, v68
	s_nop 0
	v_add_f32_e32 v68, 1.0, v68
	v_div_scale_f32 v73, s[12:13], v68, v68, v77
	v_rcp_f32_e32 v78, v73
	s_nop 0
	v_fma_f32 v80, -v73, v78, 1.0
	v_fmac_f32_e32 v78, v80, v78
	v_div_scale_f32 v80, vcc, v77, v68, v77
	v_mul_f32_e32 v81, v80, v78
	v_fma_f32 v82, -v73, v81, v80
	v_fmac_f32_e32 v81, v82, v78
	v_fma_f32 v73, -v73, v81, v80
	v_div_fmas_f32 v73, v73, v78, v81
	v_div_fixup_f32 v68, v73, v68, v77
	v_div_scale_f32 v73, s[12:13], v69, v69, v76
	v_rcp_f32_e32 v77, v73
	v_cvt_pk_bf16_f32 v67, v67, v68
	v_cvt_pk_bf16_f32 v68, v79, v71
	s_nop 0
	v_fma_f32 v78, -v73, v77, 1.0
	v_fmac_f32_e32 v77, v78, v77
	v_div_scale_f32 v78, vcc, v76, v69, v76
	v_mul_f32_e32 v80, v78, v77
	v_fma_f32 v81, -v73, v80, v78
	v_fmac_f32_e32 v80, v81, v77
	v_fma_f32 v73, -v73, v80, v78
	v_div_fmas_f32 v73, v73, v77, v80
	v_div_fixup_f32 v69, v73, v69, v76
	v_cvt_pk_bf16_f32 v69, v72, v69
	global_store_dwordx4 v[74:75], v[66:69], off offset:2304
	s_nop 1
	v_add_u32_e32 v66, 0x80, v144
	v_ashrrev_i32_e32 v67, 31, v66
	v_lshlrev_b64 v[70:71], 11, v[66:67]
	v_lshlrev_b64 v[68:69], 12, v[66:67]
	v_lshl_add_u64 v[66:67], s[86:87], 0, v[70:71]
	v_lshl_add_u64 v[66:67], v[66:67], 0, v[142:143]
	global_load_dwordx4 v[70:73], v[66:67], off
	s_waitcnt vmcnt(0)
	v_lshlrev_b32_e32 v74, 16, v70
	v_and_b32_e32 v75, 0xffff0000, v70
	v_lshlrev_b32_e32 v78, 16, v73
	v_and_b32_e32 v70, 0xffff0000, v73
	v_div_scale_f32 v73, s[12:13], v62, v62, v74
	v_rcp_f32_e32 v79, v73
	v_lshlrev_b32_e32 v77, 16, v72
	v_and_b32_e32 v72, 0xffff0000, v72
	v_lshlrev_b32_e32 v76, 16, v71
	v_fma_f32 v80, -v73, v79, 1.0
	v_fmac_f32_e32 v79, v80, v79
	v_div_scale_f32 v80, vcc, v74, v62, v74
	v_mul_f32_e32 v81, v80, v79
	v_fma_f32 v82, -v73, v81, v80
	v_fmac_f32_e32 v81, v82, v79
	v_fma_f32 v73, -v73, v81, v80
	v_div_fmas_f32 v73, v73, v79, v81
	v_div_fixup_f32 v62, v73, v62, v74
	v_div_scale_f32 v73, s[12:13], v58, v58, v77
	v_rcp_f32_e32 v74, v73
	v_and_b32_e32 v71, 0xffff0000, v71
	v_fma_f32 v79, -v73, v74, 1.0
	v_fmac_f32_e32 v74, v79, v74
	v_div_scale_f32 v79, vcc, v77, v58, v77
	v_mul_f32_e32 v80, v79, v74
	v_fma_f32 v81, -v73, v80, v79
	v_fmac_f32_e32 v80, v81, v74
	v_fma_f32 v73, -v73, v80, v79
	v_div_fmas_f32 v73, v73, v74, v80
	v_div_fixup_f32 v58, v73, v58, v77
	v_div_scale_f32 v73, s[12:13], v63, v63, v75
	v_rcp_f32_e32 v74, v73
	s_nop 0
	v_fma_f32 v77, -v73, v74, 1.0
	v_fmac_f32_e32 v74, v77, v74
	v_div_scale_f32 v77, vcc, v75, v63, v75
	v_mul_f32_e32 v79, v77, v74
	v_fma_f32 v80, -v73, v79, v77
	v_fmac_f32_e32 v79, v80, v74
	v_fma_f32 v73, -v73, v79, v77
	v_div_fmas_f32 v73, v73, v74, v79
	v_div_fixup_f32 v63, v73, v63, v75
	v_div_scale_f32 v73, s[12:13], v59, v59, v72
	v_rcp_f32_e32 v74, v73
	s_nop 0
	v_fma_f32 v75, -v73, v74, 1.0
	v_fmac_f32_e32 v74, v75, v74
	v_div_scale_f32 v75, vcc, v72, v59, v72
	v_mul_f32_e32 v77, v75, v74
	v_fma_f32 v79, -v73, v77, v75
; __device__ __forceinline__ unsigned cvt_pk_bf16(float lo, float hi) { unsigned r; asm volatile("v_cvt_pk_bf16_f32 %0, %1, %2" : "=v"(r) : "v"(lo), "v"(hi)); return r; }
; __device__ __forceinline__ float bf_lo(unsigned w) { return __uint_as_float(w << 16); }
; __device__ __forceinline__ float bf_hi(unsigned w) { return __uint_as_float(w & 0xffff0000u); }
;     __device__ __forceinline__ void operator()(const f32x4 (&acc)[2][2][4][2], const Unit& u, int ui, const LAS float* rtab, int wr, int wc, int fr, int fq) const {
;     ...
; #pragma unroll
;         for (int ai = 0; ai < 2; ++ai)
; #pragma unroll
;             for (int m = 0; m < 4; ++m) {
;                 const int row = row0 + ai * HALF + m * 16;
; #pragma unroll
;                 for (int bj = 0; bj < 2; ++bj) {
;                     const int col = col0 + bj * HALF; const u32x4 yv = *(const u32x4*)(Y + (size_t)row * 1024 + col);
;                     const f32x4 a0 = acc[ai][bj][m][0], a1 = acc[ai][bj][m][1]; float o[8];
;                     const float yy[8] = {bf_lo(yv.x), bf_hi(yv.x), bf_lo(yv.y), bf_hi(yv.y), bf_lo(yv.z), bf_hi(yv.z), bf_lo(yv.w), bf_hi(yv.w)};
; #pragma unroll
;                     for (int e = 0; e < 4; ++e) { o[e] = yy[e] / (1.0f + __expf(-a0[e])); o[4 + e] = yy[4 + e] / (1.0f + __expf(-a1[e])); }
;                     u32x4 w; w.x = cvt_pk_bf16(o[0], o[1]); w.y = cvt_pk_bf16(o[2], o[3]); w.z = cvt_pk_bf16(o[4], o[5]); w.w = cvt_pk_bf16(o[6], o[7]);
;                     *(u32x4*)(MG + (size_t)row * DM + 1024 + col) = w;
	v_fmac_f32_e32 v77, v79, v74
	v_fma_f32 v73, -v73, v77, v75
	v_div_fmas_f32 v73, v73, v74, v77
	v_div_fixup_f32 v59, v73, v59, v72
	v_div_scale_f32 v72, s[12:13], v64, v64, v76
	v_rcp_f32_e32 v73, v72
	s_nop 0
	v_fma_f32 v74, -v72, v73, 1.0
	v_fmac_f32_e32 v73, v74, v73
	v_div_scale_f32 v74, vcc, v76, v64, v76
	v_mul_f32_e32 v75, v74, v73
	v_fma_f32 v77, -v72, v75, v74
	v_fmac_f32_e32 v75, v77, v73
	v_fma_f32 v72, -v72, v75, v74
	v_div_fmas_f32 v72, v72, v73, v75
	v_div_fixup_f32 v64, v72, v64, v76
	v_div_scale_f32 v72, s[12:13], v60, v60, v78
	v_rcp_f32_e32 v73, v72
	s_nop 0
	v_fma_f32 v74, -v72, v73, 1.0
	v_fmac_f32_e32 v73, v74, v73
	v_div_scale_f32 v74, vcc, v78, v60, v78
	v_mul_f32_e32 v75, v74, v73
	v_fma_f32 v76, -v72, v75, v74
	v_fmac_f32_e32 v75, v76, v73
	v_fma_f32 v72, -v72, v75, v74
	v_div_fmas_f32 v72, v72, v73, v75
	v_div_fixup_f32 v72, v72, v60, v78
	v_mul_f32_e32 v60, 0xbfb8aa3b, v65
	v_exp_f32_e32 v60, v60
	s_nop 0
	v_add_f32_e32 v60, 1.0, v60
	v_div_scale_f32 v65, s[12:13], v60, v60, v71
	v_rcp_f32_e32 v73, v65
	s_nop 0
	v_fma_f32 v74, -v65, v73, 1.0
	v_fmac_f32_e32 v73, v74, v73
	v_div_scale_f32 v74, vcc, v71, v60, v71
	v_mul_f32_e32 v75, v74, v73
	v_fma_f32 v76, -v65, v75, v74
	v_fmac_f32_e32 v75, v76, v73
	v_fma_f32 v65, -v65, v75, v74
	v_div_fmas_f32 v65, v65, v73, v75
	v_div_fixup_f32 v65, v65, v60, v71
	v_mul_f32_e32 v60, 0xbfb8aa3b, v61
	v_exp_f32_e32 v60, v60
	s_nop 0
	v_add_f32_e32 v60, 1.0, v60
	v_div_scale_f32 v61, s[12:13], v60, v60, v70
	v_rcp_f32_e32 v71, v61
	s_nop 0
	v_fma_f32 v73, -v61, v71, 1.0
	v_fmac_f32_e32 v71, v73, v71
	v_div_scale_f32 v73, vcc, v70, v60, v70
	v_mul_f32_e32 v74, v73, v71
	v_fma_f32 v75, -v61, v74, v73
	v_fmac_f32_e32 v74, v75, v71
	v_fma_f32 v61, -v61, v74, v73
	v_div_fmas_f32 v61, v61, v71, v74
	v_div_fixup_f32 v70, v61, v60, v70
	v_cvt_pk_bf16_f32 v60, v62, v63
	v_cvt_pk_bf16_f32 v61, v64, v65
	v_cvt_pk_bf16_f32 v62, v58, v59
	v_lshl_add_u64 v[58:59], s[88:89], 0, v[68:69]
	v_cvt_pk_bf16_f32 v63, v72, v70
	v_lshl_add_u64 v[58:59], v[58:59], 0, v[142:143]
	global_store_dwordx4 v[58:59], v[60:63], off offset:2048
	global_load_dwordx4 v[60:63], v[66:67], off offset:256
	s_waitcnt vmcnt(0)
	v_lshlrev_b32_e32 v64, 16, v60
	v_and_b32_e32 v65, 0xffff0000, v60
	v_lshlrev_b32_e32 v68, 16, v63
	v_and_b32_e32 v60, 0xffff0000, v63
	v_div_scale_f32 v63, s[12:13], v54, v54, v64
	v_rcp_f32_e32 v69, v63
	v_lshlrev_b32_e32 v67, 16, v62
	v_and_b32_e32 v62, 0xffff0000, v62
	v_lshlrev_b32_e32 v66, 16, v61
	v_fma_f32 v70, -v63, v69, 1.0
	v_fmac_f32_e32 v69, v70, v69
	v_div_scale_f32 v70, vcc, v64, v54, v64
	v_mul_f32_e32 v71, v70, v69
	v_fma_f32 v72, -v63, v71, v70
	v_fmac_f32_e32 v71, v72, v69
	v_fma_f32 v63, -v63, v71, v70
	v_div_fmas_f32 v63, v63, v69, v71
	v_div_fixup_f32 v54, v63, v54, v64
	v_div_scale_f32 v63, s[12:13], v50, v50, v67
	v_rcp_f32_e32 v64, v63
	v_and_b32_e32 v61, 0xffff0000, v61
	v_fma_f32 v69, -v63, v64, 1.0
	v_fmac_f32_e32 v64, v69, v64
	v_div_scale_f32 v69, vcc, v67, v50, v67
	v_mul_f32_e32 v70, v69, v64
	v_fma_f32 v71, -v63, v70, v69
	v_fmac_f32_e32 v70, v71, v64
	v_fma_f32 v63, -v63, v70, v69
	v_div_fmas_f32 v63, v63, v64, v70
	v_div_fixup_f32 v63, v63, v50, v67
	v_mul_f32_e32 v50, 0xbfb8aa3b, v55
	v_exp_f32_e32 v50, v50
	s_nop 0
	v_add_f32_e32 v50, 1.0, v50
	v_div_scale_f32 v55, s[12:13], v50, v50, v65
	v_rcp_f32_e32 v64, v55
	s_nop 0
	v_fma_f32 v67, -v55, v64, 1.0
	v_fmac_f32_e32 v64, v67, v64
	v_div_scale_f32 v67, vcc, v65, v50, v65
	v_mul_f32_e32 v69, v67, v64
	v_fma_f32 v70, -v55, v69, v67
	v_fmac_f32_e32 v69, v70, v64
	v_fma_f32 v55, -v55, v69, v67
	v_div_fmas_f32 v55, v55, v64, v69
	v_div_fixup_f32 v50, v55, v50, v65
	v_div_scale_f32 v55, s[12:13], v51, v51, v62
	v_rcp_f32_e32 v64, v55
	v_cvt_pk_bf16_f32 v50, v54, v50
	s_nop 0
	v_fma_f32 v65, -v55, v64, 1.0
	v_fmac_f32_e32 v64, v65, v64
	v_div_scale_f32 v65, vcc, v62, v51, v62
	v_mul_f32_e32 v67, v65, v64
	v_fma_f32 v69, -v55, v67, v65
	v_fmac_f32_e32 v67, v69, v64
	v_fma_f32 v55, -v55, v67, v65
	v_div_fmas_f32 v55, v55, v64, v67
	v_div_fixup_f32 v55, v55, v51, v62
	v_mul_f32_e32 v51, 0xbfb8aa3b, v56
	v_exp_f32_e32 v51, v51
	s_nop 0
	v_add_f32_e32 v51, 1.0, v51
	v_div_scale_f32 v56, s[12:13], v51, v51, v66
	v_rcp_f32_e32 v62, v56
	s_nop 0
	v_fma_f32 v64, -v56, v62, 1.0
	v_fmac_f32_e32 v62, v64, v62
	v_div_scale_f32 v64, vcc, v66, v51, v66
	v_mul_f32_e32 v65, v64, v62
	v_fma_f32 v67, -v56, v65, v64
	v_fmac_f32_e32 v65, v67, v62
	v_fma_f32 v56, -v56, v65, v64
	v_div_fmas_f32 v56, v56, v62, v65
	v_div_fixup_f32 v51, v56, v51, v66
	v_div_scale_f32 v56, s[12:13], v52, v52, v68
	v_rcp_f32_e32 v62, v56
	s_nop 0
	v_fma_f32 v64, -v56, v62, 1.0
	v_fmac_f32_e32 v62, v64, v62
	v_div_scale_f32 v64, vcc, v68, v52, v68
	v_mul_f32_e32 v65, v64, v62
	v_fma_f32 v66, -v56, v65, v64
	v_fmac_f32_e32 v65, v66, v62
	v_fma_f32 v56, -v56, v65, v64
	v_div_fmas_f32 v56, v56, v62, v65
	v_div_fixup_f32 v56, v56, v52, v68
	v_mul_f32_e32 v52, 0xbfb8aa3b, v57
	v_exp_f32_e32 v52, v52
	s_nop 0
	v_add_f32_e32 v52, 1.0, v52
	v_div_scale_f32 v57, s[12:13], v52, v52, v61
	v_rcp_f32_e32 v62, v57
	s_nop 0
	v_fma_f32 v64, -v57, v62, 1.0
	v_fmac_f32_e32 v62, v64, v62
	v_div_scale_f32 v64, vcc, v61, v52, v61
	v_mul_f32_e32 v65, v64, v62
	v_fma_f32 v66, -v57, v65, v64
	v_fmac_f32_e32 v65, v66, v62
	v_fma_f32 v57, -v57, v65, v64
	v_div_fmas_f32 v57, v57, v62, v65
	v_div_fixup_f32 v52, v57, v52, v61
	v_div_scale_f32 v57, s[12:13], v53, v53, v60
	v_rcp_f32_e32 v61, v57
	v_cvt_pk_bf16_f32 v51, v51, v52
	v_cvt_pk_bf16_f32 v52, v63, v55
	s_nop 0
	v_fma_f32 v62, -v57, v61, 1.0
	v_fmac_f32_e32 v61, v62, v61
	v_div_scale_f32 v62, vcc, v60, v53, v60
	v_mul_f32_e32 v64, v62, v61
	v_fma_f32 v65, -v57, v64, v62
	v_fmac_f32_e32 v64, v65, v61
	v_fma_f32 v57, -v57, v64, v62
	v_div_fmas_f32 v57, v57, v61, v64
	v_div_fixup_f32 v53, v57, v53, v60
	v_cvt_pk_bf16_f32 v53, v56, v53
	global_store_dwordx4 v[58:59], v[50:53], off offset:2304
	s_nop 1
	v_add_u32_e32 v50, 0x90, v144
	v_ashrrev_i32_e32 v51, 31, v50
	v_lshlrev_b64 v[54:55], 11, v[50:51]
	v_lshlrev_b64 v[52:53], 12, v[50:51]
	v_lshl_add_u64 v[50:51], s[86:87], 0, v[54:55]
	v_lshl_add_u64 v[50:51], v[50:51], 0, v[142:143]
	global_load_dwordx4 v[54:57], v[50:51], off
	s_waitcnt vmcnt(0)
; __device__ __forceinline__ unsigned cvt_pk_bf16(float lo, float hi) { unsigned r; asm volatile("v_cvt_pk_bf16_f32 %0, %1, %2" : "=v"(r) : "v"(lo), "v"(hi)); return r; }
; __device__ __forceinline__ float bf_lo(unsigned w) { return __uint_as_float(w << 16); }
; __device__ __forceinline__ float bf_hi(unsigned w) { return __uint_as_float(w & 0xffff0000u); }
;     __device__ __forceinline__ void operator()(const f32x4 (&acc)[2][2][4][2], const Unit& u, int ui, const LAS float* rtab, int wr, int wc, int fr, int fq) const {
;     ...
; #pragma unroll
;         for (int ai = 0; ai < 2; ++ai)
; #pragma unroll
;             for (int m = 0; m < 4; ++m) {
;                 const int row = row0 + ai * HALF + m * 16;
; #pragma unroll
;                 for (int bj = 0; bj < 2; ++bj) {
;                     const int col = col0 + bj * HALF; const u32x4 yv = *(const u32x4*)(Y + (size_t)row * 1024 + col);
;                     const f32x4 a0 = acc[ai][bj][m][0], a1 = acc[ai][bj][m][1]; float o[8];
;                     const float yy[8] = {bf_lo(yv.x), bf_hi(yv.x), bf_lo(yv.y), bf_hi(yv.y), bf_lo(yv.z), bf_hi(yv.z), bf_lo(yv.w), bf_hi(yv.w)};
; #pragma unroll
;                     for (int e = 0; e < 4; ++e) { o[e] = yy[e] / (1.0f + __expf(-a0[e])); o[4 + e] = yy[4 + e] / (1.0f + __expf(-a1[e])); }
;                     u32x4 w; w.x = cvt_pk_bf16(o[0], o[1]); w.y = cvt_pk_bf16(o[2], o[3]); w.z = cvt_pk_bf16(o[4], o[5]); w.w = cvt_pk_bf16(o[6], o[7]);
;                     *(u32x4*)(MG + (size_t)row * DM + 1024 + col) = w;
	v_lshlrev_b32_e32 v58, 16, v54
	v_and_b32_e32 v59, 0xffff0000, v54
	v_lshlrev_b32_e32 v62, 16, v57
	v_and_b32_e32 v54, 0xffff0000, v57
	v_div_scale_f32 v57, s[12:13], v46, v46, v58
	v_rcp_f32_e32 v63, v57
	v_lshlrev_b32_e32 v61, 16, v56
	v_and_b32_e32 v56, 0xffff0000, v56
	v_lshlrev_b32_e32 v60, 16, v55
	v_fma_f32 v64, -v57, v63, 1.0
	v_fmac_f32_e32 v63, v64, v63
	v_div_scale_f32 v64, vcc, v58, v46, v58
	v_mul_f32_e32 v65, v64, v63
	v_fma_f32 v66, -v57, v65, v64
	v_fmac_f32_e32 v65, v66, v63
	v_fma_f32 v57, -v57, v65, v64
	v_div_fmas_f32 v57, v57, v63, v65
	v_div_fixup_f32 v46, v57, v46, v58
	v_div_scale_f32 v57, s[12:13], v42, v42, v61
	v_rcp_f32_e32 v58, v57
	v_and_b32_e32 v55, 0xffff0000, v55
	v_fma_f32 v63, -v57, v58, 1.0
	v_fmac_f32_e32 v58, v63, v58
	v_div_scale_f32 v63, vcc, v61, v42, v61
	v_mul_f32_e32 v64, v63, v58
	v_fma_f32 v65, -v57, v64, v63
	v_fmac_f32_e32 v64, v65, v58
	v_fma_f32 v57, -v57, v64, v63
	v_div_fmas_f32 v57, v57, v58, v64
	v_div_fixup_f32 v42, v57, v42, v61
	v_div_scale_f32 v57, s[12:13], v47, v47, v59
	v_rcp_f32_e32 v58, v57
	s_nop 0
	v_fma_f32 v61, -v57, v58, 1.0
	v_fmac_f32_e32 v58, v61, v58
	v_div_scale_f32 v61, vcc, v59, v47, v59
	v_mul_f32_e32 v63, v61, v58
	v_fma_f32 v64, -v57, v63, v61
	v_fmac_f32_e32 v63, v64, v58
	v_fma_f32 v57, -v57, v63, v61
	v_div_fmas_f32 v57, v57, v58, v63
	v_div_fixup_f32 v47, v57, v47, v59
	v_div_scale_f32 v57, s[12:13], v43, v43, v56
	v_rcp_f32_e32 v58, v57
	s_nop 0
	v_fma_f32 v59, -v57, v58, 1.0
	v_fmac_f32_e32 v58, v59, v58
	v_div_scale_f32 v59, vcc, v56, v43, v56
	v_mul_f32_e32 v61, v59, v58
	v_fma_f32 v63, -v57, v61, v59
	v_fmac_f32_e32 v61, v63, v58
	v_fma_f32 v57, -v57, v61, v59
	v_div_fmas_f32 v57, v57, v58, v61
	v_div_fixup_f32 v43, v57, v43, v56
	v_div_scale_f32 v56, s[12:13], v48, v48, v60
	v_rcp_f32_e32 v57, v56
	s_nop 0
	v_fma_f32 v58, -v56, v57, 1.0
	v_fmac_f32_e32 v57, v58, v57
	v_div_scale_f32 v58, vcc, v60, v48, v60
	v_mul_f32_e32 v59, v58, v57
	v_fma_f32 v61, -v56, v59, v58
	v_fmac_f32_e32 v59, v61, v57
	v_fma_f32 v56, -v56, v59, v58
	v_div_fmas_f32 v56, v56, v57, v59
	v_div_fixup_f32 v48, v56, v48, v60
	v_div_scale_f32 v56, s[12:13], v44, v44, v62
	v_rcp_f32_e32 v57, v56
	s_nop 0
	v_fma_f32 v58, -v56, v57, 1.0
	v_fmac_f32_e32 v57, v58, v57
	v_div_scale_f32 v58, vcc, v62, v44, v62
	v_mul_f32_e32 v59, v58, v57
	v_fma_f32 v60, -v56, v59, v58
	v_fmac_f32_e32 v59, v60, v57
	v_fma_f32 v56, -v56, v59, v58
	v_div_fmas_f32 v56, v56, v57, v59
	v_div_fixup_f32 v56, v56, v44, v62
	v_mul_f32_e32 v44, 0xbfb8aa3b, v49
	v_exp_f32_e32 v44, v44
	s_nop 0
	v_add_f32_e32 v44, 1.0, v44
	v_div_scale_f32 v49, s[12:13], v44, v44, v55
	v_rcp_f32_e32 v57, v49
	s_nop 0
	v_fma_f32 v58, -v49, v57, 1.0
	v_fmac_f32_e32 v57, v58, v57
	v_div_scale_f32 v58, vcc, v55, v44, v55
	v_mul_f32_e32 v59, v58, v57
	v_fma_f32 v60, -v49, v59, v58
	v_fmac_f32_e32 v59, v60, v57
	v_fma_f32 v49, -v49, v59, v58
	v_div_fmas_f32 v49, v49, v57, v59
	v_div_fixup_f32 v49, v49, v44, v55
	v_mul_f32_e32 v44, 0xbfb8aa3b, v45
	v_exp_f32_e32 v44, v44
	s_nop 0
	v_add_f32_e32 v44, 1.0, v44
	v_div_scale_f32 v45, s[12:13], v44, v44, v54
	v_rcp_f32_e32 v55, v45
	s_nop 0
	v_fma_f32 v57, -v45, v55, 1.0
	v_fmac_f32_e32 v55, v57, v55
	v_div_scale_f32 v57, vcc, v54, v44, v54
	v_mul_f32_e32 v58, v57, v55
	v_fma_f32 v59, -v45, v58, v57
	v_fmac_f32_e32 v58, v59, v55
	v_fma_f32 v45, -v45, v58, v57
	v_div_fmas_f32 v45, v45, v55, v58
	v_div_fixup_f32 v54, v45, v44, v54
	v_cvt_pk_bf16_f32 v44, v46, v47
	v_cvt_pk_bf16_f32 v45, v48, v49
	v_cvt_pk_bf16_f32 v46, v42, v43
	v_lshl_add_u64 v[42:43], s[88:89], 0, v[52:53]
	v_cvt_pk_bf16_f32 v47, v56, v54
	v_lshl_add_u64 v[42:43], v[42:43], 0, v[142:143]
	global_store_dwordx4 v[42:43], v[44:47], off offset:2048
	global_load_dwordx4 v[44:47], v[50:51], off offset:256
	s_waitcnt vmcnt(0)
	v_lshlrev_b32_e32 v48, 16, v44
	v_and_b32_e32 v49, 0xffff0000, v44
	v_lshlrev_b32_e32 v52, 16, v47
	v_and_b32_e32 v44, 0xffff0000, v47
	v_div_scale_f32 v47, s[12:13], v38, v38, v48
	v_rcp_f32_e32 v53, v47
	v_lshlrev_b32_e32 v51, 16, v46
	v_and_b32_e32 v46, 0xffff0000, v46
	v_lshlrev_b32_e32 v50, 16, v45
	v_fma_f32 v54, -v47, v53, 1.0
	v_fmac_f32_e32 v53, v54, v53
	v_div_scale_f32 v54, vcc, v48, v38, v48
	v_mul_f32_e32 v55, v54, v53
	v_fma_f32 v56, -v47, v55, v54
	v_fmac_f32_e32 v55, v56, v53
	v_fma_f32 v47, -v47, v55, v54
	v_div_fmas_f32 v47, v47, v53, v55
	v_div_fixup_f32 v38, v47, v38, v48
	v_div_scale_f32 v47, s[12:13], v34, v34, v51
	v_rcp_f32_e32 v48, v47
	v_and_b32_e32 v45, 0xffff0000, v45
	v_fma_f32 v53, -v47, v48, 1.0
	v_fmac_f32_e32 v48, v53, v48
	v_div_scale_f32 v53, vcc, v51, v34, v51
	v_mul_f32_e32 v54, v53, v48
	v_fma_f32 v55, -v47, v54, v53
	v_fmac_f32_e32 v54, v55, v48
	v_fma_f32 v47, -v47, v54, v53
	v_div_fmas_f32 v47, v47, v48, v54
	v_div_fixup_f32 v47, v47, v34, v51
	v_mul_f32_e32 v34, 0xbfb8aa3b, v39
	v_exp_f32_e32 v34, v34
	s_nop 0
	v_add_f32_e32 v34, 1.0, v34
	v_div_scale_f32 v39, s[12:13], v34, v34, v49
	v_rcp_f32_e32 v48, v39
	s_nop 0
	v_fma_f32 v51, -v39, v48, 1.0
	v_fmac_f32_e32 v48, v51, v48
	v_div_scale_f32 v51, vcc, v49, v34, v49
	v_mul_f32_e32 v53, v51, v48
	v_fma_f32 v54, -v39, v53, v51
	v_fmac_f32_e32 v53, v54, v48
	v_fma_f32 v39, -v39, v53, v51
	v_div_fmas_f32 v39, v39, v48, v53
	v_div_fixup_f32 v34, v39, v34, v49
	v_div_scale_f32 v39, s[12:13], v35, v35, v46
	v_rcp_f32_e32 v48, v39
	v_cvt_pk_bf16_f32 v34, v38, v34
	s_nop 0
	v_fma_f32 v49, -v39, v48, 1.0
	v_fmac_f32_e32 v48, v49, v48
	v_div_scale_f32 v49, vcc, v46, v35, v46
	v_mul_f32_e32 v51, v49, v48
	v_fma_f32 v53, -v39, v51, v49
	v_fmac_f32_e32 v51, v53, v48
	v_fma_f32 v39, -v39, v51, v49
	v_div_fmas_f32 v39, v39, v48, v51
; __device__ __forceinline__ unsigned cvt_pk_bf16(float lo, float hi) { unsigned r; asm volatile("v_cvt_pk_bf16_f32 %0, %1, %2" : "=v"(r) : "v"(lo), "v"(hi)); return r; }
; __device__ __forceinline__ float bf_lo(unsigned w) { return __uint_as_float(w << 16); }
; __device__ __forceinline__ float bf_hi(unsigned w) { return __uint_as_float(w & 0xffff0000u); }
;     __device__ __forceinline__ void operator()(const f32x4 (&acc)[2][2][4][2], const Unit& u, int ui, const LAS float* rtab, int wr, int wc, int fr, int fq) const {
;     ...
; #pragma unroll
;         for (int ai = 0; ai < 2; ++ai)
; #pragma unroll
;             for (int m = 0; m < 4; ++m) {
;                 const int row = row0 + ai * HALF + m * 16;
; #pragma unroll
;                 for (int bj = 0; bj < 2; ++bj) {
;                     const int col = col0 + bj * HALF; const u32x4 yv = *(const u32x4*)(Y + (size_t)row * 1024 + col);
;                     const f32x4 a0 = acc[ai][bj][m][0], a1 = acc[ai][bj][m][1]; float o[8];
;                     const float yy[8] = {bf_lo(yv.x), bf_hi(yv.x), bf_lo(yv.y), bf_hi(yv.y), bf_lo(yv.z), bf_hi(yv.z), bf_lo(yv.w), bf_hi(yv.w)};
; #pragma unroll
;                     for (int e = 0; e < 4; ++e) { o[e] = yy[e] / (1.0f + __expf(-a0[e])); o[4 + e] = yy[4 + e] / (1.0f + __expf(-a1[e])); }
;                     u32x4 w; w.x = cvt_pk_bf16(o[0], o[1]); w.y = cvt_pk_bf16(o[2], o[3]); w.z = cvt_pk_bf16(o[4], o[5]); w.w = cvt_pk_bf16(o[6], o[7]);
;                     *(u32x4*)(MG + (size_t)row * DM + 1024 + col) = w;
	v_div_fixup_f32 v39, v39, v35, v46
	v_mul_f32_e32 v35, 0xbfb8aa3b, v40
	v_exp_f32_e32 v35, v35
	s_nop 0
	v_add_f32_e32 v35, 1.0, v35
	v_div_scale_f32 v40, s[12:13], v35, v35, v50
	v_rcp_f32_e32 v46, v40
	s_nop 0
	v_fma_f32 v48, -v40, v46, 1.0
	v_fmac_f32_e32 v46, v48, v46
	v_div_scale_f32 v48, vcc, v50, v35, v50
	v_mul_f32_e32 v49, v48, v46
	v_fma_f32 v51, -v40, v49, v48
	v_fmac_f32_e32 v49, v51, v46
	v_fma_f32 v40, -v40, v49, v48
	v_div_fmas_f32 v40, v40, v46, v49
	v_div_fixup_f32 v35, v40, v35, v50
	v_div_scale_f32 v40, s[12:13], v36, v36, v52
	v_rcp_f32_e32 v46, v40
	s_nop 0
	v_fma_f32 v48, -v40, v46, 1.0
	v_fmac_f32_e32 v46, v48, v46
	v_div_scale_f32 v48, vcc, v52, v36, v52
	v_mul_f32_e32 v49, v48, v46
	v_fma_f32 v50, -v40, v49, v48
	v_fmac_f32_e32 v49, v50, v46
	v_fma_f32 v40, -v40, v49, v48
	v_div_fmas_f32 v40, v40, v46, v49
	v_div_fixup_f32 v40, v40, v36, v52
	v_mul_f32_e32 v36, 0xbfb8aa3b, v41
	v_exp_f32_e32 v36, v36
	s_nop 0
	v_add_f32_e32 v36, 1.0, v36
	v_div_scale_f32 v41, s[12:13], v36, v36, v45
	v_rcp_f32_e32 v46, v41
	s_nop 0
	v_fma_f32 v48, -v41, v46, 1.0
	v_fmac_f32_e32 v46, v48, v46
	v_div_scale_f32 v48, vcc, v45, v36, v45
	v_mul_f32_e32 v49, v48, v46
	v_fma_f32 v50, -v41, v49, v48
	v_fmac_f32_e32 v49, v50, v46
	v_fma_f32 v41, -v41, v49, v48
	v_div_fmas_f32 v41, v41, v46, v49
	v_div_fixup_f32 v36, v41, v36, v45
	v_div_scale_f32 v41, s[12:13], v37, v37, v44
	v_rcp_f32_e32 v45, v41
	v_cvt_pk_bf16_f32 v35, v35, v36
	v_cvt_pk_bf16_f32 v36, v47, v39
	s_nop 0
	v_fma_f32 v46, -v41, v45, 1.0
	v_fmac_f32_e32 v45, v46, v45
	v_div_scale_f32 v46, vcc, v44, v37, v44
	v_mul_f32_e32 v48, v46, v45
	v_fma_f32 v49, -v41, v48, v46
	v_fmac_f32_e32 v48, v49, v45
	v_fma_f32 v41, -v41, v48, v46
	v_div_fmas_f32 v41, v41, v45, v48
	v_div_fixup_f32 v37, v41, v37, v44
	v_cvt_pk_bf16_f32 v37, v40, v37
	global_store_dwordx4 v[42:43], v[34:37], off offset:2304
	s_nop 1
	v_add_u32_e32 v34, 0xa0, v144
	v_ashrrev_i32_e32 v35, 31, v34
	v_lshlrev_b64 v[38:39], 11, v[34:35]
	v_lshlrev_b64 v[36:37], 12, v[34:35]
	v_lshl_add_u64 v[34:35], s[86:87], 0, v[38:39]
	v_lshl_add_u64 v[34:35], v[34:35], 0, v[142:143]
	global_load_dwordx4 v[38:41], v[34:35], off
	s_waitcnt vmcnt(0)
	v_lshlrev_b32_e32 v42, 16, v38
	v_and_b32_e32 v43, 0xffff0000, v38
	v_lshlrev_b32_e32 v46, 16, v41
	v_and_b32_e32 v38, 0xffff0000, v41
	v_div_scale_f32 v41, s[12:13], v30, v30, v42
	v_rcp_f32_e32 v47, v41
	v_lshlrev_b32_e32 v45, 16, v40
	v_and_b32_e32 v40, 0xffff0000, v40
	v_lshlrev_b32_e32 v44, 16, v39
	v_fma_f32 v48, -v41, v47, 1.0
	v_fmac_f32_e32 v47, v48, v47
	v_div_scale_f32 v48, vcc, v42, v30, v42
	v_mul_f32_e32 v49, v48, v47
	v_fma_f32 v50, -v41, v49, v48
	v_fmac_f32_e32 v49, v50, v47
	v_fma_f32 v41, -v41, v49, v48
	v_div_fmas_f32 v41, v41, v47, v49
	v_div_fixup_f32 v30, v41, v30, v42
	v_div_scale_f32 v41, s[12:13], v26, v26, v45
	v_rcp_f32_e32 v42, v41
	v_and_b32_e32 v39, 0xffff0000, v39
	v_fma_f32 v47, -v41, v42, 1.0
	v_fmac_f32_e32 v42, v47, v42
	v_div_scale_f32 v47, vcc, v45, v26, v45
	v_mul_f32_e32 v48, v47, v42
	v_fma_f32 v49, -v41, v48, v47
	v_fmac_f32_e32 v48, v49, v42
	v_fma_f32 v41, -v41, v48, v47
	v_div_fmas_f32 v41, v41, v42, v48
	v_div_fixup_f32 v26, v41, v26, v45
	v_div_scale_f32 v41, s[12:13], v31, v31, v43
	v_rcp_f32_e32 v42, v41
	s_nop 0
	v_fma_f32 v45, -v41, v42, 1.0
	v_fmac_f32_e32 v42, v45, v42
	v_div_scale_f32 v45, vcc, v43, v31, v43
	v_mul_f32_e32 v47, v45, v42
	v_fma_f32 v48, -v41, v47, v45
	v_fmac_f32_e32 v47, v48, v42
	v_fma_f32 v41, -v41, v47, v45
	v_div_fmas_f32 v41, v41, v42, v47
	v_div_fixup_f32 v31, v41, v31, v43
	v_div_scale_f32 v41, s[12:13], v27, v27, v40
	v_rcp_f32_e32 v42, v41
	s_nop 0
	v_fma_f32 v43, -v41, v42, 1.0
	v_fmac_f32_e32 v42, v43, v42
	v_div_scale_f32 v43, vcc, v40, v27, v40
	v_mul_f32_e32 v45, v43, v42
	v_fma_f32 v47, -v41, v45, v43
	v_fmac_f32_e32 v45, v47, v42
	v_fma_f32 v41, -v41, v45, v43
	v_div_fmas_f32 v41, v41, v42, v45
	v_div_fixup_f32 v27, v41, v27, v40
	v_div_scale_f32 v40, s[12:13], v32, v32, v44
	v_rcp_f32_e32 v41, v40
	s_nop 0
	v_fma_f32 v42, -v40, v41, 1.0
	v_fmac_f32_e32 v41, v42, v41
	v_div_scale_f32 v42, vcc, v44, v32, v44
	v_mul_f32_e32 v43, v42, v41
	v_fma_f32 v45, -v40, v43, v42
	v_fmac_f32_e32 v43, v45, v41
	v_fma_f32 v40, -v40, v43, v42
	v_div_fmas_f32 v40, v40, v41, v43
	v_div_fixup_f32 v32, v40, v32, v44
	v_div_scale_f32 v40, s[12:13], v28, v28, v46
	v_rcp_f32_e32 v41, v40
	s_nop 0
	v_fma_f32 v42, -v40, v41, 1.0
	v_fmac_f32_e32 v41, v42, v41
	v_div_scale_f32 v42, vcc, v46, v28, v46
	v_mul_f32_e32 v43, v42, v41
	v_fma_f32 v44, -v40, v43, v42
	v_fmac_f32_e32 v43, v44, v41
	v_fma_f32 v40, -v40, v43, v42
	v_div_fmas_f32 v40, v40, v41, v43
	v_div_fixup_f32 v40, v40, v28, v46
	v_mul_f32_e32 v28, 0xbfb8aa3b, v33
	v_exp_f32_e32 v28, v28
	s_nop 0
	v_add_f32_e32 v28, 1.0, v28
	v_div_scale_f32 v33, s[12:13], v28, v28, v39
	v_rcp_f32_e32 v41, v33
	s_nop 0
	v_fma_f32 v42, -v33, v41, 1.0
	v_fmac_f32_e32 v41, v42, v41
	v_div_scale_f32 v42, vcc, v39, v28, v39
	v_mul_f32_e32 v43, v42, v41
	v_fma_f32 v44, -v33, v43, v42
	v_fmac_f32_e32 v43, v44, v41
	v_fma_f32 v33, -v33, v43, v42
	v_div_fmas_f32 v33, v33, v41, v43
	v_div_fixup_f32 v33, v33, v28, v39
	v_mul_f32_e32 v28, 0xbfb8aa3b, v29
	v_exp_f32_e32 v28, v28
	s_nop 0
	v_add_f32_e32 v28, 1.0, v28
	v_div_scale_f32 v29, s[12:13], v28, v28, v38
	v_rcp_f32_e32 v39, v29
	s_nop 0
	v_fma_f32 v41, -v29, v39, 1.0
	v_fmac_f32_e32 v39, v41, v39
	v_div_scale_f32 v41, vcc, v38, v28, v38
	v_mul_f32_e32 v42, v41, v39
	v_fma_f32 v43, -v29, v42, v41
	v_fmac_f32_e32 v42, v43, v39
	v_fma_f32 v29, -v29, v42, v41
	v_div_fmas_f32 v29, v29, v39, v42
	v_div_fixup_f32 v38, v29, v28, v38
	v_cvt_pk_bf16_f32 v28, v30, v31
	v_cvt_pk_bf16_f32 v29, v32, v33
	v_cvt_pk_bf16_f32 v30, v26, v27
	v_lshl_add_u64 v[26:27], s[88:89], 0, v[36:37]
	v_cvt_pk_bf16_f32 v31, v40, v38
	v_lshl_add_u64 v[26:27], v[26:27], 0, v[142:143]
	global_store_dwordx4 v[26:27], v[28:31], off offset:2048
	global_load_dwordx4 v[28:31], v[34:35], off offset:256
	s_waitcnt vmcnt(0)
; __device__ __forceinline__ unsigned cvt_pk_bf16(float lo, float hi) { unsigned r; asm volatile("v_cvt_pk_bf16_f32 %0, %1, %2" : "=v"(r) : "v"(lo), "v"(hi)); return r; }
; __device__ __forceinline__ float bf_lo(unsigned w) { return __uint_as_float(w << 16); }
; __device__ __forceinline__ float bf_hi(unsigned w) { return __uint_as_float(w & 0xffff0000u); }
;     __device__ __forceinline__ void operator()(const f32x4 (&acc)[2][2][4][2], const Unit& u, int ui, const LAS float* rtab, int wr, int wc, int fr, int fq) const {
;     ...
; #pragma unroll
;         for (int ai = 0; ai < 2; ++ai)
; #pragma unroll
;             for (int m = 0; m < 4; ++m) {
;                 const int row = row0 + ai * HALF + m * 16;
; #pragma unroll
;                 for (int bj = 0; bj < 2; ++bj) {
;                     const int col = col0 + bj * HALF; const u32x4 yv = *(const u32x4*)(Y + (size_t)row * 1024 + col);
;                     const f32x4 a0 = acc[ai][bj][m][0], a1 = acc[ai][bj][m][1]; float o[8];
;                     const float yy[8] = {bf_lo(yv.x), bf_hi(yv.x), bf_lo(yv.y), bf_hi(yv.y), bf_lo(yv.z), bf_hi(yv.z), bf_lo(yv.w), bf_hi(yv.w)};
; #pragma unroll
;                     for (int e = 0; e < 4; ++e) { o[e] = yy[e] / (1.0f + __expf(-a0[e])); o[4 + e] = yy[4 + e] / (1.0f + __expf(-a1[e])); }
;                     u32x4 w; w.x = cvt_pk_bf16(o[0], o[1]); w.y = cvt_pk_bf16(o[2], o[3]); w.z = cvt_pk_bf16(o[4], o[5]); w.w = cvt_pk_bf16(o[6], o[7]);
;                     *(u32x4*)(MG + (size_t)row * DM + 1024 + col) = w;
	v_lshlrev_b32_e32 v32, 16, v28
	v_and_b32_e32 v33, 0xffff0000, v28
	v_lshlrev_b32_e32 v36, 16, v31
	v_and_b32_e32 v28, 0xffff0000, v31
	v_div_scale_f32 v31, s[12:13], v22, v22, v32
	v_rcp_f32_e32 v37, v31
	v_lshlrev_b32_e32 v35, 16, v30
	v_and_b32_e32 v30, 0xffff0000, v30
	v_lshlrev_b32_e32 v34, 16, v29
	v_fma_f32 v38, -v31, v37, 1.0
	v_fmac_f32_e32 v37, v38, v37
	v_div_scale_f32 v38, vcc, v32, v22, v32
	v_mul_f32_e32 v39, v38, v37
	v_fma_f32 v40, -v31, v39, v38
	v_fmac_f32_e32 v39, v40, v37
	v_fma_f32 v31, -v31, v39, v38
	v_div_fmas_f32 v31, v31, v37, v39
	v_div_fixup_f32 v22, v31, v22, v32
	v_div_scale_f32 v31, s[12:13], v18, v18, v35
	v_rcp_f32_e32 v32, v31
	v_and_b32_e32 v29, 0xffff0000, v29
	v_fma_f32 v37, -v31, v32, 1.0
	v_fmac_f32_e32 v32, v37, v32
	v_div_scale_f32 v37, vcc, v35, v18, v35
	v_mul_f32_e32 v38, v37, v32
	v_fma_f32 v39, -v31, v38, v37
	v_fmac_f32_e32 v38, v39, v32
	v_fma_f32 v31, -v31, v38, v37
	v_div_fmas_f32 v31, v31, v32, v38
	v_div_fixup_f32 v31, v31, v18, v35
	v_mul_f32_e32 v18, 0xbfb8aa3b, v23
	v_exp_f32_e32 v18, v18
	s_nop 0
	v_add_f32_e32 v18, 1.0, v18
	v_div_scale_f32 v23, s[12:13], v18, v18, v33
	v_rcp_f32_e32 v32, v23
	s_nop 0
	v_fma_f32 v35, -v23, v32, 1.0
	v_fmac_f32_e32 v32, v35, v32
	v_div_scale_f32 v35, vcc, v33, v18, v33
	v_mul_f32_e32 v37, v35, v32
	v_fma_f32 v38, -v23, v37, v35
	v_fmac_f32_e32 v37, v38, v32
	v_fma_f32 v23, -v23, v37, v35
	v_div_fmas_f32 v23, v23, v32, v37
	v_div_fixup_f32 v18, v23, v18, v33
	v_div_scale_f32 v23, s[12:13], v19, v19, v30
	v_rcp_f32_e32 v32, v23
	v_cvt_pk_bf16_f32 v18, v22, v18
	s_nop 0
	v_fma_f32 v33, -v23, v32, 1.0
	v_fmac_f32_e32 v32, v33, v32
	v_div_scale_f32 v33, vcc, v30, v19, v30
	v_mul_f32_e32 v35, v33, v32
	v_fma_f32 v37, -v23, v35, v33
	v_fmac_f32_e32 v35, v37, v32
	v_fma_f32 v23, -v23, v35, v33
	v_div_fmas_f32 v23, v23, v32, v35
	v_div_fixup_f32 v23, v23, v19, v30
	v_mul_f32_e32 v19, 0xbfb8aa3b, v24
	v_exp_f32_e32 v19, v19
	s_nop 0
	v_add_f32_e32 v19, 1.0, v19
	v_div_scale_f32 v24, s[12:13], v19, v19, v34
	v_rcp_f32_e32 v30, v24
	s_nop 0
	v_fma_f32 v32, -v24, v30, 1.0
	v_fmac_f32_e32 v30, v32, v30
	v_div_scale_f32 v32, vcc, v34, v19, v34
	v_mul_f32_e32 v33, v32, v30
	v_fma_f32 v35, -v24, v33, v32
	v_fmac_f32_e32 v33, v35, v30
	v_fma_f32 v24, -v24, v33, v32
	v_div_fmas_f32 v24, v24, v30, v33
	v_div_fixup_f32 v19, v24, v19, v34
	v_div_scale_f32 v24, s[12:13], v20, v20, v36
	v_rcp_f32_e32 v30, v24
	s_nop 0
	v_fma_f32 v32, -v24, v30, 1.0
	v_fmac_f32_e32 v30, v32, v30
	v_div_scale_f32 v32, vcc, v36, v20, v36
	v_mul_f32_e32 v33, v32, v30
	v_fma_f32 v34, -v24, v33, v32
	v_fmac_f32_e32 v33, v34, v30
	v_fma_f32 v24, -v24, v33, v32
	v_div_fmas_f32 v24, v24, v30, v33
	v_div_fixup_f32 v24, v24, v20, v36
	v_mul_f32_e32 v20, 0xbfb8aa3b, v25
	v_exp_f32_e32 v20, v20
	s_nop 0
	v_add_f32_e32 v20, 1.0, v20
	v_div_scale_f32 v25, s[12:13], v20, v20, v29
	v_rcp_f32_e32 v30, v25
	s_nop 0
	v_fma_f32 v32, -v25, v30, 1.0
	v_fmac_f32_e32 v30, v32, v30
	v_div_scale_f32 v32, vcc, v29, v20, v29
	v_mul_f32_e32 v33, v32, v30
	v_fma_f32 v34, -v25, v33, v32
	v_fmac_f32_e32 v33, v34, v30
	v_fma_f32 v25, -v25, v33, v32
	v_div_fmas_f32 v25, v25, v30, v33
	v_div_fixup_f32 v20, v25, v20, v29
	v_div_scale_f32 v25, s[12:13], v21, v21, v28
	v_rcp_f32_e32 v29, v25
	v_cvt_pk_bf16_f32 v19, v19, v20
	v_cvt_pk_bf16_f32 v20, v31, v23
	s_nop 0
	v_fma_f32 v30, -v25, v29, 1.0
	v_fmac_f32_e32 v29, v30, v29
	v_div_scale_f32 v30, vcc, v28, v21, v28
	v_mul_f32_e32 v32, v30, v29
	v_fma_f32 v33, -v25, v32, v30
	v_fmac_f32_e32 v32, v33, v29
	v_fma_f32 v25, -v25, v32, v30
	v_div_fmas_f32 v25, v25, v29, v32
	v_div_fixup_f32 v21, v25, v21, v28
	v_cvt_pk_bf16_f32 v21, v24, v21
	global_store_dwordx4 v[26:27], v[18:21], off offset:2304
	s_nop 1
	v_add_u32_e32 v18, 0xb0, v144
	v_ashrrev_i32_e32 v19, 31, v18
	v_lshlrev_b64 v[22:23], 11, v[18:19]
	v_lshlrev_b64 v[20:21], 12, v[18:19]
	v_lshl_add_u64 v[18:19], s[86:87], 0, v[22:23]
	v_lshl_add_u64 v[18:19], v[18:19], 0, v[142:143]
	global_load_dwordx4 v[22:25], v[18:19], off
	s_waitcnt vmcnt(0)
	v_lshlrev_b32_e32 v26, 16, v22
	v_and_b32_e32 v27, 0xffff0000, v22
	v_lshlrev_b32_e32 v30, 16, v25
	v_and_b32_e32 v22, 0xffff0000, v25
	v_div_scale_f32 v25, s[12:13], v14, v14, v26
	v_rcp_f32_e32 v31, v25
	v_lshlrev_b32_e32 v29, 16, v24
	v_and_b32_e32 v24, 0xffff0000, v24
	v_lshlrev_b32_e32 v28, 16, v23
	v_fma_f32 v32, -v25, v31, 1.0
	v_fmac_f32_e32 v31, v32, v31
	v_div_scale_f32 v32, vcc, v26, v14, v26
	v_mul_f32_e32 v33, v32, v31
	v_fma_f32 v34, -v25, v33, v32
	v_fmac_f32_e32 v33, v34, v31
	v_fma_f32 v25, -v25, v33, v32
	v_div_fmas_f32 v25, v25, v31, v33
	v_div_fixup_f32 v14, v25, v14, v26
	v_div_scale_f32 v25, s[12:13], v10, v10, v29
	v_rcp_f32_e32 v26, v25
	v_and_b32_e32 v23, 0xffff0000, v23
	v_fma_f32 v31, -v25, v26, 1.0
	v_fmac_f32_e32 v26, v31, v26
	v_div_scale_f32 v31, vcc, v29, v10, v29
	v_mul_f32_e32 v32, v31, v26
	v_fma_f32 v33, -v25, v32, v31
	v_fmac_f32_e32 v32, v33, v26
	v_fma_f32 v25, -v25, v32, v31
	v_div_fmas_f32 v25, v25, v26, v32
	v_div_fixup_f32 v10, v25, v10, v29
	v_div_scale_f32 v25, s[12:13], v15, v15, v27
	v_rcp_f32_e32 v26, v25
	s_nop 0
	v_fma_f32 v29, -v25, v26, 1.0
	v_fmac_f32_e32 v26, v29, v26
	v_div_scale_f32 v29, vcc, v27, v15, v27
	v_mul_f32_e32 v31, v29, v26
	v_fma_f32 v32, -v25, v31, v29
	v_fmac_f32_e32 v31, v32, v26
	v_fma_f32 v25, -v25, v31, v29
	v_div_fmas_f32 v25, v25, v26, v31
	v_div_fixup_f32 v15, v25, v15, v27
	v_div_scale_f32 v25, s[12:13], v11, v11, v24
	v_rcp_f32_e32 v26, v25
	s_nop 0
	v_fma_f32 v27, -v25, v26, 1.0
	v_fmac_f32_e32 v26, v27, v26
	v_div_scale_f32 v27, vcc, v24, v11, v24
	v_mul_f32_e32 v29, v27, v26
	v_fma_f32 v31, -v25, v29, v27
; __device__ __forceinline__ unsigned cvt_pk_bf16(float lo, float hi) { unsigned r; asm volatile("v_cvt_pk_bf16_f32 %0, %1, %2" : "=v"(r) : "v"(lo), "v"(hi)); return r; }
; __device__ __forceinline__ float bf_lo(unsigned w) { return __uint_as_float(w << 16); }
; __device__ __forceinline__ float bf_hi(unsigned w) { return __uint_as_float(w & 0xffff0000u); }
; #define PG8_WAIT_V(n) asm volatile("s_waitcnt vmcnt(" #n ")" ::: "memory")
; #define PG8_BAR __builtin_amdgcn_s_barrier()
;     __device__ __forceinline__ void operator()(const f32x4 (&acc)[2][2][4][2], const Unit& u, int ui, const LAS float* rtab, int wr, int wc, int fr, int fq) const {
;     ...
;                 for (int bj = 0; bj < 2; ++bj) {
;                     const int col = col0 + bj * HALF; const u32x4 yv = *(const u32x4*)(Y + (size_t)row * 1024 + col);
;                     const f32x4 a0 = acc[ai][bj][m][0], a1 = acc[ai][bj][m][1]; float o[8];
;                     const float yy[8] = {bf_lo(yv.x), bf_hi(yv.x), bf_lo(yv.y), bf_hi(yv.y), bf_lo(yv.z), bf_hi(yv.z), bf_lo(yv.w), bf_hi(yv.w)};
; #pragma unroll
;                     for (int e = 0; e < 4; ++e) { o[e] = yy[e] / (1.0f + __expf(-a0[e])); o[4 + e] = yy[4 + e] / (1.0f + __expf(-a1[e])); }
;                     u32x4 w; w.x = cvt_pk_bf16(o[0], o[1]); w.y = cvt_pk_bf16(o[2], o[3]); w.z = cvt_pk_bf16(o[4], o[5]); w.w = cvt_pk_bf16(o[6], o[7]);
;                     *(u32x4*)(MG + (size_t)row * DM + 1024 + col) = w;
; template <class Epi, class Sched>
; __device__ __forceinline__ void gemm_phase(LAS unsigned char* lds, const Gemm g, const Sched& S, const Epi& E) {
;     ...
;         if (!has_next) break;
; #pragma unroll
;         for (int a = 0; a < 2; ++a)
; #pragma unroll
;             for (int b = 0; b < 2; ++b)
; #pragma unroll
;                 for (int m = 0; m < 4; ++m)
; #pragma unroll
;                     for (int n = 0; n < 2; ++n) acc[a][b][m][n] = (f32x4){0.f, 0.f, 0.f, 0.f};
;         cur = nxt; cA = nA; cB = nB; ++ui;
;     }
;     PG8_WAIT_V(0);
;     if (wr == 0) PG8_BAR;
;     PG8_BAR;
	v_fmac_f32_e32 v29, v31, v26
	v_fma_f32 v25, -v25, v29, v27
	v_div_fmas_f32 v25, v25, v26, v29
	v_div_fixup_f32 v11, v25, v11, v24
	v_div_scale_f32 v24, s[12:13], v16, v16, v28
	v_rcp_f32_e32 v25, v24
	s_nop 0
	v_fma_f32 v26, -v24, v25, 1.0
	v_fmac_f32_e32 v25, v26, v25
	v_div_scale_f32 v26, vcc, v28, v16, v28
	v_mul_f32_e32 v27, v26, v25
	v_fma_f32 v29, -v24, v27, v26
	v_fmac_f32_e32 v27, v29, v25
	v_fma_f32 v24, -v24, v27, v26
	v_div_fmas_f32 v24, v24, v25, v27
	v_div_fixup_f32 v16, v24, v16, v28
	v_div_scale_f32 v24, s[12:13], v12, v12, v30
	v_rcp_f32_e32 v25, v24
	s_nop 0
	v_fma_f32 v26, -v24, v25, 1.0
	v_fmac_f32_e32 v25, v26, v25
	v_div_scale_f32 v26, vcc, v30, v12, v30
	v_mul_f32_e32 v27, v26, v25
	v_fma_f32 v28, -v24, v27, v26
	v_fmac_f32_e32 v27, v28, v25
	v_fma_f32 v24, -v24, v27, v26
	v_div_fmas_f32 v24, v24, v25, v27
	v_div_fixup_f32 v24, v24, v12, v30
	v_mul_f32_e32 v12, 0xbfb8aa3b, v17
	v_exp_f32_e32 v12, v12
	s_nop 0
	v_add_f32_e32 v12, 1.0, v12
	v_div_scale_f32 v17, s[12:13], v12, v12, v23
	v_rcp_f32_e32 v25, v17
	s_nop 0
	v_fma_f32 v26, -v17, v25, 1.0
	v_fmac_f32_e32 v25, v26, v25
	v_div_scale_f32 v26, vcc, v23, v12, v23
	v_mul_f32_e32 v27, v26, v25
	v_fma_f32 v28, -v17, v27, v26
	v_fmac_f32_e32 v27, v28, v25
	v_fma_f32 v17, -v17, v27, v26
	v_div_fmas_f32 v17, v17, v25, v27
	v_div_fixup_f32 v17, v17, v12, v23
	v_mul_f32_e32 v12, 0xbfb8aa3b, v13
	v_exp_f32_e32 v12, v12
	s_nop 0
	v_add_f32_e32 v12, 1.0, v12
	v_div_scale_f32 v13, s[12:13], v12, v12, v22
	v_rcp_f32_e32 v23, v13
	s_nop 0
	v_fma_f32 v25, -v13, v23, 1.0
	v_fmac_f32_e32 v23, v25, v23
	v_div_scale_f32 v25, vcc, v22, v12, v22
	v_mul_f32_e32 v26, v25, v23
	v_fma_f32 v27, -v13, v26, v25
	v_fmac_f32_e32 v26, v27, v23
	v_fma_f32 v13, -v13, v26, v25
	v_div_fmas_f32 v13, v13, v23, v26
	v_div_fixup_f32 v22, v13, v12, v22
	v_cvt_pk_bf16_f32 v12, v14, v15
	v_cvt_pk_bf16_f32 v13, v16, v17
	v_cvt_pk_bf16_f32 v14, v10, v11
	v_lshl_add_u64 v[10:11], s[88:89], 0, v[20:21]
	v_cvt_pk_bf16_f32 v15, v24, v22
	v_lshl_add_u64 v[10:11], v[10:11], 0, v[142:143]
	global_store_dwordx4 v[10:11], v[12:15], off offset:2048
	global_load_dwordx4 v[12:15], v[18:19], off offset:256
	s_waitcnt vmcnt(0)
	v_lshlrev_b32_e32 v16, 16, v12
	v_and_b32_e32 v17, 0xffff0000, v12
	v_lshlrev_b32_e32 v20, 16, v15
	v_and_b32_e32 v12, 0xffff0000, v15
	v_div_scale_f32 v15, s[12:13], v6, v6, v16
	v_rcp_f32_e32 v21, v15
	v_lshlrev_b32_e32 v19, 16, v14
	v_and_b32_e32 v14, 0xffff0000, v14
	v_lshlrev_b32_e32 v18, 16, v13
	v_fma_f32 v22, -v15, v21, 1.0
	v_fmac_f32_e32 v21, v22, v21
	v_div_scale_f32 v22, vcc, v16, v6, v16
	v_mul_f32_e32 v23, v22, v21
	v_fma_f32 v24, -v15, v23, v22
	v_fmac_f32_e32 v23, v24, v21
	v_fma_f32 v15, -v15, v23, v22
	v_div_fmas_f32 v15, v15, v21, v23
	v_div_fixup_f32 v6, v15, v6, v16
	v_div_scale_f32 v15, s[12:13], v2, v2, v19
	v_rcp_f32_e32 v16, v15
	v_and_b32_e32 v13, 0xffff0000, v13
	v_fma_f32 v21, -v15, v16, 1.0
	v_fmac_f32_e32 v16, v21, v16
	v_div_scale_f32 v21, vcc, v19, v2, v19
	v_mul_f32_e32 v22, v21, v16
	v_fma_f32 v23, -v15, v22, v21
	v_fmac_f32_e32 v22, v23, v16
	v_fma_f32 v15, -v15, v22, v21
	v_div_fmas_f32 v15, v15, v16, v22
	v_div_fixup_f32 v15, v15, v2, v19
	v_mul_f32_e32 v2, 0xbfb8aa3b, v7
	v_exp_f32_e32 v2, v2
	s_nop 0
	v_add_f32_e32 v2, 1.0, v2
	v_div_scale_f32 v7, s[12:13], v2, v2, v17
	v_rcp_f32_e32 v16, v7
	s_nop 0
	v_fma_f32 v19, -v7, v16, 1.0
	v_fmac_f32_e32 v16, v19, v16
	v_div_scale_f32 v19, vcc, v17, v2, v17
	v_mul_f32_e32 v21, v19, v16
	v_fma_f32 v22, -v7, v21, v19
	v_fmac_f32_e32 v21, v22, v16
	v_fma_f32 v7, -v7, v21, v19
	v_div_fmas_f32 v7, v7, v16, v21
	v_div_fixup_f32 v2, v7, v2, v17
	v_div_scale_f32 v7, s[12:13], v3, v3, v14
	v_rcp_f32_e32 v16, v7
	v_cvt_pk_bf16_f32 v2, v6, v2
	s_nop 0
	v_fma_f32 v17, -v7, v16, 1.0
	v_fmac_f32_e32 v16, v17, v16
	v_div_scale_f32 v17, vcc, v14, v3, v14
	v_mul_f32_e32 v19, v17, v16
	v_fma_f32 v21, -v7, v19, v17
	v_fmac_f32_e32 v19, v21, v16
	v_fma_f32 v7, -v7, v19, v17
	v_div_fmas_f32 v7, v7, v16, v19
	v_div_fixup_f32 v7, v7, v3, v14
	v_mul_f32_e32 v3, 0xbfb8aa3b, v8
	v_exp_f32_e32 v3, v3
	s_nop 0
	v_add_f32_e32 v3, 1.0, v3
	v_div_scale_f32 v8, s[12:13], v3, v3, v18
	v_rcp_f32_e32 v14, v8
	s_nop 0
	v_fma_f32 v16, -v8, v14, 1.0
	v_fmac_f32_e32 v14, v16, v14
	v_div_scale_f32 v16, vcc, v18, v3, v18
	v_mul_f32_e32 v17, v16, v14
	v_fma_f32 v19, -v8, v17, v16
	v_fmac_f32_e32 v17, v19, v14
	v_fma_f32 v8, -v8, v17, v16
	v_div_fmas_f32 v8, v8, v14, v17
	v_div_fixup_f32 v3, v8, v3, v18
	v_div_scale_f32 v8, s[12:13], v4, v4, v20
	v_rcp_f32_e32 v14, v8
	s_nop 0
	v_fma_f32 v16, -v8, v14, 1.0
	v_fmac_f32_e32 v14, v16, v14
	v_div_scale_f32 v16, vcc, v20, v4, v20
	v_mul_f32_e32 v17, v16, v14
	v_fma_f32 v18, -v8, v17, v16
	v_fmac_f32_e32 v17, v18, v14
	v_fma_f32 v8, -v8, v17, v16
	v_div_fmas_f32 v8, v8, v14, v17
	v_div_fixup_f32 v8, v8, v4, v20
	v_mul_f32_e32 v4, 0xbfb8aa3b, v9
	v_exp_f32_e32 v4, v4
	s_nop 0
	v_add_f32_e32 v4, 1.0, v4
	v_div_scale_f32 v9, s[12:13], v4, v4, v13
	v_rcp_f32_e32 v14, v9
	s_nop 0
	v_fma_f32 v16, -v9, v14, 1.0
	v_fmac_f32_e32 v14, v16, v14
	v_div_scale_f32 v16, vcc, v13, v4, v13
	v_mul_f32_e32 v17, v16, v14
	v_fma_f32 v18, -v9, v17, v16
	v_fmac_f32_e32 v17, v18, v14
	v_fma_f32 v9, -v9, v17, v16
	v_div_fmas_f32 v9, v9, v14, v17
	v_div_fixup_f32 v4, v9, v4, v13
	v_div_scale_f32 v9, s[12:13], v5, v5, v12
	v_rcp_f32_e32 v13, v9
	s_mov_b32 s12, s0
	s_mov_b32 s13, s42
	v_cvt_pk_bf16_f32 v3, v3, v4
	v_fma_f32 v14, -v9, v13, 1.0
	v_fmac_f32_e32 v13, v14, v13
	v_div_scale_f32 v14, vcc, v12, v5, v12
	v_mul_f32_e32 v16, v14, v13
	v_fma_f32 v17, -v9, v16, v14
	v_fmac_f32_e32 v16, v17, v13
	v_fma_f32 v9, -v9, v16, v14
	v_div_fmas_f32 v9, v9, v13, v16
	v_div_fixup_f32 v5, v9, v5, v12
	s_and_b64 vcc, exec, s[40:41]
	v_cvt_pk_bf16_f32 v4, v15, v7
	v_cvt_pk_bf16_f32 v5, v8, v5
	global_store_dwordx4 v[10:11], v[2:5], off offset:2304
	s_cbranch_vccz .LBB0_661
	s_waitcnt vmcnt(0)
	s_cmpk_gt_u32 s27, 0xff
	s_cbranch_scc1 .LBB0_672
	s_barrier

; #define PG8_STAGE(bufoff, gbase, voff) do { _Pragma("unroll") for (int _i = 0; _i < 2; ++_i) \
;         __builtin_amdgcn_global_load_lds((const unsigned*)((const char*)(gbase) + (voff)[_i]), (LAS unsigned*)(lds + (bufoff) + ldsw + _i * 8192), 16, 0, 0); } while (0)
; #define PG8_LDA(dst, b, h) do { _Pragma("unroll") for (int m = 0; m < 4; ++m) _Pragma("unroll") for (int k = 0; k < 2; ++k) dst[m][k] = *(const LAS bf16x8*)(lds + PG8_SA(b, h) + aoff + m * 2048 + k * 1024); } while (0)
; #define PG8_LDB(dst, b, h) do { _Pragma("unroll") for (int n = 0; n < 2; ++n) _Pragma("unroll") for (int k = 0; k < 2; ++k) dst[n][k] = *(const LAS bf16x8*)(lds + PG8_SB(b, h) + boff + n * 2048 + k * 1024); } while (0)
; #define PG8_MMA(ai, bj, At, Bt) do { __builtin_amdgcn_s_setprio(1); _Pragma("unroll") for (int m = 0; m < 4; ++m) _Pragma("unroll") for (int n = 0; n < 2; ++n) _Pragma("unroll") for (int k = 0; k < 2; ++k) \
;         acc[ai][bj][m][n] = __builtin_amdgcn_mfma_f32_16x16x32_bf16(Bt[n][k], At[m][k], acc[ai][bj][m][n], 0, 0, 0); __builtin_amdgcn_s_setprio(0); } while (0)
; #define PG8_WAIT_L(n) asm volatile("s_waitcnt lgkmcnt(" #n ")" ::: "memory")
; #define PG8_BAR __builtin_amdgcn_s_barrier()
; #define PG8_SCHED __builtin_amdgcn_sched_barrier(0)
; template <class Epi, class Sched>
; __device__ __forceinline__ void gemm_phase(LAS unsigned char* lds, const Gemm g, const Sched& S, const Epi& E) {
;     ...
;             PG8_LDB(B0, 0, 0); PG8_SCHED; PG8_LDA(At, 0, 0); PG8_STAGE(PG8_SA(1, 1), a1 + hstepA, voffA);
;             PG8_WAIT_L(8); PG8_BAR; PG8_WAIT_L(0); PG8_MMA(0, 0, At, B0); PG8_BAR; PG8_SCHED;
;             PG8_LDB(B1, 0, 1); PG8_STAGE(PG8_SB(0, 0), b2, voffB);
;             PG8_BAR; PG8_WAIT_L(0); PG8_MMA(0, 1, At, B1); PG8_BAR;
;             PG8_LDA(At, 0, 1); PG8_STAGE(PG8_SA(0, 0), a2, voffA);
;             PG8_BAR; PG8_WAIT_L(0); PG8_MMA(1, 0, At, B0); PG8_BAR; PG8_SCHED;
;             PG8_STAGE(PG8_SB(0, 1), b2 + hstepB, voffB);
.LBB0_738:
	s_add_u32 s23, s48, 0xfff80080
	s_addc_u32 s50, s49, -1
	s_add_i32 s67, 0, 0x10000
	v_add_u32_e32 v142, s67, v162
	ds_read_b128 v[130:133], v142
	ds_read_b128 v[134:137], v142 offset:1024
	ds_read_b128 v[138:141], v142 offset:2048
	ds_read_b128 v[142:145], v142 offset:3072
	s_cmp_eq_u32 s66, 28
	s_cselect_b32 s53, s35, s50
	s_cselect_b32 s52, s59, s23
	s_cselect_b32 s51, s21, s71
	s_cselect_b32 s50, s68, s70
	v_lshl_add_u64 v[198:199], s[48:49], 0, v[178:179]
	s_add_i32 m0, s26, 0xc000
	ds_read_b128 v[146:149], v210
	ds_read_b128 v[150:153], v210 offset:1024
	ds_read_b128 v[182:185], v210 offset:2048
	ds_read_b128 v[186:189], v210 offset:3072
	ds_read_b128 v[190:193], v210 offset:4096
	ds_read_b128 v[194:197], v210 offset:5120
	ds_read_b128 v[212:215], v210 offset:6144
	ds_read_b128 v[216:219], v210 offset:7168
	global_load_lds_dwordx4 v[198:199], off
	v_lshl_add_u64 v[198:199], s[48:49], 0, v[180:181]
	s_add_i32 m0, s26, 0xe000
	s_nop 0
	global_load_lds_dwordx4 v[198:199], off
	s_waitcnt lgkmcnt(8)
	s_barrier
	s_waitcnt lgkmcnt(0)
	s_waitcnt lgkmcnt(0)
	v_mfma_f32_16x16x32_bf16 v[126:129], v[130:133], v[146:149], v[126:129]
	v_mfma_f32_16x16x32_bf16 v[122:125], v[138:141], v[146:149], v[122:125]
	v_mfma_f32_16x16x32_bf16 v[110:113], v[130:133], v[182:185], v[110:113]
	v_mfma_f32_16x16x32_bf16 v[106:109], v[138:141], v[182:185], v[106:109]
	v_mfma_f32_16x16x32_bf16 v[94:97], v[130:133], v[190:193], v[94:97]
	v_mfma_f32_16x16x32_bf16 v[90:93], v[138:141], v[190:193], v[90:93]
	v_mfma_f32_16x16x32_bf16 v[78:81], v[130:133], v[212:215], v[78:81]
	v_mfma_f32_16x16x32_bf16 v[74:77], v[138:141], v[212:215], v[74:77]
	v_mfma_f32_16x16x32_bf16 v[126:129], v[134:137], v[150:153], v[126:129]
	v_mfma_f32_16x16x32_bf16 v[122:125], v[142:145], v[150:153], v[122:125]
	v_mfma_f32_16x16x32_bf16 v[110:113], v[134:137], v[186:189], v[110:113]
	v_mfma_f32_16x16x32_bf16 v[106:109], v[142:145], v[186:189], v[106:109]
	v_mfma_f32_16x16x32_bf16 v[94:97], v[134:137], v[194:197], v[94:97]
	v_mfma_f32_16x16x32_bf16 v[90:93], v[142:145], v[194:197], v[90:93]
	v_mfma_f32_16x16x32_bf16 v[78:81], v[134:137], v[216:219], v[78:81]
	v_mfma_f32_16x16x32_bf16 v[74:77], v[142:145], v[216:219], v[74:77]
	s_barrier
	s_add_i32 s23, 0, 0x14000
	v_add_u32_e32 v198, s23, v162
	s_add_i32 s67, s67, s25
	ds_read_b128 v[220:223], v198
	ds_read_b128 v[224:227], v198 offset:1024
	ds_read_b128 v[228:231], v198 offset:2048
	ds_read_b128 v[232:235], v198 offset:3072
	v_lshl_add_u64 v[198:199], s[50:51], 0, v[174:175]
	s_mov_b32 m0, s67
	v_lshl_add_u64 v[236:237], s[50:51], 0, v[170:171]
	global_load_lds_dwordx4 v[198:199], off
	s_add_i32 m0, s67, 0x2000
	s_nop 0
	global_load_lds_dwordx4 v[236:237], off
	s_barrier
	s_waitcnt lgkmcnt(0)
	s_waitcnt lgkmcnt(0)
	v_mfma_f32_16x16x32_bf16 v[118:121], v[220:223], v[146:149], v[118:121]
	v_mfma_f32_16x16x32_bf16 v[114:117], v[228:231], v[146:149], v[114:117]
	v_mfma_f32_16x16x32_bf16 v[102:105], v[220:223], v[182:185], v[102:105]
	v_mfma_f32_16x16x32_bf16 v[98:101], v[228:231], v[182:185], v[98:101]
	v_mfma_f32_16x16x32_bf16 v[86:89], v[220:223], v[190:193], v[86:89]
	v_mfma_f32_16x16x32_bf16 v[82:85], v[228:231], v[190:193], v[82:85]
	v_mfma_f32_16x16x32_bf16 v[70:73], v[220:223], v[212:215], v[70:73]
	v_mfma_f32_16x16x32_bf16 v[66:69], v[228:231], v[212:215], v[66:69]
	v_mfma_f32_16x16x32_bf16 v[118:121], v[224:227], v[150:153], v[118:121]
	v_mfma_f32_16x16x32_bf16 v[114:117], v[232:235], v[150:153], v[114:117]
	v_mfma_f32_16x16x32_bf16 v[102:105], v[224:227], v[186:189], v[102:105]
	v_mfma_f32_16x16x32_bf16 v[98:101], v[232:235], v[186:189], v[98:101]
	v_mfma_f32_16x16x32_bf16 v[86:89], v[224:227], v[194:197], v[86:89]
	v_mfma_f32_16x16x32_bf16 v[82:85], v[232:235], v[194:197], v[82:85]
	v_mfma_f32_16x16x32_bf16 v[70:73], v[224:227], v[216:219], v[70:73]
	v_mfma_f32_16x16x32_bf16 v[66:69], v[232:235], v[216:219], v[66:69]
	s_mov_b32 m0, s26
	v_lshl_add_u64 v[238:239], s[52:53], 0, v[176:177]
	s_barrier
	ds_read_b128 v[146:149], v210 offset:16384
	ds_read_b128 v[150:153], v210 offset:17408
	ds_read_b128 v[182:185], v210 offset:18432
	ds_read_b128 v[186:189], v210 offset:19456
	ds_read_b128 v[190:193], v210 offset:20480
	ds_read_b128 v[194:197], v210 offset:21504
	ds_read_b128 v[212:215], v210 offset:22528
	ds_read_b128 v[216:219], v210 offset:23552
	global_load_lds_dwordx4 v[238:239], off
	v_lshl_add_u64 v[240:241], s[52:53], 0, v[172:173]
	s_mov_b32 m0, s27
	s_nop 0
	global_load_lds_dwordx4 v[240:241], off
	s_barrier
	s_waitcnt lgkmcnt(0)
	s_waitcnt lgkmcnt(0)
	v_mfma_f32_16x16x32_bf16 v[62:65], v[130:133], v[146:149], v[62:65]
	v_mfma_f32_16x16x32_bf16 v[58:61], v[138:141], v[146:149], v[58:61]
	v_mfma_f32_16x16x32_bf16 v[46:49], v[130:133], v[182:185], v[46:49]
	v_mfma_f32_16x16x32_bf16 v[42:45], v[138:141], v[182:185], v[42:45]
	v_mfma_f32_16x16x32_bf16 v[30:33], v[130:133], v[190:193], v[30:33]
	v_mfma_f32_16x16x32_bf16 v[26:29], v[138:141], v[190:193], v[26:29]
	v_mfma_f32_16x16x32_bf16 v[14:17], v[130:133], v[212:215], v[14:17]
	v_mfma_f32_16x16x32_bf16 v[10:13], v[138:141], v[212:215], v[10:13]
	v_mfma_f32_16x16x32_bf16 v[62:65], v[134:137], v[150:153], v[62:65]
	v_mfma_f32_16x16x32_bf16 v[58:61], v[142:145], v[150:153], v[58:61]
	v_mfma_f32_16x16x32_bf16 v[46:49], v[134:137], v[186:189], v[46:49]
	v_mfma_f32_16x16x32_bf16 v[42:45], v[142:145], v[186:189], v[42:45]
	v_mfma_f32_16x16x32_bf16 v[30:33], v[134:137], v[194:197], v[30:33]
	v_mfma_f32_16x16x32_bf16 v[26:29], v[142:145], v[194:197], v[26:29]
	v_mfma_f32_16x16x32_bf16 v[14:17], v[134:137], v[216:219], v[14:17]
	v_mfma_f32_16x16x32_bf16 v[10:13], v[142:145], v[216:219], v[10:13]
	s_barrier
; #define PG8_STAGE(bufoff, gbase, voff) do { _Pragma("unroll") for (int _i = 0; _i < 2; ++_i) \
;         __builtin_amdgcn_global_load_lds((const unsigned*)((const char*)(gbase) + (voff)[_i]), (LAS unsigned*)(lds + (bufoff) + ldsw + _i * 8192), 16, 0, 0); } while (0)
; #define PG8_LDA(dst, b, h) do { _Pragma("unroll") for (int m = 0; m < 4; ++m) _Pragma("unroll") for (int k = 0; k < 2; ++k) dst[m][k] = *(const LAS bf16x8*)(lds + PG8_SA(b, h) + aoff + m * 2048 + k * 1024); } while (0)
; #define PG8_LDB(dst, b, h) do { _Pragma("unroll") for (int n = 0; n < 2; ++n) _Pragma("unroll") for (int k = 0; k < 2; ++k) dst[n][k] = *(const LAS bf16x8*)(lds + PG8_SB(b, h) + boff + n * 2048 + k * 1024); } while (0)
; #define PG8_MMA(ai, bj, At, Bt) do { __builtin_amdgcn_s_setprio(1); _Pragma("unroll") for (int m = 0; m < 4; ++m) _Pragma("unroll") for (int n = 0; n < 2; ++n) _Pragma("unroll") for (int k = 0; k < 2; ++k) \
;         acc[ai][bj][m][n] = __builtin_amdgcn_mfma_f32_16x16x32_bf16(Bt[n][k], At[m][k], acc[ai][bj][m][n], 0, 0, 0); __builtin_amdgcn_s_setprio(0); } while (0)
; #define PG8_WAIT_V(n) asm volatile("s_waitcnt vmcnt(" #n ")" ::: "memory")
; #define PG8_WAIT_L(n) asm volatile("s_waitcnt lgkmcnt(" #n ")" ::: "memory")
; #define PG8_BAR __builtin_amdgcn_s_barrier()
; #define PG8_SCHED __builtin_amdgcn_sched_barrier(0)
; template <class Epi, class Sched>
; __device__ __forceinline__ void gemm_phase(LAS unsigned char* lds, const Gemm g, const Sched& S, const Epi& E) {
;     ...
;             PG8_STAGE(PG8_SB(0, 1), b2 + hstepB, voffB);
;             PG8_WAIT_V(6); PG8_BAR; PG8_MMA(1, 1, At, B1); PG8_BAR;
;             PG8_LDB(B0, 1, 0); PG8_SCHED; PG8_LDA(At, 1, 0); PG8_STAGE(PG8_SA(0, 1), a2 + hstepA, voffA);
;             PG8_WAIT_L(8); PG8_BAR; PG8_WAIT_L(0); PG8_MMA(0, 0, At, B0); PG8_BAR; PG8_SCHED;
;             PG8_LDB(B1, 1, 1); PG8_STAGE(PG8_SB(1, 0), b3, voffB);
;             PG8_BAR; PG8_WAIT_L(0); PG8_MMA(0, 1, At, B1); PG8_BAR;
;             PG8_LDA(At, 1, 1); PG8_STAGE(PG8_SA(1, 0), a3, voffA);
;             PG8_BAR; PG8_WAIT_L(0); PG8_MMA(1, 0, At, B0); PG8_BAR; PG8_SCHED;
	s_add_u32 s84, s50, 0x80000
	s_addc_u32 s85, s51, 0
	s_add_i32 s23, s23, s25
	v_lshl_add_u64 v[130:131], s[84:85], 0, v[174:175]
	s_mov_b32 m0, s23
	s_nop 0
	global_load_lds_dwordx4 v[130:131], off
	v_lshl_add_u64 v[130:131], s[84:85], 0, v[170:171]
	s_add_i32 m0, s23, 0x2000
	s_nop 0
	global_load_lds_dwordx4 v[130:131], off
	s_waitcnt vmcnt(6)
	s_barrier
	v_mfma_f32_16x16x32_bf16 v[54:57], v[220:223], v[146:149], v[54:57]
	v_mfma_f32_16x16x32_bf16 v[50:53], v[228:231], v[146:149], v[50:53]
	v_mfma_f32_16x16x32_bf16 v[38:41], v[220:223], v[182:185], v[38:41]
	v_mfma_f32_16x16x32_bf16 v[34:37], v[228:231], v[182:185], v[34:37]
	v_mfma_f32_16x16x32_bf16 v[22:25], v[220:223], v[190:193], v[22:25]
	v_mfma_f32_16x16x32_bf16 v[18:21], v[228:231], v[190:193], v[18:21]
	v_mfma_f32_16x16x32_bf16 v[6:9], v[220:223], v[212:215], v[6:9]
	v_mfma_f32_16x16x32_bf16 v[2:5], v[228:231], v[212:215], v[2:5]
	v_mfma_f32_16x16x32_bf16 v[54:57], v[224:227], v[150:153], v[54:57]
	v_mfma_f32_16x16x32_bf16 v[50:53], v[232:235], v[150:153], v[50:53]
	v_mfma_f32_16x16x32_bf16 v[38:41], v[224:227], v[186:189], v[38:41]
	v_mfma_f32_16x16x32_bf16 v[34:37], v[232:235], v[186:189], v[34:37]
	v_mfma_f32_16x16x32_bf16 v[22:25], v[224:227], v[194:197], v[22:25]
	v_mfma_f32_16x16x32_bf16 v[18:21], v[232:235], v[194:197], v[18:21]
	v_mfma_f32_16x16x32_bf16 v[6:9], v[224:227], v[216:219], v[6:9]
	v_mfma_f32_16x16x32_bf16 v[2:5], v[232:235], v[216:219], v[2:5]
	s_add_i32 s23, 0, 0x18000
	v_add_u32_e32 v142, s23, v162
	s_barrier
	ds_read_b128 v[130:133], v142
	ds_read_b128 v[134:137], v142 offset:1024
	ds_read_b128 v[138:141], v142 offset:2048
	ds_read_b128 v[142:145], v142 offset:3072
	s_add_u32 s52, s52, 0x80000
	s_addc_u32 s53, s53, 0
	s_mov_b32 m0, s31
	v_lshl_add_u64 v[220:221], s[52:53], 0, v[176:177]
	ds_read_b128 v[146:149], v210 offset:32768
	ds_read_b128 v[150:153], v210 offset:33792
	ds_read_b128 v[182:185], v210 offset:34816
	ds_read_b128 v[186:189], v210 offset:35840
	ds_read_b128 v[190:193], v210 offset:36864
	ds_read_b128 v[194:197], v210 offset:37888
	ds_read_b128 v[212:215], v210 offset:38912
	ds_read_b128 v[216:219], v210 offset:39936
	global_load_lds_dwordx4 v[220:221], off
	v_lshl_add_u64 v[220:221], s[52:53], 0, v[172:173]
	s_mov_b32 m0, s54
	s_nop 0
	global_load_lds_dwordx4 v[220:221], off
	s_waitcnt lgkmcnt(8)
	s_barrier
	s_waitcnt lgkmcnt(0)
	s_waitcnt lgkmcnt(0)
	v_mfma_f32_16x16x32_bf16 v[126:129], v[130:133], v[146:149], v[126:129]
	v_mfma_f32_16x16x32_bf16 v[122:125], v[138:141], v[146:149], v[122:125]
	v_mfma_f32_16x16x32_bf16 v[110:113], v[130:133], v[182:185], v[110:113]
	v_mfma_f32_16x16x32_bf16 v[106:109], v[138:141], v[182:185], v[106:109]
	v_mfma_f32_16x16x32_bf16 v[94:97], v[130:133], v[190:193], v[94:97]
	v_mfma_f32_16x16x32_bf16 v[90:93], v[138:141], v[190:193], v[90:93]
	v_mfma_f32_16x16x32_bf16 v[78:81], v[130:133], v[212:215], v[78:81]
	v_mfma_f32_16x16x32_bf16 v[74:77], v[138:141], v[212:215], v[74:77]
	v_mfma_f32_16x16x32_bf16 v[126:129], v[134:137], v[150:153], v[126:129]
	v_mfma_f32_16x16x32_bf16 v[122:125], v[142:145], v[150:153], v[122:125]
	v_mfma_f32_16x16x32_bf16 v[110:113], v[134:137], v[186:189], v[110:113]
	v_mfma_f32_16x16x32_bf16 v[106:109], v[142:145], v[186:189], v[106:109]
	v_mfma_f32_16x16x32_bf16 v[94:97], v[134:137], v[194:197], v[94:97]
	v_mfma_f32_16x16x32_bf16 v[90:93], v[142:145], v[194:197], v[90:93]
	v_mfma_f32_16x16x32_bf16 v[78:81], v[134:137], v[216:219], v[78:81]
	v_mfma_f32_16x16x32_bf16 v[74:77], v[142:145], v[216:219], v[74:77]
	s_barrier
	s_add_i32 s52, 0, 0x1c000
	s_add_i32 s23, s23, s25
	v_add_u32_e32 v211, s52, v162
	v_lshl_add_u64 v[198:199], v[198:199], 0, s[10:11]
	s_mov_b32 m0, s23
	ds_read_b128 v[220:223], v211
	ds_read_b128 v[224:227], v211 offset:1024
	ds_read_b128 v[228:231], v211 offset:2048
	ds_read_b128 v[232:235], v211 offset:3072
	global_load_lds_dwordx4 v[198:199], off
	v_lshl_add_u64 v[198:199], v[236:237], 0, s[10:11]
	s_add_i32 m0, s23, 0x2000
	s_nop 0
	global_load_lds_dwordx4 v[198:199], off
	s_barrier
	s_waitcnt lgkmcnt(0)
	s_waitcnt lgkmcnt(0)
	v_mfma_f32_16x16x32_bf16 v[118:121], v[220:223], v[146:149], v[118:121]
	v_mfma_f32_16x16x32_bf16 v[114:117], v[228:231], v[146:149], v[114:117]
	v_mfma_f32_16x16x32_bf16 v[102:105], v[220:223], v[182:185], v[102:105]
	v_mfma_f32_16x16x32_bf16 v[98:101], v[228:231], v[182:185], v[98:101]
	v_mfma_f32_16x16x32_bf16 v[86:89], v[220:223], v[190:193], v[86:89]
	v_mfma_f32_16x16x32_bf16 v[82:85], v[228:231], v[190:193], v[82:85]
	v_mfma_f32_16x16x32_bf16 v[70:73], v[220:223], v[212:215], v[70:73]
	v_mfma_f32_16x16x32_bf16 v[66:69], v[228:231], v[212:215], v[66:69]
	v_mfma_f32_16x16x32_bf16 v[118:121], v[224:227], v[150:153], v[118:121]
	v_mfma_f32_16x16x32_bf16 v[114:117], v[232:235], v[150:153], v[114:117]
	v_mfma_f32_16x16x32_bf16 v[102:105], v[224:227], v[186:189], v[102:105]
	v_mfma_f32_16x16x32_bf16 v[98:101], v[232:235], v[186:189], v[98:101]
	v_mfma_f32_16x16x32_bf16 v[86:89], v[224:227], v[194:197], v[86:89]
	v_mfma_f32_16x16x32_bf16 v[82:85], v[232:235], v[194:197], v[82:85]
	v_mfma_f32_16x16x32_bf16 v[70:73], v[224:227], v[216:219], v[70:73]
	v_mfma_f32_16x16x32_bf16 v[66:69], v[232:235], v[216:219], v[66:69]
	s_mov_b32 m0, s28
	v_lshl_add_u64 v[198:199], v[238:239], 0, s[10:11]
	s_barrier
	ds_read_b128 v[146:149], v210 offset:49152
	ds_read_b128 v[150:153], v210 offset:50176
	ds_read_b128 v[182:185], v210 offset:51200
	ds_read_b128 v[186:189], v210 offset:52224
	ds_read_b128 v[190:193], v210 offset:53248
	ds_read_b128 v[194:197], v210 offset:54272
	ds_read_b128 v[212:215], v210 offset:55296
	ds_read_b128 v[216:219], v210 offset:56320
	global_load_lds_dwordx4 v[198:199], off
	v_lshl_add_u64 v[198:199], v[240:241], 0, s[10:11]
	s_mov_b32 m0, s29
	s_nop 0
	global_load_lds_dwordx4 v[198:199], off
	s_barrier
; #define PG8_STAGE(bufoff, gbase, voff) do { _Pragma("unroll") for (int _i = 0; _i < 2; ++_i) \
;         __builtin_amdgcn_global_load_lds((const unsigned*)((const char*)(gbase) + (voff)[_i]), (LAS unsigned*)(lds + (bufoff) + ldsw + _i * 8192), 16, 0, 0); } while (0)
; #define PG8_LDA(dst, b, h) do { _Pragma("unroll") for (int m = 0; m < 4; ++m) _Pragma("unroll") for (int k = 0; k < 2; ++k) dst[m][k] = *(const LAS bf16x8*)(lds + PG8_SA(b, h) + aoff + m * 2048 + k * 1024); } while (0)
; #define PG8_MMA(ai, bj, At, Bt) do { __builtin_amdgcn_s_setprio(1); _Pragma("unroll") for (int m = 0; m < 4; ++m) _Pragma("unroll") for (int n = 0; n < 2; ++n) _Pragma("unroll") for (int k = 0; k < 2; ++k) \
;         acc[ai][bj][m][n] = __builtin_amdgcn_mfma_f32_16x16x32_bf16(Bt[n][k], At[m][k], acc[ai][bj][m][n], 0, 0, 0); __builtin_amdgcn_s_setprio(0); } while (0)
; #define PG8_WAIT_V(n) asm volatile("s_waitcnt vmcnt(" #n ")" ::: "memory")
; #define PG8_WAIT_L(n) asm volatile("s_waitcnt lgkmcnt(" #n ")" ::: "memory")
; #define PG8_BAR __builtin_amdgcn_s_barrier()
; #define PG8_SCHED __builtin_amdgcn_sched_barrier(0)
; template <class Epi, class Sched>
; __device__ __forceinline__ void gemm_phase(LAS unsigned char* lds, const Gemm g, const Sched& S, const Epi& E) {
;     ...
;             PG8_BAR; PG8_WAIT_L(0); PG8_MMA(0, 1, At, B1); PG8_BAR;
;             PG8_LDA(At, 1, 1); PG8_STAGE(PG8_SA(1, 0), a3, voffA);
;             PG8_BAR; PG8_WAIT_L(0); PG8_MMA(1, 0, At, B0); PG8_BAR; PG8_SCHED;
;             PG8_STAGE(PG8_SB(1, 1), b3 + hstepB, voffB);
;             PG8_WAIT_V(6); PG8_BAR; PG8_MMA(1, 1, At, B1); PG8_BAR;
	s_waitcnt lgkmcnt(0)
	s_waitcnt lgkmcnt(0)
	v_mfma_f32_16x16x32_bf16 v[62:65], v[130:133], v[146:149], v[62:65]
	v_mfma_f32_16x16x32_bf16 v[58:61], v[138:141], v[146:149], v[58:61]
	v_mfma_f32_16x16x32_bf16 v[46:49], v[130:133], v[182:185], v[46:49]
	v_mfma_f32_16x16x32_bf16 v[42:45], v[138:141], v[182:185], v[42:45]
	v_mfma_f32_16x16x32_bf16 v[30:33], v[130:133], v[190:193], v[30:33]
	v_mfma_f32_16x16x32_bf16 v[26:29], v[138:141], v[190:193], v[26:29]
	v_mfma_f32_16x16x32_bf16 v[14:17], v[130:133], v[212:215], v[14:17]
	v_mfma_f32_16x16x32_bf16 v[10:13], v[138:141], v[212:215], v[10:13]
	v_mfma_f32_16x16x32_bf16 v[62:65], v[134:137], v[150:153], v[62:65]
	v_mfma_f32_16x16x32_bf16 v[58:61], v[142:145], v[150:153], v[58:61]
	v_mfma_f32_16x16x32_bf16 v[46:49], v[134:137], v[186:189], v[46:49]
	v_mfma_f32_16x16x32_bf16 v[42:45], v[142:145], v[186:189], v[42:45]
	v_mfma_f32_16x16x32_bf16 v[30:33], v[134:137], v[194:197], v[30:33]
	v_mfma_f32_16x16x32_bf16 v[26:29], v[142:145], v[194:197], v[26:29]
	v_mfma_f32_16x16x32_bf16 v[14:17], v[134:137], v[216:219], v[14:17]
	v_mfma_f32_16x16x32_bf16 v[10:13], v[142:145], v[216:219], v[10:13]
	s_barrier
	s_add_u32 s50, s50, 0x80080
	s_addc_u32 s51, s51, 0
	s_add_i32 s23, s52, s25
	v_lshl_add_u64 v[130:131], s[50:51], 0, v[174:175]
	s_mov_b32 m0, s23
	s_nop 0
	global_load_lds_dwordx4 v[130:131], off
	v_lshl_add_u64 v[130:131], s[50:51], 0, v[170:171]
	s_add_i32 m0, s23, 0x2000
	s_nop 0
	global_load_lds_dwordx4 v[130:131], off
	s_waitcnt vmcnt(6)
	s_barrier
	v_mfma_f32_16x16x32_bf16 v[54:57], v[220:223], v[146:149], v[54:57]
	v_mfma_f32_16x16x32_bf16 v[50:53], v[228:231], v[146:149], v[50:53]
	v_mfma_f32_16x16x32_bf16 v[38:41], v[220:223], v[182:185], v[38:41]
	v_mfma_f32_16x16x32_bf16 v[34:37], v[228:231], v[182:185], v[34:37]
	v_mfma_f32_16x16x32_bf16 v[22:25], v[220:223], v[190:193], v[22:25]
	v_mfma_f32_16x16x32_bf16 v[18:21], v[228:231], v[190:193], v[18:21]
	v_mfma_f32_16x16x32_bf16 v[6:9], v[220:223], v[212:215], v[6:9]
	v_mfma_f32_16x16x32_bf16 v[2:5], v[228:231], v[212:215], v[2:5]
	v_mfma_f32_16x16x32_bf16 v[54:57], v[224:227], v[150:153], v[54:57]
	v_mfma_f32_16x16x32_bf16 v[50:53], v[232:235], v[150:153], v[50:53]
	v_mfma_f32_16x16x32_bf16 v[38:41], v[224:227], v[186:189], v[38:41]
	v_mfma_f32_16x16x32_bf16 v[34:37], v[232:235], v[186:189], v[34:37]
	v_mfma_f32_16x16x32_bf16 v[22:25], v[224:227], v[194:197], v[22:25]
	v_mfma_f32_16x16x32_bf16 v[18:21], v[232:235], v[194:197], v[18:21]
	v_mfma_f32_16x16x32_bf16 v[6:9], v[224:227], v[216:219], v[6:9]
	v_mfma_f32_16x16x32_bf16 v[2:5], v[232:235], v[216:219], v[2:5]
	s_add_i32 s66, s66, 2
	s_add_u32 s48, s48, 0x100
	s_addc_u32 s49, s49, 0
	s_add_u32 s70, s70, 0x100
	s_addc_u32 s71, s71, 0
	s_cmp_gt_u32 s66, 29
	s_barrier
	s_cbranch_scc0 .LBB0_738
; __device__ __forceinline__ unsigned cvt_pk_bf16(float lo, float hi) { unsigned r; asm volatile("v_cvt_pk_bf16_f32 %0, %1, %2" : "=v"(r) : "v"(lo), "v"(hi)); return r; }
; __device__ __forceinline__ float bf_lo(unsigned w) { return __uint_as_float(w << 16); }
; __device__ __forceinline__ float bf_hi(unsigned w) { return __uint_as_float(w & 0xffff0000u); }
;     __device__ __forceinline__ void operator()(const f32x4 (&acc)[2][2][4][2], const Unit& u, int ui, const LAS float* rtab, int wr, int wc, int fr, int fq) const {
;         const int row0 = u.pm * BM + wr * 64 + fr, col0 = u.pn * BM + wc * 32 + 8 * fq;
; #pragma unroll
;         for (int ai = 0; ai < 2; ++ai) {
;             u32x4 xv[4][2];
; #pragma unroll
;             for (int m = 0; m < 4; ++m)
; #pragma unroll
;                 for (int bj = 0; bj < 2; ++bj) xv[m][bj] = *(const u32x4*)(XB + (size_t)(row0 + ai * HALF + m * 16) * DM + col0 + bj * HALF);
; #pragma unroll
;             for (int m = 0; m < 4; ++m) { const int row = row0 + ai * HALF + m * 16; float ss = 0.f;
; #pragma unroll
;                 for (int bj = 0; bj < 2; ++bj) {
;                     const f32x4 a0 = acc[ai][bj][m][0], a1 = acc[ai][bj][m][1]; const u32x4 xo = xv[m][bj]; u32x4 w;
;                     w.x = cvt_pk_bf16(bf_lo(xo.x) + a0[0], bf_hi(xo.x) + a0[1]); w.y = cvt_pk_bf16(bf_lo(xo.y) + a0[2], bf_hi(xo.y) + a0[3]);
;                     w.z = cvt_pk_bf16(bf_lo(xo.z) + a1[0], bf_hi(xo.z) + a1[1]); w.w = cvt_pk_bf16(bf_lo(xo.w) + a1[2], bf_hi(xo.w) + a1[3]);
;                     *(u32x4*)(XB + (size_t)row * DM + col0 + bj * HALF) = w;
; #pragma unroll
;                     for (int e = 0; e < 4; ++e) { const float lo = bf_lo(w[e]), hi = bf_hi(w[e]); ss += lo * lo + hi * hi; }
;                 }
;                 ss += __shfl_xor(ss, 16); ss += __shfl_xor(ss, 32);
;                 if (fq == 0) ssq_next[(size_t)row * 32 + (u.pn & 7) * 4 + wc] = ss; }
	v_lshl_or_b32 v182, s57, 8, v209
	v_lshl_add_u32 v186, s58, 8, v1
	v_ashrrev_i32_e32 v183, 31, v182
	v_lshlrev_b64 v[130:131], 1, v[182:183]
	v_ashrrev_i32_e32 v187, 31, v186
	v_lshl_add_u64 v[184:185], s[74:75], 0, v[130:131]
	v_lshlrev_b64 v[132:133], 12, v[186:187]
	v_lshl_add_u64 v[134:135], v[184:185], 0, v[132:133]
	global_load_dwordx4 v[212:215], v[134:135], off
	global_load_dwordx4 v[216:219], v[134:135], off offset:256
	v_or_b32_e32 v196, 16, v186
	v_or_b32_e32 v192, 32, v186
	v_or_b32_e32 v188, 48, v186
	v_ashrrev_i32_e32 v197, 31, v196
	v_ashrrev_i32_e32 v193, 31, v192
	v_ashrrev_i32_e32 v189, 31, v188
	v_lshlrev_b64 v[198:199], 12, v[196:197]
	v_lshlrev_b64 v[194:195], 12, v[192:193]
	v_lshlrev_b64 v[190:191], 12, v[188:189]
	v_lshl_add_u64 v[132:133], s[74:75], 0, v[132:133]
	v_lshl_add_u64 v[134:135], v[184:185], 0, v[198:199]
	v_lshl_add_u64 v[136:137], v[184:185], 0, v[194:195]
	v_lshl_add_u64 v[220:221], v[184:185], 0, v[190:191]
	v_lshl_add_u64 v[222:223], v[132:133], 0, v[130:131]
	global_load_dwordx4 v[150:153], v[134:135], off
	global_load_dwordx4 v[146:149], v[134:135], off offset:256
	global_load_dwordx4 v[142:145], v[136:137], off
	global_load_dwordx4 v[138:141], v[136:137], off offset:256
	s_nop 0
	global_load_dwordx4 v[134:137], v[220:221], off
	global_load_dwordx4 v[130:133], v[220:221], off offset:256
	s_lshl_b32 s21, s57, 2
	s_and_b32 s21, s21, 28
	s_waitcnt vmcnt(0)
	v_lshlrev_b32_e32 v211, 16, v212
	v_and_b32_e32 v212, 0xffff0000, v212
	v_lshlrev_b32_e32 v220, 16, v213
	v_and_b32_e32 v213, 0xffff0000, v213
	v_lshlrev_b32_e32 v221, 16, v214
	v_and_b32_e32 v214, 0xffff0000, v214
	v_lshlrev_b32_e32 v227, 16, v218
	v_and_b32_e32 v218, 0xffff0000, v218
	v_lshlrev_b32_e32 v224, 16, v215
	v_and_b32_e32 v215, 0xffff0000, v215
	v_lshlrev_b32_e32 v228, 16, v219
	v_and_b32_e32 v219, 0xffff0000, v219
	v_add_f32_e32 v126, v126, v211
	v_add_f32_e32 v127, v127, v212
	v_add_f32_e32 v128, v128, v220
	v_add_f32_e32 v129, v129, v213
	v_add_f32_e32 v122, v122, v221
	v_add_f32_e32 v123, v123, v214
	v_add_f32_e32 v211, v114, v227
	v_add_f32_e32 v212, v115, v218
	v_cvt_pk_bf16_f32 v114, v126, v127
	v_cvt_pk_bf16_f32 v115, v128, v129
	v_add_f32_e32 v124, v124, v224
	v_add_f32_e32 v125, v125, v215
	v_add_f32_e32 v213, v116, v228
	v_add_f32_e32 v214, v117, v219
	v_cvt_pk_bf16_f32 v116, v122, v123
	v_cvt_pk_bf16_f32 v117, v124, v125
	global_store_dwordx4 v[222:223], v[114:117], off
	v_lshlrev_b32_e32 v122, 16, v114
	v_lshlrev_b32_e32 v123, 16, v115
	v_and_b32_e32 v114, 0xffff0000, v114
	v_and_b32_e32 v115, 0xffff0000, v115
	v_lshlrev_b32_e32 v225, 16, v216
	v_lshlrev_b32_e32 v124, 16, v116
	v_and_b32_e32 v116, 0xffff0000, v116
	v_mul_f32_e32 v114, v114, v114
	v_mul_f32_e32 v115, v115, v115
	v_and_b32_e32 v216, 0xffff0000, v216
	v_add_f32_e32 v118, v118, v225
	v_lshlrev_b32_e32 v125, 16, v117
	v_and_b32_e32 v117, 0xffff0000, v117
	v_mul_f32_e32 v116, v116, v116
	v_fmac_f32_e32 v114, v122, v122
	v_fmac_f32_e32 v115, v123, v123
	v_lshlrev_b32_e32 v226, 16, v217
	v_and_b32_e32 v217, 0xffff0000, v217
	v_add_f32_e32 v119, v119, v216
	v_cvt_pk_bf16_f32 v118, v118, v119
	v_mul_f32_e32 v117, v117, v117
	v_and_b32_e32 v127, 0xffff0000, v118
	v_fmac_f32_e32 v116, v124, v124
	v_add_f32_e32 v114, v114, v115
	v_add_f32_e32 v120, v120, v226
	v_add_f32_e32 v121, v121, v217
	v_cvt_pk_bf16_f32 v119, v120, v121
	v_lshlrev_b32_e32 v126, 16, v118
	v_fmac_f32_e32 v117, v125, v125
	v_mul_f32_e32 v122, v127, v127
	v_add_f32_e32 v114, v114, v116
	v_and_b32_e32 v116, 0xffff0000, v119
	v_fmac_f32_e32 v122, v126, v126
	v_add_f32_e32 v114, v114, v117
	v_lshlrev_b32_e32 v115, 16, v119
	v_mul_f32_e32 v116, v116, v116
	v_add_f32_e32 v114, v114, v122
	v_fmac_f32_e32 v116, v115, v115
	v_cvt_pk_bf16_f32 v120, v211, v212
	v_add_f32_e32 v114, v114, v116
	v_and_b32_e32 v116, 0xffff0000, v120
	v_lshlrev_b32_e32 v115, 16, v120
	v_mul_f32_e32 v116, v116, v116
	v_fmac_f32_e32 v116, v115, v115
	v_cvt_pk_bf16_f32 v121, v213, v214
	v_add_f32_e32 v114, v114, v116
	v_and_b32_e32 v116, 0xffff0000, v121
	v_lshlrev_b32_e32 v115, 16, v121
	v_mul_f32_e32 v116, v116, v116
	v_fmac_f32_e32 v116, v115, v115
	v_add_f32_e32 v115, v114, v116
	v_and_b32_e32 v116, 64, v207
	v_xor_b32_e32 v114, 16, v207
	v_add_u32_e32 v117, 64, v116
	v_cmp_lt_i32_e32 vcc, v114, v117
	global_store_dwordx4 v[222:223], v[118:121], off offset:256
	s_nop 0
	v_cndmask_b32_e32 v114, v207, v114, vcc
	v_lshlrev_b32_e32 v114, 2, v114
	ds_bpermute_b32 v116, v114, v115
	s_waitcnt lgkmcnt(0)
	v_add_f32_e32 v116, v115, v116
	v_xor_b32_e32 v115, 32, v207
	v_cmp_lt_i32_e32 vcc, v115, v117
	s_nop 1
	v_cndmask_b32_e32 v115, v207, v115, vcc
	v_lshlrev_b32_e32 v115, 2, v115
	ds_bpermute_b32 v117, v115, v116
	s_and_saveexec_b64 s[48:49], s[42:43]
	s_cbranch_execz .LBB0_741
	s_waitcnt lgkmcnt(0)
	v_add_f32_e32 v118, v116, v117
	v_lshlrev_b64 v[116:117], 7, v[186:187]
	v_lshl_add_u64 v[116:117], s[0:1], 0, v[116:117]
	s_lshl_b32 s68, s21, 2
	v_lshl_add_u64 v[116:117], v[116:117], 0, s[68:69]
	s_lshl_b32 s68, s55, 2
	v_lshl_add_u64 v[116:117], v[116:117], 0, s[68:69]
	global_store_dword v[116:117], v118, off

; #define PG8_STAGE(bufoff, gbase, voff) do { _Pragma("unroll") for (int _i = 0; _i < 2; ++_i) \
;         __builtin_amdgcn_global_load_lds((const unsigned*)((const char*)(gbase) + (voff)[_i]), (LAS unsigned*)(lds + (bufoff) + ldsw + _i * 8192), 16, 0, 0); } while (0)
; #define PG8_LDA(dst, b, h) do { _Pragma("unroll") for (int m = 0; m < 4; ++m) _Pragma("unroll") for (int k = 0; k < 2; ++k) dst[m][k] = *(const LAS bf16x8*)(lds + PG8_SA(b, h) + aoff + m * 2048 + k * 1024); } while (0)
; #define PG8_LDB(dst, b, h) do { _Pragma("unroll") for (int n = 0; n < 2; ++n) _Pragma("unroll") for (int k = 0; k < 2; ++k) dst[n][k] = *(const LAS bf16x8*)(lds + PG8_SB(b, h) + boff + n * 2048 + k * 1024); } while (0)
; #define PG8_MMA(ai, bj, At, Bt) do { __builtin_amdgcn_s_setprio(1); _Pragma("unroll") for (int m = 0; m < 4; ++m) _Pragma("unroll") for (int n = 0; n < 2; ++n) _Pragma("unroll") for (int k = 0; k < 2; ++k) \
;         acc[ai][bj][m][n] = __builtin_amdgcn_mfma_f32_16x16x32_bf16(Bt[n][k], At[m][k], acc[ai][bj][m][n], 0, 0, 0); __builtin_amdgcn_s_setprio(0); } while (0)
; #define PG8_WAIT_L(n) asm volatile("s_waitcnt lgkmcnt(" #n ")" ::: "memory")
; #define PG8_BAR __builtin_amdgcn_s_barrier()
; #define PG8_SCHED __builtin_amdgcn_sched_barrier(0)
; template <class Epi, class Sched>
; __device__ __forceinline__ void gemm_phase(LAS unsigned char* lds, const Gemm g, const Sched& S, const Epi& E) {
;     ...
;             PG8_LDB(B0, 0, 0); PG8_SCHED; PG8_LDA(At, 0, 0); PG8_STAGE(PG8_SA(1, 1), a1 + hstepA, voffA);
;             PG8_WAIT_L(8); PG8_BAR; PG8_WAIT_L(0); PG8_MMA(0, 0, At, B0); PG8_BAR; PG8_SCHED;
;             PG8_LDB(B1, 0, 1); PG8_STAGE(PG8_SB(0, 0), b2, voffB);
;             PG8_BAR; PG8_WAIT_L(0); PG8_MMA(0, 1, At, B1); PG8_BAR;
;             PG8_LDA(At, 0, 1); PG8_STAGE(PG8_SA(0, 0), a2, voffA);
;             PG8_BAR; PG8_WAIT_L(0); PG8_MMA(1, 0, At, B0); PG8_BAR; PG8_SCHED;
;             PG8_STAGE(PG8_SB(0, 1), b2 + hstepB, voffB);
.LBB0_830:
	s_add_u32 s23, s44, 0xfff80080
	s_addc_u32 s46, s45, -1
	s_add_i32 s67, 0, 0x10000
	v_add_u32_e32 v162, s67, v142
	ds_read_b128 v[146:149], v162
	ds_read_b128 v[150:153], v162 offset:1024
	ds_read_b128 v[170:173], v162 offset:2048
	ds_read_b128 v[174:177], v162 offset:3072
	s_cmp_eq_u32 s66, 28
	s_cselect_b32 s49, s21, s46
	s_cselect_b32 s48, s56, s23
	s_cselect_b32 s47, s1, s59
	s_cselect_b32 s46, s57, s58
	v_lshl_add_u64 v[198:199], s[44:45], 0, v[138:139]
	s_add_i32 m0, s27, 0xc000
	ds_read_b128 v[178:181], v145
	ds_read_b128 v[182:185], v145 offset:1024
	ds_read_b128 v[186:189], v145 offset:2048
	ds_read_b128 v[190:193], v145 offset:3072
	ds_read_b128 v[194:197], v145 offset:4096
	ds_read_b128 v[210:213], v145 offset:5120
	ds_read_b128 v[214:217], v145 offset:6144
	ds_read_b128 v[218:221], v145 offset:7168
	global_load_lds_dwordx4 v[198:199], off
	v_lshl_add_u64 v[198:199], s[44:45], 0, v[140:141]
	s_add_i32 m0, s27, 0xe000
	s_nop 0
	global_load_lds_dwordx4 v[198:199], off
	s_waitcnt lgkmcnt(8)
	s_barrier
	s_waitcnt lgkmcnt(0)
	s_waitcnt lgkmcnt(0)
	v_mfma_f32_16x16x32_bf16 v[126:129], v[146:149], v[178:181], v[126:129]
	v_mfma_f32_16x16x32_bf16 v[122:125], v[170:173], v[178:181], v[122:125]
	v_mfma_f32_16x16x32_bf16 v[110:113], v[146:149], v[186:189], v[110:113]
	v_mfma_f32_16x16x32_bf16 v[106:109], v[170:173], v[186:189], v[106:109]
	v_mfma_f32_16x16x32_bf16 v[94:97], v[146:149], v[194:197], v[94:97]
	v_mfma_f32_16x16x32_bf16 v[90:93], v[170:173], v[194:197], v[90:93]
	v_mfma_f32_16x16x32_bf16 v[78:81], v[146:149], v[214:217], v[78:81]
	v_mfma_f32_16x16x32_bf16 v[74:77], v[170:173], v[214:217], v[74:77]
	v_mfma_f32_16x16x32_bf16 v[126:129], v[150:153], v[182:185], v[126:129]
	v_mfma_f32_16x16x32_bf16 v[122:125], v[174:177], v[182:185], v[122:125]
	v_mfma_f32_16x16x32_bf16 v[110:113], v[150:153], v[190:193], v[110:113]
	v_mfma_f32_16x16x32_bf16 v[106:109], v[174:177], v[190:193], v[106:109]
	v_mfma_f32_16x16x32_bf16 v[94:97], v[150:153], v[210:213], v[94:97]
	v_mfma_f32_16x16x32_bf16 v[90:93], v[174:177], v[210:213], v[90:93]
	v_mfma_f32_16x16x32_bf16 v[78:81], v[150:153], v[218:221], v[78:81]
	v_mfma_f32_16x16x32_bf16 v[74:77], v[174:177], v[218:221], v[74:77]
	s_barrier
	s_add_i32 s23, 0, 0x14000
	s_add_i32 s67, s67, s26
	v_add_u32_e32 v162, s23, v142
	v_lshl_add_u64 v[198:199], s[46:47], 0, v[134:135]
	s_mov_b32 m0, s67
	ds_read_b128 v[222:225], v162
	ds_read_b128 v[226:229], v162 offset:1024
	ds_read_b128 v[230:233], v162 offset:2048
	ds_read_b128 v[234:237], v162 offset:3072
	global_load_lds_dwordx4 v[198:199], off
	v_lshl_add_u64 v[238:239], s[46:47], 0, v[130:131]
	s_add_i32 m0, s67, 0x2000
	s_nop 0
	global_load_lds_dwordx4 v[238:239], off
	s_barrier
	s_waitcnt lgkmcnt(0)
	s_waitcnt lgkmcnt(0)
	v_mfma_f32_16x16x32_bf16 v[118:121], v[222:225], v[178:181], v[118:121]
	v_mfma_f32_16x16x32_bf16 v[114:117], v[230:233], v[178:181], v[114:117]
	v_mfma_f32_16x16x32_bf16 v[102:105], v[222:225], v[186:189], v[102:105]
	v_mfma_f32_16x16x32_bf16 v[98:101], v[230:233], v[186:189], v[98:101]
	v_mfma_f32_16x16x32_bf16 v[86:89], v[222:225], v[194:197], v[86:89]
	v_mfma_f32_16x16x32_bf16 v[82:85], v[230:233], v[194:197], v[82:85]
	v_mfma_f32_16x16x32_bf16 v[70:73], v[222:225], v[214:217], v[70:73]
	v_mfma_f32_16x16x32_bf16 v[66:69], v[230:233], v[214:217], v[66:69]
	v_mfma_f32_16x16x32_bf16 v[118:121], v[226:229], v[182:185], v[118:121]
	v_mfma_f32_16x16x32_bf16 v[114:117], v[234:237], v[182:185], v[114:117]
	v_mfma_f32_16x16x32_bf16 v[102:105], v[226:229], v[190:193], v[102:105]
	v_mfma_f32_16x16x32_bf16 v[98:101], v[234:237], v[190:193], v[98:101]
	v_mfma_f32_16x16x32_bf16 v[86:89], v[226:229], v[210:213], v[86:89]
	v_mfma_f32_16x16x32_bf16 v[82:85], v[234:237], v[210:213], v[82:85]
	v_mfma_f32_16x16x32_bf16 v[70:73], v[226:229], v[218:221], v[70:73]
	v_mfma_f32_16x16x32_bf16 v[66:69], v[234:237], v[218:221], v[66:69]
	s_mov_b32 m0, s27
	v_lshl_add_u64 v[240:241], s[48:49], 0, v[136:137]
	s_barrier
	ds_read_b128 v[178:181], v145 offset:16384
	ds_read_b128 v[182:185], v145 offset:17408
	ds_read_b128 v[186:189], v145 offset:18432
	ds_read_b128 v[190:193], v145 offset:19456
	ds_read_b128 v[194:197], v145 offset:20480
	ds_read_b128 v[210:213], v145 offset:21504
	ds_read_b128 v[214:217], v145 offset:22528
	ds_read_b128 v[218:221], v145 offset:23552
	global_load_lds_dwordx4 v[240:241], off
	v_lshl_add_u64 v[242:243], s[48:49], 0, v[132:133]
	s_mov_b32 m0, s28
	s_nop 0
	global_load_lds_dwordx4 v[242:243], off
	s_barrier
	s_waitcnt lgkmcnt(0)
	s_waitcnt lgkmcnt(0)
	v_mfma_f32_16x16x32_bf16 v[62:65], v[146:149], v[178:181], v[62:65]
	v_mfma_f32_16x16x32_bf16 v[58:61], v[170:173], v[178:181], v[58:61]
	v_mfma_f32_16x16x32_bf16 v[46:49], v[146:149], v[186:189], v[46:49]
	v_mfma_f32_16x16x32_bf16 v[42:45], v[170:173], v[186:189], v[42:45]
	v_mfma_f32_16x16x32_bf16 v[30:33], v[146:149], v[194:197], v[30:33]
	v_mfma_f32_16x16x32_bf16 v[26:29], v[170:173], v[194:197], v[26:29]
	v_mfma_f32_16x16x32_bf16 v[14:17], v[146:149], v[214:217], v[14:17]
	v_mfma_f32_16x16x32_bf16 v[10:13], v[170:173], v[214:217], v[10:13]
	v_mfma_f32_16x16x32_bf16 v[62:65], v[150:153], v[182:185], v[62:65]
	v_mfma_f32_16x16x32_bf16 v[58:61], v[174:177], v[182:185], v[58:61]
	v_mfma_f32_16x16x32_bf16 v[46:49], v[150:153], v[190:193], v[46:49]
	v_mfma_f32_16x16x32_bf16 v[42:45], v[174:177], v[190:193], v[42:45]
	v_mfma_f32_16x16x32_bf16 v[30:33], v[150:153], v[210:213], v[30:33]
	v_mfma_f32_16x16x32_bf16 v[26:29], v[174:177], v[210:213], v[26:29]
	v_mfma_f32_16x16x32_bf16 v[14:17], v[150:153], v[218:221], v[14:17]
	v_mfma_f32_16x16x32_bf16 v[10:13], v[174:177], v[218:221], v[10:13]
	s_barrier
; #define PG8_STAGE(bufoff, gbase, voff) do { _Pragma("unroll") for (int _i = 0; _i < 2; ++_i) \
;         __builtin_amdgcn_global_load_lds((const unsigned*)((const char*)(gbase) + (voff)[_i]), (LAS unsigned*)(lds + (bufoff) + ldsw + _i * 8192), 16, 0, 0); } while (0)
; #define PG8_LDA(dst, b, h) do { _Pragma("unroll") for (int m = 0; m < 4; ++m) _Pragma("unroll") for (int k = 0; k < 2; ++k) dst[m][k] = *(const LAS bf16x8*)(lds + PG8_SA(b, h) + aoff + m * 2048 + k * 1024); } while (0)
; #define PG8_LDB(dst, b, h) do { _Pragma("unroll") for (int n = 0; n < 2; ++n) _Pragma("unroll") for (int k = 0; k < 2; ++k) dst[n][k] = *(const LAS bf16x8*)(lds + PG8_SB(b, h) + boff + n * 2048 + k * 1024); } while (0)
; #define PG8_MMA(ai, bj, At, Bt) do { __builtin_amdgcn_s_setprio(1); _Pragma("unroll") for (int m = 0; m < 4; ++m) _Pragma("unroll") for (int n = 0; n < 2; ++n) _Pragma("unroll") for (int k = 0; k < 2; ++k) \
;         acc[ai][bj][m][n] = __builtin_amdgcn_mfma_f32_16x16x32_bf16(Bt[n][k], At[m][k], acc[ai][bj][m][n], 0, 0, 0); __builtin_amdgcn_s_setprio(0); } while (0)
; #define PG8_WAIT_V(n) asm volatile("s_waitcnt vmcnt(" #n ")" ::: "memory")
; #define PG8_WAIT_L(n) asm volatile("s_waitcnt lgkmcnt(" #n ")" ::: "memory")
; #define PG8_BAR __builtin_amdgcn_s_barrier()
; #define PG8_SCHED __builtin_amdgcn_sched_barrier(0)
; template <class Epi, class Sched>
; __device__ __forceinline__ void gemm_phase(LAS unsigned char* lds, const Gemm g, const Sched& S, const Epi& E) {
;     ...
;             PG8_STAGE(PG8_SB(0, 1), b2 + hstepB, voffB);
;             PG8_WAIT_V(6); PG8_BAR; PG8_MMA(1, 1, At, B1); PG8_BAR;
;             PG8_LDB(B0, 1, 0); PG8_SCHED; PG8_LDA(At, 1, 0); PG8_STAGE(PG8_SA(0, 1), a2 + hstepA, voffA);
;             PG8_WAIT_L(8); PG8_BAR; PG8_WAIT_L(0); PG8_MMA(0, 0, At, B0); PG8_BAR; PG8_SCHED;
;             PG8_LDB(B1, 1, 1); PG8_STAGE(PG8_SB(1, 0), b3, voffB);
;             PG8_BAR; PG8_WAIT_L(0); PG8_MMA(0, 1, At, B1); PG8_BAR;
;             PG8_LDA(At, 1, 1); PG8_STAGE(PG8_SA(1, 0), a3, voffA);
;             PG8_BAR; PG8_WAIT_L(0); PG8_MMA(1, 0, At, B0); PG8_BAR; PG8_SCHED;
	s_add_u32 s70, s46, 0x80000
	s_addc_u32 s71, s47, 0
	s_add_i32 s23, s23, s26
	v_lshl_add_u64 v[146:147], s[70:71], 0, v[134:135]
	s_mov_b32 m0, s23
	s_nop 0
	global_load_lds_dwordx4 v[146:147], off
	v_lshl_add_u64 v[146:147], s[70:71], 0, v[130:131]
	s_add_i32 m0, s23, 0x2000
	s_nop 0
	global_load_lds_dwordx4 v[146:147], off
	s_waitcnt vmcnt(6)
	s_barrier
	v_mfma_f32_16x16x32_bf16 v[54:57], v[222:225], v[178:181], v[54:57]
	v_mfma_f32_16x16x32_bf16 v[50:53], v[230:233], v[178:181], v[50:53]
	v_mfma_f32_16x16x32_bf16 v[38:41], v[222:225], v[186:189], v[38:41]
	v_mfma_f32_16x16x32_bf16 v[34:37], v[230:233], v[186:189], v[34:37]
	v_mfma_f32_16x16x32_bf16 v[22:25], v[222:225], v[194:197], v[22:25]
	v_mfma_f32_16x16x32_bf16 v[18:21], v[230:233], v[194:197], v[18:21]
	v_mfma_f32_16x16x32_bf16 v[6:9], v[222:225], v[214:217], v[6:9]
	v_mfma_f32_16x16x32_bf16 v[2:5], v[230:233], v[214:217], v[2:5]
	v_mfma_f32_16x16x32_bf16 v[54:57], v[226:229], v[182:185], v[54:57]
	v_mfma_f32_16x16x32_bf16 v[50:53], v[234:237], v[182:185], v[50:53]
	v_mfma_f32_16x16x32_bf16 v[38:41], v[226:229], v[190:193], v[38:41]
	v_mfma_f32_16x16x32_bf16 v[34:37], v[234:237], v[190:193], v[34:37]
	v_mfma_f32_16x16x32_bf16 v[22:25], v[226:229], v[210:213], v[22:25]
	v_mfma_f32_16x16x32_bf16 v[18:21], v[234:237], v[210:213], v[18:21]
	v_mfma_f32_16x16x32_bf16 v[6:9], v[226:229], v[218:221], v[6:9]
	v_mfma_f32_16x16x32_bf16 v[2:5], v[234:237], v[218:221], v[2:5]
	s_add_i32 s23, 0, 0x18000
	v_add_u32_e32 v162, s23, v142
	s_barrier
	ds_read_b128 v[146:149], v162
	ds_read_b128 v[150:153], v162 offset:1024
	ds_read_b128 v[170:173], v162 offset:2048
	ds_read_b128 v[174:177], v162 offset:3072
	s_add_u32 s48, s48, 0x80000
	s_addc_u32 s49, s49, 0
	s_mov_b32 m0, s29
	v_lshl_add_u64 v[222:223], s[48:49], 0, v[136:137]
	ds_read_b128 v[178:181], v145 offset:32768
	ds_read_b128 v[182:185], v145 offset:33792
	ds_read_b128 v[186:189], v145 offset:34816
	ds_read_b128 v[190:193], v145 offset:35840
	ds_read_b128 v[194:197], v145 offset:36864
	ds_read_b128 v[210:213], v145 offset:37888
	ds_read_b128 v[214:217], v145 offset:38912
	ds_read_b128 v[218:221], v145 offset:39936
	global_load_lds_dwordx4 v[222:223], off
	v_lshl_add_u64 v[222:223], s[48:49], 0, v[132:133]
	s_mov_b32 m0, s31
	s_nop 0
	global_load_lds_dwordx4 v[222:223], off
	s_waitcnt lgkmcnt(8)
	s_barrier
	s_waitcnt lgkmcnt(0)
	s_waitcnt lgkmcnt(0)
	v_mfma_f32_16x16x32_bf16 v[126:129], v[146:149], v[178:181], v[126:129]
	v_mfma_f32_16x16x32_bf16 v[122:125], v[170:173], v[178:181], v[122:125]
	v_mfma_f32_16x16x32_bf16 v[110:113], v[146:149], v[186:189], v[110:113]
	v_mfma_f32_16x16x32_bf16 v[106:109], v[170:173], v[186:189], v[106:109]
	v_mfma_f32_16x16x32_bf16 v[94:97], v[146:149], v[194:197], v[94:97]
	v_mfma_f32_16x16x32_bf16 v[90:93], v[170:173], v[194:197], v[90:93]
	v_mfma_f32_16x16x32_bf16 v[78:81], v[146:149], v[214:217], v[78:81]
	v_mfma_f32_16x16x32_bf16 v[74:77], v[170:173], v[214:217], v[74:77]
	v_mfma_f32_16x16x32_bf16 v[126:129], v[150:153], v[182:185], v[126:129]
	v_mfma_f32_16x16x32_bf16 v[122:125], v[174:177], v[182:185], v[122:125]
	v_mfma_f32_16x16x32_bf16 v[110:113], v[150:153], v[190:193], v[110:113]
	v_mfma_f32_16x16x32_bf16 v[106:109], v[174:177], v[190:193], v[106:109]
	v_mfma_f32_16x16x32_bf16 v[94:97], v[150:153], v[210:213], v[94:97]
	v_mfma_f32_16x16x32_bf16 v[90:93], v[174:177], v[210:213], v[90:93]
	v_mfma_f32_16x16x32_bf16 v[78:81], v[150:153], v[218:221], v[78:81]
	v_mfma_f32_16x16x32_bf16 v[74:77], v[174:177], v[218:221], v[74:77]
	s_barrier
	s_add_i32 s48, 0, 0x1c000
	s_add_i32 s23, s23, s26
	v_add_u32_e32 v162, s48, v142
	v_lshl_add_u64 v[198:199], v[198:199], 0, s[10:11]
	s_mov_b32 m0, s23
	ds_read_b128 v[222:225], v162
	ds_read_b128 v[226:229], v162 offset:1024
	ds_read_b128 v[230:233], v162 offset:2048
	ds_read_b128 v[234:237], v162 offset:3072
	global_load_lds_dwordx4 v[198:199], off
	v_lshl_add_u64 v[198:199], v[238:239], 0, s[10:11]
	s_add_i32 m0, s23, 0x2000
	s_nop 0
	global_load_lds_dwordx4 v[198:199], off
	s_barrier
	s_waitcnt lgkmcnt(0)
	s_waitcnt lgkmcnt(0)
	v_mfma_f32_16x16x32_bf16 v[118:121], v[222:225], v[178:181], v[118:121]
	v_mfma_f32_16x16x32_bf16 v[114:117], v[230:233], v[178:181], v[114:117]
	v_mfma_f32_16x16x32_bf16 v[102:105], v[222:225], v[186:189], v[102:105]
	v_mfma_f32_16x16x32_bf16 v[98:101], v[230:233], v[186:189], v[98:101]
	v_mfma_f32_16x16x32_bf16 v[86:89], v[222:225], v[194:197], v[86:89]
	v_mfma_f32_16x16x32_bf16 v[82:85], v[230:233], v[194:197], v[82:85]
	v_mfma_f32_16x16x32_bf16 v[70:73], v[222:225], v[214:217], v[70:73]
	v_mfma_f32_16x16x32_bf16 v[66:69], v[230:233], v[214:217], v[66:69]
	v_mfma_f32_16x16x32_bf16 v[118:121], v[226:229], v[182:185], v[118:121]
	v_mfma_f32_16x16x32_bf16 v[114:117], v[234:237], v[182:185], v[114:117]
	v_mfma_f32_16x16x32_bf16 v[102:105], v[226:229], v[190:193], v[102:105]
	v_mfma_f32_16x16x32_bf16 v[98:101], v[234:237], v[190:193], v[98:101]
	v_mfma_f32_16x16x32_bf16 v[86:89], v[226:229], v[210:213], v[86:89]
	v_mfma_f32_16x16x32_bf16 v[82:85], v[234:237], v[210:213], v[82:85]
	v_mfma_f32_16x16x32_bf16 v[70:73], v[226:229], v[218:221], v[70:73]
	v_mfma_f32_16x16x32_bf16 v[66:69], v[234:237], v[218:221], v[66:69]
	s_mov_b32 m0, s50
	v_lshl_add_u64 v[198:199], v[240:241], 0, s[10:11]
	s_barrier
	ds_read_b128 v[178:181], v145 offset:49152
	ds_read_b128 v[182:185], v145 offset:50176
	ds_read_b128 v[186:189], v145 offset:51200
	ds_read_b128 v[190:193], v145 offset:52224
	ds_read_b128 v[194:197], v145 offset:53248
	ds_read_b128 v[210:213], v145 offset:54272
	ds_read_b128 v[214:217], v145 offset:55296
	ds_read_b128 v[218:221], v145 offset:56320
	global_load_lds_dwordx4 v[198:199], off
	v_lshl_add_u64 v[198:199], v[242:243], 0, s[10:11]
	s_mov_b32 m0, s51
	s_nop 0
	global_load_lds_dwordx4 v[198:199], off
	s_barrier
; __device__ __forceinline__ unsigned cvt_pk_bf16(float lo, float hi) { unsigned r; asm volatile("v_cvt_pk_bf16_f32 %0, %1, %2" : "=v"(r) : "v"(lo), "v"(hi)); return r; }
; #define PG8_STAGE(bufoff, gbase, voff) do { _Pragma("unroll") for (int _i = 0; _i < 2; ++_i) \
;         __builtin_amdgcn_global_load_lds((const unsigned*)((const char*)(gbase) + (voff)[_i]), (LAS unsigned*)(lds + (bufoff) + ldsw + _i * 8192), 16, 0, 0); } while (0)
; #define PG8_LDA(dst, b, h) do { _Pragma("unroll") for (int m = 0; m < 4; ++m) _Pragma("unroll") for (int k = 0; k < 2; ++k) dst[m][k] = *(const LAS bf16x8*)(lds + PG8_SA(b, h) + aoff + m * 2048 + k * 1024); } while (0)
; #define PG8_MMA(ai, bj, At, Bt) do { __builtin_amdgcn_s_setprio(1); _Pragma("unroll") for (int m = 0; m < 4; ++m) _Pragma("unroll") for (int n = 0; n < 2; ++n) _Pragma("unroll") for (int k = 0; k < 2; ++k) \
;         acc[ai][bj][m][n] = __builtin_amdgcn_mfma_f32_16x16x32_bf16(Bt[n][k], At[m][k], acc[ai][bj][m][n], 0, 0, 0); __builtin_amdgcn_s_setprio(0); } while (0)
;     __device__ __forceinline__ void operator()(const f32x4 (&acc)[2][2][4][2], const Unit& u, int ui, const LAS float* rtab, int wr, int wc, int fr, int fq) const {
;     ...
;                 const int row = row0 + ai * HALF + m * 16; const float rs = rtab[ui * 256 + wr * 64 + fr + ai * HALF + m * 16];
; #pragma unroll
;                 for (int bj = 0; bj < 2; ++bj) {
;                     f32x4 v0 = acc[ai][bj][m][0] * rs, v1 = acc[ai][bj][m][1] * rs;
; #pragma unroll
;                     for (int e = 0; e < 4; ++e) { const float a = fmaxf(v0[e], 0.f), b = fmaxf(v1[e], 0.f); v0[e] = a * a; v1[e] = b * b; }
;                     u32x4 w; w.x = cvt_pk_bf16(v0[0], v0[1]); w.y = cvt_pk_bf16(v0[2], v0[3]); w.z = cvt_pk_bf16(v1[0], v1[1]); w.w = cvt_pk_bf16(v1[2], v1[3]);
;                     *(u32x4*)(H + (size_t)row * DFF + col0 + bj * HALF) = w;
; template <class Epi, class Sched>
; __device__ __forceinline__ void gemm_phase(LAS unsigned char* lds, const Gemm g, const Sched& S, const Epi& E) {
;     ...
;             PG8_BAR; PG8_WAIT_L(0); PG8_MMA(0, 1, At, B1); PG8_BAR;
;             PG8_LDA(At, 1, 1); PG8_STAGE(PG8_SA(1, 0), a3, voffA);
;             PG8_BAR; PG8_WAIT_L(0); PG8_MMA(1, 0, At, B0); PG8_BAR; PG8_SCHED;
;             PG8_STAGE(PG8_SB(1, 1), b3 + hstepB, voffB);
;             PG8_WAIT_V(6); PG8_BAR; PG8_MMA(1, 1, At, B1); PG8_BAR;
	s_waitcnt lgkmcnt(0)
	s_waitcnt lgkmcnt(0)
	v_mfma_f32_16x16x32_bf16 v[62:65], v[146:149], v[178:181], v[62:65]
	v_mfma_f32_16x16x32_bf16 v[58:61], v[170:173], v[178:181], v[58:61]
	v_mfma_f32_16x16x32_bf16 v[46:49], v[146:149], v[186:189], v[46:49]
	v_mfma_f32_16x16x32_bf16 v[42:45], v[170:173], v[186:189], v[42:45]
	v_mfma_f32_16x16x32_bf16 v[30:33], v[146:149], v[194:197], v[30:33]
	v_mfma_f32_16x16x32_bf16 v[26:29], v[170:173], v[194:197], v[26:29]
	v_mfma_f32_16x16x32_bf16 v[14:17], v[146:149], v[214:217], v[14:17]
	v_mfma_f32_16x16x32_bf16 v[10:13], v[170:173], v[214:217], v[10:13]
	v_mfma_f32_16x16x32_bf16 v[62:65], v[150:153], v[182:185], v[62:65]
	v_mfma_f32_16x16x32_bf16 v[58:61], v[174:177], v[182:185], v[58:61]
	v_mfma_f32_16x16x32_bf16 v[46:49], v[150:153], v[190:193], v[46:49]
	v_mfma_f32_16x16x32_bf16 v[42:45], v[174:177], v[190:193], v[42:45]
	v_mfma_f32_16x16x32_bf16 v[30:33], v[150:153], v[210:213], v[30:33]
	v_mfma_f32_16x16x32_bf16 v[26:29], v[174:177], v[210:213], v[26:29]
	v_mfma_f32_16x16x32_bf16 v[14:17], v[150:153], v[218:221], v[14:17]
	v_mfma_f32_16x16x32_bf16 v[10:13], v[174:177], v[218:221], v[10:13]
	s_barrier
	s_add_u32 s46, s46, 0x80080
	s_addc_u32 s47, s47, 0
	s_add_i32 s23, s48, s26
	v_lshl_add_u64 v[146:147], s[46:47], 0, v[134:135]
	s_mov_b32 m0, s23
	s_nop 0
	global_load_lds_dwordx4 v[146:147], off
	v_lshl_add_u64 v[146:147], s[46:47], 0, v[130:131]
	s_add_i32 m0, s23, 0x2000
	s_nop 0
	global_load_lds_dwordx4 v[146:147], off
	s_waitcnt vmcnt(6)
	s_barrier
	v_mfma_f32_16x16x32_bf16 v[54:57], v[222:225], v[178:181], v[54:57]
	v_mfma_f32_16x16x32_bf16 v[50:53], v[230:233], v[178:181], v[50:53]
	v_mfma_f32_16x16x32_bf16 v[38:41], v[222:225], v[186:189], v[38:41]
	v_mfma_f32_16x16x32_bf16 v[34:37], v[230:233], v[186:189], v[34:37]
	v_mfma_f32_16x16x32_bf16 v[22:25], v[222:225], v[194:197], v[22:25]
	v_mfma_f32_16x16x32_bf16 v[18:21], v[230:233], v[194:197], v[18:21]
	v_mfma_f32_16x16x32_bf16 v[6:9], v[222:225], v[214:217], v[6:9]
	v_mfma_f32_16x16x32_bf16 v[2:5], v[230:233], v[214:217], v[2:5]
	v_mfma_f32_16x16x32_bf16 v[54:57], v[226:229], v[182:185], v[54:57]
	v_mfma_f32_16x16x32_bf16 v[50:53], v[234:237], v[182:185], v[50:53]
	v_mfma_f32_16x16x32_bf16 v[38:41], v[226:229], v[190:193], v[38:41]
	v_mfma_f32_16x16x32_bf16 v[34:37], v[234:237], v[190:193], v[34:37]
	v_mfma_f32_16x16x32_bf16 v[22:25], v[226:229], v[210:213], v[22:25]
	v_mfma_f32_16x16x32_bf16 v[18:21], v[234:237], v[210:213], v[18:21]
	v_mfma_f32_16x16x32_bf16 v[6:9], v[226:229], v[218:221], v[6:9]
	v_mfma_f32_16x16x32_bf16 v[2:5], v[234:237], v[218:221], v[2:5]
	s_add_i32 s66, s66, 2
	s_add_u32 s44, s44, 0x100
	s_addc_u32 s45, s45, 0
	s_add_u32 s58, s58, 0x100
	s_addc_u32 s59, s59, 0
	s_cmp_gt_u32 s66, 29
	s_barrier
	s_cbranch_scc0 .LBB0_830
	v_lshl_add_u32 v146, s55, 10, v143
	ds_read_b32 v150, v146
	v_lshl_add_u32 v148, s54, 8, v1
	v_lshl_or_b32 v152, s53, 8, v144
	v_ashrrev_i32_e32 v149, 31, v148
	v_ashrrev_i32_e32 v153, 31, v152
	s_waitcnt lgkmcnt(0)
	v_pk_mul_f32 v[124:125], v[124:125], v[150:151] op_sel_hi:[1,0]
	v_pk_mul_f32 v[128:129], v[128:129], v[150:151] op_sel_hi:[1,0]
	v_pk_mul_f32 v[126:127], v[126:127], v[150:151] op_sel_hi:[1,0]
	v_pk_mul_f32 v[122:123], v[122:123], v[150:151] op_sel_hi:[1,0]
	v_max_f32_e32 v124, 0, v124
	v_max_f32_e32 v126, 0, v126
	v_max_f32_e32 v122, 0, v122
	v_max_f32_e32 v123, 0, v123
	v_max_f32_e32 v128, 0, v128
	v_mul_f32_e32 v147, v124, v124
	v_max_f32_e32 v124, 0, v129
	v_lshlrev_b64 v[170:171], 14, v[148:149]
	v_mul_f32_e32 v126, v126, v126
	v_mul_f32_e32 v122, v122, v122
	v_max_f32_e32 v127, 0, v127
	v_mul_f32_e32 v123, v123, v123
	v_mul_f32_e32 v128, v128, v128
	v_max_f32_e32 v125, 0, v125
	v_mul_f32_e32 v129, v124, v124
	v_mul_f32_e32 v127, v127, v127
	v_mul_f32_e32 v149, v125, v125
	v_cvt_pk_bf16_f32 v124, v126, v127
	v_cvt_pk_bf16_f32 v125, v128, v129
	v_cvt_pk_bf16_f32 v126, v122, v123
	v_lshl_add_u64 v[122:123], s[72:73], 0, v[170:171]
	v_lshlrev_b64 v[128:129], 1, v[152:153]
	v_pk_mul_f32 v[116:117], v[116:117], v[150:151] op_sel_hi:[1,0]
	v_pk_mul_f32 v[114:115], v[114:115], v[150:151] op_sel_hi:[1,0]
	v_lshl_add_u64 v[122:123], v[122:123], 0, v[128:129]
	v_pk_mul_f32 v[120:121], v[120:121], v[150:151] op_sel_hi:[1,0]
	v_pk_mul_f32 v[118:119], v[118:119], v[150:151] op_sel_hi:[1,0]
	v_max_f32_e32 v114, 0, v114
	v_max_f32_e32 v115, 0, v115
	v_max_f32_e32 v116, 0, v116
	v_cvt_pk_bf16_f32 v127, v147, v149
	global_store_dwordx4 v[122:123], v[124:127], off
	v_max_f32_e32 v118, 0, v118
	v_max_f32_e32 v117, 0, v117
	v_mul_f32_e32 v124, v114, v114
	v_max_f32_e32 v114, 0, v119
	v_mul_f32_e32 v119, v115, v115
	v_max_f32_e32 v115, 0, v120
	v_mul_f32_e32 v120, v116, v116
	v_max_f32_e32 v116, 0, v121
	v_mul_f32_e32 v118, v118, v118
	v_mul_f32_e32 v114, v114, v114
	v_mul_f32_e32 v115, v115, v115
	v_mul_f32_e32 v116, v116, v116
	v_mul_f32_e32 v117, v117, v117
	v_cvt_pk_bf16_f32 v114, v118, v114
	v_cvt_pk_bf16_f32 v115, v115, v116
	v_cvt_pk_bf16_f32 v116, v124, v119
	v_cvt_pk_bf16_f32 v117, v120, v117
	ds_read_b32 v118, v146 offset:64
	global_store_dwordx4 v[122:123], v[114:117], off offset:256
	s_mov_b32 s1, 0x200000
	s_mov_b64 s[44:45], 0x240000
	v_or_b32_e32 v114, 16, v148
	s_waitcnt lgkmcnt(0)
; __device__ __forceinline__ unsigned cvt_pk_bf16(float lo, float hi) { unsigned r; asm volatile("v_cvt_pk_bf16_f32 %0, %1, %2" : "=v"(r) : "v"(lo), "v"(hi)); return r; }
;     __device__ __forceinline__ void operator()(const f32x4 (&acc)[2][2][4][2], const Unit& u, int ui, const LAS float* rtab, int wr, int wc, int fr, int fq) const {
;     ...
;         for (int ai = 0; ai < 2; ++ai)
; #pragma unroll
;             for (int m = 0; m < 4; ++m) {
;                 const int row = row0 + ai * HALF + m * 16; const float rs = rtab[ui * 256 + wr * 64 + fr + ai * HALF + m * 16];
; #pragma unroll
;                 for (int bj = 0; bj < 2; ++bj) {
;                     f32x4 v0 = acc[ai][bj][m][0] * rs, v1 = acc[ai][bj][m][1] * rs;
; #pragma unroll
;                     for (int e = 0; e < 4; ++e) { const float a = fmaxf(v0[e], 0.f), b = fmaxf(v1[e], 0.f); v0[e] = a * a; v1[e] = b * b; }
;                     u32x4 w; w.x = cvt_pk_bf16(v0[0], v0[1]); w.y = cvt_pk_bf16(v0[2], v0[3]); w.z = cvt_pk_bf16(v1[0], v1[1]); w.w = cvt_pk_bf16(v1[2], v1[3]);
;                     *(u32x4*)(H + (size_t)row * DFF + col0 + bj * HALF) = w;
	v_pk_mul_f32 v[108:109], v[108:109], v[118:119] op_sel_hi:[1,0]
	v_pk_mul_f32 v[106:107], v[106:107], v[118:119] op_sel_hi:[1,0]
	v_pk_mul_f32 v[112:113], v[112:113], v[118:119] op_sel_hi:[1,0]
	v_pk_mul_f32 v[110:111], v[110:111], v[118:119] op_sel_hi:[1,0]
	v_max_f32_e32 v106, 0, v106
	v_max_f32_e32 v107, 0, v107
	v_max_f32_e32 v108, 0, v108
	v_ashrrev_i32_e32 v115, 31, v114
	v_max_f32_e32 v110, 0, v110
	v_mul_f32_e32 v116, v106, v106
	v_max_f32_e32 v106, 0, v111
	v_mul_f32_e32 v111, v107, v107
	v_max_f32_e32 v107, 0, v112
	v_mul_f32_e32 v112, v108, v108
	v_max_f32_e32 v108, 0, v113
	v_lshlrev_b64 v[114:115], 14, v[114:115]
	v_mul_f32_e32 v110, v110, v110
	v_mul_f32_e32 v106, v106, v106
	v_mul_f32_e32 v107, v107, v107
	v_mul_f32_e32 v108, v108, v108
	v_max_f32_e32 v109, 0, v109
	v_cvt_pk_bf16_f32 v106, v110, v106
	v_cvt_pk_bf16_f32 v107, v107, v108
	v_cvt_pk_bf16_f32 v108, v116, v111
	v_lshl_add_u64 v[110:111], s[72:73], 0, v[114:115]
	v_pk_mul_f32 v[100:101], v[100:101], v[118:119] op_sel_hi:[1,0]
	v_pk_mul_f32 v[98:99], v[98:99], v[118:119] op_sel_hi:[1,0]
	v_mul_f32_e32 v109, v109, v109
	v_lshl_add_u64 v[110:111], v[110:111], 0, v[128:129]
	v_pk_mul_f32 v[104:105], v[104:105], v[118:119] op_sel_hi:[1,0]
	v_pk_mul_f32 v[102:103], v[102:103], v[118:119] op_sel_hi:[1,0]
	v_max_f32_e32 v98, 0, v98
	v_max_f32_e32 v99, 0, v99
	v_max_f32_e32 v100, 0, v100
	v_cvt_pk_bf16_f32 v109, v112, v109
	global_store_dwordx4 v[110:111], v[106:109], off
	v_max_f32_e32 v102, 0, v102
	v_max_f32_e32 v101, 0, v101
	v_mul_f32_e32 v106, v98, v98
	v_max_f32_e32 v98, 0, v103
	v_mul_f32_e32 v103, v99, v99
	v_max_f32_e32 v99, 0, v104
	v_mul_f32_e32 v104, v100, v100
	v_max_f32_e32 v100, 0, v105
	v_mul_f32_e32 v102, v102, v102
	v_mul_f32_e32 v98, v98, v98
	v_mul_f32_e32 v99, v99, v99
	v_mul_f32_e32 v100, v100, v100
	v_mul_f32_e32 v101, v101, v101
	v_cvt_pk_bf16_f32 v98, v102, v98
	v_cvt_pk_bf16_f32 v99, v99, v100
	v_cvt_pk_bf16_f32 v100, v106, v103
	v_cvt_pk_bf16_f32 v101, v104, v101
	ds_read_b32 v102, v146 offset:128
	global_store_dwordx4 v[110:111], v[98:101], off offset:256
	s_mov_b32 s54, s20
	s_mov_b32 s53, s0
	v_or_b32_e32 v98, 32, v148
	s_waitcnt lgkmcnt(0)
	v_pk_mul_f32 v[92:93], v[92:93], v[102:103] op_sel_hi:[1,0]
	v_pk_mul_f32 v[90:91], v[90:91], v[102:103] op_sel_hi:[1,0]
	v_pk_mul_f32 v[96:97], v[96:97], v[102:103] op_sel_hi:[1,0]
	v_pk_mul_f32 v[94:95], v[94:95], v[102:103] op_sel_hi:[1,0]
	v_max_f32_e32 v90, 0, v90
	v_max_f32_e32 v91, 0, v91
	v_max_f32_e32 v92, 0, v92
	v_ashrrev_i32_e32 v99, 31, v98
	v_max_f32_e32 v94, 0, v94
	v_mul_f32_e32 v100, v90, v90
	v_max_f32_e32 v90, 0, v95
	v_mul_f32_e32 v95, v91, v91
	v_max_f32_e32 v91, 0, v96
	v_mul_f32_e32 v96, v92, v92
	v_max_f32_e32 v92, 0, v97
	v_lshlrev_b64 v[98:99], 14, v[98:99]
	v_mul_f32_e32 v94, v94, v94
	v_mul_f32_e32 v90, v90, v90
	v_mul_f32_e32 v91, v91, v91
	v_mul_f32_e32 v92, v92, v92
	v_max_f32_e32 v93, 0, v93
	v_cvt_pk_bf16_f32 v90, v94, v90
	v_cvt_pk_bf16_f32 v91, v91, v92
	v_cvt_pk_bf16_f32 v92, v100, v95
	v_lshl_add_u64 v[94:95], s[72:73], 0, v[98:99]
	v_pk_mul_f32 v[84:85], v[84:85], v[102:103] op_sel_hi:[1,0]
	v_pk_mul_f32 v[82:83], v[82:83], v[102:103] op_sel_hi:[1,0]
	v_mul_f32_e32 v93, v93, v93
	v_lshl_add_u64 v[94:95], v[94:95], 0, v[128:129]
	v_pk_mul_f32 v[88:89], v[88:89], v[102:103] op_sel_hi:[1,0]
	v_pk_mul_f32 v[86:87], v[86:87], v[102:103] op_sel_hi:[1,0]
	v_max_f32_e32 v82, 0, v82
	v_max_f32_e32 v83, 0, v83
	v_max_f32_e32 v84, 0, v84
	v_cvt_pk_bf16_f32 v93, v96, v93
	global_store_dwordx4 v[94:95], v[90:93], off
	v_max_f32_e32 v86, 0, v86
	v_max_f32_e32 v85, 0, v85
	v_mul_f32_e32 v90, v82, v82
	v_max_f32_e32 v82, 0, v87
	v_mul_f32_e32 v87, v83, v83
	v_max_f32_e32 v83, 0, v88
	v_mul_f32_e32 v88, v84, v84
	v_max_f32_e32 v84, 0, v89
	v_mul_f32_e32 v86, v86, v86
	v_mul_f32_e32 v82, v82, v82
	v_mul_f32_e32 v83, v83, v83
	v_mul_f32_e32 v84, v84, v84
	v_mul_f32_e32 v85, v85, v85
	v_cvt_pk_bf16_f32 v82, v86, v82
	v_cvt_pk_bf16_f32 v83, v83, v84
	v_cvt_pk_bf16_f32 v84, v90, v87
	v_cvt_pk_bf16_f32 v85, v88, v85
	ds_read_b32 v86, v146 offset:192
	global_store_dwordx4 v[94:95], v[82:85], off offset:256
	s_mov_b64 s[46:47], s[36:37]
	s_mov_b32 s55, s52
	v_or_b32_e32 v82, 48, v148
	s_waitcnt lgkmcnt(0)
	v_pk_mul_f32 v[76:77], v[76:77], v[86:87] op_sel_hi:[1,0]
	v_pk_mul_f32 v[74:75], v[74:75], v[86:87] op_sel_hi:[1,0]
	v_pk_mul_f32 v[80:81], v[80:81], v[86:87] op_sel_hi:[1,0]
	v_pk_mul_f32 v[78:79], v[78:79], v[86:87] op_sel_hi:[1,0]
	v_max_f32_e32 v74, 0, v74
	v_max_f32_e32 v75, 0, v75
	v_max_f32_e32 v76, 0, v76
	v_ashrrev_i32_e32 v83, 31, v82
	v_max_f32_e32 v78, 0, v78
	v_mul_f32_e32 v84, v74, v74
	v_max_f32_e32 v74, 0, v79
	v_mul_f32_e32 v79, v75, v75
	v_max_f32_e32 v75, 0, v80
	v_mul_f32_e32 v80, v76, v76
	v_max_f32_e32 v76, 0, v81
	v_lshlrev_b64 v[82:83], 14, v[82:83]
	v_mul_f32_e32 v78, v78, v78
	v_mul_f32_e32 v74, v74, v74
	v_mul_f32_e32 v75, v75, v75
	v_mul_f32_e32 v76, v76, v76
	v_max_f32_e32 v77, 0, v77
	v_cvt_pk_bf16_f32 v74, v78, v74
	v_cvt_pk_bf16_f32 v75, v75, v76
	v_cvt_pk_bf16_f32 v76, v84, v79
	v_lshl_add_u64 v[78:79], s[72:73], 0, v[82:83]
	v_pk_mul_f32 v[68:69], v[68:69], v[86:87] op_sel_hi:[1,0]
	v_pk_mul_f32 v[66:67], v[66:67], v[86:87] op_sel_hi:[1,0]
	v_mul_f32_e32 v77, v77, v77
	v_lshl_add_u64 v[78:79], v[78:79], 0, v[128:129]
	v_pk_mul_f32 v[72:73], v[72:73], v[86:87] op_sel_hi:[1,0]
	v_pk_mul_f32 v[70:71], v[70:71], v[86:87] op_sel_hi:[1,0]
	v_max_f32_e32 v66, 0, v66
	v_max_f32_e32 v67, 0, v67
	v_max_f32_e32 v68, 0, v68
	v_cvt_pk_bf16_f32 v77, v80, v77
	global_store_dwordx4 v[78:79], v[74:77], off
	v_max_f32_e32 v70, 0, v70
	v_max_f32_e32 v69, 0, v69
	v_mul_f32_e32 v74, v66, v66
	v_max_f32_e32 v66, 0, v71
	v_mul_f32_e32 v71, v67, v67
	v_max_f32_e32 v67, 0, v72
	v_mul_f32_e32 v72, v68, v68
	v_max_f32_e32 v68, 0, v73
	v_mul_f32_e32 v70, v70, v70
	v_mul_f32_e32 v66, v66, v66
	v_mul_f32_e32 v67, v67, v67
	v_mul_f32_e32 v68, v68, v68
	v_mul_f32_e32 v69, v69, v69
	v_cvt_pk_bf16_f32 v66, v70, v66
	v_cvt_pk_bf16_f32 v67, v67, v68
	v_cvt_pk_bf16_f32 v68, v74, v71
	v_cvt_pk_bf16_f32 v69, v72, v69
	ds_read_b32 v70, v146 offset:512
	global_store_dwordx4 v[78:79], v[66:69], off offset:256
	s_waitcnt lgkmcnt(0)
; __device__ __forceinline__ unsigned cvt_pk_bf16(float lo, float hi) { unsigned r; asm volatile("v_cvt_pk_bf16_f32 %0, %1, %2" : "=v"(r) : "v"(lo), "v"(hi)); return r; }
;     __device__ __forceinline__ void operator()(const f32x4 (&acc)[2][2][4][2], const Unit& u, int ui, const LAS float* rtab, int wr, int wc, int fr, int fq) const {
;     ...
;         for (int ai = 0; ai < 2; ++ai)
; #pragma unroll
;             for (int m = 0; m < 4; ++m) {
;                 const int row = row0 + ai * HALF + m * 16; const float rs = rtab[ui * 256 + wr * 64 + fr + ai * HALF + m * 16];
; #pragma unroll
;                 for (int bj = 0; bj < 2; ++bj) {
;                     f32x4 v0 = acc[ai][bj][m][0] * rs, v1 = acc[ai][bj][m][1] * rs;
; #pragma unroll
;                     for (int e = 0; e < 4; ++e) { const float a = fmaxf(v0[e], 0.f), b = fmaxf(v1[e], 0.f); v0[e] = a * a; v1[e] = b * b; }
;                     u32x4 w; w.x = cvt_pk_bf16(v0[0], v0[1]); w.y = cvt_pk_bf16(v0[2], v0[3]); w.z = cvt_pk_bf16(v1[0], v1[1]); w.w = cvt_pk_bf16(v1[2], v1[3]);
;                     *(u32x4*)(H + (size_t)row * DFF + col0 + bj * HALF) = w;
	v_pk_mul_f32 v[58:59], v[58:59], v[70:71] op_sel_hi:[1,0]
	v_pk_mul_f32 v[62:63], v[62:63], v[70:71] op_sel_hi:[1,0]
	v_pk_mul_f32 v[60:61], v[60:61], v[70:71] op_sel_hi:[1,0]
	v_max_f32_e32 v58, 0, v58
	v_pk_mul_f32 v[64:65], v[64:65], v[70:71] op_sel_hi:[1,0]
	v_max_f32_e32 v62, 0, v62
	v_mul_f32_e32 v66, v58, v58
	v_max_f32_e32 v58, 0, v63
	v_max_f32_e32 v59, 0, v59
	v_max_f32_e32 v60, 0, v60
	v_mul_f32_e32 v62, v62, v62
	v_mul_f32_e32 v58, v58, v58
	v_mul_f32_e32 v63, v59, v59
	v_max_f32_e32 v59, 0, v64
	v_mul_f32_e32 v64, v60, v60
	v_max_f32_e32 v60, 0, v65
	v_mul_f32_e32 v59, v59, v59
	v_max_f32_e32 v61, 0, v61
	v_mul_f32_e32 v60, v60, v60
	v_cvt_pk_bf16_f32 v58, v62, v58
	v_add_co_u32_e32 v62, vcc, s1, v122
	v_pk_mul_f32 v[52:53], v[52:53], v[70:71] op_sel_hi:[1,0]
	v_pk_mul_f32 v[50:51], v[50:51], v[70:71] op_sel_hi:[1,0]
	v_mul_f32_e32 v61, v61, v61
	v_cvt_pk_bf16_f32 v59, v59, v60
	v_cvt_pk_bf16_f32 v60, v66, v63
	v_addc_co_u32_e32 v63, vcc, 0, v123, vcc
	v_pk_mul_f32 v[56:57], v[56:57], v[70:71] op_sel_hi:[1,0]
	v_pk_mul_f32 v[54:55], v[54:55], v[70:71] op_sel_hi:[1,0]
	v_max_f32_e32 v50, 0, v50
	v_max_f32_e32 v51, 0, v51
	v_max_f32_e32 v52, 0, v52
	v_cvt_pk_bf16_f32 v61, v64, v61
	global_store_dwordx4 v[62:63], v[58:61], off
	v_max_f32_e32 v54, 0, v54
	v_max_f32_e32 v53, 0, v53
	v_mul_f32_e32 v58, v50, v50
	v_max_f32_e32 v50, 0, v55
	v_mul_f32_e32 v55, v51, v51
	v_max_f32_e32 v51, 0, v56
	v_mul_f32_e32 v56, v52, v52
	v_max_f32_e32 v52, 0, v57
	v_mul_f32_e32 v54, v54, v54
	v_mul_f32_e32 v50, v50, v50
	v_mul_f32_e32 v51, v51, v51
	v_mul_f32_e32 v52, v52, v52
	v_mul_f32_e32 v53, v53, v53
	v_cvt_pk_bf16_f32 v50, v54, v50
	v_cvt_pk_bf16_f32 v51, v51, v52
	v_cvt_pk_bf16_f32 v52, v58, v55
	v_cvt_pk_bf16_f32 v53, v56, v53
	ds_read_b32 v54, v146 offset:576
	v_lshl_add_u64 v[56:57], v[122:123], 0, s[84:85]
	global_store_dwordx4 v[56:57], v[50:53], off offset:256
	s_mov_b32 s1, 0x240000
	s_waitcnt lgkmcnt(0)
	v_pk_mul_f32 v[42:43], v[42:43], v[54:55] op_sel_hi:[1,0]
	v_pk_mul_f32 v[46:47], v[46:47], v[54:55] op_sel_hi:[1,0]
	v_pk_mul_f32 v[44:45], v[44:45], v[54:55] op_sel_hi:[1,0]
	v_max_f32_e32 v42, 0, v42
	v_pk_mul_f32 v[48:49], v[48:49], v[54:55] op_sel_hi:[1,0]
	v_max_f32_e32 v46, 0, v46
	v_mul_f32_e32 v50, v42, v42
	v_max_f32_e32 v42, 0, v47
	v_max_f32_e32 v43, 0, v43
	v_max_f32_e32 v44, 0, v44
	v_mul_f32_e32 v46, v46, v46
	v_mul_f32_e32 v42, v42, v42
	v_mul_f32_e32 v47, v43, v43
	v_max_f32_e32 v43, 0, v48
	v_mul_f32_e32 v48, v44, v44
	v_max_f32_e32 v44, 0, v49
	v_mul_f32_e32 v43, v43, v43
	v_max_f32_e32 v45, 0, v45
	v_mul_f32_e32 v44, v44, v44
	v_cvt_pk_bf16_f32 v42, v46, v42
	v_add_co_u32_e32 v46, vcc, s1, v122
	v_pk_mul_f32 v[36:37], v[36:37], v[54:55] op_sel_hi:[1,0]
	v_pk_mul_f32 v[34:35], v[34:35], v[54:55] op_sel_hi:[1,0]
	v_mul_f32_e32 v45, v45, v45
	v_cvt_pk_bf16_f32 v43, v43, v44
	v_cvt_pk_bf16_f32 v44, v50, v47
	v_addc_co_u32_e32 v47, vcc, 0, v123, vcc
	v_pk_mul_f32 v[40:41], v[40:41], v[54:55] op_sel_hi:[1,0]
	v_pk_mul_f32 v[38:39], v[38:39], v[54:55] op_sel_hi:[1,0]
	v_max_f32_e32 v34, 0, v34
	v_max_f32_e32 v35, 0, v35
	v_max_f32_e32 v36, 0, v36
	v_cvt_pk_bf16_f32 v45, v48, v45
	global_store_dwordx4 v[46:47], v[42:45], off
	v_max_f32_e32 v38, 0, v38
	v_max_f32_e32 v37, 0, v37
	v_mul_f32_e32 v42, v34, v34
	v_max_f32_e32 v34, 0, v39
	v_mul_f32_e32 v39, v35, v35
	v_max_f32_e32 v35, 0, v40
	v_mul_f32_e32 v40, v36, v36
	v_max_f32_e32 v36, 0, v41
	v_mul_f32_e32 v38, v38, v38
	v_mul_f32_e32 v34, v34, v34
	v_mul_f32_e32 v35, v35, v35
	v_mul_f32_e32 v36, v36, v36
	v_mul_f32_e32 v37, v37, v37
	v_cvt_pk_bf16_f32 v34, v38, v34
	v_cvt_pk_bf16_f32 v35, v35, v36
	v_cvt_pk_bf16_f32 v36, v42, v39
	v_cvt_pk_bf16_f32 v37, v40, v37
	ds_read_b32 v38, v146 offset:640
	v_lshl_add_u64 v[40:41], v[122:123], 0, s[44:45]
	global_store_dwordx4 v[40:41], v[34:37], off offset:256
	s_mov_b32 s1, 0x280000
	s_mov_b64 s[44:45], 0x280000
	s_waitcnt lgkmcnt(0)
; __device__ __forceinline__ unsigned cvt_pk_bf16(float lo, float hi) { unsigned r; asm volatile("v_cvt_pk_bf16_f32 %0, %1, %2" : "=v"(r) : "v"(lo), "v"(hi)); return r; }
; #define PG8_WAIT_V(n) asm volatile("s_waitcnt vmcnt(" #n ")" ::: "memory")
; #define PG8_BAR __builtin_amdgcn_s_barrier()
;     __device__ __forceinline__ void operator()(const f32x4 (&acc)[2][2][4][2], const Unit& u, int ui, const LAS float* rtab, int wr, int wc, int fr, int fq) const {
;     ...
;         for (int ai = 0; ai < 2; ++ai)
; #pragma unroll
;             for (int m = 0; m < 4; ++m) {
;                 const int row = row0 + ai * HALF + m * 16; const float rs = rtab[ui * 256 + wr * 64 + fr + ai * HALF + m * 16];
; #pragma unroll
;                 for (int bj = 0; bj < 2; ++bj) {
;                     f32x4 v0 = acc[ai][bj][m][0] * rs, v1 = acc[ai][bj][m][1] * rs;
; #pragma unroll
;                     for (int e = 0; e < 4; ++e) { const float a = fmaxf(v0[e], 0.f), b = fmaxf(v1[e], 0.f); v0[e] = a * a; v1[e] = b * b; }
;                     u32x4 w; w.x = cvt_pk_bf16(v0[0], v0[1]); w.y = cvt_pk_bf16(v0[2], v0[3]); w.z = cvt_pk_bf16(v1[0], v1[1]); w.w = cvt_pk_bf16(v1[2], v1[3]);
;                     *(u32x4*)(H + (size_t)row * DFF + col0 + bj * HALF) = w;
; template <class Epi, class Sched>
; __device__ __forceinline__ void gemm_phase(LAS unsigned char* lds, const Gemm g, const Sched& S, const Epi& E) {
;     ...
;         if (!has_next) break;
; #pragma unroll
;         for (int a = 0; a < 2; ++a)
; #pragma unroll
;             for (int b = 0; b < 2; ++b)
; #pragma unroll
;                 for (int m = 0; m < 4; ++m)
; #pragma unroll
;                     for (int n = 0; n < 2; ++n) acc[a][b][m][n] = (f32x4){0.f, 0.f, 0.f, 0.f};
;         cur = nxt; cA = nA; cB = nB; ++ui;
;     }
;     PG8_WAIT_V(0);
;     if (wr == 0) PG8_BAR;
;     PG8_BAR;
	v_pk_mul_f32 v[26:27], v[26:27], v[38:39] op_sel_hi:[1,0]
	v_pk_mul_f32 v[30:31], v[30:31], v[38:39] op_sel_hi:[1,0]
	v_pk_mul_f32 v[28:29], v[28:29], v[38:39] op_sel_hi:[1,0]
	v_max_f32_e32 v26, 0, v26
	v_pk_mul_f32 v[32:33], v[32:33], v[38:39] op_sel_hi:[1,0]
	v_max_f32_e32 v30, 0, v30
	v_mul_f32_e32 v34, v26, v26
	v_max_f32_e32 v26, 0, v31
	v_max_f32_e32 v27, 0, v27
	v_max_f32_e32 v28, 0, v28
	v_mul_f32_e32 v30, v30, v30
	v_mul_f32_e32 v26, v26, v26
	v_mul_f32_e32 v31, v27, v27
	v_max_f32_e32 v27, 0, v32
	v_mul_f32_e32 v32, v28, v28
	v_max_f32_e32 v28, 0, v33
	v_mul_f32_e32 v27, v27, v27
	v_max_f32_e32 v29, 0, v29
	v_mul_f32_e32 v28, v28, v28
	v_cvt_pk_bf16_f32 v26, v30, v26
	v_add_co_u32_e32 v30, vcc, s1, v122
	v_pk_mul_f32 v[20:21], v[20:21], v[38:39] op_sel_hi:[1,0]
	v_pk_mul_f32 v[18:19], v[18:19], v[38:39] op_sel_hi:[1,0]
	v_mul_f32_e32 v29, v29, v29
	v_cvt_pk_bf16_f32 v27, v27, v28
	v_cvt_pk_bf16_f32 v28, v34, v31
	v_addc_co_u32_e32 v31, vcc, 0, v123, vcc
	v_pk_mul_f32 v[24:25], v[24:25], v[38:39] op_sel_hi:[1,0]
	v_pk_mul_f32 v[22:23], v[22:23], v[38:39] op_sel_hi:[1,0]
	v_max_f32_e32 v18, 0, v18
	v_max_f32_e32 v19, 0, v19
	v_max_f32_e32 v20, 0, v20
	v_cvt_pk_bf16_f32 v29, v32, v29
	global_store_dwordx4 v[30:31], v[26:29], off
	v_max_f32_e32 v22, 0, v22
	v_max_f32_e32 v21, 0, v21
	v_mul_f32_e32 v26, v18, v18
	v_max_f32_e32 v18, 0, v23
	v_mul_f32_e32 v23, v19, v19
	v_max_f32_e32 v19, 0, v24
	v_mul_f32_e32 v24, v20, v20
	v_max_f32_e32 v20, 0, v25
	v_mul_f32_e32 v22, v22, v22
	v_mul_f32_e32 v18, v18, v18
	v_mul_f32_e32 v19, v19, v19
	v_mul_f32_e32 v20, v20, v20
	v_mul_f32_e32 v21, v21, v21
	v_cvt_pk_bf16_f32 v18, v22, v18
	v_cvt_pk_bf16_f32 v19, v19, v20
	v_cvt_pk_bf16_f32 v20, v26, v23
	v_cvt_pk_bf16_f32 v21, v24, v21
	ds_read_b32 v22, v146 offset:704
	v_lshl_add_u64 v[24:25], v[122:123], 0, s[44:45]
	global_store_dwordx4 v[24:25], v[18:21], off offset:256
	s_mov_b32 s1, 0x2c0000
	s_mov_b64 s[44:45], 0x2c0000
	s_waitcnt lgkmcnt(0)
	v_pk_mul_f32 v[12:13], v[12:13], v[22:23] op_sel_hi:[1,0]
	v_pk_mul_f32 v[10:11], v[10:11], v[22:23] op_sel_hi:[1,0]
	v_pk_mul_f32 v[16:17], v[16:17], v[22:23] op_sel_hi:[1,0]
	v_pk_mul_f32 v[14:15], v[14:15], v[22:23] op_sel_hi:[1,0]
	v_max_f32_e32 v10, 0, v10
	v_max_f32_e32 v11, 0, v11
	v_max_f32_e32 v12, 0, v12
	v_mul_f32_e32 v18, v10, v10
	v_max_f32_e32 v10, 0, v15
	v_mul_f32_e32 v15, v11, v11
	v_max_f32_e32 v11, 0, v16
	v_mul_f32_e32 v16, v12, v12
	v_max_f32_e32 v12, 0, v17
	v_max_f32_e32 v13, 0, v13
	v_max_f32_e32 v14, 0, v14
	v_mul_f32_e32 v10, v10, v10
	v_mul_f32_e32 v11, v11, v11
	v_mul_f32_e32 v12, v12, v12
	v_mul_f32_e32 v13, v13, v13
	v_mul_f32_e32 v14, v14, v14
	v_cvt_pk_bf16_f32 v10, v14, v10
	v_cvt_pk_bf16_f32 v11, v11, v12
	v_cvt_pk_bf16_f32 v12, v18, v15
	v_cvt_pk_bf16_f32 v13, v16, v13
	v_add_co_u32_e32 v16, vcc, s1, v122
	v_pk_mul_f32 v[4:5], v[4:5], v[22:23] op_sel_hi:[1,0]
	v_pk_mul_f32 v[2:3], v[2:3], v[22:23] op_sel_hi:[1,0]
	v_addc_co_u32_e32 v17, vcc, 0, v123, vcc
	v_pk_mul_f32 v[8:9], v[8:9], v[22:23] op_sel_hi:[1,0]
	v_pk_mul_f32 v[6:7], v[6:7], v[22:23] op_sel_hi:[1,0]
	v_max_f32_e32 v2, 0, v2
	v_max_f32_e32 v3, 0, v3
	v_max_f32_e32 v4, 0, v4
	global_store_dwordx4 v[16:17], v[10:13], off
	v_max_f32_e32 v5, 0, v5
	v_lshl_add_u64 v[14:15], v[122:123], 0, s[44:45]
	v_mul_f32_e32 v10, v2, v2
	v_max_f32_e32 v2, 0, v7
	v_mul_f32_e32 v7, v3, v3
	v_max_f32_e32 v3, 0, v8
	v_mul_f32_e32 v8, v4, v4
	v_max_f32_e32 v4, 0, v9
	v_max_f32_e32 v6, 0, v6
	v_mul_f32_e32 v2, v2, v2
	v_mul_f32_e32 v3, v3, v3
	v_mul_f32_e32 v4, v4, v4
	v_mul_f32_e32 v5, v5, v5
	s_and_b64 vcc, exec, s[42:43]
	s_mov_b64 s[44:45], s[34:35]
	v_mul_f32_e32 v6, v6, v6
	v_cvt_pk_bf16_f32 v2, v6, v2
	v_cvt_pk_bf16_f32 v3, v3, v4
	v_cvt_pk_bf16_f32 v4, v10, v7
	v_cvt_pk_bf16_f32 v5, v8, v5
	global_store_dwordx4 v[14:15], v[2:5], off offset:256
	s_cbranch_vccz .LBB0_823
	s_waitcnt vmcnt(0)
	s_cmpk_gt_u32 s13, 0xff
	s_cbranch_scc1 .LBB0_834
	s_barrier

; #define PG8_STAGE(bufoff, gbase, voff) do { _Pragma("unroll") for (int _i = 0; _i < 2; ++_i) \
;         __builtin_amdgcn_global_load_lds((const unsigned*)((const char*)(gbase) + (voff)[_i]), (LAS unsigned*)(lds + (bufoff) + ldsw + _i * 8192), 16, 0, 0); } while (0)
; #define PG8_LDA(dst, b, h) do { _Pragma("unroll") for (int m = 0; m < 4; ++m) _Pragma("unroll") for (int k = 0; k < 2; ++k) dst[m][k] = *(const LAS bf16x8*)(lds + PG8_SA(b, h) + aoff + m * 2048 + k * 1024); } while (0)
; #define PG8_LDB(dst, b, h) do { _Pragma("unroll") for (int n = 0; n < 2; ++n) _Pragma("unroll") for (int k = 0; k < 2; ++k) dst[n][k] = *(const LAS bf16x8*)(lds + PG8_SB(b, h) + boff + n * 2048 + k * 1024); } while (0)
; #define PG8_MMA(ai, bj, At, Bt) do { __builtin_amdgcn_s_setprio(1); _Pragma("unroll") for (int m = 0; m < 4; ++m) _Pragma("unroll") for (int n = 0; n < 2; ++n) _Pragma("unroll") for (int k = 0; k < 2; ++k) \
;         acc[ai][bj][m][n] = __builtin_amdgcn_mfma_f32_16x16x32_bf16(Bt[n][k], At[m][k], acc[ai][bj][m][n], 0, 0, 0); __builtin_amdgcn_s_setprio(0); } while (0)
; #define PG8_WAIT_L(n) asm volatile("s_waitcnt lgkmcnt(" #n ")" ::: "memory")
; #define PG8_BAR __builtin_amdgcn_s_barrier()
; #define PG8_SCHED __builtin_amdgcn_sched_barrier(0)
; template <class Epi, class Sched>
; __device__ __forceinline__ void gemm_phase(LAS unsigned char* lds, const Gemm g, const Sched& S, const Epi& E) {
;     ...
;             PG8_LDB(B0, 0, 0); PG8_SCHED; PG8_LDA(At, 0, 0); PG8_STAGE(PG8_SA(1, 1), a1 + hstepA, voffA);
;             PG8_WAIT_L(8); PG8_BAR; PG8_WAIT_L(0); PG8_MMA(0, 0, At, B0); PG8_BAR; PG8_SCHED;
;             PG8_LDB(B1, 0, 1); PG8_STAGE(PG8_SB(0, 0), b2, voffB);
;             PG8_BAR; PG8_WAIT_L(0); PG8_MMA(0, 1, At, B1); PG8_BAR;
;             PG8_LDA(At, 0, 1); PG8_STAGE(PG8_SA(0, 0), a2, voffA);
;             PG8_BAR; PG8_WAIT_L(0); PG8_MMA(1, 0, At, B0); PG8_BAR; PG8_SCHED;
;             PG8_STAGE(PG8_SB(0, 1), b2 + hstepB, voffB);
.LBB0_899:
	s_add_u32 s23, s44, 0xffe00080
	s_addc_u32 s46, s45, -1
	s_add_i32 s67, 0, 0x10000
	v_add_u32_e32 v142, s67, v162
	ds_read_b128 v[130:133], v142
	ds_read_b128 v[134:137], v142 offset:1024
	ds_read_b128 v[138:141], v142 offset:2048
	ds_read_b128 v[142:145], v142 offset:3072
	s_cmpk_eq_i32 s66, 0x7c
	s_cselect_b32 s49, s25, s46
	s_cselect_b32 s48, s57, s23
	s_cselect_b32 s47, s21, s68
	s_cselect_b32 s46, s58, s59
	v_lshl_add_u64 v[198:199], s[44:45], 0, v[178:179]
	s_add_i32 m0, s31, 0xc000
	ds_read_b128 v[146:149], v210
	ds_read_b128 v[150:153], v210 offset:1024
	ds_read_b128 v[182:185], v210 offset:2048
	ds_read_b128 v[186:189], v210 offset:3072
	ds_read_b128 v[190:193], v210 offset:4096
	ds_read_b128 v[194:197], v210 offset:5120
	ds_read_b128 v[212:215], v210 offset:6144
	ds_read_b128 v[216:219], v210 offset:7168
	global_load_lds_dwordx4 v[198:199], off
	v_lshl_add_u64 v[198:199], s[44:45], 0, v[180:181]
	s_add_i32 m0, s31, 0xe000
	s_nop 0
	global_load_lds_dwordx4 v[198:199], off
	s_waitcnt lgkmcnt(8)
	s_barrier
	s_waitcnt lgkmcnt(0)
	s_waitcnt lgkmcnt(0)
	v_mfma_f32_16x16x32_bf16 v[126:129], v[130:133], v[146:149], v[126:129]
	v_mfma_f32_16x16x32_bf16 v[122:125], v[138:141], v[146:149], v[122:125]
	v_mfma_f32_16x16x32_bf16 v[110:113], v[130:133], v[182:185], v[110:113]
	v_mfma_f32_16x16x32_bf16 v[106:109], v[138:141], v[182:185], v[106:109]
	v_mfma_f32_16x16x32_bf16 v[94:97], v[130:133], v[190:193], v[94:97]
	v_mfma_f32_16x16x32_bf16 v[90:93], v[138:141], v[190:193], v[90:93]
	v_mfma_f32_16x16x32_bf16 v[78:81], v[130:133], v[212:215], v[78:81]
	v_mfma_f32_16x16x32_bf16 v[74:77], v[138:141], v[212:215], v[74:77]
	v_mfma_f32_16x16x32_bf16 v[126:129], v[134:137], v[150:153], v[126:129]
	v_mfma_f32_16x16x32_bf16 v[122:125], v[142:145], v[150:153], v[122:125]
	v_mfma_f32_16x16x32_bf16 v[110:113], v[134:137], v[186:189], v[110:113]
	v_mfma_f32_16x16x32_bf16 v[106:109], v[142:145], v[186:189], v[106:109]
	v_mfma_f32_16x16x32_bf16 v[94:97], v[134:137], v[194:197], v[94:97]
	v_mfma_f32_16x16x32_bf16 v[90:93], v[142:145], v[194:197], v[90:93]
	v_mfma_f32_16x16x32_bf16 v[78:81], v[134:137], v[216:219], v[78:81]
	v_mfma_f32_16x16x32_bf16 v[74:77], v[142:145], v[216:219], v[74:77]
	s_barrier
	s_add_i32 s23, 0, 0x14000
	v_add_u32_e32 v198, s23, v162
	s_add_i32 s67, s67, s27
	ds_read_b128 v[220:223], v198
	ds_read_b128 v[224:227], v198 offset:1024
	ds_read_b128 v[228:231], v198 offset:2048
	ds_read_b128 v[232:235], v198 offset:3072
	v_lshl_add_u64 v[198:199], s[46:47], 0, v[174:175]
	s_mov_b32 m0, s67
	v_lshl_add_u64 v[236:237], s[46:47], 0, v[170:171]
	global_load_lds_dwordx4 v[198:199], off
	s_add_i32 m0, s67, 0x2000
	s_nop 0
	global_load_lds_dwordx4 v[236:237], off
	s_barrier
	s_waitcnt lgkmcnt(0)
	s_waitcnt lgkmcnt(0)
	v_mfma_f32_16x16x32_bf16 v[118:121], v[220:223], v[146:149], v[118:121]
	v_mfma_f32_16x16x32_bf16 v[114:117], v[228:231], v[146:149], v[114:117]
	v_mfma_f32_16x16x32_bf16 v[102:105], v[220:223], v[182:185], v[102:105]
	v_mfma_f32_16x16x32_bf16 v[98:101], v[228:231], v[182:185], v[98:101]
	v_mfma_f32_16x16x32_bf16 v[86:89], v[220:223], v[190:193], v[86:89]
	v_mfma_f32_16x16x32_bf16 v[82:85], v[228:231], v[190:193], v[82:85]
	v_mfma_f32_16x16x32_bf16 v[70:73], v[220:223], v[212:215], v[70:73]
	v_mfma_f32_16x16x32_bf16 v[66:69], v[228:231], v[212:215], v[66:69]
	v_mfma_f32_16x16x32_bf16 v[118:121], v[224:227], v[150:153], v[118:121]
	v_mfma_f32_16x16x32_bf16 v[114:117], v[232:235], v[150:153], v[114:117]
	v_mfma_f32_16x16x32_bf16 v[102:105], v[224:227], v[186:189], v[102:105]
	v_mfma_f32_16x16x32_bf16 v[98:101], v[232:235], v[186:189], v[98:101]
	v_mfma_f32_16x16x32_bf16 v[86:89], v[224:227], v[194:197], v[86:89]
	v_mfma_f32_16x16x32_bf16 v[82:85], v[232:235], v[194:197], v[82:85]
	v_mfma_f32_16x16x32_bf16 v[70:73], v[224:227], v[216:219], v[70:73]
	v_mfma_f32_16x16x32_bf16 v[66:69], v[232:235], v[216:219], v[66:69]
	s_mov_b32 m0, s31
	v_lshl_add_u64 v[238:239], s[48:49], 0, v[176:177]
	s_barrier
	ds_read_b128 v[146:149], v210 offset:16384
	ds_read_b128 v[150:153], v210 offset:17408
	ds_read_b128 v[182:185], v210 offset:18432
	ds_read_b128 v[186:189], v210 offset:19456
	ds_read_b128 v[190:193], v210 offset:20480
	ds_read_b128 v[194:197], v210 offset:21504
	ds_read_b128 v[212:215], v210 offset:22528
	ds_read_b128 v[216:219], v210 offset:23552
	global_load_lds_dwordx4 v[238:239], off
	v_lshl_add_u64 v[240:241], s[48:49], 0, v[172:173]
	s_mov_b32 m0, s50
	s_nop 0
	global_load_lds_dwordx4 v[240:241], off
	s_barrier
	s_waitcnt lgkmcnt(0)
	s_waitcnt lgkmcnt(0)
	v_mfma_f32_16x16x32_bf16 v[62:65], v[130:133], v[146:149], v[62:65]
	v_mfma_f32_16x16x32_bf16 v[58:61], v[138:141], v[146:149], v[58:61]
	v_mfma_f32_16x16x32_bf16 v[46:49], v[130:133], v[182:185], v[46:49]
	v_mfma_f32_16x16x32_bf16 v[42:45], v[138:141], v[182:185], v[42:45]
	v_mfma_f32_16x16x32_bf16 v[30:33], v[130:133], v[190:193], v[30:33]
	v_mfma_f32_16x16x32_bf16 v[26:29], v[138:141], v[190:193], v[26:29]
	v_mfma_f32_16x16x32_bf16 v[14:17], v[130:133], v[212:215], v[14:17]
	v_mfma_f32_16x16x32_bf16 v[10:13], v[138:141], v[212:215], v[10:13]
	v_mfma_f32_16x16x32_bf16 v[62:65], v[134:137], v[150:153], v[62:65]
	v_mfma_f32_16x16x32_bf16 v[58:61], v[142:145], v[150:153], v[58:61]
	v_mfma_f32_16x16x32_bf16 v[46:49], v[134:137], v[186:189], v[46:49]
	v_mfma_f32_16x16x32_bf16 v[42:45], v[142:145], v[186:189], v[42:45]
	v_mfma_f32_16x16x32_bf16 v[30:33], v[134:137], v[194:197], v[30:33]
	v_mfma_f32_16x16x32_bf16 v[26:29], v[142:145], v[194:197], v[26:29]
	v_mfma_f32_16x16x32_bf16 v[14:17], v[134:137], v[216:219], v[14:17]
	v_mfma_f32_16x16x32_bf16 v[10:13], v[142:145], v[216:219], v[10:13]
	s_barrier
; #define PG8_STAGE(bufoff, gbase, voff) do { _Pragma("unroll") for (int _i = 0; _i < 2; ++_i) \
;         __builtin_amdgcn_global_load_lds((const unsigned*)((const char*)(gbase) + (voff)[_i]), (LAS unsigned*)(lds + (bufoff) + ldsw + _i * 8192), 16, 0, 0); } while (0)
; #define PG8_LDA(dst, b, h) do { _Pragma("unroll") for (int m = 0; m < 4; ++m) _Pragma("unroll") for (int k = 0; k < 2; ++k) dst[m][k] = *(const LAS bf16x8*)(lds + PG8_SA(b, h) + aoff + m * 2048 + k * 1024); } while (0)
; #define PG8_LDB(dst, b, h) do { _Pragma("unroll") for (int n = 0; n < 2; ++n) _Pragma("unroll") for (int k = 0; k < 2; ++k) dst[n][k] = *(const LAS bf16x8*)(lds + PG8_SB(b, h) + boff + n * 2048 + k * 1024); } while (0)
; #define PG8_MMA(ai, bj, At, Bt) do { __builtin_amdgcn_s_setprio(1); _Pragma("unroll") for (int m = 0; m < 4; ++m) _Pragma("unroll") for (int n = 0; n < 2; ++n) _Pragma("unroll") for (int k = 0; k < 2; ++k) \
;         acc[ai][bj][m][n] = __builtin_amdgcn_mfma_f32_16x16x32_bf16(Bt[n][k], At[m][k], acc[ai][bj][m][n], 0, 0, 0); __builtin_amdgcn_s_setprio(0); } while (0)
; #define PG8_WAIT_V(n) asm volatile("s_waitcnt vmcnt(" #n ")" ::: "memory")
; #define PG8_WAIT_L(n) asm volatile("s_waitcnt lgkmcnt(" #n ")" ::: "memory")
; #define PG8_BAR __builtin_amdgcn_s_barrier()
; #define PG8_SCHED __builtin_amdgcn_sched_barrier(0)
; template <class Epi, class Sched>
; __device__ __forceinline__ void gemm_phase(LAS unsigned char* lds, const Gemm g, const Sched& S, const Epi& E) {
;     ...
;             PG8_STAGE(PG8_SB(0, 1), b2 + hstepB, voffB);
;             PG8_WAIT_V(6); PG8_BAR; PG8_MMA(1, 1, At, B1); PG8_BAR;
;             PG8_LDB(B0, 1, 0); PG8_SCHED; PG8_LDA(At, 1, 0); PG8_STAGE(PG8_SA(0, 1), a2 + hstepA, voffA);
;             PG8_WAIT_L(8); PG8_BAR; PG8_WAIT_L(0); PG8_MMA(0, 0, At, B0); PG8_BAR; PG8_SCHED;
;             PG8_LDB(B1, 1, 1); PG8_STAGE(PG8_SB(1, 0), b3, voffB);
;             PG8_BAR; PG8_WAIT_L(0); PG8_MMA(0, 1, At, B1); PG8_BAR;
;             PG8_LDA(At, 1, 1); PG8_STAGE(PG8_SA(1, 0), a3, voffA);
	s_add_u32 s70, s46, 0x200000
	s_addc_u32 s71, s47, 0
	s_add_i32 s23, s23, s27
	v_lshl_add_u64 v[130:131], s[70:71], 0, v[174:175]
	s_mov_b32 m0, s23
	s_nop 0
	global_load_lds_dwordx4 v[130:131], off
	v_lshl_add_u64 v[130:131], s[70:71], 0, v[170:171]
	s_add_i32 m0, s23, 0x2000
	s_nop 0
	global_load_lds_dwordx4 v[130:131], off
	s_waitcnt vmcnt(6)
	s_barrier
	v_mfma_f32_16x16x32_bf16 v[54:57], v[220:223], v[146:149], v[54:57]
	v_mfma_f32_16x16x32_bf16 v[50:53], v[228:231], v[146:149], v[50:53]
	v_mfma_f32_16x16x32_bf16 v[38:41], v[220:223], v[182:185], v[38:41]
	v_mfma_f32_16x16x32_bf16 v[34:37], v[228:231], v[182:185], v[34:37]
	v_mfma_f32_16x16x32_bf16 v[22:25], v[220:223], v[190:193], v[22:25]
	v_mfma_f32_16x16x32_bf16 v[18:21], v[228:231], v[190:193], v[18:21]
	v_mfma_f32_16x16x32_bf16 v[6:9], v[220:223], v[212:215], v[6:9]
	v_mfma_f32_16x16x32_bf16 v[2:5], v[228:231], v[212:215], v[2:5]
	v_mfma_f32_16x16x32_bf16 v[54:57], v[224:227], v[150:153], v[54:57]
	v_mfma_f32_16x16x32_bf16 v[50:53], v[232:235], v[150:153], v[50:53]
	v_mfma_f32_16x16x32_bf16 v[38:41], v[224:227], v[186:189], v[38:41]
	v_mfma_f32_16x16x32_bf16 v[34:37], v[232:235], v[186:189], v[34:37]
	v_mfma_f32_16x16x32_bf16 v[22:25], v[224:227], v[194:197], v[22:25]
	v_mfma_f32_16x16x32_bf16 v[18:21], v[232:235], v[194:197], v[18:21]
	v_mfma_f32_16x16x32_bf16 v[6:9], v[224:227], v[216:219], v[6:9]
	v_mfma_f32_16x16x32_bf16 v[2:5], v[232:235], v[216:219], v[2:5]
	s_add_i32 s23, 0, 0x18000
	v_add_u32_e32 v142, s23, v162
	s_barrier
	ds_read_b128 v[130:133], v142
	ds_read_b128 v[134:137], v142 offset:1024
	ds_read_b128 v[138:141], v142 offset:2048
	ds_read_b128 v[142:145], v142 offset:3072
	s_add_u32 s48, s48, 0x200000
	s_addc_u32 s49, s49, 0
	s_mov_b32 m0, s51
	v_lshl_add_u64 v[220:221], s[48:49], 0, v[176:177]
	ds_read_b128 v[146:149], v210 offset:32768
	ds_read_b128 v[150:153], v210 offset:33792
	ds_read_b128 v[182:185], v210 offset:34816
	ds_read_b128 v[186:189], v210 offset:35840
	ds_read_b128 v[190:193], v210 offset:36864
	ds_read_b128 v[194:197], v210 offset:37888
	ds_read_b128 v[212:215], v210 offset:38912
	ds_read_b128 v[216:219], v210 offset:39936
	global_load_lds_dwordx4 v[220:221], off
	v_lshl_add_u64 v[220:221], s[48:49], 0, v[172:173]
	s_mov_b32 m0, s52
	s_nop 0
	global_load_lds_dwordx4 v[220:221], off
	s_waitcnt lgkmcnt(8)
	s_barrier
	s_waitcnt lgkmcnt(0)
	s_waitcnt lgkmcnt(0)
	v_mfma_f32_16x16x32_bf16 v[126:129], v[130:133], v[146:149], v[126:129]
	v_mfma_f32_16x16x32_bf16 v[122:125], v[138:141], v[146:149], v[122:125]
	v_mfma_f32_16x16x32_bf16 v[110:113], v[130:133], v[182:185], v[110:113]
	v_mfma_f32_16x16x32_bf16 v[106:109], v[138:141], v[182:185], v[106:109]
	v_mfma_f32_16x16x32_bf16 v[94:97], v[130:133], v[190:193], v[94:97]
	v_mfma_f32_16x16x32_bf16 v[90:93], v[138:141], v[190:193], v[90:93]
	v_mfma_f32_16x16x32_bf16 v[78:81], v[130:133], v[212:215], v[78:81]
	v_mfma_f32_16x16x32_bf16 v[74:77], v[138:141], v[212:215], v[74:77]
	v_mfma_f32_16x16x32_bf16 v[126:129], v[134:137], v[150:153], v[126:129]
	v_mfma_f32_16x16x32_bf16 v[122:125], v[142:145], v[150:153], v[122:125]
	v_mfma_f32_16x16x32_bf16 v[110:113], v[134:137], v[186:189], v[110:113]
	v_mfma_f32_16x16x32_bf16 v[106:109], v[142:145], v[186:189], v[106:109]
	v_mfma_f32_16x16x32_bf16 v[94:97], v[134:137], v[194:197], v[94:97]
	v_mfma_f32_16x16x32_bf16 v[90:93], v[142:145], v[194:197], v[90:93]
	v_mfma_f32_16x16x32_bf16 v[78:81], v[134:137], v[216:219], v[78:81]
	v_mfma_f32_16x16x32_bf16 v[74:77], v[142:145], v[216:219], v[74:77]
	s_barrier
	s_add_i32 s48, 0, 0x1c000
	s_add_i32 s23, s23, s27
	v_add_u32_e32 v211, s48, v162
	v_lshl_add_u64 v[198:199], v[198:199], 0, s[10:11]
	s_mov_b32 m0, s23
	ds_read_b128 v[220:223], v211
	ds_read_b128 v[224:227], v211 offset:1024
	ds_read_b128 v[228:231], v211 offset:2048
	ds_read_b128 v[232:235], v211 offset:3072
	global_load_lds_dwordx4 v[198:199], off
	v_lshl_add_u64 v[198:199], v[236:237], 0, s[10:11]
	s_add_i32 m0, s23, 0x2000
	s_nop 0
	global_load_lds_dwordx4 v[198:199], off
	s_barrier
	s_waitcnt lgkmcnt(0)
	s_waitcnt lgkmcnt(0)
	v_mfma_f32_16x16x32_bf16 v[118:121], v[220:223], v[146:149], v[118:121]
	v_mfma_f32_16x16x32_bf16 v[114:117], v[228:231], v[146:149], v[114:117]
	v_mfma_f32_16x16x32_bf16 v[102:105], v[220:223], v[182:185], v[102:105]
	v_mfma_f32_16x16x32_bf16 v[98:101], v[228:231], v[182:185], v[98:101]
	v_mfma_f32_16x16x32_bf16 v[86:89], v[220:223], v[190:193], v[86:89]
	v_mfma_f32_16x16x32_bf16 v[82:85], v[228:231], v[190:193], v[82:85]
	v_mfma_f32_16x16x32_bf16 v[70:73], v[220:223], v[212:215], v[70:73]
	v_mfma_f32_16x16x32_bf16 v[66:69], v[228:231], v[212:215], v[66:69]
	v_mfma_f32_16x16x32_bf16 v[118:121], v[224:227], v[150:153], v[118:121]
	v_mfma_f32_16x16x32_bf16 v[114:117], v[232:235], v[150:153], v[114:117]
	v_mfma_f32_16x16x32_bf16 v[102:105], v[224:227], v[186:189], v[102:105]
	v_mfma_f32_16x16x32_bf16 v[98:101], v[232:235], v[186:189], v[98:101]
	v_mfma_f32_16x16x32_bf16 v[86:89], v[224:227], v[194:197], v[86:89]
	v_mfma_f32_16x16x32_bf16 v[82:85], v[232:235], v[194:197], v[82:85]
	v_mfma_f32_16x16x32_bf16 v[70:73], v[224:227], v[216:219], v[70:73]
	v_mfma_f32_16x16x32_bf16 v[66:69], v[232:235], v[216:219], v[66:69]
	s_mov_b32 m0, s28
	v_lshl_add_u64 v[198:199], v[238:239], 0, s[10:11]
	s_barrier
	ds_read_b128 v[146:149], v210 offset:49152
	ds_read_b128 v[150:153], v210 offset:50176
	ds_read_b128 v[182:185], v210 offset:51200
	ds_read_b128 v[186:189], v210 offset:52224
	ds_read_b128 v[190:193], v210 offset:53248
	ds_read_b128 v[194:197], v210 offset:54272
	ds_read_b128 v[212:215], v210 offset:55296
	ds_read_b128 v[216:219], v210 offset:56320
	global_load_lds_dwordx4 v[198:199], off
	v_lshl_add_u64 v[198:199], v[240:241], 0, s[10:11]
	s_mov_b32 m0, s29
	s_nop 0
	global_load_lds_dwordx4 v[198:199], off
	s_barrier
; #define PG8_STAGE(bufoff, gbase, voff) do { _Pragma("unroll") for (int _i = 0; _i < 2; ++_i) \
;         __builtin_amdgcn_global_load_lds((const unsigned*)((const char*)(gbase) + (voff)[_i]), (LAS unsigned*)(lds + (bufoff) + ldsw + _i * 8192), 16, 0, 0); } while (0)
; #define PG8_MMA(ai, bj, At, Bt) do { __builtin_amdgcn_s_setprio(1); _Pragma("unroll") for (int m = 0; m < 4; ++m) _Pragma("unroll") for (int n = 0; n < 2; ++n) _Pragma("unroll") for (int k = 0; k < 2; ++k) \
;         acc[ai][bj][m][n] = __builtin_amdgcn_mfma_f32_16x16x32_bf16(Bt[n][k], At[m][k], acc[ai][bj][m][n], 0, 0, 0); __builtin_amdgcn_s_setprio(0); } while (0)
; #define PG8_WAIT_V(n) asm volatile("s_waitcnt vmcnt(" #n ")" ::: "memory")
; #define PG8_WAIT_L(n) asm volatile("s_waitcnt lgkmcnt(" #n ")" ::: "memory")
; #define PG8_BAR __builtin_amdgcn_s_barrier()
; #define PG8_SCHED __builtin_amdgcn_sched_barrier(0)
; template <class Epi, class Sched>
; __device__ __forceinline__ void gemm_phase(LAS unsigned char* lds, const Gemm g, const Sched& S, const Epi& E) {
;     ...
;             PG8_BAR; PG8_WAIT_L(0); PG8_MMA(1, 0, At, B0); PG8_BAR; PG8_SCHED;
;             PG8_STAGE(PG8_SB(1, 1), b3 + hstepB, voffB);
;             PG8_WAIT_V(6); PG8_BAR; PG8_MMA(1, 1, At, B1); PG8_BAR;
	s_waitcnt lgkmcnt(0)
	s_waitcnt lgkmcnt(0)
	v_mfma_f32_16x16x32_bf16 v[62:65], v[130:133], v[146:149], v[62:65]
	v_mfma_f32_16x16x32_bf16 v[58:61], v[138:141], v[146:149], v[58:61]
	v_mfma_f32_16x16x32_bf16 v[46:49], v[130:133], v[182:185], v[46:49]
	v_mfma_f32_16x16x32_bf16 v[42:45], v[138:141], v[182:185], v[42:45]
	v_mfma_f32_16x16x32_bf16 v[30:33], v[130:133], v[190:193], v[30:33]
	v_mfma_f32_16x16x32_bf16 v[26:29], v[138:141], v[190:193], v[26:29]
	v_mfma_f32_16x16x32_bf16 v[14:17], v[130:133], v[212:215], v[14:17]
	v_mfma_f32_16x16x32_bf16 v[10:13], v[138:141], v[212:215], v[10:13]
	v_mfma_f32_16x16x32_bf16 v[62:65], v[134:137], v[150:153], v[62:65]
	v_mfma_f32_16x16x32_bf16 v[58:61], v[142:145], v[150:153], v[58:61]
	v_mfma_f32_16x16x32_bf16 v[46:49], v[134:137], v[186:189], v[46:49]
	v_mfma_f32_16x16x32_bf16 v[42:45], v[142:145], v[186:189], v[42:45]
	v_mfma_f32_16x16x32_bf16 v[30:33], v[134:137], v[194:197], v[30:33]
	v_mfma_f32_16x16x32_bf16 v[26:29], v[142:145], v[194:197], v[26:29]
	v_mfma_f32_16x16x32_bf16 v[14:17], v[134:137], v[216:219], v[14:17]
	v_mfma_f32_16x16x32_bf16 v[10:13], v[142:145], v[216:219], v[10:13]
	s_barrier
	s_add_u32 s46, s46, 0x200080
	s_addc_u32 s47, s47, 0
	s_add_i32 s23, s48, s27
	v_lshl_add_u64 v[130:131], s[46:47], 0, v[174:175]
	s_mov_b32 m0, s23
	s_nop 0
	global_load_lds_dwordx4 v[130:131], off
	v_lshl_add_u64 v[130:131], s[46:47], 0, v[170:171]
	s_add_i32 m0, s23, 0x2000
	s_nop 0
	global_load_lds_dwordx4 v[130:131], off
	s_waitcnt vmcnt(6)
	s_barrier
	v_mfma_f32_16x16x32_bf16 v[54:57], v[220:223], v[146:149], v[54:57]
	v_mfma_f32_16x16x32_bf16 v[50:53], v[228:231], v[146:149], v[50:53]
	v_mfma_f32_16x16x32_bf16 v[38:41], v[220:223], v[182:185], v[38:41]
	v_mfma_f32_16x16x32_bf16 v[34:37], v[228:231], v[182:185], v[34:37]
	v_mfma_f32_16x16x32_bf16 v[22:25], v[220:223], v[190:193], v[22:25]
	v_mfma_f32_16x16x32_bf16 v[18:21], v[228:231], v[190:193], v[18:21]
	v_mfma_f32_16x16x32_bf16 v[6:9], v[220:223], v[212:215], v[6:9]
	v_mfma_f32_16x16x32_bf16 v[2:5], v[228:231], v[212:215], v[2:5]
	v_mfma_f32_16x16x32_bf16 v[54:57], v[224:227], v[150:153], v[54:57]
	v_mfma_f32_16x16x32_bf16 v[50:53], v[232:235], v[150:153], v[50:53]
	v_mfma_f32_16x16x32_bf16 v[38:41], v[224:227], v[186:189], v[38:41]
	v_mfma_f32_16x16x32_bf16 v[34:37], v[232:235], v[186:189], v[34:37]
	v_mfma_f32_16x16x32_bf16 v[22:25], v[224:227], v[194:197], v[22:25]
	v_mfma_f32_16x16x32_bf16 v[18:21], v[232:235], v[194:197], v[18:21]
	v_mfma_f32_16x16x32_bf16 v[6:9], v[224:227], v[216:219], v[6:9]
	v_mfma_f32_16x16x32_bf16 v[2:5], v[232:235], v[216:219], v[2:5]
	s_add_i32 s66, s66, 2
	s_add_u32 s44, s44, 0x100
	s_addc_u32 s45, s45, 0
	s_add_u32 s59, s59, 0x100
	s_addc_u32 s68, s68, 0
	s_cmpk_gt_u32 s66, 0x7d
	s_barrier
	s_cbranch_scc0 .LBB0_899
; __device__ __forceinline__ unsigned cvt_pk_bf16(float lo, float hi) { unsigned r; asm volatile("v_cvt_pk_bf16_f32 %0, %1, %2" : "=v"(r) : "v"(lo), "v"(hi)); return r; }
; __device__ __forceinline__ float bf_lo(unsigned w) { return __uint_as_float(w << 16); }
; __device__ __forceinline__ float bf_hi(unsigned w) { return __uint_as_float(w & 0xffff0000u); }
;     __device__ __forceinline__ void operator()(const f32x4 (&acc)[2][2][4][2], const Unit& u, int ui, const LAS float* rtab, int wr, int wc, int fr, int fq) const {
;         const int row0 = u.pm * BM + wr * 64 + fr, col0 = u.pn * BM + wc * 32 + 8 * fq;
; #pragma unroll
;         for (int ai = 0; ai < 2; ++ai) {
;             u32x4 xv[4][2];
; #pragma unroll
;             for (int m = 0; m < 4; ++m)
; #pragma unroll
;                 for (int bj = 0; bj < 2; ++bj) xv[m][bj] = *(const u32x4*)(XB + (size_t)(row0 + ai * HALF + m * 16) * DM + col0 + bj * HALF);
; #pragma unroll
;             for (int m = 0; m < 4; ++m) { const int row = row0 + ai * HALF + m * 16; float ss = 0.f;
; #pragma unroll
;                 for (int bj = 0; bj < 2; ++bj) {
;                     const f32x4 a0 = acc[ai][bj][m][0], a1 = acc[ai][bj][m][1]; const u32x4 xo = xv[m][bj]; u32x4 w;
;                     w.x = cvt_pk_bf16(bf_lo(xo.x) + a0[0], bf_hi(xo.x) + a0[1]); w.y = cvt_pk_bf16(bf_lo(xo.y) + a0[2], bf_hi(xo.y) + a0[3]);
;                     w.z = cvt_pk_bf16(bf_lo(xo.z) + a1[0], bf_hi(xo.z) + a1[1]); w.w = cvt_pk_bf16(bf_lo(xo.w) + a1[2], bf_hi(xo.w) + a1[3]);
;                     *(u32x4*)(XB + (size_t)row * DM + col0 + bj * HALF) = w;
; #pragma unroll
;                     for (int e = 0; e < 4; ++e) { const float lo = bf_lo(w[e]), hi = bf_hi(w[e]); ss += lo * lo + hi * hi; }
;                 }
;                 ss += __shfl_xor(ss, 16); ss += __shfl_xor(ss, 32);
;                 if (fq == 0) ssq_next[(size_t)row * 32 + (u.pn & 7) * 4 + wc] = ss; }
	v_lshl_or_b32 v182, s55, 8, v209
	v_lshl_add_u32 v186, s56, 8, v1
	v_ashrrev_i32_e32 v183, 31, v182
	v_lshlrev_b64 v[130:131], 1, v[182:183]
	v_ashrrev_i32_e32 v187, 31, v186
	v_lshl_add_u64 v[184:185], s[74:75], 0, v[130:131]
	v_lshlrev_b64 v[132:133], 12, v[186:187]
	v_lshl_add_u64 v[134:135], v[184:185], 0, v[132:133]
	global_load_dwordx4 v[212:215], v[134:135], off
	global_load_dwordx4 v[216:219], v[134:135], off offset:256
	v_or_b32_e32 v196, 16, v186
	v_or_b32_e32 v192, 32, v186
	v_or_b32_e32 v188, 48, v186
	v_ashrrev_i32_e32 v197, 31, v196
	v_ashrrev_i32_e32 v193, 31, v192
	v_ashrrev_i32_e32 v189, 31, v188
	v_lshlrev_b64 v[198:199], 12, v[196:197]
	v_lshlrev_b64 v[194:195], 12, v[192:193]
	v_lshlrev_b64 v[190:191], 12, v[188:189]
	v_lshl_add_u64 v[132:133], s[74:75], 0, v[132:133]
	v_lshl_add_u64 v[134:135], v[184:185], 0, v[198:199]
	v_lshl_add_u64 v[136:137], v[184:185], 0, v[194:195]
	v_lshl_add_u64 v[220:221], v[184:185], 0, v[190:191]
	v_lshl_add_u64 v[222:223], v[132:133], 0, v[130:131]
	global_load_dwordx4 v[150:153], v[134:135], off
	global_load_dwordx4 v[146:149], v[134:135], off offset:256
	global_load_dwordx4 v[142:145], v[136:137], off
	global_load_dwordx4 v[138:141], v[136:137], off offset:256
	s_nop 0
	global_load_dwordx4 v[134:137], v[220:221], off
	global_load_dwordx4 v[130:133], v[220:221], off offset:256
	s_lshl_b32 s21, s55, 2
	s_and_b32 s21, s21, 28
	s_waitcnt vmcnt(0)
	v_lshlrev_b32_e32 v211, 16, v212
	v_and_b32_e32 v212, 0xffff0000, v212
	v_lshlrev_b32_e32 v220, 16, v213
	v_and_b32_e32 v213, 0xffff0000, v213
	v_lshlrev_b32_e32 v221, 16, v214
	v_and_b32_e32 v214, 0xffff0000, v214
	v_lshlrev_b32_e32 v227, 16, v218
	v_and_b32_e32 v218, 0xffff0000, v218
	v_lshlrev_b32_e32 v224, 16, v215
	v_and_b32_e32 v215, 0xffff0000, v215
	v_lshlrev_b32_e32 v228, 16, v219
	v_and_b32_e32 v219, 0xffff0000, v219
	v_add_f32_e32 v126, v126, v211
	v_add_f32_e32 v127, v127, v212
	v_add_f32_e32 v128, v128, v220
	v_add_f32_e32 v129, v129, v213
	v_add_f32_e32 v122, v122, v221
	v_add_f32_e32 v123, v123, v214
	v_add_f32_e32 v211, v114, v227
	v_add_f32_e32 v212, v115, v218
	v_cvt_pk_bf16_f32 v114, v126, v127
	v_cvt_pk_bf16_f32 v115, v128, v129
	v_add_f32_e32 v124, v124, v224
	v_add_f32_e32 v125, v125, v215
	v_add_f32_e32 v213, v116, v228
	v_add_f32_e32 v214, v117, v219
	v_cvt_pk_bf16_f32 v116, v122, v123
	v_cvt_pk_bf16_f32 v117, v124, v125
	global_store_dwordx4 v[222:223], v[114:117], off
	v_lshlrev_b32_e32 v122, 16, v114
	v_lshlrev_b32_e32 v123, 16, v115
	v_and_b32_e32 v114, 0xffff0000, v114
	v_and_b32_e32 v115, 0xffff0000, v115
	v_lshlrev_b32_e32 v225, 16, v216
	v_lshlrev_b32_e32 v124, 16, v116
	v_and_b32_e32 v116, 0xffff0000, v116
	v_mul_f32_e32 v114, v114, v114
	v_mul_f32_e32 v115, v115, v115
	v_and_b32_e32 v216, 0xffff0000, v216
	v_add_f32_e32 v118, v118, v225
	v_lshlrev_b32_e32 v125, 16, v117
	v_and_b32_e32 v117, 0xffff0000, v117
	v_mul_f32_e32 v116, v116, v116
	v_fmac_f32_e32 v114, v122, v122
	v_fmac_f32_e32 v115, v123, v123
	v_lshlrev_b32_e32 v226, 16, v217
	v_and_b32_e32 v217, 0xffff0000, v217
	v_add_f32_e32 v119, v119, v216
	v_cvt_pk_bf16_f32 v118, v118, v119
	v_mul_f32_e32 v117, v117, v117
	v_and_b32_e32 v127, 0xffff0000, v118
	v_fmac_f32_e32 v116, v124, v124
	v_add_f32_e32 v114, v114, v115
	v_add_f32_e32 v120, v120, v226
	v_add_f32_e32 v121, v121, v217
	v_cvt_pk_bf16_f32 v119, v120, v121
	v_lshlrev_b32_e32 v126, 16, v118
	v_fmac_f32_e32 v117, v125, v125
	v_mul_f32_e32 v122, v127, v127
	v_add_f32_e32 v114, v114, v116
	v_and_b32_e32 v116, 0xffff0000, v119
	v_fmac_f32_e32 v122, v126, v126
	v_add_f32_e32 v114, v114, v117
	v_lshlrev_b32_e32 v115, 16, v119
	v_mul_f32_e32 v116, v116, v116
	v_add_f32_e32 v114, v114, v122
	v_fmac_f32_e32 v116, v115, v115
	v_cvt_pk_bf16_f32 v120, v211, v212
	v_add_f32_e32 v114, v114, v116
	v_and_b32_e32 v116, 0xffff0000, v120
	v_lshlrev_b32_e32 v115, 16, v120
	v_mul_f32_e32 v116, v116, v116
	v_fmac_f32_e32 v116, v115, v115
	v_cvt_pk_bf16_f32 v121, v213, v214
	v_add_f32_e32 v114, v114, v116
	v_and_b32_e32 v116, 0xffff0000, v121
	v_lshlrev_b32_e32 v115, 16, v121
	v_mul_f32_e32 v116, v116, v116
	v_fmac_f32_e32 v116, v115, v115
	v_add_f32_e32 v115, v114, v116
	v_and_b32_e32 v116, 64, v207
	v_xor_b32_e32 v114, 16, v207
	v_add_u32_e32 v117, 64, v116
	v_cmp_lt_i32_e32 vcc, v114, v117
	global_store_dwordx4 v[222:223], v[118:121], off offset:256
	s_nop 0
	v_cndmask_b32_e32 v114, v207, v114, vcc
	v_lshlrev_b32_e32 v114, 2, v114
	ds_bpermute_b32 v116, v114, v115
	s_waitcnt lgkmcnt(0)
	v_add_f32_e32 v116, v115, v116
	v_xor_b32_e32 v115, 32, v207
	v_cmp_lt_i32_e32 vcc, v115, v117
	s_nop 1
	v_cndmask_b32_e32 v115, v207, v115, vcc
	v_lshlrev_b32_e32 v115, 2, v115
	ds_bpermute_b32 v117, v115, v116
	s_and_saveexec_b64 s[44:45], s[40:41]
	s_cbranch_execz .LBB0_902
	s_waitcnt lgkmcnt(0)
	v_add_f32_e32 v118, v116, v117
	v_lshlrev_b64 v[116:117], 7, v[186:187]
	v_lshl_add_u64 v[116:117], s[0:1], 0, v[116:117]
	s_lshl_b32 s68, s21, 2
	v_lshl_add_u64 v[116:117], v[116:117], 0, s[68:69]
	s_lshl_b32 s68, s53, 2
	v_lshl_add_u64 v[116:117], v[116:117], 0, s[68:69]
	global_store_dword v[116:117], v118, off
